# speedup vs baseline: 1.0078x; 1.0033x over previous
; #define PG8_STAGE(bufoff, gbase, voff) do { _Pragma("unroll") for (int _i = 0; _i < 2; ++_i) \
;         __builtin_amdgcn_global_load_lds((const unsigned*)((const char*)(gbase) + (voff)[_i]), (PG8_LAS unsigned*)(lds + (bufoff) + ldsw + _i * 8192), 16, 0, 0); } while (0)
; #define PG8_LDA(dst, b, h) do { _Pragma("unroll") for (int m = 0; m < 4; ++m) _Pragma("unroll") for (int k = 0; k < 2; ++k) dst[m][k] = *(const PG8_LAS bf16x8*)(lds + PG8_SA(b, h) + aoff + m * 2048 + k * 1024); } while (0)
; #define PG8_LDB(dst, b, h) do { _Pragma("unroll") for (int n = 0; n < 2; ++n) _Pragma("unroll") for (int k = 0; k < 2; ++k) dst[n][k] = *(const PG8_LAS bf16x8*)(lds + PG8_SB(b, h) + boff + n * 2048 + k * 1024); } while (0)
; #define PG8_MMA(ai, bj, At, Bt) do { __builtin_amdgcn_s_setprio(1); _Pragma("unroll") for (int m = 0; m < 4; ++m) _Pragma("unroll") for (int n = 0; n < 2; ++n) _Pragma("unroll") for (int k = 0; k < 2; ++k) \
;         acc[ai][bj][m][n] = __builtin_amdgcn_mfma_f32_16x16x32_bf16(Bt[n][k], At[m][k], acc[ai][bj][m][n], 0, 0, 0); __builtin_amdgcn_s_setprio(0); } while (0)
; #define PG8_WAIT_V(n) asm volatile("s_waitcnt vmcnt(" #n ")" ::: "memory")
; #define PG8_WAIT_L(n) asm volatile("s_waitcnt lgkmcnt(" #n ")" ::: "memory")
; #define PG8_BAR __builtin_amdgcn_s_barrier()
; #define PG8_SCHED __builtin_amdgcn_sched_barrier(0)
; template <class Epi, class Sched, bool ALIGN_EPI = false, bool SP2 = false>
; __device__ __forceinline__ void gemm_phase(PG8_LAS unsigned char* lds, const Gemm g, const Sched& S, const Epi& E) {
;     ...
;         for (int t = 0; t < nt; t += 2) {
;             const bool last = (t == nt - 2);
;             const char* a1 = cA + (size_t)(t + 1) * kstep;
;             const char* a2 = last ? nA : cA + (size_t)(t + 2) * kstep; const char* b2 = last ? nB : cB + (size_t)(t + 2) * kstep;
;             const char* a3 = a2 + kstep; const char* b3 = b2 + kstep;
;             if (last && has_next) S.a_ready(nxt);
;             if constexpr (SP2) {
;             PG8_LDB(B0, 0, 0); PG8_LDB(B1, 0, 1); PG8_SCHED; PG8_LDA(At, 0, 0); PG8_STAGE(PG8_SA(1, 1), a1 + hstep, voffA);
;             PG8_WAIT_V(8); PG8_WAIT_L(0); PG8_BAR; PG8_MMA(0, 0, At, B0); PG8_MMA(0, 1, At, B1); PG8_BAR; PG8_SCHED;
;             PG8_LDA(At, 0, 1); PG8_STAGE(PG8_SB(0, 0), b2, voffB); PG8_STAGE(PG8_SB(0, 1), b2 + hstep, voffB); PG8_STAGE(PG8_SA(0, 0), a2, voffA);
.LBB0_121:
	ds_read_b128 v[148:151], v159
	ds_read_b128 v[168:171], v159 offset:1024
	ds_read_b128 v[172:175], v159 offset:2048
	ds_read_b128 v[176:179], v159 offset:3072
	ds_read_b128 v[180:183], v160
	ds_read_b128 v[184:187], v160 offset:1024
	ds_read_b128 v[188:191], v160 offset:2048
	ds_read_b128 v[192:195], v160 offset:3072
	s_add_i32 s46, s42, 2
	s_add_u32 s47, s6, 0x80
	s_addc_u32 s43, s7, 0
	s_cmp_eq_u32 s93, s42
	s_cselect_b32 s42, s38, s47
	s_cselect_b32 s43, s39, s43
	s_cselect_b32 s69, s41, vcc_lo
	s_cselect_b32 s68, s40, s0
	v_lshl_add_u64 v[152:153], s[6:7], 0, v[142:143]
	s_add_i32 m0, s64, 0xc000
	ds_read_b128 v[196:199], v161
	ds_read_b128 v[200:203], v161 offset:1024
	ds_read_b128 v[204:207], v161 offset:2048
	ds_read_b128 v[208:211], v161 offset:3072
	ds_read_b128 v[212:215], v161 offset:4096
	ds_read_b128 v[216:219], v161 offset:5120
	ds_read_b128 v[220:223], v161 offset:6144
	ds_read_b128 v[224:227], v161 offset:7168
	global_load_lds_dwordx4 v[152:153], off
	v_lshl_add_u64 v[152:153], s[6:7], 0, v[140:141]
	s_add_i32 m0, s64, 0xe000
	s_nop 0
	global_load_lds_dwordx4 v[152:153], off
	s_waitcnt vmcnt(8)
	s_waitcnt lgkmcnt(0)
	s_barrier
	v_mfma_f32_16x16x32_bf16 v[126:129], v[148:151], v[196:199], v[126:129]
	v_mfma_f32_16x16x32_bf16 v[122:125], v[172:175], v[196:199], v[122:125]
	v_mfma_f32_16x16x32_bf16 v[110:113], v[148:151], v[204:207], v[110:113]
	v_mfma_f32_16x16x32_bf16 v[106:109], v[172:175], v[204:207], v[106:109]
	v_mfma_f32_16x16x32_bf16 v[94:97], v[148:151], v[212:215], v[94:97]
	v_mfma_f32_16x16x32_bf16 v[90:93], v[172:175], v[212:215], v[90:93]
	v_mfma_f32_16x16x32_bf16 v[78:81], v[148:151], v[220:223], v[78:81]
	v_mfma_f32_16x16x32_bf16 v[74:77], v[172:175], v[220:223], v[74:77]
	v_mfma_f32_16x16x32_bf16 v[126:129], v[168:171], v[200:203], v[126:129]
	v_mfma_f32_16x16x32_bf16 v[122:125], v[176:179], v[200:203], v[122:125]
	v_mfma_f32_16x16x32_bf16 v[110:113], v[168:171], v[208:211], v[110:113]
	v_mfma_f32_16x16x32_bf16 v[106:109], v[176:179], v[208:211], v[106:109]
	v_mfma_f32_16x16x32_bf16 v[94:97], v[168:171], v[216:219], v[94:97]
	v_mfma_f32_16x16x32_bf16 v[90:93], v[176:179], v[216:219], v[90:93]
	v_mfma_f32_16x16x32_bf16 v[78:81], v[168:171], v[224:227], v[78:81]
	v_mfma_f32_16x16x32_bf16 v[74:77], v[176:179], v[224:227], v[74:77]
	v_mfma_f32_16x16x32_bf16 v[118:121], v[180:183], v[196:199], v[118:121]
	v_mfma_f32_16x16x32_bf16 v[114:117], v[188:191], v[196:199], v[114:117]
	v_mfma_f32_16x16x32_bf16 v[102:105], v[180:183], v[204:207], v[102:105]
	v_mfma_f32_16x16x32_bf16 v[98:101], v[188:191], v[204:207], v[98:101]
	v_mfma_f32_16x16x32_bf16 v[86:89], v[180:183], v[212:215], v[86:89]
	v_mfma_f32_16x16x32_bf16 v[82:85], v[188:191], v[212:215], v[82:85]
	v_mfma_f32_16x16x32_bf16 v[70:73], v[180:183], v[220:223], v[70:73]
	v_mfma_f32_16x16x32_bf16 v[66:69], v[188:191], v[220:223], v[66:69]
	v_mfma_f32_16x16x32_bf16 v[118:121], v[184:187], v[200:203], v[118:121]
	v_mfma_f32_16x16x32_bf16 v[114:117], v[192:195], v[200:203], v[114:117]
	v_mfma_f32_16x16x32_bf16 v[102:105], v[184:187], v[208:211], v[102:105]
	v_mfma_f32_16x16x32_bf16 v[98:101], v[192:195], v[208:211], v[98:101]
	v_mfma_f32_16x16x32_bf16 v[86:89], v[184:187], v[216:219], v[86:89]
	v_mfma_f32_16x16x32_bf16 v[82:85], v[192:195], v[216:219], v[82:85]
	v_mfma_f32_16x16x32_bf16 v[70:73], v[184:187], v[224:227], v[70:73]
	v_mfma_f32_16x16x32_bf16 v[66:69], v[192:195], v[224:227], v[66:69]
	s_barrier
	s_add_i32 s47, s97, s55
	v_lshl_add_u64 v[152:153], s[68:69], 0, v[132:133]
	s_mov_b32 m0, s47
	ds_read_b128 v[196:199], v161 offset:16384
	ds_read_b128 v[200:203], v161 offset:17408
	ds_read_b128 v[204:207], v161 offset:18432
	ds_read_b128 v[208:211], v161 offset:19456
	ds_read_b128 v[212:215], v161 offset:20480
	ds_read_b128 v[216:219], v161 offset:21504
	ds_read_b128 v[220:223], v161 offset:22528
	ds_read_b128 v[224:227], v161 offset:23552
	global_load_lds_dwordx4 v[152:153], off
	s_add_i32 m0, s47, 0x2000
	v_lshl_add_u64 v[228:229], s[68:69], 0, v[136:137]
	s_add_u32 s68, s68, s10
	s_addc_u32 s69, s69, s11
	s_add_i32 s47, s80, s55
	global_load_lds_dwordx4 v[228:229], off
	v_lshl_add_u64 v[230:231], s[68:69], 0, v[132:133]
	s_mov_b32 m0, s47
	v_lshl_add_u64 v[232:233], s[68:69], 0, v[136:137]
	global_load_lds_dwordx4 v[230:231], off
	s_add_i32 m0, s47, 0x2000
	v_lshl_add_u64 v[234:235], s[42:43], 0, v[130:131]
	global_load_lds_dwordx4 v[232:233], off
	s_mov_b32 m0, s64
	v_lshl_add_u64 v[236:237], s[42:43], 0, v[134:135]
	global_load_lds_dwordx4 v[234:235], off
	s_mov_b32 m0, s65
	s_nop 0
	global_load_lds_dwordx4 v[236:237], off
	s_waitcnt vmcnt(8)
	s_waitcnt lgkmcnt(0)
	s_barrier
; #define PG8_STAGE(bufoff, gbase, voff) do { _Pragma("unroll") for (int _i = 0; _i < 2; ++_i) \
;         __builtin_amdgcn_global_load_lds((const unsigned*)((const char*)(gbase) + (voff)[_i]), (PG8_LAS unsigned*)(lds + (bufoff) + ldsw + _i * 8192), 16, 0, 0); } while (0)
; #define PG8_LDA(dst, b, h) do { _Pragma("unroll") for (int m = 0; m < 4; ++m) _Pragma("unroll") for (int k = 0; k < 2; ++k) dst[m][k] = *(const PG8_LAS bf16x8*)(lds + PG8_SA(b, h) + aoff + m * 2048 + k * 1024); } while (0)
; #define PG8_LDB(dst, b, h) do { _Pragma("unroll") for (int n = 0; n < 2; ++n) _Pragma("unroll") for (int k = 0; k < 2; ++k) dst[n][k] = *(const PG8_LAS bf16x8*)(lds + PG8_SB(b, h) + boff + n * 2048 + k * 1024); } while (0)
; #define PG8_MMA(ai, bj, At, Bt) do { __builtin_amdgcn_s_setprio(1); _Pragma("unroll") for (int m = 0; m < 4; ++m) _Pragma("unroll") for (int n = 0; n < 2; ++n) _Pragma("unroll") for (int k = 0; k < 2; ++k) \
;         acc[ai][bj][m][n] = __builtin_amdgcn_mfma_f32_16x16x32_bf16(Bt[n][k], At[m][k], acc[ai][bj][m][n], 0, 0, 0); __builtin_amdgcn_s_setprio(0); } while (0)
; #define PG8_WAIT_V(n) asm volatile("s_waitcnt vmcnt(" #n ")" ::: "memory")
; #define PG8_WAIT_L(n) asm volatile("s_waitcnt lgkmcnt(" #n ")" ::: "memory")
; #define PG8_BAR __builtin_amdgcn_s_barrier()
; #define PG8_SCHED __builtin_amdgcn_sched_barrier(0)
; template <class Epi, class Sched, bool ALIGN_EPI = false, bool SP2 = false>
; __device__ __forceinline__ void gemm_phase(PG8_LAS unsigned char* lds, const Gemm g, const Sched& S, const Epi& E) {
;     ...
;             PG8_WAIT_V(8); PG8_WAIT_L(0); PG8_BAR; PG8_MMA(1, 0, At, B0); PG8_MMA(1, 1, At, B1); PG8_BAR; PG8_SCHED;
;             PG8_LDB(B0, 1, 0); PG8_LDB(B1, 1, 1); PG8_SCHED; PG8_LDA(At, 1, 0); PG8_STAGE(PG8_SA(0, 1), a2 + hstep, voffA);
;             PG8_WAIT_V(8); PG8_WAIT_L(0); PG8_BAR; PG8_MMA(0, 0, At, B0); PG8_MMA(0, 1, At, B1); PG8_BAR; PG8_SCHED;
	v_mfma_f32_16x16x32_bf16 v[62:65], v[148:151], v[196:199], v[62:65]
	v_mfma_f32_16x16x32_bf16 v[58:61], v[172:175], v[196:199], v[58:61]
	v_mfma_f32_16x16x32_bf16 v[46:49], v[148:151], v[204:207], v[46:49]
	v_mfma_f32_16x16x32_bf16 v[42:45], v[172:175], v[204:207], v[42:45]
	v_mfma_f32_16x16x32_bf16 v[30:33], v[148:151], v[212:215], v[30:33]
	v_mfma_f32_16x16x32_bf16 v[26:29], v[172:175], v[212:215], v[26:29]
	v_mfma_f32_16x16x32_bf16 v[14:17], v[148:151], v[220:223], v[14:17]
	v_mfma_f32_16x16x32_bf16 v[10:13], v[172:175], v[220:223], v[10:13]
	v_mfma_f32_16x16x32_bf16 v[62:65], v[168:171], v[200:203], v[62:65]
	v_mfma_f32_16x16x32_bf16 v[58:61], v[176:179], v[200:203], v[58:61]
	v_mfma_f32_16x16x32_bf16 v[46:49], v[168:171], v[208:211], v[46:49]
	v_mfma_f32_16x16x32_bf16 v[42:45], v[176:179], v[208:211], v[42:45]
	v_mfma_f32_16x16x32_bf16 v[30:33], v[168:171], v[216:219], v[30:33]
	v_mfma_f32_16x16x32_bf16 v[26:29], v[176:179], v[216:219], v[26:29]
	v_mfma_f32_16x16x32_bf16 v[14:17], v[168:171], v[224:227], v[14:17]
	v_mfma_f32_16x16x32_bf16 v[10:13], v[176:179], v[224:227], v[10:13]
	v_mfma_f32_16x16x32_bf16 v[54:57], v[180:183], v[196:199], v[54:57]
	v_mfma_f32_16x16x32_bf16 v[50:53], v[188:191], v[196:199], v[50:53]
	v_mfma_f32_16x16x32_bf16 v[38:41], v[180:183], v[204:207], v[38:41]
	v_mfma_f32_16x16x32_bf16 v[34:37], v[188:191], v[204:207], v[34:37]
	v_mfma_f32_16x16x32_bf16 v[22:25], v[180:183], v[212:215], v[22:25]
	v_mfma_f32_16x16x32_bf16 v[18:21], v[188:191], v[212:215], v[18:21]
	v_mfma_f32_16x16x32_bf16 v[6:9], v[180:183], v[220:223], v[6:9]
	v_mfma_f32_16x16x32_bf16 v[2:5], v[188:191], v[220:223], v[2:5]
	v_mfma_f32_16x16x32_bf16 v[54:57], v[184:187], v[200:203], v[54:57]
	v_mfma_f32_16x16x32_bf16 v[50:53], v[192:195], v[200:203], v[50:53]
	v_mfma_f32_16x16x32_bf16 v[38:41], v[184:187], v[208:211], v[38:41]
	v_mfma_f32_16x16x32_bf16 v[34:37], v[192:195], v[208:211], v[34:37]
	v_mfma_f32_16x16x32_bf16 v[22:25], v[184:187], v[216:219], v[22:25]
	v_mfma_f32_16x16x32_bf16 v[18:21], v[192:195], v[216:219], v[18:21]
	v_mfma_f32_16x16x32_bf16 v[6:9], v[184:187], v[224:227], v[6:9]
	v_mfma_f32_16x16x32_bf16 v[2:5], v[192:195], v[224:227], v[2:5]
	s_barrier
	s_add_i32 s47, 0, 0x18000
	v_add_u32_e32 v138, s47, v154
	s_add_i32 s68, 0, 0x1c000
	ds_read_b128 v[148:151], v138
	ds_read_b128 v[168:171], v138 offset:1024
	ds_read_b128 v[172:175], v138 offset:2048
	ds_read_b128 v[176:179], v138 offset:3072
	v_add_u32_e32 v138, s68, v154
	ds_read_b128 v[180:183], v138
	ds_read_b128 v[184:187], v138 offset:1024
	ds_read_b128 v[188:191], v138 offset:2048
	ds_read_b128 v[192:195], v138 offset:3072
	s_add_u32 s42, s42, s10
	s_addc_u32 s43, s43, s11
	s_mov_b32 m0, s66
	v_lshl_add_u64 v[238:239], s[42:43], 0, v[130:131]
	ds_read_b128 v[196:199], v161 offset:32768
	ds_read_b128 v[200:203], v161 offset:33792
	ds_read_b128 v[204:207], v161 offset:34816
	ds_read_b128 v[208:211], v161 offset:35840
	ds_read_b128 v[212:215], v161 offset:36864
	ds_read_b128 v[216:219], v161 offset:37888
	ds_read_b128 v[220:223], v161 offset:38912
	ds_read_b128 v[224:227], v161 offset:39936
	global_load_lds_dwordx4 v[238:239], off
	v_lshl_add_u64 v[238:239], s[42:43], 0, v[134:135]
	s_mov_b32 m0, s67
	s_nop 0
	global_load_lds_dwordx4 v[238:239], off
	s_waitcnt vmcnt(8)
	s_waitcnt lgkmcnt(0)
	s_barrier
	v_mfma_f32_16x16x32_bf16 v[126:129], v[148:151], v[196:199], v[126:129]
	v_mfma_f32_16x16x32_bf16 v[122:125], v[172:175], v[196:199], v[122:125]
	v_mfma_f32_16x16x32_bf16 v[110:113], v[148:151], v[204:207], v[110:113]
	v_mfma_f32_16x16x32_bf16 v[106:109], v[172:175], v[204:207], v[106:109]
	v_mfma_f32_16x16x32_bf16 v[94:97], v[148:151], v[212:215], v[94:97]
	v_mfma_f32_16x16x32_bf16 v[90:93], v[172:175], v[212:215], v[90:93]
	v_mfma_f32_16x16x32_bf16 v[78:81], v[148:151], v[220:223], v[78:81]
	v_mfma_f32_16x16x32_bf16 v[74:77], v[172:175], v[220:223], v[74:77]
	v_mfma_f32_16x16x32_bf16 v[126:129], v[168:171], v[200:203], v[126:129]
	v_mfma_f32_16x16x32_bf16 v[122:125], v[176:179], v[200:203], v[122:125]
	v_mfma_f32_16x16x32_bf16 v[110:113], v[168:171], v[208:211], v[110:113]
	v_mfma_f32_16x16x32_bf16 v[106:109], v[176:179], v[208:211], v[106:109]
	v_mfma_f32_16x16x32_bf16 v[94:97], v[168:171], v[216:219], v[94:97]
	v_mfma_f32_16x16x32_bf16 v[90:93], v[176:179], v[216:219], v[90:93]
	v_mfma_f32_16x16x32_bf16 v[78:81], v[168:171], v[224:227], v[78:81]
	v_mfma_f32_16x16x32_bf16 v[74:77], v[176:179], v[224:227], v[74:77]
	v_mfma_f32_16x16x32_bf16 v[118:121], v[180:183], v[196:199], v[118:121]
	v_mfma_f32_16x16x32_bf16 v[114:117], v[188:191], v[196:199], v[114:117]
	v_mfma_f32_16x16x32_bf16 v[102:105], v[180:183], v[204:207], v[102:105]
	v_mfma_f32_16x16x32_bf16 v[98:101], v[188:191], v[204:207], v[98:101]
	v_mfma_f32_16x16x32_bf16 v[86:89], v[180:183], v[212:215], v[86:89]
	v_mfma_f32_16x16x32_bf16 v[82:85], v[188:191], v[212:215], v[82:85]
	v_mfma_f32_16x16x32_bf16 v[70:73], v[180:183], v[220:223], v[70:73]
	v_mfma_f32_16x16x32_bf16 v[66:69], v[188:191], v[220:223], v[66:69]
	v_mfma_f32_16x16x32_bf16 v[118:121], v[184:187], v[200:203], v[118:121]
	v_mfma_f32_16x16x32_bf16 v[114:117], v[192:195], v[200:203], v[114:117]
	v_mfma_f32_16x16x32_bf16 v[102:105], v[184:187], v[208:211], v[102:105]
	v_mfma_f32_16x16x32_bf16 v[98:101], v[192:195], v[208:211], v[98:101]
	v_mfma_f32_16x16x32_bf16 v[86:89], v[184:187], v[216:219], v[86:89]
	v_mfma_f32_16x16x32_bf16 v[82:85], v[192:195], v[216:219], v[82:85]
	v_mfma_f32_16x16x32_bf16 v[70:73], v[184:187], v[224:227], v[70:73]
	v_mfma_f32_16x16x32_bf16 v[66:69], v[192:195], v[224:227], v[66:69]
	s_barrier
; #define PG8_STAGE(bufoff, gbase, voff) do { _Pragma("unroll") for (int _i = 0; _i < 2; ++_i) \
;         __builtin_amdgcn_global_load_lds((const unsigned*)((const char*)(gbase) + (voff)[_i]), (PG8_LAS unsigned*)(lds + (bufoff) + ldsw + _i * 8192), 16, 0, 0); } while (0)
; #define PG8_LDA(dst, b, h) do { _Pragma("unroll") for (int m = 0; m < 4; ++m) _Pragma("unroll") for (int k = 0; k < 2; ++k) dst[m][k] = *(const PG8_LAS bf16x8*)(lds + PG8_SA(b, h) + aoff + m * 2048 + k * 1024); } while (0)
; #define PG8_MMA(ai, bj, At, Bt) do { __builtin_amdgcn_s_setprio(1); _Pragma("unroll") for (int m = 0; m < 4; ++m) _Pragma("unroll") for (int n = 0; n < 2; ++n) _Pragma("unroll") for (int k = 0; k < 2; ++k) \
;         acc[ai][bj][m][n] = __builtin_amdgcn_mfma_f32_16x16x32_bf16(Bt[n][k], At[m][k], acc[ai][bj][m][n], 0, 0, 0); __builtin_amdgcn_s_setprio(0); } while (0)
; #define PG8_WAIT_V(n) asm volatile("s_waitcnt vmcnt(" #n ")" ::: "memory")
; #define PG8_WAIT_L(n) asm volatile("s_waitcnt lgkmcnt(" #n ")" ::: "memory")
; #define PG8_BAR __builtin_amdgcn_s_barrier()
; #define PG8_SCHED __builtin_amdgcn_sched_barrier(0)
; template <class Epi, class Sched, bool ALIGN_EPI = false, bool SP2 = false>
; __device__ __forceinline__ void gemm_phase(PG8_LAS unsigned char* lds, const Gemm g, const Sched& S, const Epi& E) {
;     ...
;         for (int t = 0; t < nt; t += 2) {
;     ...
;             PG8_LDA(At, 1, 1); PG8_STAGE(PG8_SB(1, 0), b3, voffB); PG8_STAGE(PG8_SB(1, 1), b3 + hstep, voffB); PG8_STAGE(PG8_SA(1, 0), a3, voffA);
;             PG8_WAIT_V(8); PG8_WAIT_L(0); PG8_BAR; PG8_MMA(1, 0, At, B0); PG8_MMA(1, 1, At, B1); PG8_BAR; PG8_SCHED;
	s_add_i32 s42, s47, s55
	v_lshl_add_u64 v[152:153], v[152:153], 0, s[30:31]
	s_mov_b32 m0, s42
	ds_read_b128 v[196:199], v161 offset:49152
	ds_read_b128 v[200:203], v161 offset:50176
	ds_read_b128 v[204:207], v161 offset:51200
	ds_read_b128 v[208:211], v161 offset:52224
	ds_read_b128 v[212:215], v161 offset:53248
	ds_read_b128 v[216:219], v161 offset:54272
	ds_read_b128 v[220:223], v161 offset:55296
	ds_read_b128 v[224:227], v161 offset:56320
	global_load_lds_dwordx4 v[152:153], off
	v_lshl_add_u64 v[152:153], v[228:229], 0, s[30:31]
	s_add_i32 m0, s42, 0x2000
	s_add_i32 s42, s68, s55
	global_load_lds_dwordx4 v[152:153], off
	v_lshl_add_u64 v[152:153], v[230:231], 0, s[30:31]
	s_mov_b32 m0, s42
	s_nop 0
	global_load_lds_dwordx4 v[152:153], off
	v_lshl_add_u64 v[152:153], v[232:233], 0, s[30:31]
	s_add_i32 m0, s42, 0x2000
	s_nop 0
	global_load_lds_dwordx4 v[152:153], off
	v_lshl_add_u64 v[152:153], v[234:235], 0, s[30:31]
	s_mov_b32 m0, s89
	s_nop 0
	global_load_lds_dwordx4 v[152:153], off
	v_lshl_add_u64 v[152:153], v[236:237], 0, s[30:31]
	s_mov_b32 m0, s90
	s_nop 0
	global_load_lds_dwordx4 v[152:153], off
	s_waitcnt vmcnt(8)
	s_waitcnt lgkmcnt(0)
	s_barrier
	v_mfma_f32_16x16x32_bf16 v[62:65], v[148:151], v[196:199], v[62:65]
	v_mfma_f32_16x16x32_bf16 v[58:61], v[172:175], v[196:199], v[58:61]
	v_mfma_f32_16x16x32_bf16 v[46:49], v[148:151], v[204:207], v[46:49]
	v_mfma_f32_16x16x32_bf16 v[42:45], v[172:175], v[204:207], v[42:45]
	v_mfma_f32_16x16x32_bf16 v[30:33], v[148:151], v[212:215], v[30:33]
	v_mfma_f32_16x16x32_bf16 v[26:29], v[172:175], v[212:215], v[26:29]
	v_mfma_f32_16x16x32_bf16 v[14:17], v[148:151], v[220:223], v[14:17]
	v_mfma_f32_16x16x32_bf16 v[10:13], v[172:175], v[220:223], v[10:13]
	v_mfma_f32_16x16x32_bf16 v[62:65], v[168:171], v[200:203], v[62:65]
	v_mfma_f32_16x16x32_bf16 v[58:61], v[176:179], v[200:203], v[58:61]
	v_mfma_f32_16x16x32_bf16 v[46:49], v[168:171], v[208:211], v[46:49]
	v_mfma_f32_16x16x32_bf16 v[42:45], v[176:179], v[208:211], v[42:45]
	v_mfma_f32_16x16x32_bf16 v[30:33], v[168:171], v[216:219], v[30:33]
	v_mfma_f32_16x16x32_bf16 v[26:29], v[176:179], v[216:219], v[26:29]
	v_mfma_f32_16x16x32_bf16 v[14:17], v[168:171], v[224:227], v[14:17]
	v_mfma_f32_16x16x32_bf16 v[10:13], v[176:179], v[224:227], v[10:13]
	v_mfma_f32_16x16x32_bf16 v[54:57], v[180:183], v[196:199], v[54:57]
	v_mfma_f32_16x16x32_bf16 v[50:53], v[188:191], v[196:199], v[50:53]
	v_mfma_f32_16x16x32_bf16 v[38:41], v[180:183], v[204:207], v[38:41]
	v_mfma_f32_16x16x32_bf16 v[34:37], v[188:191], v[204:207], v[34:37]
	v_mfma_f32_16x16x32_bf16 v[22:25], v[180:183], v[212:215], v[22:25]
	v_mfma_f32_16x16x32_bf16 v[18:21], v[188:191], v[212:215], v[18:21]
	v_mfma_f32_16x16x32_bf16 v[6:9], v[180:183], v[220:223], v[6:9]
	v_mfma_f32_16x16x32_bf16 v[2:5], v[188:191], v[220:223], v[2:5]
	v_mfma_f32_16x16x32_bf16 v[54:57], v[184:187], v[200:203], v[54:57]
	v_mfma_f32_16x16x32_bf16 v[50:53], v[192:195], v[200:203], v[50:53]
	v_mfma_f32_16x16x32_bf16 v[38:41], v[184:187], v[208:211], v[38:41]
	v_mfma_f32_16x16x32_bf16 v[34:37], v[192:195], v[208:211], v[34:37]
	v_mfma_f32_16x16x32_bf16 v[22:25], v[184:187], v[216:219], v[22:25]
	v_mfma_f32_16x16x32_bf16 v[18:21], v[192:195], v[216:219], v[18:21]
	v_mfma_f32_16x16x32_bf16 v[6:9], v[184:187], v[224:227], v[6:9]
	v_mfma_f32_16x16x32_bf16 v[2:5], v[192:195], v[224:227], v[2:5]
	s_barrier
	s_add_u32 s0, s0, 0x100
	s_addc_u32 vcc_lo, vcc_lo, 0
	s_add_u32 s6, s6, 0x100
	s_addc_u32 s7, s7, 0
	s_cmp_ge_i32 s46, s91
	s_mov_b32 s42, s46
	s_cbranch_scc0 .LBB0_121

; #define PG8_STAGE(bufoff, gbase, voff) do { _Pragma("unroll") for (int _i = 0; _i < 2; ++_i) \
;         __builtin_amdgcn_global_load_lds((const unsigned*)((const char*)(gbase) + (voff)[_i]), (PG8_LAS unsigned*)(lds + (bufoff) + ldsw + _i * 8192), 16, 0, 0); } while (0)
; #define PG8_LDA(dst, b, h) do { _Pragma("unroll") for (int m = 0; m < 4; ++m) _Pragma("unroll") for (int k = 0; k < 2; ++k) dst[m][k] = *(const PG8_LAS bf16x8*)(lds + PG8_SA(b, h) + aoff + m * 2048 + k * 1024); } while (0)
; #define PG8_LDB(dst, b, h) do { _Pragma("unroll") for (int n = 0; n < 2; ++n) _Pragma("unroll") for (int k = 0; k < 2; ++k) dst[n][k] = *(const PG8_LAS bf16x8*)(lds + PG8_SB(b, h) + boff + n * 2048 + k * 1024); } while (0)
; #define PG8_MMA(ai, bj, At, Bt) do { __builtin_amdgcn_s_setprio(1); _Pragma("unroll") for (int m = 0; m < 4; ++m) _Pragma("unroll") for (int n = 0; n < 2; ++n) _Pragma("unroll") for (int k = 0; k < 2; ++k) \
;         acc[ai][bj][m][n] = __builtin_amdgcn_mfma_f32_16x16x32_bf16(Bt[n][k], At[m][k], acc[ai][bj][m][n], 0, 0, 0); __builtin_amdgcn_s_setprio(0); } while (0)
; #define PG8_WAIT_V(n) asm volatile("s_waitcnt vmcnt(" #n ")" ::: "memory")
; #define PG8_WAIT_L(n) asm volatile("s_waitcnt lgkmcnt(" #n ")" ::: "memory")
; #define PG8_BAR __builtin_amdgcn_s_barrier()
; #define PG8_SCHED __builtin_amdgcn_sched_barrier(0)
; template <class Epi, class Sched, bool ALIGN_EPI = false, bool SP2 = false>
; __device__ __forceinline__ void gemm_phase(PG8_LAS unsigned char* lds, const Gemm g, const Sched& S, const Epi& E) {
;     ...
;         for (int t = 0; t < nt; t += 2) {
;             const bool last = (t == nt - 2);
;             const char* a1 = cA + (size_t)(t + 1) * kstep;
;             const char* a2 = last ? nA : cA + (size_t)(t + 2) * kstep; const char* b2 = last ? nB : cB + (size_t)(t + 2) * kstep;
;             const char* a3 = a2 + kstep; const char* b3 = b2 + kstep;
;             if (last && has_next) S.a_ready(nxt);
;             if constexpr (SP2) {
;             PG8_LDB(B0, 0, 0); PG8_LDB(B1, 0, 1); PG8_SCHED; PG8_LDA(At, 0, 0); PG8_STAGE(PG8_SA(1, 1), a1 + hstep, voffA);
;             PG8_WAIT_V(8); PG8_WAIT_L(0); PG8_BAR; PG8_MMA(0, 0, At, B0); PG8_MMA(0, 1, At, B1); PG8_BAR; PG8_SCHED;
;             PG8_LDA(At, 0, 1); PG8_STAGE(PG8_SB(0, 0), b2, voffB); PG8_STAGE(PG8_SB(0, 1), b2 + hstep, voffB); PG8_STAGE(PG8_SA(0, 0), a2, voffA);
.LBB0_497:
	ds_read_b128 v[146:149], v152
	ds_read_b128 v[156:159], v152 offset:1024
	ds_read_b128 v[160:163], v152 offset:2048
	ds_read_b128 v[164:167], v152 offset:3072
	ds_read_b128 v[168:171], v153
	ds_read_b128 v[172:175], v153 offset:1024
	ds_read_b128 v[176:179], v153 offset:2048
	ds_read_b128 v[180:183], v153 offset:3072
	s_add_i32 s60, s34, 2
	s_add_u32 s61, s30, 0x80
	s_addc_u32 s35, s31, 0
	s_cmp_eq_u32 s44, s34
	s_cselect_b32 s34, s6, s61
	s_cselect_b32 s35, s7, s35
	s_cselect_b32 s63, s29, s59
	s_cselect_b32 s62, s28, s58
	v_lshl_add_u64 v[216:217], s[30:31], 0, v[140:141]
	s_add_i32 m0, s39, 0xc000
	ds_read_b128 v[184:187], v154
	ds_read_b128 v[188:191], v154 offset:1024
	ds_read_b128 v[192:195], v154 offset:2048
	ds_read_b128 v[196:199], v154 offset:3072
	ds_read_b128 v[200:203], v154 offset:4096
	ds_read_b128 v[204:207], v154 offset:5120
	ds_read_b128 v[208:211], v154 offset:6144
	ds_read_b128 v[212:215], v154 offset:7168
	global_load_lds_dwordx4 v[216:217], off
	v_lshl_add_u64 v[216:217], s[30:31], 0, v[138:139]
	s_add_i32 m0, s39, 0xe000
	s_nop 0
	global_load_lds_dwordx4 v[216:217], off
	s_waitcnt vmcnt(8)
	s_waitcnt lgkmcnt(0)
	s_barrier
	v_mfma_f32_16x16x32_bf16 v[126:129], v[146:149], v[184:187], v[126:129]
	v_mfma_f32_16x16x32_bf16 v[122:125], v[160:163], v[184:187], v[122:125]
	v_mfma_f32_16x16x32_bf16 v[110:113], v[146:149], v[192:195], v[110:113]
	v_mfma_f32_16x16x32_bf16 v[106:109], v[160:163], v[192:195], v[106:109]
	v_mfma_f32_16x16x32_bf16 v[94:97], v[146:149], v[200:203], v[94:97]
	v_mfma_f32_16x16x32_bf16 v[90:93], v[160:163], v[200:203], v[90:93]
	v_mfma_f32_16x16x32_bf16 v[78:81], v[146:149], v[208:211], v[78:81]
	v_mfma_f32_16x16x32_bf16 v[74:77], v[160:163], v[208:211], v[74:77]
	v_mfma_f32_16x16x32_bf16 v[126:129], v[156:159], v[188:191], v[126:129]
	v_mfma_f32_16x16x32_bf16 v[122:125], v[164:167], v[188:191], v[122:125]
	v_mfma_f32_16x16x32_bf16 v[110:113], v[156:159], v[196:199], v[110:113]
	v_mfma_f32_16x16x32_bf16 v[106:109], v[164:167], v[196:199], v[106:109]
	v_mfma_f32_16x16x32_bf16 v[94:97], v[156:159], v[204:207], v[94:97]
	v_mfma_f32_16x16x32_bf16 v[90:93], v[164:167], v[204:207], v[90:93]
	v_mfma_f32_16x16x32_bf16 v[78:81], v[156:159], v[212:215], v[78:81]
	v_mfma_f32_16x16x32_bf16 v[74:77], v[164:167], v[212:215], v[74:77]
	v_mfma_f32_16x16x32_bf16 v[118:121], v[168:171], v[184:187], v[118:121]
	v_mfma_f32_16x16x32_bf16 v[114:117], v[176:179], v[184:187], v[114:117]
	v_mfma_f32_16x16x32_bf16 v[102:105], v[168:171], v[192:195], v[102:105]
	v_mfma_f32_16x16x32_bf16 v[98:101], v[176:179], v[192:195], v[98:101]
	v_mfma_f32_16x16x32_bf16 v[86:89], v[168:171], v[200:203], v[86:89]
	v_mfma_f32_16x16x32_bf16 v[82:85], v[176:179], v[200:203], v[82:85]
	v_mfma_f32_16x16x32_bf16 v[70:73], v[168:171], v[208:211], v[70:73]
	v_mfma_f32_16x16x32_bf16 v[66:69], v[176:179], v[208:211], v[66:69]
	v_mfma_f32_16x16x32_bf16 v[118:121], v[172:175], v[188:191], v[118:121]
	v_mfma_f32_16x16x32_bf16 v[114:117], v[180:183], v[188:191], v[114:117]
	v_mfma_f32_16x16x32_bf16 v[102:105], v[172:175], v[196:199], v[102:105]
	v_mfma_f32_16x16x32_bf16 v[98:101], v[180:183], v[196:199], v[98:101]
	v_mfma_f32_16x16x32_bf16 v[86:89], v[172:175], v[204:207], v[86:89]
	v_mfma_f32_16x16x32_bf16 v[82:85], v[180:183], v[204:207], v[82:85]
	v_mfma_f32_16x16x32_bf16 v[70:73], v[172:175], v[212:215], v[70:73]
	v_mfma_f32_16x16x32_bf16 v[66:69], v[180:183], v[212:215], v[66:69]
	s_barrier
	s_add_i32 s61, s54, s38
	v_lshl_add_u64 v[216:217], s[62:63], 0, v[132:133]
	s_mov_b32 m0, s61
	ds_read_b128 v[184:187], v154 offset:16384
	ds_read_b128 v[188:191], v154 offset:17408
	ds_read_b128 v[192:195], v154 offset:18432
	ds_read_b128 v[196:199], v154 offset:19456
	ds_read_b128 v[200:203], v154 offset:20480
	ds_read_b128 v[204:207], v154 offset:21504
	ds_read_b128 v[208:211], v154 offset:22528
	ds_read_b128 v[212:215], v154 offset:23552
	global_load_lds_dwordx4 v[216:217], off
	s_add_i32 m0, s61, 0x2000
	v_lshl_add_u64 v[218:219], s[62:63], 0, v[136:137]
	s_add_u32 s62, s62, s12
	s_addc_u32 s63, s63, s13
	s_add_i32 s61, s55, s38
	global_load_lds_dwordx4 v[218:219], off
	v_lshl_add_u64 v[220:221], s[62:63], 0, v[132:133]
	s_mov_b32 m0, s61
	v_lshl_add_u64 v[222:223], s[62:63], 0, v[136:137]
	global_load_lds_dwordx4 v[220:221], off
	s_add_i32 m0, s61, 0x2000
	v_lshl_add_u64 v[224:225], s[34:35], 0, v[130:131]
	global_load_lds_dwordx4 v[222:223], off
	s_mov_b32 m0, s39
	v_lshl_add_u64 v[226:227], s[34:35], 0, v[134:135]
	global_load_lds_dwordx4 v[224:225], off
	s_mov_b32 m0, s40
	s_nop 0
	global_load_lds_dwordx4 v[226:227], off
	s_waitcnt vmcnt(8)
	s_waitcnt lgkmcnt(0)
	s_barrier
; #define PG8_STAGE(bufoff, gbase, voff) do { _Pragma("unroll") for (int _i = 0; _i < 2; ++_i) \
;         __builtin_amdgcn_global_load_lds((const unsigned*)((const char*)(gbase) + (voff)[_i]), (PG8_LAS unsigned*)(lds + (bufoff) + ldsw + _i * 8192), 16, 0, 0); } while (0)
; #define PG8_LDA(dst, b, h) do { _Pragma("unroll") for (int m = 0; m < 4; ++m) _Pragma("unroll") for (int k = 0; k < 2; ++k) dst[m][k] = *(const PG8_LAS bf16x8*)(lds + PG8_SA(b, h) + aoff + m * 2048 + k * 1024); } while (0)
; #define PG8_LDB(dst, b, h) do { _Pragma("unroll") for (int n = 0; n < 2; ++n) _Pragma("unroll") for (int k = 0; k < 2; ++k) dst[n][k] = *(const PG8_LAS bf16x8*)(lds + PG8_SB(b, h) + boff + n * 2048 + k * 1024); } while (0)
; #define PG8_MMA(ai, bj, At, Bt) do { __builtin_amdgcn_s_setprio(1); _Pragma("unroll") for (int m = 0; m < 4; ++m) _Pragma("unroll") for (int n = 0; n < 2; ++n) _Pragma("unroll") for (int k = 0; k < 2; ++k) \
;         acc[ai][bj][m][n] = __builtin_amdgcn_mfma_f32_16x16x32_bf16(Bt[n][k], At[m][k], acc[ai][bj][m][n], 0, 0, 0); __builtin_amdgcn_s_setprio(0); } while (0)
; #define PG8_WAIT_V(n) asm volatile("s_waitcnt vmcnt(" #n ")" ::: "memory")
; #define PG8_WAIT_L(n) asm volatile("s_waitcnt lgkmcnt(" #n ")" ::: "memory")
; #define PG8_BAR __builtin_amdgcn_s_barrier()
; #define PG8_SCHED __builtin_amdgcn_sched_barrier(0)
; template <class Epi, class Sched, bool ALIGN_EPI = false, bool SP2 = false>
; __device__ __forceinline__ void gemm_phase(PG8_LAS unsigned char* lds, const Gemm g, const Sched& S, const Epi& E) {
;     ...
;             PG8_WAIT_V(8); PG8_WAIT_L(0); PG8_BAR; PG8_MMA(1, 0, At, B0); PG8_MMA(1, 1, At, B1); PG8_BAR; PG8_SCHED;
;             PG8_LDB(B0, 1, 0); PG8_LDB(B1, 1, 1); PG8_SCHED; PG8_LDA(At, 1, 0); PG8_STAGE(PG8_SA(0, 1), a2 + hstep, voffA);
;             PG8_WAIT_V(8); PG8_WAIT_L(0); PG8_BAR; PG8_MMA(0, 0, At, B0); PG8_MMA(0, 1, At, B1); PG8_BAR; PG8_SCHED;
	v_mfma_f32_16x16x32_bf16 v[62:65], v[146:149], v[184:187], v[62:65]
	v_mfma_f32_16x16x32_bf16 v[58:61], v[160:163], v[184:187], v[58:61]
	v_mfma_f32_16x16x32_bf16 v[46:49], v[146:149], v[192:195], v[46:49]
	v_mfma_f32_16x16x32_bf16 v[42:45], v[160:163], v[192:195], v[42:45]
	v_mfma_f32_16x16x32_bf16 v[30:33], v[146:149], v[200:203], v[30:33]
	v_mfma_f32_16x16x32_bf16 v[26:29], v[160:163], v[200:203], v[26:29]
	v_mfma_f32_16x16x32_bf16 v[14:17], v[146:149], v[208:211], v[14:17]
	v_mfma_f32_16x16x32_bf16 v[10:13], v[160:163], v[208:211], v[10:13]
	v_mfma_f32_16x16x32_bf16 v[62:65], v[156:159], v[188:191], v[62:65]
	v_mfma_f32_16x16x32_bf16 v[58:61], v[164:167], v[188:191], v[58:61]
	v_mfma_f32_16x16x32_bf16 v[46:49], v[156:159], v[196:199], v[46:49]
	v_mfma_f32_16x16x32_bf16 v[42:45], v[164:167], v[196:199], v[42:45]
	v_mfma_f32_16x16x32_bf16 v[30:33], v[156:159], v[204:207], v[30:33]
	v_mfma_f32_16x16x32_bf16 v[26:29], v[164:167], v[204:207], v[26:29]
	v_mfma_f32_16x16x32_bf16 v[14:17], v[156:159], v[212:215], v[14:17]
	v_mfma_f32_16x16x32_bf16 v[10:13], v[164:167], v[212:215], v[10:13]
	v_mfma_f32_16x16x32_bf16 v[54:57], v[168:171], v[184:187], v[54:57]
	v_mfma_f32_16x16x32_bf16 v[50:53], v[176:179], v[184:187], v[50:53]
	v_mfma_f32_16x16x32_bf16 v[38:41], v[168:171], v[192:195], v[38:41]
	v_mfma_f32_16x16x32_bf16 v[34:37], v[176:179], v[192:195], v[34:37]
	v_mfma_f32_16x16x32_bf16 v[22:25], v[168:171], v[200:203], v[22:25]
	v_mfma_f32_16x16x32_bf16 v[18:21], v[176:179], v[200:203], v[18:21]
	v_mfma_f32_16x16x32_bf16 v[6:9], v[168:171], v[208:211], v[6:9]
	v_mfma_f32_16x16x32_bf16 v[2:5], v[176:179], v[208:211], v[2:5]
	v_mfma_f32_16x16x32_bf16 v[54:57], v[172:175], v[188:191], v[54:57]
	v_mfma_f32_16x16x32_bf16 v[50:53], v[180:183], v[188:191], v[50:53]
	v_mfma_f32_16x16x32_bf16 v[38:41], v[172:175], v[196:199], v[38:41]
	v_mfma_f32_16x16x32_bf16 v[34:37], v[180:183], v[196:199], v[34:37]
	v_mfma_f32_16x16x32_bf16 v[22:25], v[172:175], v[204:207], v[22:25]
	v_mfma_f32_16x16x32_bf16 v[18:21], v[180:183], v[204:207], v[18:21]
	v_mfma_f32_16x16x32_bf16 v[6:9], v[172:175], v[212:215], v[6:9]
	v_mfma_f32_16x16x32_bf16 v[2:5], v[180:183], v[212:215], v[2:5]
	s_barrier
	s_add_i32 s61, 0, 0x18000
	v_add_u32_e32 v155, s61, v150
	s_add_i32 s62, 0, 0x1c000
	ds_read_b128 v[146:149], v155
	ds_read_b128 v[156:159], v155 offset:1024
	ds_read_b128 v[160:163], v155 offset:2048
	ds_read_b128 v[164:167], v155 offset:3072
	v_add_u32_e32 v155, s62, v150
	ds_read_b128 v[168:171], v155
	ds_read_b128 v[172:175], v155 offset:1024
	ds_read_b128 v[176:179], v155 offset:2048
	ds_read_b128 v[180:183], v155 offset:3072
	s_add_u32 s34, s34, s12
	s_addc_u32 s35, s35, s13
	s_mov_b32 m0, s41
	v_lshl_add_u64 v[228:229], s[34:35], 0, v[130:131]
	ds_read_b128 v[184:187], v154 offset:32768
	ds_read_b128 v[188:191], v154 offset:33792
	ds_read_b128 v[192:195], v154 offset:34816
	ds_read_b128 v[196:199], v154 offset:35840
	ds_read_b128 v[200:203], v154 offset:36864
	ds_read_b128 v[204:207], v154 offset:37888
	ds_read_b128 v[208:211], v154 offset:38912
	ds_read_b128 v[212:215], v154 offset:39936
	global_load_lds_dwordx4 v[228:229], off
	v_lshl_add_u64 v[228:229], s[34:35], 0, v[134:135]
	s_mov_b32 m0, s42
	s_nop 0
	global_load_lds_dwordx4 v[228:229], off
	s_waitcnt vmcnt(8)
	s_waitcnt lgkmcnt(0)
	s_barrier
	v_mfma_f32_16x16x32_bf16 v[126:129], v[146:149], v[184:187], v[126:129]
	v_mfma_f32_16x16x32_bf16 v[122:125], v[160:163], v[184:187], v[122:125]
	v_mfma_f32_16x16x32_bf16 v[110:113], v[146:149], v[192:195], v[110:113]
	v_mfma_f32_16x16x32_bf16 v[106:109], v[160:163], v[192:195], v[106:109]
	v_mfma_f32_16x16x32_bf16 v[94:97], v[146:149], v[200:203], v[94:97]
	v_mfma_f32_16x16x32_bf16 v[90:93], v[160:163], v[200:203], v[90:93]
	v_mfma_f32_16x16x32_bf16 v[78:81], v[146:149], v[208:211], v[78:81]
	v_mfma_f32_16x16x32_bf16 v[74:77], v[160:163], v[208:211], v[74:77]
	v_mfma_f32_16x16x32_bf16 v[126:129], v[156:159], v[188:191], v[126:129]
	v_mfma_f32_16x16x32_bf16 v[122:125], v[164:167], v[188:191], v[122:125]
	v_mfma_f32_16x16x32_bf16 v[110:113], v[156:159], v[196:199], v[110:113]
	v_mfma_f32_16x16x32_bf16 v[106:109], v[164:167], v[196:199], v[106:109]
	v_mfma_f32_16x16x32_bf16 v[94:97], v[156:159], v[204:207], v[94:97]
	v_mfma_f32_16x16x32_bf16 v[90:93], v[164:167], v[204:207], v[90:93]
	v_mfma_f32_16x16x32_bf16 v[78:81], v[156:159], v[212:215], v[78:81]
	v_mfma_f32_16x16x32_bf16 v[74:77], v[164:167], v[212:215], v[74:77]
	v_mfma_f32_16x16x32_bf16 v[118:121], v[168:171], v[184:187], v[118:121]
	v_mfma_f32_16x16x32_bf16 v[114:117], v[176:179], v[184:187], v[114:117]
	v_mfma_f32_16x16x32_bf16 v[102:105], v[168:171], v[192:195], v[102:105]
	v_mfma_f32_16x16x32_bf16 v[98:101], v[176:179], v[192:195], v[98:101]
	v_mfma_f32_16x16x32_bf16 v[86:89], v[168:171], v[200:203], v[86:89]
	v_mfma_f32_16x16x32_bf16 v[82:85], v[176:179], v[200:203], v[82:85]
	v_mfma_f32_16x16x32_bf16 v[70:73], v[168:171], v[208:211], v[70:73]
	v_mfma_f32_16x16x32_bf16 v[66:69], v[176:179], v[208:211], v[66:69]
	v_mfma_f32_16x16x32_bf16 v[118:121], v[172:175], v[188:191], v[118:121]
	v_mfma_f32_16x16x32_bf16 v[114:117], v[180:183], v[188:191], v[114:117]
	v_mfma_f32_16x16x32_bf16 v[102:105], v[172:175], v[196:199], v[102:105]
	v_mfma_f32_16x16x32_bf16 v[98:101], v[180:183], v[196:199], v[98:101]
	v_mfma_f32_16x16x32_bf16 v[86:89], v[172:175], v[204:207], v[86:89]
	v_mfma_f32_16x16x32_bf16 v[82:85], v[180:183], v[204:207], v[82:85]
	v_mfma_f32_16x16x32_bf16 v[70:73], v[172:175], v[212:215], v[70:73]
	v_mfma_f32_16x16x32_bf16 v[66:69], v[180:183], v[212:215], v[66:69]
	s_barrier
; #define PG8_STAGE(bufoff, gbase, voff) do { _Pragma("unroll") for (int _i = 0; _i < 2; ++_i) \
;         __builtin_amdgcn_global_load_lds((const unsigned*)((const char*)(gbase) + (voff)[_i]), (PG8_LAS unsigned*)(lds + (bufoff) + ldsw + _i * 8192), 16, 0, 0); } while (0)
; #define PG8_LDA(dst, b, h) do { _Pragma("unroll") for (int m = 0; m < 4; ++m) _Pragma("unroll") for (int k = 0; k < 2; ++k) dst[m][k] = *(const PG8_LAS bf16x8*)(lds + PG8_SA(b, h) + aoff + m * 2048 + k * 1024); } while (0)
; #define PG8_MMA(ai, bj, At, Bt) do { __builtin_amdgcn_s_setprio(1); _Pragma("unroll") for (int m = 0; m < 4; ++m) _Pragma("unroll") for (int n = 0; n < 2; ++n) _Pragma("unroll") for (int k = 0; k < 2; ++k) \
;         acc[ai][bj][m][n] = __builtin_amdgcn_mfma_f32_16x16x32_bf16(Bt[n][k], At[m][k], acc[ai][bj][m][n], 0, 0, 0); __builtin_amdgcn_s_setprio(0); } while (0)
; #define PG8_WAIT_V(n) asm volatile("s_waitcnt vmcnt(" #n ")" ::: "memory")
; #define PG8_WAIT_L(n) asm volatile("s_waitcnt lgkmcnt(" #n ")" ::: "memory")
; #define PG8_BAR __builtin_amdgcn_s_barrier()
; #define PG8_SCHED __builtin_amdgcn_sched_barrier(0)
; template <class Epi, class Sched, bool ALIGN_EPI = false, bool SP2 = false>
; __device__ __forceinline__ void gemm_phase(PG8_LAS unsigned char* lds, const Gemm g, const Sched& S, const Epi& E) {
;     ...
;         for (int t = 0; t < nt; t += 2) {
;     ...
;             PG8_LDA(At, 1, 1); PG8_STAGE(PG8_SB(1, 0), b3, voffB); PG8_STAGE(PG8_SB(1, 1), b3 + hstep, voffB); PG8_STAGE(PG8_SA(1, 0), a3, voffA);
;             PG8_WAIT_V(8); PG8_WAIT_L(0); PG8_BAR; PG8_MMA(1, 0, At, B0); PG8_MMA(1, 1, At, B1); PG8_BAR; PG8_SCHED;
	s_add_i32 s34, s61, s38
	v_lshl_add_u64 v[216:217], v[216:217], 0, s[20:21]
	s_mov_b32 m0, s34
	ds_read_b128 v[184:187], v154 offset:49152
	ds_read_b128 v[188:191], v154 offset:50176
	ds_read_b128 v[192:195], v154 offset:51200
	ds_read_b128 v[196:199], v154 offset:52224
	ds_read_b128 v[200:203], v154 offset:53248
	ds_read_b128 v[204:207], v154 offset:54272
	ds_read_b128 v[208:211], v154 offset:55296
	ds_read_b128 v[212:215], v154 offset:56320
	global_load_lds_dwordx4 v[216:217], off
	v_lshl_add_u64 v[216:217], v[218:219], 0, s[20:21]
	s_add_i32 m0, s34, 0x2000
	s_add_i32 s34, s62, s38
	global_load_lds_dwordx4 v[216:217], off
	v_lshl_add_u64 v[216:217], v[220:221], 0, s[20:21]
	s_mov_b32 m0, s34
	s_nop 0
	global_load_lds_dwordx4 v[216:217], off
	v_lshl_add_u64 v[216:217], v[222:223], 0, s[20:21]
	s_add_i32 m0, s34, 0x2000
	s_nop 0
	global_load_lds_dwordx4 v[216:217], off
	v_lshl_add_u64 v[216:217], v[224:225], 0, s[20:21]
	s_mov_b32 m0, s46
	s_nop 0
	global_load_lds_dwordx4 v[216:217], off
	v_lshl_add_u64 v[216:217], v[226:227], 0, s[20:21]
	s_mov_b32 m0, s47
	s_nop 0
	global_load_lds_dwordx4 v[216:217], off
	s_waitcnt vmcnt(8)
	s_waitcnt lgkmcnt(0)
	s_barrier
	v_mfma_f32_16x16x32_bf16 v[62:65], v[146:149], v[184:187], v[62:65]
	v_mfma_f32_16x16x32_bf16 v[58:61], v[160:163], v[184:187], v[58:61]
	v_mfma_f32_16x16x32_bf16 v[46:49], v[146:149], v[192:195], v[46:49]
	v_mfma_f32_16x16x32_bf16 v[42:45], v[160:163], v[192:195], v[42:45]
	v_mfma_f32_16x16x32_bf16 v[30:33], v[146:149], v[200:203], v[30:33]
	v_mfma_f32_16x16x32_bf16 v[26:29], v[160:163], v[200:203], v[26:29]
	v_mfma_f32_16x16x32_bf16 v[14:17], v[146:149], v[208:211], v[14:17]
	v_mfma_f32_16x16x32_bf16 v[10:13], v[160:163], v[208:211], v[10:13]
	v_mfma_f32_16x16x32_bf16 v[62:65], v[156:159], v[188:191], v[62:65]
	v_mfma_f32_16x16x32_bf16 v[58:61], v[164:167], v[188:191], v[58:61]
	v_mfma_f32_16x16x32_bf16 v[46:49], v[156:159], v[196:199], v[46:49]
	v_mfma_f32_16x16x32_bf16 v[42:45], v[164:167], v[196:199], v[42:45]
	v_mfma_f32_16x16x32_bf16 v[30:33], v[156:159], v[204:207], v[30:33]
	v_mfma_f32_16x16x32_bf16 v[26:29], v[164:167], v[204:207], v[26:29]
	v_mfma_f32_16x16x32_bf16 v[14:17], v[156:159], v[212:215], v[14:17]
	v_mfma_f32_16x16x32_bf16 v[10:13], v[164:167], v[212:215], v[10:13]
	v_mfma_f32_16x16x32_bf16 v[54:57], v[168:171], v[184:187], v[54:57]
	v_mfma_f32_16x16x32_bf16 v[50:53], v[176:179], v[184:187], v[50:53]
	v_mfma_f32_16x16x32_bf16 v[38:41], v[168:171], v[192:195], v[38:41]
	v_mfma_f32_16x16x32_bf16 v[34:37], v[176:179], v[192:195], v[34:37]
	v_mfma_f32_16x16x32_bf16 v[22:25], v[168:171], v[200:203], v[22:25]
	v_mfma_f32_16x16x32_bf16 v[18:21], v[176:179], v[200:203], v[18:21]
	v_mfma_f32_16x16x32_bf16 v[6:9], v[168:171], v[208:211], v[6:9]
	v_mfma_f32_16x16x32_bf16 v[2:5], v[176:179], v[208:211], v[2:5]
	v_mfma_f32_16x16x32_bf16 v[54:57], v[172:175], v[188:191], v[54:57]
	v_mfma_f32_16x16x32_bf16 v[50:53], v[180:183], v[188:191], v[50:53]
	v_mfma_f32_16x16x32_bf16 v[38:41], v[172:175], v[196:199], v[38:41]
	v_mfma_f32_16x16x32_bf16 v[34:37], v[180:183], v[196:199], v[34:37]
	v_mfma_f32_16x16x32_bf16 v[22:25], v[172:175], v[204:207], v[22:25]
	v_mfma_f32_16x16x32_bf16 v[18:21], v[180:183], v[204:207], v[18:21]
	v_mfma_f32_16x16x32_bf16 v[6:9], v[172:175], v[212:215], v[6:9]
	v_mfma_f32_16x16x32_bf16 v[2:5], v[180:183], v[212:215], v[2:5]
	s_barrier
	s_add_u32 s58, s58, 0x100
	s_addc_u32 s59, s59, 0
	s_add_u32 s30, s30, 0x100
	s_addc_u32 s31, s31, 0
	s_cmp_ge_i32 s60, s52
	s_mov_b32 s34, s60
	s_cbranch_scc0 .LBB0_497

; #define PG8_STAGE(bufoff, gbase, voff) do { _Pragma("unroll") for (int _i = 0; _i < 2; ++_i) \
;         __builtin_amdgcn_global_load_lds((const unsigned*)((const char*)(gbase) + (voff)[_i]), (PG8_LAS unsigned*)(lds + (bufoff) + ldsw + _i * 8192), 16, 0, 0); } while (0)
; #define PG8_LDA(dst, b, h) do { _Pragma("unroll") for (int m = 0; m < 4; ++m) _Pragma("unroll") for (int k = 0; k < 2; ++k) dst[m][k] = *(const PG8_LAS bf16x8*)(lds + PG8_SA(b, h) + aoff + m * 2048 + k * 1024); } while (0)
; #define PG8_LDB(dst, b, h) do { _Pragma("unroll") for (int n = 0; n < 2; ++n) _Pragma("unroll") for (int k = 0; k < 2; ++k) dst[n][k] = *(const PG8_LAS bf16x8*)(lds + PG8_SB(b, h) + boff + n * 2048 + k * 1024); } while (0)
; #define PG8_MMA(ai, bj, At, Bt) do { __builtin_amdgcn_s_setprio(1); _Pragma("unroll") for (int m = 0; m < 4; ++m) _Pragma("unroll") for (int n = 0; n < 2; ++n) _Pragma("unroll") for (int k = 0; k < 2; ++k) \
;         acc[ai][bj][m][n] = __builtin_amdgcn_mfma_f32_16x16x32_bf16(Bt[n][k], At[m][k], acc[ai][bj][m][n], 0, 0, 0); __builtin_amdgcn_s_setprio(0); } while (0)
; #define PG8_WAIT_V(n) asm volatile("s_waitcnt vmcnt(" #n ")" ::: "memory")
; #define PG8_WAIT_L(n) asm volatile("s_waitcnt lgkmcnt(" #n ")" ::: "memory")
; #define PG8_BAR __builtin_amdgcn_s_barrier()
; #define PG8_SCHED __builtin_amdgcn_sched_barrier(0)
; template <class Epi, class Sched, bool ALIGN_EPI = false, bool SP2 = false>
; __device__ __forceinline__ void gemm_phase(PG8_LAS unsigned char* lds, const Gemm g, const Sched& S, const Epi& E) {
;     ...
;         for (int t = 0; t < nt; t += 2) {
;             const bool last = (t == nt - 2);
;             const char* a1 = cA + (size_t)(t + 1) * kstep;
;             const char* a2 = last ? nA : cA + (size_t)(t + 2) * kstep; const char* b2 = last ? nB : cB + (size_t)(t + 2) * kstep;
;             const char* a3 = a2 + kstep; const char* b3 = b2 + kstep;
;             if (last && has_next) S.a_ready(nxt);
;             if constexpr (SP2) {
;             PG8_LDB(B0, 0, 0); PG8_LDB(B1, 0, 1); PG8_SCHED; PG8_LDA(At, 0, 0); PG8_STAGE(PG8_SA(1, 1), a1 + hstep, voffA);
;             PG8_WAIT_V(8); PG8_WAIT_L(0); PG8_BAR; PG8_MMA(0, 0, At, B0); PG8_MMA(0, 1, At, B1); PG8_BAR; PG8_SCHED;
;             PG8_LDA(At, 0, 1); PG8_STAGE(PG8_SB(0, 0), b2, voffB); PG8_STAGE(PG8_SB(0, 1), b2 + hstep, voffB); PG8_STAGE(PG8_SA(0, 0), a2, voffA);
.LBB0_582:
	ds_read_b128 v[152:155], v148
	ds_read_b128 v[156:159], v148 offset:1024
	ds_read_b128 v[160:163], v148 offset:2048
	ds_read_b128 v[164:167], v148 offset:3072
	ds_read_b128 v[168:171], v149
	ds_read_b128 v[172:175], v149 offset:1024
	ds_read_b128 v[176:179], v149 offset:2048
	ds_read_b128 v[180:183], v149 offset:3072
	s_add_i32 s60, s30, 2
	s_add_u32 s61, s28, 0x80
	s_addc_u32 s31, s29, 0
	s_cmp_eq_u32 s45, s30
	s_cselect_b32 s30, s6, s61
	s_cselect_b32 s31, s7, s31
	s_cselect_b32 s63, s25, s59
	s_cselect_b32 s62, s24, s58
	v_lshl_add_u64 v[216:217], s[28:29], 0, v[140:141]
	s_add_i32 m0, s0, 0xc000
	ds_read_b128 v[184:187], v150
	ds_read_b128 v[188:191], v150 offset:1024
	ds_read_b128 v[192:195], v150 offset:2048
	ds_read_b128 v[196:199], v150 offset:3072
	ds_read_b128 v[200:203], v150 offset:4096
	ds_read_b128 v[204:207], v150 offset:5120
	ds_read_b128 v[208:211], v150 offset:6144
	ds_read_b128 v[212:215], v150 offset:7168
	global_load_lds_dwordx4 v[216:217], off
	v_lshl_add_u64 v[216:217], s[28:29], 0, v[138:139]
	s_add_i32 m0, s0, 0xe000
	s_nop 0
	global_load_lds_dwordx4 v[216:217], off
	s_waitcnt vmcnt(8)
	s_waitcnt lgkmcnt(0)
	s_barrier
	v_mfma_f32_16x16x32_bf16 v[122:125], v[152:155], v[184:187], v[122:125]
	v_mfma_f32_16x16x32_bf16 v[126:129], v[160:163], v[184:187], v[126:129]
	v_mfma_f32_16x16x32_bf16 v[110:113], v[152:155], v[192:195], v[110:113]
	v_mfma_f32_16x16x32_bf16 v[106:109], v[160:163], v[192:195], v[106:109]
	v_mfma_f32_16x16x32_bf16 v[94:97], v[152:155], v[200:203], v[94:97]
	v_mfma_f32_16x16x32_bf16 v[90:93], v[160:163], v[200:203], v[90:93]
	v_mfma_f32_16x16x32_bf16 v[78:81], v[152:155], v[208:211], v[78:81]
	v_mfma_f32_16x16x32_bf16 v[74:77], v[160:163], v[208:211], v[74:77]
	v_mfma_f32_16x16x32_bf16 v[122:125], v[156:159], v[188:191], v[122:125]
	v_mfma_f32_16x16x32_bf16 v[126:129], v[164:167], v[188:191], v[126:129]
	v_mfma_f32_16x16x32_bf16 v[110:113], v[156:159], v[196:199], v[110:113]
	v_mfma_f32_16x16x32_bf16 v[106:109], v[164:167], v[196:199], v[106:109]
	v_mfma_f32_16x16x32_bf16 v[94:97], v[156:159], v[204:207], v[94:97]
	v_mfma_f32_16x16x32_bf16 v[90:93], v[164:167], v[204:207], v[90:93]
	v_mfma_f32_16x16x32_bf16 v[78:81], v[156:159], v[212:215], v[78:81]
	v_mfma_f32_16x16x32_bf16 v[74:77], v[164:167], v[212:215], v[74:77]
	v_mfma_f32_16x16x32_bf16 v[118:121], v[168:171], v[184:187], v[118:121]
	v_mfma_f32_16x16x32_bf16 v[114:117], v[176:179], v[184:187], v[114:117]
	v_mfma_f32_16x16x32_bf16 v[102:105], v[168:171], v[192:195], v[102:105]
	v_mfma_f32_16x16x32_bf16 v[98:101], v[176:179], v[192:195], v[98:101]
	v_mfma_f32_16x16x32_bf16 v[86:89], v[168:171], v[200:203], v[86:89]
	v_mfma_f32_16x16x32_bf16 v[82:85], v[176:179], v[200:203], v[82:85]
	v_mfma_f32_16x16x32_bf16 v[70:73], v[168:171], v[208:211], v[70:73]
	v_mfma_f32_16x16x32_bf16 v[66:69], v[176:179], v[208:211], v[66:69]
	v_mfma_f32_16x16x32_bf16 v[118:121], v[172:175], v[188:191], v[118:121]
	v_mfma_f32_16x16x32_bf16 v[114:117], v[180:183], v[188:191], v[114:117]
	v_mfma_f32_16x16x32_bf16 v[102:105], v[172:175], v[196:199], v[102:105]
	v_mfma_f32_16x16x32_bf16 v[98:101], v[180:183], v[196:199], v[98:101]
	v_mfma_f32_16x16x32_bf16 v[86:89], v[172:175], v[204:207], v[86:89]
	v_mfma_f32_16x16x32_bf16 v[82:85], v[180:183], v[204:207], v[82:85]
	v_mfma_f32_16x16x32_bf16 v[70:73], v[172:175], v[212:215], v[70:73]
	v_mfma_f32_16x16x32_bf16 v[66:69], v[180:183], v[212:215], v[66:69]
	s_barrier
	s_add_i32 s61, s52, s38
	v_lshl_add_u64 v[216:217], s[62:63], 0, v[132:133]
	s_mov_b32 m0, s61
	ds_read_b128 v[184:187], v150 offset:16384
	ds_read_b128 v[188:191], v150 offset:17408
	ds_read_b128 v[192:195], v150 offset:18432
	ds_read_b128 v[196:199], v150 offset:19456
	ds_read_b128 v[200:203], v150 offset:20480
	ds_read_b128 v[204:207], v150 offset:21504
	ds_read_b128 v[208:211], v150 offset:22528
	ds_read_b128 v[212:215], v150 offset:23552
	global_load_lds_dwordx4 v[216:217], off
	s_add_i32 m0, s61, 0x2000
	v_lshl_add_u64 v[218:219], s[62:63], 0, v[136:137]
	s_add_u32 s62, s62, s10
	s_addc_u32 s63, s63, s11
	s_add_i32 s61, s53, s38
	global_load_lds_dwordx4 v[218:219], off
	v_lshl_add_u64 v[220:221], s[62:63], 0, v[132:133]
	s_mov_b32 m0, s61
	v_lshl_add_u64 v[222:223], s[62:63], 0, v[136:137]
	global_load_lds_dwordx4 v[220:221], off
	s_add_i32 m0, s61, 0x2000
	v_lshl_add_u64 v[224:225], s[30:31], 0, v[130:131]
	global_load_lds_dwordx4 v[222:223], off
	s_mov_b32 m0, s0
	v_lshl_add_u64 v[226:227], s[30:31], 0, v[134:135]
	global_load_lds_dwordx4 v[224:225], off
	s_mov_b32 m0, s1
	s_nop 0
	global_load_lds_dwordx4 v[226:227], off
	s_waitcnt vmcnt(8)
	s_waitcnt lgkmcnt(0)
	s_barrier
; #define PG8_STAGE(bufoff, gbase, voff) do { _Pragma("unroll") for (int _i = 0; _i < 2; ++_i) \
;         __builtin_amdgcn_global_load_lds((const unsigned*)((const char*)(gbase) + (voff)[_i]), (PG8_LAS unsigned*)(lds + (bufoff) + ldsw + _i * 8192), 16, 0, 0); } while (0)
; #define PG8_LDA(dst, b, h) do { _Pragma("unroll") for (int m = 0; m < 4; ++m) _Pragma("unroll") for (int k = 0; k < 2; ++k) dst[m][k] = *(const PG8_LAS bf16x8*)(lds + PG8_SA(b, h) + aoff + m * 2048 + k * 1024); } while (0)
; #define PG8_LDB(dst, b, h) do { _Pragma("unroll") for (int n = 0; n < 2; ++n) _Pragma("unroll") for (int k = 0; k < 2; ++k) dst[n][k] = *(const PG8_LAS bf16x8*)(lds + PG8_SB(b, h) + boff + n * 2048 + k * 1024); } while (0)
; #define PG8_MMA(ai, bj, At, Bt) do { __builtin_amdgcn_s_setprio(1); _Pragma("unroll") for (int m = 0; m < 4; ++m) _Pragma("unroll") for (int n = 0; n < 2; ++n) _Pragma("unroll") for (int k = 0; k < 2; ++k) \
;         acc[ai][bj][m][n] = __builtin_amdgcn_mfma_f32_16x16x32_bf16(Bt[n][k], At[m][k], acc[ai][bj][m][n], 0, 0, 0); __builtin_amdgcn_s_setprio(0); } while (0)
; #define PG8_WAIT_V(n) asm volatile("s_waitcnt vmcnt(" #n ")" ::: "memory")
; #define PG8_WAIT_L(n) asm volatile("s_waitcnt lgkmcnt(" #n ")" ::: "memory")
; #define PG8_BAR __builtin_amdgcn_s_barrier()
; #define PG8_SCHED __builtin_amdgcn_sched_barrier(0)
; template <class Epi, class Sched, bool ALIGN_EPI = false, bool SP2 = false>
; __device__ __forceinline__ void gemm_phase(PG8_LAS unsigned char* lds, const Gemm g, const Sched& S, const Epi& E) {
;     ...
;             PG8_WAIT_V(8); PG8_WAIT_L(0); PG8_BAR; PG8_MMA(1, 0, At, B0); PG8_MMA(1, 1, At, B1); PG8_BAR; PG8_SCHED;
;             PG8_LDB(B0, 1, 0); PG8_LDB(B1, 1, 1); PG8_SCHED; PG8_LDA(At, 1, 0); PG8_STAGE(PG8_SA(0, 1), a2 + hstep, voffA);
;             PG8_WAIT_V(8); PG8_WAIT_L(0); PG8_BAR; PG8_MMA(0, 0, At, B0); PG8_MMA(0, 1, At, B1); PG8_BAR; PG8_SCHED;
	v_mfma_f32_16x16x32_bf16 v[62:65], v[152:155], v[184:187], v[62:65]
	v_mfma_f32_16x16x32_bf16 v[58:61], v[160:163], v[184:187], v[58:61]
	v_mfma_f32_16x16x32_bf16 v[46:49], v[152:155], v[192:195], v[46:49]
	v_mfma_f32_16x16x32_bf16 v[42:45], v[160:163], v[192:195], v[42:45]
	v_mfma_f32_16x16x32_bf16 v[30:33], v[152:155], v[200:203], v[30:33]
	v_mfma_f32_16x16x32_bf16 v[26:29], v[160:163], v[200:203], v[26:29]
	v_mfma_f32_16x16x32_bf16 v[14:17], v[152:155], v[208:211], v[14:17]
	v_mfma_f32_16x16x32_bf16 v[10:13], v[160:163], v[208:211], v[10:13]
	v_mfma_f32_16x16x32_bf16 v[62:65], v[156:159], v[188:191], v[62:65]
	v_mfma_f32_16x16x32_bf16 v[58:61], v[164:167], v[188:191], v[58:61]
	v_mfma_f32_16x16x32_bf16 v[46:49], v[156:159], v[196:199], v[46:49]
	v_mfma_f32_16x16x32_bf16 v[42:45], v[164:167], v[196:199], v[42:45]
	v_mfma_f32_16x16x32_bf16 v[30:33], v[156:159], v[204:207], v[30:33]
	v_mfma_f32_16x16x32_bf16 v[26:29], v[164:167], v[204:207], v[26:29]
	v_mfma_f32_16x16x32_bf16 v[14:17], v[156:159], v[212:215], v[14:17]
	v_mfma_f32_16x16x32_bf16 v[10:13], v[164:167], v[212:215], v[10:13]
	v_mfma_f32_16x16x32_bf16 v[54:57], v[168:171], v[184:187], v[54:57]
	v_mfma_f32_16x16x32_bf16 v[50:53], v[176:179], v[184:187], v[50:53]
	v_mfma_f32_16x16x32_bf16 v[38:41], v[168:171], v[192:195], v[38:41]
	v_mfma_f32_16x16x32_bf16 v[34:37], v[176:179], v[192:195], v[34:37]
	v_mfma_f32_16x16x32_bf16 v[22:25], v[168:171], v[200:203], v[22:25]
	v_mfma_f32_16x16x32_bf16 v[18:21], v[176:179], v[200:203], v[18:21]
	v_mfma_f32_16x16x32_bf16 v[6:9], v[168:171], v[208:211], v[6:9]
	v_mfma_f32_16x16x32_bf16 v[2:5], v[176:179], v[208:211], v[2:5]
	v_mfma_f32_16x16x32_bf16 v[54:57], v[172:175], v[188:191], v[54:57]
	v_mfma_f32_16x16x32_bf16 v[50:53], v[180:183], v[188:191], v[50:53]
	v_mfma_f32_16x16x32_bf16 v[38:41], v[172:175], v[196:199], v[38:41]
	v_mfma_f32_16x16x32_bf16 v[34:37], v[180:183], v[196:199], v[34:37]
	v_mfma_f32_16x16x32_bf16 v[22:25], v[172:175], v[204:207], v[22:25]
	v_mfma_f32_16x16x32_bf16 v[18:21], v[180:183], v[204:207], v[18:21]
	v_mfma_f32_16x16x32_bf16 v[6:9], v[172:175], v[212:215], v[6:9]
	v_mfma_f32_16x16x32_bf16 v[2:5], v[180:183], v[212:215], v[2:5]
	s_barrier
	s_add_i32 s61, 0, 0x18000
	v_add_u32_e32 v151, s61, v146
	s_add_i32 s62, 0, 0x1c000
	ds_read_b128 v[152:155], v151
	ds_read_b128 v[156:159], v151 offset:1024
	ds_read_b128 v[160:163], v151 offset:2048
	ds_read_b128 v[164:167], v151 offset:3072
	v_add_u32_e32 v151, s62, v146
	ds_read_b128 v[168:171], v151
	ds_read_b128 v[172:175], v151 offset:1024
	ds_read_b128 v[176:179], v151 offset:2048
	ds_read_b128 v[180:183], v151 offset:3072
	s_add_u32 s30, s30, s10
	s_addc_u32 s31, s31, s11
	s_mov_b32 m0, s39
	v_lshl_add_u64 v[228:229], s[30:31], 0, v[130:131]
	ds_read_b128 v[184:187], v150 offset:32768
	ds_read_b128 v[188:191], v150 offset:33792
	ds_read_b128 v[192:195], v150 offset:34816
	ds_read_b128 v[196:199], v150 offset:35840
	ds_read_b128 v[200:203], v150 offset:36864
	ds_read_b128 v[204:207], v150 offset:37888
	ds_read_b128 v[208:211], v150 offset:38912
	ds_read_b128 v[212:215], v150 offset:39936
	global_load_lds_dwordx4 v[228:229], off
	v_lshl_add_u64 v[228:229], s[30:31], 0, v[134:135]
	s_mov_b32 m0, s40
	s_nop 0
	global_load_lds_dwordx4 v[228:229], off
	s_waitcnt vmcnt(8)
	s_waitcnt lgkmcnt(0)
	s_barrier
	v_mfma_f32_16x16x32_bf16 v[122:125], v[152:155], v[184:187], v[122:125]
	v_mfma_f32_16x16x32_bf16 v[126:129], v[160:163], v[184:187], v[126:129]
	v_mfma_f32_16x16x32_bf16 v[110:113], v[152:155], v[192:195], v[110:113]
	v_mfma_f32_16x16x32_bf16 v[106:109], v[160:163], v[192:195], v[106:109]
	v_mfma_f32_16x16x32_bf16 v[94:97], v[152:155], v[200:203], v[94:97]
	v_mfma_f32_16x16x32_bf16 v[90:93], v[160:163], v[200:203], v[90:93]
	v_mfma_f32_16x16x32_bf16 v[78:81], v[152:155], v[208:211], v[78:81]
	v_mfma_f32_16x16x32_bf16 v[74:77], v[160:163], v[208:211], v[74:77]
	v_mfma_f32_16x16x32_bf16 v[122:125], v[156:159], v[188:191], v[122:125]
	v_mfma_f32_16x16x32_bf16 v[126:129], v[164:167], v[188:191], v[126:129]
	v_mfma_f32_16x16x32_bf16 v[110:113], v[156:159], v[196:199], v[110:113]
	v_mfma_f32_16x16x32_bf16 v[106:109], v[164:167], v[196:199], v[106:109]
	v_mfma_f32_16x16x32_bf16 v[94:97], v[156:159], v[204:207], v[94:97]
	v_mfma_f32_16x16x32_bf16 v[90:93], v[164:167], v[204:207], v[90:93]
	v_mfma_f32_16x16x32_bf16 v[78:81], v[156:159], v[212:215], v[78:81]
	v_mfma_f32_16x16x32_bf16 v[74:77], v[164:167], v[212:215], v[74:77]
	v_mfma_f32_16x16x32_bf16 v[118:121], v[168:171], v[184:187], v[118:121]
	v_mfma_f32_16x16x32_bf16 v[114:117], v[176:179], v[184:187], v[114:117]
	v_mfma_f32_16x16x32_bf16 v[102:105], v[168:171], v[192:195], v[102:105]
	v_mfma_f32_16x16x32_bf16 v[98:101], v[176:179], v[192:195], v[98:101]
	v_mfma_f32_16x16x32_bf16 v[86:89], v[168:171], v[200:203], v[86:89]
	v_mfma_f32_16x16x32_bf16 v[82:85], v[176:179], v[200:203], v[82:85]
	v_mfma_f32_16x16x32_bf16 v[70:73], v[168:171], v[208:211], v[70:73]
	v_mfma_f32_16x16x32_bf16 v[66:69], v[176:179], v[208:211], v[66:69]
	v_mfma_f32_16x16x32_bf16 v[118:121], v[172:175], v[188:191], v[118:121]
	v_mfma_f32_16x16x32_bf16 v[114:117], v[180:183], v[188:191], v[114:117]
	v_mfma_f32_16x16x32_bf16 v[102:105], v[172:175], v[196:199], v[102:105]
	v_mfma_f32_16x16x32_bf16 v[98:101], v[180:183], v[196:199], v[98:101]
	v_mfma_f32_16x16x32_bf16 v[86:89], v[172:175], v[204:207], v[86:89]
	v_mfma_f32_16x16x32_bf16 v[82:85], v[180:183], v[204:207], v[82:85]
	v_mfma_f32_16x16x32_bf16 v[70:73], v[172:175], v[212:215], v[70:73]
	v_mfma_f32_16x16x32_bf16 v[66:69], v[180:183], v[212:215], v[66:69]
	s_barrier
; #define PG8_STAGE(bufoff, gbase, voff) do { _Pragma("unroll") for (int _i = 0; _i < 2; ++_i) \
;         __builtin_amdgcn_global_load_lds((const unsigned*)((const char*)(gbase) + (voff)[_i]), (PG8_LAS unsigned*)(lds + (bufoff) + ldsw + _i * 8192), 16, 0, 0); } while (0)
; #define PG8_LDA(dst, b, h) do { _Pragma("unroll") for (int m = 0; m < 4; ++m) _Pragma("unroll") for (int k = 0; k < 2; ++k) dst[m][k] = *(const PG8_LAS bf16x8*)(lds + PG8_SA(b, h) + aoff + m * 2048 + k * 1024); } while (0)
; #define PG8_MMA(ai, bj, At, Bt) do { __builtin_amdgcn_s_setprio(1); _Pragma("unroll") for (int m = 0; m < 4; ++m) _Pragma("unroll") for (int n = 0; n < 2; ++n) _Pragma("unroll") for (int k = 0; k < 2; ++k) \
;         acc[ai][bj][m][n] = __builtin_amdgcn_mfma_f32_16x16x32_bf16(Bt[n][k], At[m][k], acc[ai][bj][m][n], 0, 0, 0); __builtin_amdgcn_s_setprio(0); } while (0)
; #define PG8_WAIT_V(n) asm volatile("s_waitcnt vmcnt(" #n ")" ::: "memory")
; #define PG8_WAIT_L(n) asm volatile("s_waitcnt lgkmcnt(" #n ")" ::: "memory")
; #define PG8_BAR __builtin_amdgcn_s_barrier()
; #define PG8_SCHED __builtin_amdgcn_sched_barrier(0)
; template <class Epi, class Sched, bool ALIGN_EPI = false, bool SP2 = false>
; __device__ __forceinline__ void gemm_phase(PG8_LAS unsigned char* lds, const Gemm g, const Sched& S, const Epi& E) {
;     ...
;         for (int t = 0; t < nt; t += 2) {
;     ...
;             PG8_LDA(At, 1, 1); PG8_STAGE(PG8_SB(1, 0), b3, voffB); PG8_STAGE(PG8_SB(1, 1), b3 + hstep, voffB); PG8_STAGE(PG8_SA(1, 0), a3, voffA);
;             PG8_WAIT_V(8); PG8_WAIT_L(0); PG8_BAR; PG8_MMA(1, 0, At, B0); PG8_MMA(1, 1, At, B1); PG8_BAR; PG8_SCHED;
	s_add_i32 s30, s61, s38
	v_lshl_add_u64 v[216:217], v[216:217], 0, s[18:19]
	s_mov_b32 m0, s30
	ds_read_b128 v[184:187], v150 offset:49152
	ds_read_b128 v[188:191], v150 offset:50176
	ds_read_b128 v[192:195], v150 offset:51200
	ds_read_b128 v[196:199], v150 offset:52224
	ds_read_b128 v[200:203], v150 offset:53248
	ds_read_b128 v[204:207], v150 offset:54272
	ds_read_b128 v[208:211], v150 offset:55296
	ds_read_b128 v[212:215], v150 offset:56320
	global_load_lds_dwordx4 v[216:217], off
	v_lshl_add_u64 v[216:217], v[218:219], 0, s[18:19]
	s_add_i32 m0, s30, 0x2000
	s_add_i32 s30, s62, s38
	global_load_lds_dwordx4 v[216:217], off
	v_lshl_add_u64 v[216:217], v[220:221], 0, s[18:19]
	s_mov_b32 m0, s30
	s_nop 0
	global_load_lds_dwordx4 v[216:217], off
	v_lshl_add_u64 v[216:217], v[222:223], 0, s[18:19]
	s_add_i32 m0, s30, 0x2000
	s_nop 0
	global_load_lds_dwordx4 v[216:217], off
	v_lshl_add_u64 v[216:217], v[224:225], 0, s[18:19]
	s_mov_b32 m0, s42
	s_nop 0
	global_load_lds_dwordx4 v[216:217], off
	v_lshl_add_u64 v[216:217], v[226:227], 0, s[18:19]
	s_mov_b32 m0, s43
	s_nop 0
	global_load_lds_dwordx4 v[216:217], off
	s_waitcnt vmcnt(8)
	s_waitcnt lgkmcnt(0)
	s_barrier
	v_mfma_f32_16x16x32_bf16 v[62:65], v[152:155], v[184:187], v[62:65]
	v_mfma_f32_16x16x32_bf16 v[58:61], v[160:163], v[184:187], v[58:61]
	v_mfma_f32_16x16x32_bf16 v[46:49], v[152:155], v[192:195], v[46:49]
	v_mfma_f32_16x16x32_bf16 v[42:45], v[160:163], v[192:195], v[42:45]
	v_mfma_f32_16x16x32_bf16 v[30:33], v[152:155], v[200:203], v[30:33]
	v_mfma_f32_16x16x32_bf16 v[26:29], v[160:163], v[200:203], v[26:29]
	v_mfma_f32_16x16x32_bf16 v[14:17], v[152:155], v[208:211], v[14:17]
	v_mfma_f32_16x16x32_bf16 v[10:13], v[160:163], v[208:211], v[10:13]
	v_mfma_f32_16x16x32_bf16 v[62:65], v[156:159], v[188:191], v[62:65]
	v_mfma_f32_16x16x32_bf16 v[58:61], v[164:167], v[188:191], v[58:61]
	v_mfma_f32_16x16x32_bf16 v[46:49], v[156:159], v[196:199], v[46:49]
	v_mfma_f32_16x16x32_bf16 v[42:45], v[164:167], v[196:199], v[42:45]
	v_mfma_f32_16x16x32_bf16 v[30:33], v[156:159], v[204:207], v[30:33]
	v_mfma_f32_16x16x32_bf16 v[26:29], v[164:167], v[204:207], v[26:29]
	v_mfma_f32_16x16x32_bf16 v[14:17], v[156:159], v[212:215], v[14:17]
	v_mfma_f32_16x16x32_bf16 v[10:13], v[164:167], v[212:215], v[10:13]
	v_mfma_f32_16x16x32_bf16 v[54:57], v[168:171], v[184:187], v[54:57]
	v_mfma_f32_16x16x32_bf16 v[50:53], v[176:179], v[184:187], v[50:53]
	v_mfma_f32_16x16x32_bf16 v[38:41], v[168:171], v[192:195], v[38:41]
	v_mfma_f32_16x16x32_bf16 v[34:37], v[176:179], v[192:195], v[34:37]
	v_mfma_f32_16x16x32_bf16 v[22:25], v[168:171], v[200:203], v[22:25]
	v_mfma_f32_16x16x32_bf16 v[18:21], v[176:179], v[200:203], v[18:21]
	v_mfma_f32_16x16x32_bf16 v[6:9], v[168:171], v[208:211], v[6:9]
	v_mfma_f32_16x16x32_bf16 v[2:5], v[176:179], v[208:211], v[2:5]
	v_mfma_f32_16x16x32_bf16 v[54:57], v[172:175], v[188:191], v[54:57]
	v_mfma_f32_16x16x32_bf16 v[50:53], v[180:183], v[188:191], v[50:53]
	v_mfma_f32_16x16x32_bf16 v[38:41], v[172:175], v[196:199], v[38:41]
	v_mfma_f32_16x16x32_bf16 v[34:37], v[180:183], v[196:199], v[34:37]
	v_mfma_f32_16x16x32_bf16 v[22:25], v[172:175], v[204:207], v[22:25]
	v_mfma_f32_16x16x32_bf16 v[18:21], v[180:183], v[204:207], v[18:21]
	v_mfma_f32_16x16x32_bf16 v[6:9], v[172:175], v[212:215], v[6:9]
	v_mfma_f32_16x16x32_bf16 v[2:5], v[180:183], v[212:215], v[2:5]
	s_barrier
	s_add_u32 s58, s58, 0x100
	s_addc_u32 s59, s59, 0
	s_add_u32 s28, s28, 0x100
	s_addc_u32 s29, s29, 0
	s_cmp_ge_i32 s60, s44
	s_mov_b32 s30, s60
	s_cbranch_scc0 .LBB0_582

; #define PG8_STAGE(bufoff, gbase, voff) do { _Pragma("unroll") for (int _i = 0; _i < 2; ++_i) \
;         __builtin_amdgcn_global_load_lds((const unsigned*)((const char*)(gbase) + (voff)[_i]), (PG8_LAS unsigned*)(lds + (bufoff) + ldsw + _i * 8192), 16, 0, 0); } while (0)
; #define PG8_LDA(dst, b, h) do { _Pragma("unroll") for (int m = 0; m < 4; ++m) _Pragma("unroll") for (int k = 0; k < 2; ++k) dst[m][k] = *(const PG8_LAS bf16x8*)(lds + PG8_SA(b, h) + aoff + m * 2048 + k * 1024); } while (0)
; #define PG8_LDB(dst, b, h) do { _Pragma("unroll") for (int n = 0; n < 2; ++n) _Pragma("unroll") for (int k = 0; k < 2; ++k) dst[n][k] = *(const PG8_LAS bf16x8*)(lds + PG8_SB(b, h) + boff + n * 2048 + k * 1024); } while (0)
; #define PG8_MMA(ai, bj, At, Bt) do { __builtin_amdgcn_s_setprio(1); _Pragma("unroll") for (int m = 0; m < 4; ++m) _Pragma("unroll") for (int n = 0; n < 2; ++n) _Pragma("unroll") for (int k = 0; k < 2; ++k) \
;         acc[ai][bj][m][n] = __builtin_amdgcn_mfma_f32_16x16x32_bf16(Bt[n][k], At[m][k], acc[ai][bj][m][n], 0, 0, 0); __builtin_amdgcn_s_setprio(0); } while (0)
; #define PG8_WAIT_V(n) asm volatile("s_waitcnt vmcnt(" #n ")" ::: "memory")
; #define PG8_WAIT_L(n) asm volatile("s_waitcnt lgkmcnt(" #n ")" ::: "memory")
; #define PG8_BAR __builtin_amdgcn_s_barrier()
; #define PG8_SCHED __builtin_amdgcn_sched_barrier(0)
; template <class Epi, class Sched, bool ALIGN_EPI = false, bool SP2 = false>
; __device__ __forceinline__ void gemm_phase(PG8_LAS unsigned char* lds, const Gemm g, const Sched& S, const Epi& E) {
;     ...
;         for (int t = 0; t < nt; t += 2) {
;             const bool last = (t == nt - 2);
;             const char* a1 = cA + (size_t)(t + 1) * kstep;
;             const char* a2 = last ? nA : cA + (size_t)(t + 2) * kstep; const char* b2 = last ? nB : cB + (size_t)(t + 2) * kstep;
;             const char* a3 = a2 + kstep; const char* b3 = b2 + kstep;
;             if (last && has_next) S.a_ready(nxt);
;             if constexpr (SP2) {
;             PG8_LDB(B0, 0, 0); PG8_LDB(B1, 0, 1); PG8_SCHED; PG8_LDA(At, 0, 0); PG8_STAGE(PG8_SA(1, 1), a1 + hstep, voffA);
;             PG8_WAIT_V(8); PG8_WAIT_L(0); PG8_BAR; PG8_MMA(0, 0, At, B0); PG8_MMA(0, 1, At, B1); PG8_BAR; PG8_SCHED;
;             PG8_LDA(At, 0, 1); PG8_STAGE(PG8_SB(0, 0), b2, voffB); PG8_STAGE(PG8_SB(0, 1), b2 + hstep, voffB); PG8_STAGE(PG8_SA(0, 0), a2, voffA);
.LBB0_749:
	ds_read_b128 v[152:155], v148
	ds_read_b128 v[156:159], v148 offset:1024
	ds_read_b128 v[160:163], v148 offset:2048
	ds_read_b128 v[164:167], v148 offset:3072
	ds_read_b128 v[168:171], v149
	ds_read_b128 v[172:175], v149 offset:1024
	ds_read_b128 v[176:179], v149 offset:2048
	ds_read_b128 v[180:183], v149 offset:3072
	s_add_i32 s60, s30, 2
	s_add_u32 s61, s28, 0x80
	s_addc_u32 s31, s29, 0
	s_cmp_eq_u32 s48, s30
	s_cselect_b32 s30, s6, s61
	s_cselect_b32 s31, s7, s31
	s_cselect_b32 s63, s25, s59
	s_cselect_b32 s62, s24, s58
	v_lshl_add_u64 v[216:217], s[28:29], 0, v[140:141]
	s_add_i32 m0, s40, 0xc000
	ds_read_b128 v[184:187], v150
	ds_read_b128 v[188:191], v150 offset:1024
	ds_read_b128 v[192:195], v150 offset:2048
	ds_read_b128 v[196:199], v150 offset:3072
	ds_read_b128 v[200:203], v150 offset:4096
	ds_read_b128 v[204:207], v150 offset:5120
	ds_read_b128 v[208:211], v150 offset:6144
	ds_read_b128 v[212:215], v150 offset:7168
	global_load_lds_dwordx4 v[216:217], off
	v_lshl_add_u64 v[216:217], s[28:29], 0, v[138:139]
	s_add_i32 m0, s40, 0xe000
	s_nop 0
	global_load_lds_dwordx4 v[216:217], off
	s_waitcnt vmcnt(8)
	s_waitcnt lgkmcnt(0)
	s_barrier
	v_mfma_f32_16x16x32_bf16 v[122:125], v[152:155], v[184:187], v[122:125]
	v_mfma_f32_16x16x32_bf16 v[118:121], v[160:163], v[184:187], v[118:121]
	v_mfma_f32_16x16x32_bf16 v[110:113], v[152:155], v[192:195], v[110:113]
	v_mfma_f32_16x16x32_bf16 v[102:105], v[160:163], v[192:195], v[102:105]
	v_mfma_f32_16x16x32_bf16 v[94:97], v[152:155], v[200:203], v[94:97]
	v_mfma_f32_16x16x32_bf16 v[86:89], v[160:163], v[200:203], v[86:89]
	v_mfma_f32_16x16x32_bf16 v[78:81], v[152:155], v[208:211], v[78:81]
	v_mfma_f32_16x16x32_bf16 v[70:73], v[160:163], v[208:211], v[70:73]
	v_mfma_f32_16x16x32_bf16 v[122:125], v[156:159], v[188:191], v[122:125]
	v_mfma_f32_16x16x32_bf16 v[118:121], v[164:167], v[188:191], v[118:121]
	v_mfma_f32_16x16x32_bf16 v[110:113], v[156:159], v[196:199], v[110:113]
	v_mfma_f32_16x16x32_bf16 v[102:105], v[164:167], v[196:199], v[102:105]
	v_mfma_f32_16x16x32_bf16 v[94:97], v[156:159], v[204:207], v[94:97]
	v_mfma_f32_16x16x32_bf16 v[86:89], v[164:167], v[204:207], v[86:89]
	v_mfma_f32_16x16x32_bf16 v[78:81], v[156:159], v[212:215], v[78:81]
	v_mfma_f32_16x16x32_bf16 v[70:73], v[164:167], v[212:215], v[70:73]
	v_mfma_f32_16x16x32_bf16 v[126:129], v[168:171], v[184:187], v[126:129]
	v_mfma_f32_16x16x32_bf16 v[114:117], v[176:179], v[184:187], v[114:117]
	v_mfma_f32_16x16x32_bf16 v[106:109], v[168:171], v[192:195], v[106:109]
	v_mfma_f32_16x16x32_bf16 v[98:101], v[176:179], v[192:195], v[98:101]
	v_mfma_f32_16x16x32_bf16 v[90:93], v[168:171], v[200:203], v[90:93]
	v_mfma_f32_16x16x32_bf16 v[82:85], v[176:179], v[200:203], v[82:85]
	v_mfma_f32_16x16x32_bf16 v[74:77], v[168:171], v[208:211], v[74:77]
	v_mfma_f32_16x16x32_bf16 v[66:69], v[176:179], v[208:211], v[66:69]
	v_mfma_f32_16x16x32_bf16 v[126:129], v[172:175], v[188:191], v[126:129]
	v_mfma_f32_16x16x32_bf16 v[114:117], v[180:183], v[188:191], v[114:117]
	v_mfma_f32_16x16x32_bf16 v[106:109], v[172:175], v[196:199], v[106:109]
	v_mfma_f32_16x16x32_bf16 v[98:101], v[180:183], v[196:199], v[98:101]
	v_mfma_f32_16x16x32_bf16 v[90:93], v[172:175], v[204:207], v[90:93]
	v_mfma_f32_16x16x32_bf16 v[82:85], v[180:183], v[204:207], v[82:85]
	v_mfma_f32_16x16x32_bf16 v[74:77], v[172:175], v[212:215], v[74:77]
	v_mfma_f32_16x16x32_bf16 v[66:69], v[180:183], v[212:215], v[66:69]
	s_barrier
	s_add_i32 s61, s53, s37
	v_lshl_add_u64 v[216:217], s[62:63], 0, v[134:135]
	s_mov_b32 m0, s61
	ds_read_b128 v[184:187], v150 offset:16384
	ds_read_b128 v[188:191], v150 offset:17408
	ds_read_b128 v[192:195], v150 offset:18432
	ds_read_b128 v[196:199], v150 offset:19456
	ds_read_b128 v[200:203], v150 offset:20480
	ds_read_b128 v[204:207], v150 offset:21504
	ds_read_b128 v[208:211], v150 offset:22528
	ds_read_b128 v[212:215], v150 offset:23552
	global_load_lds_dwordx4 v[216:217], off
	s_add_i32 m0, s61, 0x2000
	v_lshl_add_u64 v[218:219], s[62:63], 0, v[130:131]
	s_add_u32 s62, s62, s10
	s_addc_u32 s63, s63, s11
	s_add_i32 s61, s54, s37
	global_load_lds_dwordx4 v[218:219], off
	v_lshl_add_u64 v[220:221], s[62:63], 0, v[134:135]
	s_mov_b32 m0, s61
	v_lshl_add_u64 v[222:223], s[62:63], 0, v[130:131]
	global_load_lds_dwordx4 v[220:221], off
	s_add_i32 m0, s61, 0x2000
	v_lshl_add_u64 v[224:225], s[30:31], 0, v[136:137]
	global_load_lds_dwordx4 v[222:223], off
	s_mov_b32 m0, s40
	v_lshl_add_u64 v[226:227], s[30:31], 0, v[132:133]
	global_load_lds_dwordx4 v[224:225], off
	s_mov_b32 m0, s41
	s_nop 0
	global_load_lds_dwordx4 v[226:227], off
	s_waitcnt vmcnt(8)
	s_waitcnt lgkmcnt(0)
	s_barrier
; #define PG8_STAGE(bufoff, gbase, voff) do { _Pragma("unroll") for (int _i = 0; _i < 2; ++_i) \
;         __builtin_amdgcn_global_load_lds((const unsigned*)((const char*)(gbase) + (voff)[_i]), (PG8_LAS unsigned*)(lds + (bufoff) + ldsw + _i * 8192), 16, 0, 0); } while (0)
; #define PG8_LDA(dst, b, h) do { _Pragma("unroll") for (int m = 0; m < 4; ++m) _Pragma("unroll") for (int k = 0; k < 2; ++k) dst[m][k] = *(const PG8_LAS bf16x8*)(lds + PG8_SA(b, h) + aoff + m * 2048 + k * 1024); } while (0)
; #define PG8_LDB(dst, b, h) do { _Pragma("unroll") for (int n = 0; n < 2; ++n) _Pragma("unroll") for (int k = 0; k < 2; ++k) dst[n][k] = *(const PG8_LAS bf16x8*)(lds + PG8_SB(b, h) + boff + n * 2048 + k * 1024); } while (0)
; #define PG8_MMA(ai, bj, At, Bt) do { __builtin_amdgcn_s_setprio(1); _Pragma("unroll") for (int m = 0; m < 4; ++m) _Pragma("unroll") for (int n = 0; n < 2; ++n) _Pragma("unroll") for (int k = 0; k < 2; ++k) \
;         acc[ai][bj][m][n] = __builtin_amdgcn_mfma_f32_16x16x32_bf16(Bt[n][k], At[m][k], acc[ai][bj][m][n], 0, 0, 0); __builtin_amdgcn_s_setprio(0); } while (0)
; #define PG8_WAIT_V(n) asm volatile("s_waitcnt vmcnt(" #n ")" ::: "memory")
; #define PG8_WAIT_L(n) asm volatile("s_waitcnt lgkmcnt(" #n ")" ::: "memory")
; #define PG8_BAR __builtin_amdgcn_s_barrier()
; #define PG8_SCHED __builtin_amdgcn_sched_barrier(0)
; template <class Epi, class Sched, bool ALIGN_EPI = false, bool SP2 = false>
; __device__ __forceinline__ void gemm_phase(PG8_LAS unsigned char* lds, const Gemm g, const Sched& S, const Epi& E) {
;     ...
;             PG8_WAIT_V(8); PG8_WAIT_L(0); PG8_BAR; PG8_MMA(1, 0, At, B0); PG8_MMA(1, 1, At, B1); PG8_BAR; PG8_SCHED;
;             PG8_LDB(B0, 1, 0); PG8_LDB(B1, 1, 1); PG8_SCHED; PG8_LDA(At, 1, 0); PG8_STAGE(PG8_SA(0, 1), a2 + hstep, voffA);
;             PG8_WAIT_V(8); PG8_WAIT_L(0); PG8_BAR; PG8_MMA(0, 0, At, B0); PG8_MMA(0, 1, At, B1); PG8_BAR; PG8_SCHED;
	v_mfma_f32_16x16x32_bf16 v[62:65], v[152:155], v[184:187], v[62:65]
	v_mfma_f32_16x16x32_bf16 v[54:57], v[160:163], v[184:187], v[54:57]
	v_mfma_f32_16x16x32_bf16 v[46:49], v[152:155], v[192:195], v[46:49]
	v_mfma_f32_16x16x32_bf16 v[38:41], v[160:163], v[192:195], v[38:41]
	v_mfma_f32_16x16x32_bf16 v[30:33], v[152:155], v[200:203], v[30:33]
	v_mfma_f32_16x16x32_bf16 v[22:25], v[160:163], v[200:203], v[22:25]
	v_mfma_f32_16x16x32_bf16 v[14:17], v[152:155], v[208:211], v[14:17]
	v_mfma_f32_16x16x32_bf16 v[6:9], v[160:163], v[208:211], v[6:9]
	v_mfma_f32_16x16x32_bf16 v[62:65], v[156:159], v[188:191], v[62:65]
	v_mfma_f32_16x16x32_bf16 v[54:57], v[164:167], v[188:191], v[54:57]
	v_mfma_f32_16x16x32_bf16 v[46:49], v[156:159], v[196:199], v[46:49]
	v_mfma_f32_16x16x32_bf16 v[38:41], v[164:167], v[196:199], v[38:41]
	v_mfma_f32_16x16x32_bf16 v[30:33], v[156:159], v[204:207], v[30:33]
	v_mfma_f32_16x16x32_bf16 v[22:25], v[164:167], v[204:207], v[22:25]
	v_mfma_f32_16x16x32_bf16 v[14:17], v[156:159], v[212:215], v[14:17]
	v_mfma_f32_16x16x32_bf16 v[6:9], v[164:167], v[212:215], v[6:9]
	v_mfma_f32_16x16x32_bf16 v[58:61], v[168:171], v[184:187], v[58:61]
	v_mfma_f32_16x16x32_bf16 v[50:53], v[176:179], v[184:187], v[50:53]
	v_mfma_f32_16x16x32_bf16 v[42:45], v[168:171], v[192:195], v[42:45]
	v_mfma_f32_16x16x32_bf16 v[34:37], v[176:179], v[192:195], v[34:37]
	v_mfma_f32_16x16x32_bf16 v[26:29], v[168:171], v[200:203], v[26:29]
	v_mfma_f32_16x16x32_bf16 v[18:21], v[176:179], v[200:203], v[18:21]
	v_mfma_f32_16x16x32_bf16 v[10:13], v[168:171], v[208:211], v[10:13]
	v_mfma_f32_16x16x32_bf16 v[2:5], v[176:179], v[208:211], v[2:5]
	v_mfma_f32_16x16x32_bf16 v[58:61], v[172:175], v[188:191], v[58:61]
	v_mfma_f32_16x16x32_bf16 v[50:53], v[180:183], v[188:191], v[50:53]
	v_mfma_f32_16x16x32_bf16 v[42:45], v[172:175], v[196:199], v[42:45]
	v_mfma_f32_16x16x32_bf16 v[34:37], v[180:183], v[196:199], v[34:37]
	v_mfma_f32_16x16x32_bf16 v[26:29], v[172:175], v[204:207], v[26:29]
	v_mfma_f32_16x16x32_bf16 v[18:21], v[180:183], v[204:207], v[18:21]
	v_mfma_f32_16x16x32_bf16 v[10:13], v[172:175], v[212:215], v[10:13]
	v_mfma_f32_16x16x32_bf16 v[2:5], v[180:183], v[212:215], v[2:5]
	s_barrier
	s_add_i32 s61, 0, 0x18000
	v_add_u32_e32 v151, s61, v146
	s_add_i32 s62, 0, 0x1c000
	ds_read_b128 v[152:155], v151
	ds_read_b128 v[156:159], v151 offset:1024
	ds_read_b128 v[160:163], v151 offset:2048
	ds_read_b128 v[164:167], v151 offset:3072
	v_add_u32_e32 v151, s62, v146
	ds_read_b128 v[168:171], v151
	ds_read_b128 v[172:175], v151 offset:1024
	ds_read_b128 v[176:179], v151 offset:2048
	ds_read_b128 v[180:183], v151 offset:3072
	s_add_u32 s30, s30, s10
	s_addc_u32 s31, s31, s11
	s_mov_b32 m0, s42
	v_lshl_add_u64 v[228:229], s[30:31], 0, v[136:137]
	ds_read_b128 v[184:187], v150 offset:32768
	ds_read_b128 v[188:191], v150 offset:33792
	ds_read_b128 v[192:195], v150 offset:34816
	ds_read_b128 v[196:199], v150 offset:35840
	ds_read_b128 v[200:203], v150 offset:36864
	ds_read_b128 v[204:207], v150 offset:37888
	ds_read_b128 v[208:211], v150 offset:38912
	ds_read_b128 v[212:215], v150 offset:39936
	global_load_lds_dwordx4 v[228:229], off
	v_lshl_add_u64 v[228:229], s[30:31], 0, v[132:133]
	s_mov_b32 m0, s43
	s_nop 0
	global_load_lds_dwordx4 v[228:229], off
	s_waitcnt vmcnt(8)
	s_waitcnt lgkmcnt(0)
	s_barrier
	v_mfma_f32_16x16x32_bf16 v[122:125], v[152:155], v[184:187], v[122:125]
	v_mfma_f32_16x16x32_bf16 v[118:121], v[160:163], v[184:187], v[118:121]
	v_mfma_f32_16x16x32_bf16 v[110:113], v[152:155], v[192:195], v[110:113]
	v_mfma_f32_16x16x32_bf16 v[102:105], v[160:163], v[192:195], v[102:105]
	v_mfma_f32_16x16x32_bf16 v[94:97], v[152:155], v[200:203], v[94:97]
	v_mfma_f32_16x16x32_bf16 v[86:89], v[160:163], v[200:203], v[86:89]
	v_mfma_f32_16x16x32_bf16 v[78:81], v[152:155], v[208:211], v[78:81]
	v_mfma_f32_16x16x32_bf16 v[70:73], v[160:163], v[208:211], v[70:73]
	v_mfma_f32_16x16x32_bf16 v[122:125], v[156:159], v[188:191], v[122:125]
	v_mfma_f32_16x16x32_bf16 v[118:121], v[164:167], v[188:191], v[118:121]
	v_mfma_f32_16x16x32_bf16 v[110:113], v[156:159], v[196:199], v[110:113]
	v_mfma_f32_16x16x32_bf16 v[102:105], v[164:167], v[196:199], v[102:105]
	v_mfma_f32_16x16x32_bf16 v[94:97], v[156:159], v[204:207], v[94:97]
	v_mfma_f32_16x16x32_bf16 v[86:89], v[164:167], v[204:207], v[86:89]
	v_mfma_f32_16x16x32_bf16 v[78:81], v[156:159], v[212:215], v[78:81]
	v_mfma_f32_16x16x32_bf16 v[70:73], v[164:167], v[212:215], v[70:73]
	v_mfma_f32_16x16x32_bf16 v[126:129], v[168:171], v[184:187], v[126:129]
	v_mfma_f32_16x16x32_bf16 v[114:117], v[176:179], v[184:187], v[114:117]
	v_mfma_f32_16x16x32_bf16 v[106:109], v[168:171], v[192:195], v[106:109]
	v_mfma_f32_16x16x32_bf16 v[98:101], v[176:179], v[192:195], v[98:101]
	v_mfma_f32_16x16x32_bf16 v[90:93], v[168:171], v[200:203], v[90:93]
	v_mfma_f32_16x16x32_bf16 v[82:85], v[176:179], v[200:203], v[82:85]
	v_mfma_f32_16x16x32_bf16 v[74:77], v[168:171], v[208:211], v[74:77]
	v_mfma_f32_16x16x32_bf16 v[66:69], v[176:179], v[208:211], v[66:69]
	v_mfma_f32_16x16x32_bf16 v[126:129], v[172:175], v[188:191], v[126:129]
	v_mfma_f32_16x16x32_bf16 v[114:117], v[180:183], v[188:191], v[114:117]
	v_mfma_f32_16x16x32_bf16 v[106:109], v[172:175], v[196:199], v[106:109]
	v_mfma_f32_16x16x32_bf16 v[98:101], v[180:183], v[196:199], v[98:101]
	v_mfma_f32_16x16x32_bf16 v[90:93], v[172:175], v[204:207], v[90:93]
	v_mfma_f32_16x16x32_bf16 v[82:85], v[180:183], v[204:207], v[82:85]
	v_mfma_f32_16x16x32_bf16 v[74:77], v[172:175], v[212:215], v[74:77]
	v_mfma_f32_16x16x32_bf16 v[66:69], v[180:183], v[212:215], v[66:69]
	s_barrier
; #define PG8_STAGE(bufoff, gbase, voff) do { _Pragma("unroll") for (int _i = 0; _i < 2; ++_i) \
;         __builtin_amdgcn_global_load_lds((const unsigned*)((const char*)(gbase) + (voff)[_i]), (PG8_LAS unsigned*)(lds + (bufoff) + ldsw + _i * 8192), 16, 0, 0); } while (0)
; #define PG8_LDA(dst, b, h) do { _Pragma("unroll") for (int m = 0; m < 4; ++m) _Pragma("unroll") for (int k = 0; k < 2; ++k) dst[m][k] = *(const PG8_LAS bf16x8*)(lds + PG8_SA(b, h) + aoff + m * 2048 + k * 1024); } while (0)
; #define PG8_MMA(ai, bj, At, Bt) do { __builtin_amdgcn_s_setprio(1); _Pragma("unroll") for (int m = 0; m < 4; ++m) _Pragma("unroll") for (int n = 0; n < 2; ++n) _Pragma("unroll") for (int k = 0; k < 2; ++k) \
;         acc[ai][bj][m][n] = __builtin_amdgcn_mfma_f32_16x16x32_bf16(Bt[n][k], At[m][k], acc[ai][bj][m][n], 0, 0, 0); __builtin_amdgcn_s_setprio(0); } while (0)
; #define PG8_WAIT_V(n) asm volatile("s_waitcnt vmcnt(" #n ")" ::: "memory")
; #define PG8_WAIT_L(n) asm volatile("s_waitcnt lgkmcnt(" #n ")" ::: "memory")
; #define PG8_BAR __builtin_amdgcn_s_barrier()
; #define PG8_SCHED __builtin_amdgcn_sched_barrier(0)
; template <class Epi, class Sched, bool ALIGN_EPI = false, bool SP2 = false>
; __device__ __forceinline__ void gemm_phase(PG8_LAS unsigned char* lds, const Gemm g, const Sched& S, const Epi& E) {
;     ...
;         for (int t = 0; t < nt; t += 2) {
;     ...
;             PG8_LDA(At, 1, 1); PG8_STAGE(PG8_SB(1, 0), b3, voffB); PG8_STAGE(PG8_SB(1, 1), b3 + hstep, voffB); PG8_STAGE(PG8_SA(1, 0), a3, voffA);
;             PG8_WAIT_V(8); PG8_WAIT_L(0); PG8_BAR; PG8_MMA(1, 0, At, B0); PG8_MMA(1, 1, At, B1); PG8_BAR; PG8_SCHED;
	s_add_i32 s30, s61, s37
	v_lshl_add_u64 v[216:217], v[216:217], 0, s[18:19]
	s_mov_b32 m0, s30
	ds_read_b128 v[184:187], v150 offset:49152
	ds_read_b128 v[188:191], v150 offset:50176
	ds_read_b128 v[192:195], v150 offset:51200
	ds_read_b128 v[196:199], v150 offset:52224
	ds_read_b128 v[200:203], v150 offset:53248
	ds_read_b128 v[204:207], v150 offset:54272
	ds_read_b128 v[208:211], v150 offset:55296
	ds_read_b128 v[212:215], v150 offset:56320
	global_load_lds_dwordx4 v[216:217], off
	v_lshl_add_u64 v[216:217], v[218:219], 0, s[18:19]
	s_add_i32 m0, s30, 0x2000
	s_add_i32 s30, s62, s37
	global_load_lds_dwordx4 v[216:217], off
	v_lshl_add_u64 v[216:217], v[220:221], 0, s[18:19]
	s_mov_b32 m0, s30
	s_nop 0
	global_load_lds_dwordx4 v[216:217], off
	v_lshl_add_u64 v[216:217], v[222:223], 0, s[18:19]
	s_add_i32 m0, s30, 0x2000
	s_nop 0
	global_load_lds_dwordx4 v[216:217], off
	v_lshl_add_u64 v[216:217], v[224:225], 0, s[18:19]
	s_mov_b32 m0, s45
	s_nop 0
	global_load_lds_dwordx4 v[216:217], off
	v_lshl_add_u64 v[216:217], v[226:227], 0, s[18:19]
	s_mov_b32 m0, s46
	s_nop 0
	global_load_lds_dwordx4 v[216:217], off
	s_waitcnt vmcnt(8)
	s_waitcnt lgkmcnt(0)
	s_barrier
	v_mfma_f32_16x16x32_bf16 v[62:65], v[152:155], v[184:187], v[62:65]
	v_mfma_f32_16x16x32_bf16 v[54:57], v[160:163], v[184:187], v[54:57]
	v_mfma_f32_16x16x32_bf16 v[46:49], v[152:155], v[192:195], v[46:49]
	v_mfma_f32_16x16x32_bf16 v[38:41], v[160:163], v[192:195], v[38:41]
	v_mfma_f32_16x16x32_bf16 v[30:33], v[152:155], v[200:203], v[30:33]
	v_mfma_f32_16x16x32_bf16 v[22:25], v[160:163], v[200:203], v[22:25]
	v_mfma_f32_16x16x32_bf16 v[14:17], v[152:155], v[208:211], v[14:17]
	v_mfma_f32_16x16x32_bf16 v[6:9], v[160:163], v[208:211], v[6:9]
	v_mfma_f32_16x16x32_bf16 v[62:65], v[156:159], v[188:191], v[62:65]
	v_mfma_f32_16x16x32_bf16 v[54:57], v[164:167], v[188:191], v[54:57]
	v_mfma_f32_16x16x32_bf16 v[46:49], v[156:159], v[196:199], v[46:49]
	v_mfma_f32_16x16x32_bf16 v[38:41], v[164:167], v[196:199], v[38:41]
	v_mfma_f32_16x16x32_bf16 v[30:33], v[156:159], v[204:207], v[30:33]
	v_mfma_f32_16x16x32_bf16 v[22:25], v[164:167], v[204:207], v[22:25]
	v_mfma_f32_16x16x32_bf16 v[14:17], v[156:159], v[212:215], v[14:17]
	v_mfma_f32_16x16x32_bf16 v[6:9], v[164:167], v[212:215], v[6:9]
	v_mfma_f32_16x16x32_bf16 v[58:61], v[168:171], v[184:187], v[58:61]
	v_mfma_f32_16x16x32_bf16 v[50:53], v[176:179], v[184:187], v[50:53]
	v_mfma_f32_16x16x32_bf16 v[42:45], v[168:171], v[192:195], v[42:45]
	v_mfma_f32_16x16x32_bf16 v[34:37], v[176:179], v[192:195], v[34:37]
	v_mfma_f32_16x16x32_bf16 v[26:29], v[168:171], v[200:203], v[26:29]
	v_mfma_f32_16x16x32_bf16 v[18:21], v[176:179], v[200:203], v[18:21]
	v_mfma_f32_16x16x32_bf16 v[10:13], v[168:171], v[208:211], v[10:13]
	v_mfma_f32_16x16x32_bf16 v[2:5], v[176:179], v[208:211], v[2:5]
	v_mfma_f32_16x16x32_bf16 v[58:61], v[172:175], v[188:191], v[58:61]
	v_mfma_f32_16x16x32_bf16 v[50:53], v[180:183], v[188:191], v[50:53]
	v_mfma_f32_16x16x32_bf16 v[42:45], v[172:175], v[196:199], v[42:45]
	v_mfma_f32_16x16x32_bf16 v[34:37], v[180:183], v[196:199], v[34:37]
	v_mfma_f32_16x16x32_bf16 v[26:29], v[172:175], v[204:207], v[26:29]
	v_mfma_f32_16x16x32_bf16 v[18:21], v[180:183], v[204:207], v[18:21]
	v_mfma_f32_16x16x32_bf16 v[10:13], v[172:175], v[212:215], v[10:13]
	v_mfma_f32_16x16x32_bf16 v[2:5], v[180:183], v[212:215], v[2:5]
	s_barrier
	s_add_u32 s58, s58, 0x100
	s_addc_u32 s59, s59, 0
	s_add_u32 s28, s28, 0x100
	s_addc_u32 s29, s29, 0
	s_cmp_ge_i32 s60, s47
	s_mov_b32 s30, s60
	s_cbranch_scc0 .LBB0_749

; #define PG8_STAGE(bufoff, gbase, voff) do { _Pragma("unroll") for (int _i = 0; _i < 2; ++_i) \
;         __builtin_amdgcn_global_load_lds((const unsigned*)((const char*)(gbase) + (voff)[_i]), (PG8_LAS unsigned*)(lds + (bufoff) + ldsw + _i * 8192), 16, 0, 0); } while (0)
; #define PG8_LDA(dst, b, h) do { _Pragma("unroll") for (int m = 0; m < 4; ++m) _Pragma("unroll") for (int k = 0; k < 2; ++k) dst[m][k] = *(const PG8_LAS bf16x8*)(lds + PG8_SA(b, h) + aoff + m * 2048 + k * 1024); } while (0)
; #define PG8_LDB(dst, b, h) do { _Pragma("unroll") for (int n = 0; n < 2; ++n) _Pragma("unroll") for (int k = 0; k < 2; ++k) dst[n][k] = *(const PG8_LAS bf16x8*)(lds + PG8_SB(b, h) + boff + n * 2048 + k * 1024); } while (0)
; #define PG8_MMA(ai, bj, At, Bt) do { __builtin_amdgcn_s_setprio(1); _Pragma("unroll") for (int m = 0; m < 4; ++m) _Pragma("unroll") for (int n = 0; n < 2; ++n) _Pragma("unroll") for (int k = 0; k < 2; ++k) \
;         acc[ai][bj][m][n] = __builtin_amdgcn_mfma_f32_16x16x32_bf16(Bt[n][k], At[m][k], acc[ai][bj][m][n], 0, 0, 0); __builtin_amdgcn_s_setprio(0); } while (0)
; #define PG8_WAIT_V(n) asm volatile("s_waitcnt vmcnt(" #n ")" ::: "memory")
; #define PG8_WAIT_L(n) asm volatile("s_waitcnt lgkmcnt(" #n ")" ::: "memory")
; #define PG8_BAR __builtin_amdgcn_s_barrier()
; #define PG8_SCHED __builtin_amdgcn_sched_barrier(0)
; template <class Epi, class Sched, bool ALIGN_EPI = false, bool SP2 = false>
; __device__ __forceinline__ void gemm_phase(PG8_LAS unsigned char* lds, const Gemm g, const Sched& S, const Epi& E) {
;     ...
;         for (int t = 0; t < nt; t += 2) {
;             const bool last = (t == nt - 2);
;             const char* a1 = cA + (size_t)(t + 1) * kstep;
;             const char* a2 = last ? nA : cA + (size_t)(t + 2) * kstep; const char* b2 = last ? nB : cB + (size_t)(t + 2) * kstep;
;             const char* a3 = a2 + kstep; const char* b3 = b2 + kstep;
;             if (last && has_next) S.a_ready(nxt);
;             if constexpr (SP2) {
;             PG8_LDB(B0, 0, 0); PG8_LDB(B1, 0, 1); PG8_SCHED; PG8_LDA(At, 0, 0); PG8_STAGE(PG8_SA(1, 1), a1 + hstep, voffA);
;             PG8_WAIT_V(8); PG8_WAIT_L(0); PG8_BAR; PG8_MMA(0, 0, At, B0); PG8_MMA(0, 1, At, B1); PG8_BAR; PG8_SCHED;
;             PG8_LDA(At, 0, 1); PG8_STAGE(PG8_SB(0, 0), b2, voffB); PG8_STAGE(PG8_SB(0, 1), b2 + hstep, voffB); PG8_STAGE(PG8_SA(0, 0), a2, voffA);
.LBB0_834:
	ds_read_b128 v[152:155], v148
	ds_read_b128 v[156:159], v148 offset:1024
	ds_read_b128 v[160:163], v148 offset:2048
	ds_read_b128 v[164:167], v148 offset:3072
	ds_read_b128 v[168:171], v149
	ds_read_b128 v[172:175], v149 offset:1024
	ds_read_b128 v[176:179], v149 offset:2048
	ds_read_b128 v[180:183], v149 offset:3072
	s_add_i32 s58, s30, 2
	s_add_u32 s59, s28, 0x80
	s_addc_u32 s31, s29, 0
	s_cmp_eq_u32 s45, s30
	s_cselect_b32 s30, s6, s59
	s_cselect_b32 s31, s7, s31
	s_cselect_b32 s61, s25, s57
	s_cselect_b32 s60, s24, s56
	v_lshl_add_u64 v[216:217], s[28:29], 0, v[140:141]
	s_add_i32 m0, s0, 0xc000
	ds_read_b128 v[184:187], v150
	ds_read_b128 v[188:191], v150 offset:1024
	ds_read_b128 v[192:195], v150 offset:2048
	ds_read_b128 v[196:199], v150 offset:3072
	ds_read_b128 v[200:203], v150 offset:4096
	ds_read_b128 v[204:207], v150 offset:5120
	ds_read_b128 v[208:211], v150 offset:6144
	ds_read_b128 v[212:215], v150 offset:7168
	global_load_lds_dwordx4 v[216:217], off
	v_lshl_add_u64 v[216:217], s[28:29], 0, v[138:139]
	s_add_i32 m0, s0, 0xe000
	s_nop 0
	global_load_lds_dwordx4 v[216:217], off
	s_waitcnt vmcnt(8)
	s_waitcnt lgkmcnt(0)
	s_barrier
	v_mfma_f32_16x16x32_bf16 v[122:125], v[152:155], v[184:187], v[122:125]
	v_mfma_f32_16x16x32_bf16 v[126:129], v[160:163], v[184:187], v[126:129]
	v_mfma_f32_16x16x32_bf16 v[110:113], v[152:155], v[192:195], v[110:113]
	v_mfma_f32_16x16x32_bf16 v[106:109], v[160:163], v[192:195], v[106:109]
	v_mfma_f32_16x16x32_bf16 v[94:97], v[152:155], v[200:203], v[94:97]
	v_mfma_f32_16x16x32_bf16 v[90:93], v[160:163], v[200:203], v[90:93]
	v_mfma_f32_16x16x32_bf16 v[78:81], v[152:155], v[208:211], v[78:81]
	v_mfma_f32_16x16x32_bf16 v[74:77], v[160:163], v[208:211], v[74:77]
	v_mfma_f32_16x16x32_bf16 v[122:125], v[156:159], v[188:191], v[122:125]
	v_mfma_f32_16x16x32_bf16 v[126:129], v[164:167], v[188:191], v[126:129]
	v_mfma_f32_16x16x32_bf16 v[110:113], v[156:159], v[196:199], v[110:113]
	v_mfma_f32_16x16x32_bf16 v[106:109], v[164:167], v[196:199], v[106:109]
	v_mfma_f32_16x16x32_bf16 v[94:97], v[156:159], v[204:207], v[94:97]
	v_mfma_f32_16x16x32_bf16 v[90:93], v[164:167], v[204:207], v[90:93]
	v_mfma_f32_16x16x32_bf16 v[78:81], v[156:159], v[212:215], v[78:81]
	v_mfma_f32_16x16x32_bf16 v[74:77], v[164:167], v[212:215], v[74:77]
	v_mfma_f32_16x16x32_bf16 v[118:121], v[168:171], v[184:187], v[118:121]
	v_mfma_f32_16x16x32_bf16 v[114:117], v[176:179], v[184:187], v[114:117]
	v_mfma_f32_16x16x32_bf16 v[102:105], v[168:171], v[192:195], v[102:105]
	v_mfma_f32_16x16x32_bf16 v[98:101], v[176:179], v[192:195], v[98:101]
	v_mfma_f32_16x16x32_bf16 v[86:89], v[168:171], v[200:203], v[86:89]
	v_mfma_f32_16x16x32_bf16 v[82:85], v[176:179], v[200:203], v[82:85]
	v_mfma_f32_16x16x32_bf16 v[70:73], v[168:171], v[208:211], v[70:73]
	v_mfma_f32_16x16x32_bf16 v[66:69], v[176:179], v[208:211], v[66:69]
	v_mfma_f32_16x16x32_bf16 v[118:121], v[172:175], v[188:191], v[118:121]
	v_mfma_f32_16x16x32_bf16 v[114:117], v[180:183], v[188:191], v[114:117]
	v_mfma_f32_16x16x32_bf16 v[102:105], v[172:175], v[196:199], v[102:105]
	v_mfma_f32_16x16x32_bf16 v[98:101], v[180:183], v[196:199], v[98:101]
	v_mfma_f32_16x16x32_bf16 v[86:89], v[172:175], v[204:207], v[86:89]
	v_mfma_f32_16x16x32_bf16 v[82:85], v[180:183], v[204:207], v[82:85]
	v_mfma_f32_16x16x32_bf16 v[70:73], v[172:175], v[212:215], v[70:73]
	v_mfma_f32_16x16x32_bf16 v[66:69], v[180:183], v[212:215], v[66:69]
	s_barrier
	s_add_i32 s59, s48, s38
	v_lshl_add_u64 v[216:217], s[60:61], 0, v[132:133]
	s_mov_b32 m0, s59
	ds_read_b128 v[184:187], v150 offset:16384
	ds_read_b128 v[188:191], v150 offset:17408
	ds_read_b128 v[192:195], v150 offset:18432
	ds_read_b128 v[196:199], v150 offset:19456
	ds_read_b128 v[200:203], v150 offset:20480
	ds_read_b128 v[204:207], v150 offset:21504
	ds_read_b128 v[208:211], v150 offset:22528
	ds_read_b128 v[212:215], v150 offset:23552
	global_load_lds_dwordx4 v[216:217], off
	s_add_i32 m0, s59, 0x2000
	v_lshl_add_u64 v[218:219], s[60:61], 0, v[136:137]
	s_add_u32 s60, s60, s10
	s_addc_u32 s61, s61, s11
	s_add_i32 s59, s49, s38
	global_load_lds_dwordx4 v[218:219], off
	v_lshl_add_u64 v[220:221], s[60:61], 0, v[132:133]
	s_mov_b32 m0, s59
	v_lshl_add_u64 v[222:223], s[60:61], 0, v[136:137]
	global_load_lds_dwordx4 v[220:221], off
	s_add_i32 m0, s59, 0x2000
	v_lshl_add_u64 v[224:225], s[30:31], 0, v[130:131]
	global_load_lds_dwordx4 v[222:223], off
	s_mov_b32 m0, s0
	v_lshl_add_u64 v[226:227], s[30:31], 0, v[134:135]
	global_load_lds_dwordx4 v[224:225], off
	s_mov_b32 m0, s1
	s_nop 0
	global_load_lds_dwordx4 v[226:227], off
	s_waitcnt vmcnt(8)
	s_waitcnt lgkmcnt(0)
	s_barrier
; #define PG8_STAGE(bufoff, gbase, voff) do { _Pragma("unroll") for (int _i = 0; _i < 2; ++_i) \
;         __builtin_amdgcn_global_load_lds((const unsigned*)((const char*)(gbase) + (voff)[_i]), (PG8_LAS unsigned*)(lds + (bufoff) + ldsw + _i * 8192), 16, 0, 0); } while (0)
; #define PG8_LDA(dst, b, h) do { _Pragma("unroll") for (int m = 0; m < 4; ++m) _Pragma("unroll") for (int k = 0; k < 2; ++k) dst[m][k] = *(const PG8_LAS bf16x8*)(lds + PG8_SA(b, h) + aoff + m * 2048 + k * 1024); } while (0)
; #define PG8_LDB(dst, b, h) do { _Pragma("unroll") for (int n = 0; n < 2; ++n) _Pragma("unroll") for (int k = 0; k < 2; ++k) dst[n][k] = *(const PG8_LAS bf16x8*)(lds + PG8_SB(b, h) + boff + n * 2048 + k * 1024); } while (0)
; #define PG8_MMA(ai, bj, At, Bt) do { __builtin_amdgcn_s_setprio(1); _Pragma("unroll") for (int m = 0; m < 4; ++m) _Pragma("unroll") for (int n = 0; n < 2; ++n) _Pragma("unroll") for (int k = 0; k < 2; ++k) \
;         acc[ai][bj][m][n] = __builtin_amdgcn_mfma_f32_16x16x32_bf16(Bt[n][k], At[m][k], acc[ai][bj][m][n], 0, 0, 0); __builtin_amdgcn_s_setprio(0); } while (0)
; #define PG8_WAIT_V(n) asm volatile("s_waitcnt vmcnt(" #n ")" ::: "memory")
; #define PG8_WAIT_L(n) asm volatile("s_waitcnt lgkmcnt(" #n ")" ::: "memory")
; #define PG8_BAR __builtin_amdgcn_s_barrier()
; #define PG8_SCHED __builtin_amdgcn_sched_barrier(0)
; template <class Epi, class Sched, bool ALIGN_EPI = false, bool SP2 = false>
; __device__ __forceinline__ void gemm_phase(PG8_LAS unsigned char* lds, const Gemm g, const Sched& S, const Epi& E) {
;     ...
;             PG8_WAIT_V(8); PG8_WAIT_L(0); PG8_BAR; PG8_MMA(1, 0, At, B0); PG8_MMA(1, 1, At, B1); PG8_BAR; PG8_SCHED;
;             PG8_LDB(B0, 1, 0); PG8_LDB(B1, 1, 1); PG8_SCHED; PG8_LDA(At, 1, 0); PG8_STAGE(PG8_SA(0, 1), a2 + hstep, voffA);
;             PG8_WAIT_V(8); PG8_WAIT_L(0); PG8_BAR; PG8_MMA(0, 0, At, B0); PG8_MMA(0, 1, At, B1); PG8_BAR; PG8_SCHED;
	v_mfma_f32_16x16x32_bf16 v[62:65], v[152:155], v[184:187], v[62:65]
	v_mfma_f32_16x16x32_bf16 v[58:61], v[160:163], v[184:187], v[58:61]
	v_mfma_f32_16x16x32_bf16 v[46:49], v[152:155], v[192:195], v[46:49]
	v_mfma_f32_16x16x32_bf16 v[42:45], v[160:163], v[192:195], v[42:45]
	v_mfma_f32_16x16x32_bf16 v[30:33], v[152:155], v[200:203], v[30:33]
	v_mfma_f32_16x16x32_bf16 v[26:29], v[160:163], v[200:203], v[26:29]
	v_mfma_f32_16x16x32_bf16 v[14:17], v[152:155], v[208:211], v[14:17]
	v_mfma_f32_16x16x32_bf16 v[10:13], v[160:163], v[208:211], v[10:13]
	v_mfma_f32_16x16x32_bf16 v[62:65], v[156:159], v[188:191], v[62:65]
	v_mfma_f32_16x16x32_bf16 v[58:61], v[164:167], v[188:191], v[58:61]
	v_mfma_f32_16x16x32_bf16 v[46:49], v[156:159], v[196:199], v[46:49]
	v_mfma_f32_16x16x32_bf16 v[42:45], v[164:167], v[196:199], v[42:45]
	v_mfma_f32_16x16x32_bf16 v[30:33], v[156:159], v[204:207], v[30:33]
	v_mfma_f32_16x16x32_bf16 v[26:29], v[164:167], v[204:207], v[26:29]
	v_mfma_f32_16x16x32_bf16 v[14:17], v[156:159], v[212:215], v[14:17]
	v_mfma_f32_16x16x32_bf16 v[10:13], v[164:167], v[212:215], v[10:13]
	v_mfma_f32_16x16x32_bf16 v[54:57], v[168:171], v[184:187], v[54:57]
	v_mfma_f32_16x16x32_bf16 v[50:53], v[176:179], v[184:187], v[50:53]
	v_mfma_f32_16x16x32_bf16 v[38:41], v[168:171], v[192:195], v[38:41]
	v_mfma_f32_16x16x32_bf16 v[34:37], v[176:179], v[192:195], v[34:37]
	v_mfma_f32_16x16x32_bf16 v[22:25], v[168:171], v[200:203], v[22:25]
	v_mfma_f32_16x16x32_bf16 v[18:21], v[176:179], v[200:203], v[18:21]
	v_mfma_f32_16x16x32_bf16 v[6:9], v[168:171], v[208:211], v[6:9]
	v_mfma_f32_16x16x32_bf16 v[2:5], v[176:179], v[208:211], v[2:5]
	v_mfma_f32_16x16x32_bf16 v[54:57], v[172:175], v[188:191], v[54:57]
	v_mfma_f32_16x16x32_bf16 v[50:53], v[180:183], v[188:191], v[50:53]
	v_mfma_f32_16x16x32_bf16 v[38:41], v[172:175], v[196:199], v[38:41]
	v_mfma_f32_16x16x32_bf16 v[34:37], v[180:183], v[196:199], v[34:37]
	v_mfma_f32_16x16x32_bf16 v[22:25], v[172:175], v[204:207], v[22:25]
	v_mfma_f32_16x16x32_bf16 v[18:21], v[180:183], v[204:207], v[18:21]
	v_mfma_f32_16x16x32_bf16 v[6:9], v[172:175], v[212:215], v[6:9]
	v_mfma_f32_16x16x32_bf16 v[2:5], v[180:183], v[212:215], v[2:5]
	s_barrier
	s_add_i32 s59, 0, 0x18000
	v_add_u32_e32 v151, s59, v146
	s_add_i32 s60, 0, 0x1c000
	ds_read_b128 v[152:155], v151
	ds_read_b128 v[156:159], v151 offset:1024
	ds_read_b128 v[160:163], v151 offset:2048
	ds_read_b128 v[164:167], v151 offset:3072
	v_add_u32_e32 v151, s60, v146
	ds_read_b128 v[168:171], v151
	ds_read_b128 v[172:175], v151 offset:1024
	ds_read_b128 v[176:179], v151 offset:2048
	ds_read_b128 v[180:183], v151 offset:3072
	s_add_u32 s30, s30, s10
	s_addc_u32 s31, s31, s11
	s_mov_b32 m0, s39
	v_lshl_add_u64 v[228:229], s[30:31], 0, v[130:131]
	ds_read_b128 v[184:187], v150 offset:32768
	ds_read_b128 v[188:191], v150 offset:33792
	ds_read_b128 v[192:195], v150 offset:34816
	ds_read_b128 v[196:199], v150 offset:35840
	ds_read_b128 v[200:203], v150 offset:36864
	ds_read_b128 v[204:207], v150 offset:37888
	ds_read_b128 v[208:211], v150 offset:38912
	ds_read_b128 v[212:215], v150 offset:39936
	global_load_lds_dwordx4 v[228:229], off
	v_lshl_add_u64 v[228:229], s[30:31], 0, v[134:135]
	s_mov_b32 m0, s40
	s_nop 0
	global_load_lds_dwordx4 v[228:229], off
	s_waitcnt vmcnt(8)
	s_waitcnt lgkmcnt(0)
	s_barrier
	v_mfma_f32_16x16x32_bf16 v[122:125], v[152:155], v[184:187], v[122:125]
	v_mfma_f32_16x16x32_bf16 v[126:129], v[160:163], v[184:187], v[126:129]
	v_mfma_f32_16x16x32_bf16 v[110:113], v[152:155], v[192:195], v[110:113]
	v_mfma_f32_16x16x32_bf16 v[106:109], v[160:163], v[192:195], v[106:109]
	v_mfma_f32_16x16x32_bf16 v[94:97], v[152:155], v[200:203], v[94:97]
	v_mfma_f32_16x16x32_bf16 v[90:93], v[160:163], v[200:203], v[90:93]
	v_mfma_f32_16x16x32_bf16 v[78:81], v[152:155], v[208:211], v[78:81]
	v_mfma_f32_16x16x32_bf16 v[74:77], v[160:163], v[208:211], v[74:77]
	v_mfma_f32_16x16x32_bf16 v[122:125], v[156:159], v[188:191], v[122:125]
	v_mfma_f32_16x16x32_bf16 v[126:129], v[164:167], v[188:191], v[126:129]
	v_mfma_f32_16x16x32_bf16 v[110:113], v[156:159], v[196:199], v[110:113]
	v_mfma_f32_16x16x32_bf16 v[106:109], v[164:167], v[196:199], v[106:109]
	v_mfma_f32_16x16x32_bf16 v[94:97], v[156:159], v[204:207], v[94:97]
	v_mfma_f32_16x16x32_bf16 v[90:93], v[164:167], v[204:207], v[90:93]
	v_mfma_f32_16x16x32_bf16 v[78:81], v[156:159], v[212:215], v[78:81]
	v_mfma_f32_16x16x32_bf16 v[74:77], v[164:167], v[212:215], v[74:77]
	v_mfma_f32_16x16x32_bf16 v[118:121], v[168:171], v[184:187], v[118:121]
	v_mfma_f32_16x16x32_bf16 v[114:117], v[176:179], v[184:187], v[114:117]
	v_mfma_f32_16x16x32_bf16 v[102:105], v[168:171], v[192:195], v[102:105]
	v_mfma_f32_16x16x32_bf16 v[98:101], v[176:179], v[192:195], v[98:101]
	v_mfma_f32_16x16x32_bf16 v[86:89], v[168:171], v[200:203], v[86:89]
	v_mfma_f32_16x16x32_bf16 v[82:85], v[176:179], v[200:203], v[82:85]
	v_mfma_f32_16x16x32_bf16 v[70:73], v[168:171], v[208:211], v[70:73]
	v_mfma_f32_16x16x32_bf16 v[66:69], v[176:179], v[208:211], v[66:69]
	v_mfma_f32_16x16x32_bf16 v[118:121], v[172:175], v[188:191], v[118:121]
	v_mfma_f32_16x16x32_bf16 v[114:117], v[180:183], v[188:191], v[114:117]
	v_mfma_f32_16x16x32_bf16 v[102:105], v[172:175], v[196:199], v[102:105]
	v_mfma_f32_16x16x32_bf16 v[98:101], v[180:183], v[196:199], v[98:101]
	v_mfma_f32_16x16x32_bf16 v[86:89], v[172:175], v[204:207], v[86:89]
	v_mfma_f32_16x16x32_bf16 v[82:85], v[180:183], v[204:207], v[82:85]
	v_mfma_f32_16x16x32_bf16 v[70:73], v[172:175], v[212:215], v[70:73]
	v_mfma_f32_16x16x32_bf16 v[66:69], v[180:183], v[212:215], v[66:69]
	s_barrier
; #define PG8_STAGE(bufoff, gbase, voff) do { _Pragma("unroll") for (int _i = 0; _i < 2; ++_i) \
;         __builtin_amdgcn_global_load_lds((const unsigned*)((const char*)(gbase) + (voff)[_i]), (PG8_LAS unsigned*)(lds + (bufoff) + ldsw + _i * 8192), 16, 0, 0); } while (0)
; #define PG8_LDA(dst, b, h) do { _Pragma("unroll") for (int m = 0; m < 4; ++m) _Pragma("unroll") for (int k = 0; k < 2; ++k) dst[m][k] = *(const PG8_LAS bf16x8*)(lds + PG8_SA(b, h) + aoff + m * 2048 + k * 1024); } while (0)
; #define PG8_MMA(ai, bj, At, Bt) do { __builtin_amdgcn_s_setprio(1); _Pragma("unroll") for (int m = 0; m < 4; ++m) _Pragma("unroll") for (int n = 0; n < 2; ++n) _Pragma("unroll") for (int k = 0; k < 2; ++k) \
;         acc[ai][bj][m][n] = __builtin_amdgcn_mfma_f32_16x16x32_bf16(Bt[n][k], At[m][k], acc[ai][bj][m][n], 0, 0, 0); __builtin_amdgcn_s_setprio(0); } while (0)
; #define PG8_WAIT_V(n) asm volatile("s_waitcnt vmcnt(" #n ")" ::: "memory")
; #define PG8_WAIT_L(n) asm volatile("s_waitcnt lgkmcnt(" #n ")" ::: "memory")
; #define PG8_BAR __builtin_amdgcn_s_barrier()
; #define PG8_SCHED __builtin_amdgcn_sched_barrier(0)
; template <class Epi, class Sched, bool ALIGN_EPI = false, bool SP2 = false>
; __device__ __forceinline__ void gemm_phase(PG8_LAS unsigned char* lds, const Gemm g, const Sched& S, const Epi& E) {
;     ...
;         for (int t = 0; t < nt; t += 2) {
;     ...
;             PG8_LDA(At, 1, 1); PG8_STAGE(PG8_SB(1, 0), b3, voffB); PG8_STAGE(PG8_SB(1, 1), b3 + hstep, voffB); PG8_STAGE(PG8_SA(1, 0), a3, voffA);
;             PG8_WAIT_V(8); PG8_WAIT_L(0); PG8_BAR; PG8_MMA(1, 0, At, B0); PG8_MMA(1, 1, At, B1); PG8_BAR; PG8_SCHED;
	s_add_i32 s30, s59, s38
	v_lshl_add_u64 v[216:217], v[216:217], 0, s[18:19]
	s_mov_b32 m0, s30
	ds_read_b128 v[184:187], v150 offset:49152
	ds_read_b128 v[188:191], v150 offset:50176
	ds_read_b128 v[192:195], v150 offset:51200
	ds_read_b128 v[196:199], v150 offset:52224
	ds_read_b128 v[200:203], v150 offset:53248
	ds_read_b128 v[204:207], v150 offset:54272
	ds_read_b128 v[208:211], v150 offset:55296
	ds_read_b128 v[212:215], v150 offset:56320
	global_load_lds_dwordx4 v[216:217], off
	v_lshl_add_u64 v[216:217], v[218:219], 0, s[18:19]
	s_add_i32 m0, s30, 0x2000
	s_add_i32 s30, s60, s38
	global_load_lds_dwordx4 v[216:217], off
	v_lshl_add_u64 v[216:217], v[220:221], 0, s[18:19]
	s_mov_b32 m0, s30
	s_nop 0
	global_load_lds_dwordx4 v[216:217], off
	v_lshl_add_u64 v[216:217], v[222:223], 0, s[18:19]
	s_add_i32 m0, s30, 0x2000
	s_nop 0
	global_load_lds_dwordx4 v[216:217], off
	v_lshl_add_u64 v[216:217], v[224:225], 0, s[18:19]
	s_mov_b32 m0, s42
	s_nop 0
	global_load_lds_dwordx4 v[216:217], off
	v_lshl_add_u64 v[216:217], v[226:227], 0, s[18:19]
	s_mov_b32 m0, s43
	s_nop 0
	global_load_lds_dwordx4 v[216:217], off
	s_waitcnt vmcnt(8)
	s_waitcnt lgkmcnt(0)
	s_barrier
	v_mfma_f32_16x16x32_bf16 v[62:65], v[152:155], v[184:187], v[62:65]
	v_mfma_f32_16x16x32_bf16 v[58:61], v[160:163], v[184:187], v[58:61]
	v_mfma_f32_16x16x32_bf16 v[46:49], v[152:155], v[192:195], v[46:49]
	v_mfma_f32_16x16x32_bf16 v[42:45], v[160:163], v[192:195], v[42:45]
	v_mfma_f32_16x16x32_bf16 v[30:33], v[152:155], v[200:203], v[30:33]
	v_mfma_f32_16x16x32_bf16 v[26:29], v[160:163], v[200:203], v[26:29]
	v_mfma_f32_16x16x32_bf16 v[14:17], v[152:155], v[208:211], v[14:17]
	v_mfma_f32_16x16x32_bf16 v[10:13], v[160:163], v[208:211], v[10:13]
	v_mfma_f32_16x16x32_bf16 v[62:65], v[156:159], v[188:191], v[62:65]
	v_mfma_f32_16x16x32_bf16 v[58:61], v[164:167], v[188:191], v[58:61]
	v_mfma_f32_16x16x32_bf16 v[46:49], v[156:159], v[196:199], v[46:49]
	v_mfma_f32_16x16x32_bf16 v[42:45], v[164:167], v[196:199], v[42:45]
	v_mfma_f32_16x16x32_bf16 v[30:33], v[156:159], v[204:207], v[30:33]
	v_mfma_f32_16x16x32_bf16 v[26:29], v[164:167], v[204:207], v[26:29]
	v_mfma_f32_16x16x32_bf16 v[14:17], v[156:159], v[212:215], v[14:17]
	v_mfma_f32_16x16x32_bf16 v[10:13], v[164:167], v[212:215], v[10:13]
	v_mfma_f32_16x16x32_bf16 v[54:57], v[168:171], v[184:187], v[54:57]
	v_mfma_f32_16x16x32_bf16 v[50:53], v[176:179], v[184:187], v[50:53]
	v_mfma_f32_16x16x32_bf16 v[38:41], v[168:171], v[192:195], v[38:41]
	v_mfma_f32_16x16x32_bf16 v[34:37], v[176:179], v[192:195], v[34:37]
	v_mfma_f32_16x16x32_bf16 v[22:25], v[168:171], v[200:203], v[22:25]
	v_mfma_f32_16x16x32_bf16 v[18:21], v[176:179], v[200:203], v[18:21]
	v_mfma_f32_16x16x32_bf16 v[6:9], v[168:171], v[208:211], v[6:9]
	v_mfma_f32_16x16x32_bf16 v[2:5], v[176:179], v[208:211], v[2:5]
	v_mfma_f32_16x16x32_bf16 v[54:57], v[172:175], v[188:191], v[54:57]
	v_mfma_f32_16x16x32_bf16 v[50:53], v[180:183], v[188:191], v[50:53]
	v_mfma_f32_16x16x32_bf16 v[38:41], v[172:175], v[196:199], v[38:41]
	v_mfma_f32_16x16x32_bf16 v[34:37], v[180:183], v[196:199], v[34:37]
	v_mfma_f32_16x16x32_bf16 v[22:25], v[172:175], v[204:207], v[22:25]
	v_mfma_f32_16x16x32_bf16 v[18:21], v[180:183], v[204:207], v[18:21]
	v_mfma_f32_16x16x32_bf16 v[6:9], v[172:175], v[212:215], v[6:9]
	v_mfma_f32_16x16x32_bf16 v[2:5], v[180:183], v[212:215], v[2:5]
	s_barrier
	s_add_u32 s56, s56, 0x100
	s_addc_u32 s57, s57, 0
	s_add_u32 s28, s28, 0x100
	s_addc_u32 s29, s29, 0
	s_cmp_ge_i32 s58, s44
	s_mov_b32 s30, s58
	s_cbranch_scc0 .LBB0_834

; #define PG8_STAGE(bufoff, gbase, voff) do { _Pragma("unroll") for (int _i = 0; _i < 2; ++_i) \
;         __builtin_amdgcn_global_load_lds((const unsigned*)((const char*)(gbase) + (voff)[_i]), (PG8_LAS unsigned*)(lds + (bufoff) + ldsw + _i * 8192), 16, 0, 0); } while (0)
; #define PG8_LDA(dst, b, h) do { _Pragma("unroll") for (int m = 0; m < 4; ++m) _Pragma("unroll") for (int k = 0; k < 2; ++k) dst[m][k] = *(const PG8_LAS bf16x8*)(lds + PG8_SA(b, h) + aoff + m * 2048 + k * 1024); } while (0)
; #define PG8_LDB(dst, b, h) do { _Pragma("unroll") for (int n = 0; n < 2; ++n) _Pragma("unroll") for (int k = 0; k < 2; ++k) dst[n][k] = *(const PG8_LAS bf16x8*)(lds + PG8_SB(b, h) + boff + n * 2048 + k * 1024); } while (0)
; #define PG8_MMA(ai, bj, At, Bt) do { __builtin_amdgcn_s_setprio(1); _Pragma("unroll") for (int m = 0; m < 4; ++m) _Pragma("unroll") for (int n = 0; n < 2; ++n) _Pragma("unroll") for (int k = 0; k < 2; ++k) \
;         acc[ai][bj][m][n] = __builtin_amdgcn_mfma_f32_16x16x32_bf16(Bt[n][k], At[m][k], acc[ai][bj][m][n], 0, 0, 0); __builtin_amdgcn_s_setprio(0); } while (0)
; #define PG8_WAIT_V(n) asm volatile("s_waitcnt vmcnt(" #n ")" ::: "memory")
; #define PG8_WAIT_L(n) asm volatile("s_waitcnt lgkmcnt(" #n ")" ::: "memory")
; #define PG8_BAR __builtin_amdgcn_s_barrier()
; #define PG8_SCHED __builtin_amdgcn_sched_barrier(0)
; template <class Epi, class Sched, bool ALIGN_EPI = false, bool SP2 = false>
; __device__ __forceinline__ void gemm_phase(PG8_LAS unsigned char* lds, const Gemm g, const Sched& S, const Epi& E) {
;     ...
;         for (int t = 0; t < nt; t += 2) {
;             const bool last = (t == nt - 2);
;             const char* a1 = cA + (size_t)(t + 1) * kstep;
;             const char* a2 = last ? nA : cA + (size_t)(t + 2) * kstep; const char* b2 = last ? nB : cB + (size_t)(t + 2) * kstep;
;             const char* a3 = a2 + kstep; const char* b3 = b2 + kstep;
;             if (last && has_next) S.a_ready(nxt);
;             if constexpr (SP2) {
;             PG8_LDB(B0, 0, 0); PG8_LDB(B1, 0, 1); PG8_SCHED; PG8_LDA(At, 0, 0); PG8_STAGE(PG8_SA(1, 1), a1 + hstep, voffA);
;             PG8_WAIT_V(8); PG8_WAIT_L(0); PG8_BAR; PG8_MMA(0, 0, At, B0); PG8_MMA(0, 1, At, B1); PG8_BAR; PG8_SCHED;
;             PG8_LDA(At, 0, 1); PG8_STAGE(PG8_SB(0, 0), b2, voffB); PG8_STAGE(PG8_SB(0, 1), b2 + hstep, voffB); PG8_STAGE(PG8_SA(0, 0), a2, voffA);
.LBB0_1154:
	ds_read_b128 v[130:133], v160
	ds_read_b128 v[134:137], v160 offset:1024
	ds_read_b128 v[164:167], v160 offset:2048
	ds_read_b128 v[168:171], v160 offset:3072
	ds_read_b128 v[172:175], v161
	ds_read_b128 v[176:179], v161 offset:1024
	ds_read_b128 v[180:183], v161 offset:2048
	ds_read_b128 v[184:187], v161 offset:3072
	s_add_i32 s81, s36, 2
	s_add_u32 s70, s34, 0x80
	s_addc_u32 s37, s35, 0
	s_cmp_eq_u32 s55, s36
	s_cselect_b32 s36, s4, s70
	s_cselect_b32 s37, s5, s37
	s_cselect_b32 s71, s31, s80
	s_cselect_b32 s70, s30, s45
	v_lshl_add_u64 v[158:159], s[34:35], 0, v[152:153]
	s_add_i32 m0, s42, 0xc000
	ds_read_b128 v[188:191], v162
	ds_read_b128 v[192:195], v162 offset:1024
	ds_read_b128 v[196:199], v162 offset:2048
	ds_read_b128 v[200:203], v162 offset:3072
	ds_read_b128 v[204:207], v162 offset:4096
	ds_read_b128 v[208:211], v162 offset:5120
	ds_read_b128 v[212:215], v162 offset:6144
	ds_read_b128 v[216:219], v162 offset:7168
	global_load_lds_dwordx4 v[158:159], off
	v_lshl_add_u64 v[158:159], s[34:35], 0, v[150:151]
	s_add_i32 m0, s42, 0xe000
	s_nop 0
	global_load_lds_dwordx4 v[158:159], off
	s_waitcnt vmcnt(8)
	s_waitcnt lgkmcnt(0)
	s_barrier
	v_mfma_f32_16x16x32_bf16 v[126:129], v[130:133], v[188:191], v[126:129]
	v_mfma_f32_16x16x32_bf16 v[122:125], v[164:167], v[188:191], v[122:125]
	v_mfma_f32_16x16x32_bf16 v[110:113], v[130:133], v[196:199], v[110:113]
	v_mfma_f32_16x16x32_bf16 v[106:109], v[164:167], v[196:199], v[106:109]
	v_mfma_f32_16x16x32_bf16 v[94:97], v[130:133], v[204:207], v[94:97]
	v_mfma_f32_16x16x32_bf16 v[90:93], v[164:167], v[204:207], v[90:93]
	v_mfma_f32_16x16x32_bf16 v[78:81], v[130:133], v[212:215], v[78:81]
	v_mfma_f32_16x16x32_bf16 v[74:77], v[164:167], v[212:215], v[74:77]
	v_mfma_f32_16x16x32_bf16 v[126:129], v[134:137], v[192:195], v[126:129]
	v_mfma_f32_16x16x32_bf16 v[122:125], v[168:171], v[192:195], v[122:125]
	v_mfma_f32_16x16x32_bf16 v[110:113], v[134:137], v[200:203], v[110:113]
	v_mfma_f32_16x16x32_bf16 v[106:109], v[168:171], v[200:203], v[106:109]
	v_mfma_f32_16x16x32_bf16 v[94:97], v[134:137], v[208:211], v[94:97]
	v_mfma_f32_16x16x32_bf16 v[90:93], v[168:171], v[208:211], v[90:93]
	v_mfma_f32_16x16x32_bf16 v[78:81], v[134:137], v[216:219], v[78:81]
	v_mfma_f32_16x16x32_bf16 v[74:77], v[168:171], v[216:219], v[74:77]
	v_mfma_f32_16x16x32_bf16 v[118:121], v[172:175], v[188:191], v[118:121]
	v_mfma_f32_16x16x32_bf16 v[114:117], v[180:183], v[188:191], v[114:117]
	v_mfma_f32_16x16x32_bf16 v[102:105], v[172:175], v[196:199], v[102:105]
	v_mfma_f32_16x16x32_bf16 v[98:101], v[180:183], v[196:199], v[98:101]
	v_mfma_f32_16x16x32_bf16 v[86:89], v[172:175], v[204:207], v[86:89]
	v_mfma_f32_16x16x32_bf16 v[82:85], v[180:183], v[204:207], v[82:85]
	v_mfma_f32_16x16x32_bf16 v[70:73], v[172:175], v[212:215], v[70:73]
	v_mfma_f32_16x16x32_bf16 v[66:69], v[180:183], v[212:215], v[66:69]
	v_mfma_f32_16x16x32_bf16 v[118:121], v[176:179], v[192:195], v[118:121]
	v_mfma_f32_16x16x32_bf16 v[114:117], v[184:187], v[192:195], v[114:117]
	v_mfma_f32_16x16x32_bf16 v[102:105], v[176:179], v[200:203], v[102:105]
	v_mfma_f32_16x16x32_bf16 v[98:101], v[184:187], v[200:203], v[98:101]
	v_mfma_f32_16x16x32_bf16 v[86:89], v[176:179], v[208:211], v[86:89]
	v_mfma_f32_16x16x32_bf16 v[82:85], v[184:187], v[208:211], v[82:85]
	v_mfma_f32_16x16x32_bf16 v[70:73], v[176:179], v[216:219], v[70:73]
	v_mfma_f32_16x16x32_bf16 v[66:69], v[184:187], v[216:219], v[66:69]
	s_barrier
	s_add_i32 s72, s69, s41
	v_lshl_add_u64 v[158:159], s[70:71], 0, v[140:141]
	s_mov_b32 m0, s72
	ds_read_b128 v[188:191], v162 offset:16384
	ds_read_b128 v[192:195], v162 offset:17408
	ds_read_b128 v[196:199], v162 offset:18432
	ds_read_b128 v[200:203], v162 offset:19456
	ds_read_b128 v[204:207], v162 offset:20480
	ds_read_b128 v[208:211], v162 offset:21504
	ds_read_b128 v[212:215], v162 offset:22528
	ds_read_b128 v[216:219], v162 offset:23552
	global_load_lds_dwordx4 v[158:159], off
	s_add_i32 m0, s72, 0x2000
	v_lshl_add_u64 v[220:221], s[70:71], 0, v[144:145]
	s_add_u32 s70, s70, s8
	s_addc_u32 s71, s71, s9
	s_add_i32 s72, s86, s41
	global_load_lds_dwordx4 v[220:221], off
	v_lshl_add_u64 v[222:223], s[70:71], 0, v[140:141]
	s_mov_b32 m0, s72
	v_lshl_add_u64 v[224:225], s[70:71], 0, v[144:145]
	global_load_lds_dwordx4 v[222:223], off
	s_add_i32 m0, s72, 0x2000
	v_lshl_add_u64 v[226:227], s[36:37], 0, v[138:139]
	global_load_lds_dwordx4 v[224:225], off
	s_mov_b32 m0, s42
	v_lshl_add_u64 v[228:229], s[36:37], 0, v[142:143]
	global_load_lds_dwordx4 v[226:227], off
	s_mov_b32 m0, s46
	s_nop 0
	global_load_lds_dwordx4 v[228:229], off
	s_waitcnt vmcnt(8)
	s_waitcnt lgkmcnt(0)
	s_barrier
; #define PG8_STAGE(bufoff, gbase, voff) do { _Pragma("unroll") for (int _i = 0; _i < 2; ++_i) \
;         __builtin_amdgcn_global_load_lds((const unsigned*)((const char*)(gbase) + (voff)[_i]), (PG8_LAS unsigned*)(lds + (bufoff) + ldsw + _i * 8192), 16, 0, 0); } while (0)
; #define PG8_LDA(dst, b, h) do { _Pragma("unroll") for (int m = 0; m < 4; ++m) _Pragma("unroll") for (int k = 0; k < 2; ++k) dst[m][k] = *(const PG8_LAS bf16x8*)(lds + PG8_SA(b, h) + aoff + m * 2048 + k * 1024); } while (0)
; #define PG8_LDB(dst, b, h) do { _Pragma("unroll") for (int n = 0; n < 2; ++n) _Pragma("unroll") for (int k = 0; k < 2; ++k) dst[n][k] = *(const PG8_LAS bf16x8*)(lds + PG8_SB(b, h) + boff + n * 2048 + k * 1024); } while (0)
; #define PG8_MMA(ai, bj, At, Bt) do { __builtin_amdgcn_s_setprio(1); _Pragma("unroll") for (int m = 0; m < 4; ++m) _Pragma("unroll") for (int n = 0; n < 2; ++n) _Pragma("unroll") for (int k = 0; k < 2; ++k) \
;         acc[ai][bj][m][n] = __builtin_amdgcn_mfma_f32_16x16x32_bf16(Bt[n][k], At[m][k], acc[ai][bj][m][n], 0, 0, 0); __builtin_amdgcn_s_setprio(0); } while (0)
; #define PG8_WAIT_V(n) asm volatile("s_waitcnt vmcnt(" #n ")" ::: "memory")
; #define PG8_WAIT_L(n) asm volatile("s_waitcnt lgkmcnt(" #n ")" ::: "memory")
; #define PG8_BAR __builtin_amdgcn_s_barrier()
; #define PG8_SCHED __builtin_amdgcn_sched_barrier(0)
; template <class Epi, class Sched, bool ALIGN_EPI = false, bool SP2 = false>
; __device__ __forceinline__ void gemm_phase(PG8_LAS unsigned char* lds, const Gemm g, const Sched& S, const Epi& E) {
;     ...
;             PG8_WAIT_V(8); PG8_WAIT_L(0); PG8_BAR; PG8_MMA(1, 0, At, B0); PG8_MMA(1, 1, At, B1); PG8_BAR; PG8_SCHED;
;             PG8_LDB(B0, 1, 0); PG8_LDB(B1, 1, 1); PG8_SCHED; PG8_LDA(At, 1, 0); PG8_STAGE(PG8_SA(0, 1), a2 + hstep, voffA);
;             PG8_WAIT_V(8); PG8_WAIT_L(0); PG8_BAR; PG8_MMA(0, 0, At, B0); PG8_MMA(0, 1, At, B1); PG8_BAR; PG8_SCHED;
	v_mfma_f32_16x16x32_bf16 v[62:65], v[130:133], v[188:191], v[62:65]
	v_mfma_f32_16x16x32_bf16 v[58:61], v[164:167], v[188:191], v[58:61]
	v_mfma_f32_16x16x32_bf16 v[46:49], v[130:133], v[196:199], v[46:49]
	v_mfma_f32_16x16x32_bf16 v[42:45], v[164:167], v[196:199], v[42:45]
	v_mfma_f32_16x16x32_bf16 v[30:33], v[130:133], v[204:207], v[30:33]
	v_mfma_f32_16x16x32_bf16 v[26:29], v[164:167], v[204:207], v[26:29]
	v_mfma_f32_16x16x32_bf16 v[14:17], v[130:133], v[212:215], v[14:17]
	v_mfma_f32_16x16x32_bf16 v[10:13], v[164:167], v[212:215], v[10:13]
	v_mfma_f32_16x16x32_bf16 v[62:65], v[134:137], v[192:195], v[62:65]
	v_mfma_f32_16x16x32_bf16 v[58:61], v[168:171], v[192:195], v[58:61]
	v_mfma_f32_16x16x32_bf16 v[46:49], v[134:137], v[200:203], v[46:49]
	v_mfma_f32_16x16x32_bf16 v[42:45], v[168:171], v[200:203], v[42:45]
	v_mfma_f32_16x16x32_bf16 v[30:33], v[134:137], v[208:211], v[30:33]
	v_mfma_f32_16x16x32_bf16 v[26:29], v[168:171], v[208:211], v[26:29]
	v_mfma_f32_16x16x32_bf16 v[14:17], v[134:137], v[216:219], v[14:17]
	v_mfma_f32_16x16x32_bf16 v[10:13], v[168:171], v[216:219], v[10:13]
	v_mfma_f32_16x16x32_bf16 v[54:57], v[172:175], v[188:191], v[54:57]
	v_mfma_f32_16x16x32_bf16 v[50:53], v[180:183], v[188:191], v[50:53]
	v_mfma_f32_16x16x32_bf16 v[38:41], v[172:175], v[196:199], v[38:41]
	v_mfma_f32_16x16x32_bf16 v[34:37], v[180:183], v[196:199], v[34:37]
	v_mfma_f32_16x16x32_bf16 v[22:25], v[172:175], v[204:207], v[22:25]
	v_mfma_f32_16x16x32_bf16 v[18:21], v[180:183], v[204:207], v[18:21]
	v_mfma_f32_16x16x32_bf16 v[6:9], v[172:175], v[212:215], v[6:9]
	v_mfma_f32_16x16x32_bf16 v[2:5], v[180:183], v[212:215], v[2:5]
	v_mfma_f32_16x16x32_bf16 v[54:57], v[176:179], v[192:195], v[54:57]
	v_mfma_f32_16x16x32_bf16 v[50:53], v[184:187], v[192:195], v[50:53]
	v_mfma_f32_16x16x32_bf16 v[38:41], v[176:179], v[200:203], v[38:41]
	v_mfma_f32_16x16x32_bf16 v[34:37], v[184:187], v[200:203], v[34:37]
	v_mfma_f32_16x16x32_bf16 v[22:25], v[176:179], v[208:211], v[22:25]
	v_mfma_f32_16x16x32_bf16 v[18:21], v[184:187], v[208:211], v[18:21]
	v_mfma_f32_16x16x32_bf16 v[6:9], v[176:179], v[216:219], v[6:9]
	v_mfma_f32_16x16x32_bf16 v[2:5], v[184:187], v[216:219], v[2:5]
	s_barrier
	s_add_i32 s70, 0, 0x18000
	v_add_u32_e32 v146, s70, v149
	s_add_i32 s71, 0, 0x1c000
	ds_read_b128 v[130:133], v146
	ds_read_b128 v[134:137], v146 offset:1024
	ds_read_b128 v[164:167], v146 offset:2048
	ds_read_b128 v[168:171], v146 offset:3072
	v_add_u32_e32 v146, s71, v149
	ds_read_b128 v[172:175], v146
	ds_read_b128 v[176:179], v146 offset:1024
	ds_read_b128 v[180:183], v146 offset:2048
	ds_read_b128 v[184:187], v146 offset:3072
	s_add_u32 s36, s36, s8
	s_addc_u32 s37, s37, s9
	s_mov_b32 m0, s47
	v_lshl_add_u64 v[230:231], s[36:37], 0, v[138:139]
	ds_read_b128 v[188:191], v162 offset:32768
	ds_read_b128 v[192:195], v162 offset:33792
	ds_read_b128 v[196:199], v162 offset:34816
	ds_read_b128 v[200:203], v162 offset:35840
	ds_read_b128 v[204:207], v162 offset:36864
	ds_read_b128 v[208:211], v162 offset:37888
	ds_read_b128 v[212:215], v162 offset:38912
	ds_read_b128 v[216:219], v162 offset:39936
	global_load_lds_dwordx4 v[230:231], off
	v_lshl_add_u64 v[230:231], s[36:37], 0, v[142:143]
	s_mov_b32 m0, s48
	s_nop 0
	global_load_lds_dwordx4 v[230:231], off
	s_waitcnt vmcnt(8)
	s_waitcnt lgkmcnt(0)
	s_barrier
	v_mfma_f32_16x16x32_bf16 v[126:129], v[130:133], v[188:191], v[126:129]
	v_mfma_f32_16x16x32_bf16 v[122:125], v[164:167], v[188:191], v[122:125]
	v_mfma_f32_16x16x32_bf16 v[110:113], v[130:133], v[196:199], v[110:113]
	v_mfma_f32_16x16x32_bf16 v[106:109], v[164:167], v[196:199], v[106:109]
	v_mfma_f32_16x16x32_bf16 v[94:97], v[130:133], v[204:207], v[94:97]
	v_mfma_f32_16x16x32_bf16 v[90:93], v[164:167], v[204:207], v[90:93]
	v_mfma_f32_16x16x32_bf16 v[78:81], v[130:133], v[212:215], v[78:81]
	v_mfma_f32_16x16x32_bf16 v[74:77], v[164:167], v[212:215], v[74:77]
	v_mfma_f32_16x16x32_bf16 v[126:129], v[134:137], v[192:195], v[126:129]
	v_mfma_f32_16x16x32_bf16 v[122:125], v[168:171], v[192:195], v[122:125]
	v_mfma_f32_16x16x32_bf16 v[110:113], v[134:137], v[200:203], v[110:113]
	v_mfma_f32_16x16x32_bf16 v[106:109], v[168:171], v[200:203], v[106:109]
	v_mfma_f32_16x16x32_bf16 v[94:97], v[134:137], v[208:211], v[94:97]
	v_mfma_f32_16x16x32_bf16 v[90:93], v[168:171], v[208:211], v[90:93]
	v_mfma_f32_16x16x32_bf16 v[78:81], v[134:137], v[216:219], v[78:81]
	v_mfma_f32_16x16x32_bf16 v[74:77], v[168:171], v[216:219], v[74:77]
	v_mfma_f32_16x16x32_bf16 v[118:121], v[172:175], v[188:191], v[118:121]
	v_mfma_f32_16x16x32_bf16 v[114:117], v[180:183], v[188:191], v[114:117]
	v_mfma_f32_16x16x32_bf16 v[102:105], v[172:175], v[196:199], v[102:105]
	v_mfma_f32_16x16x32_bf16 v[98:101], v[180:183], v[196:199], v[98:101]
	v_mfma_f32_16x16x32_bf16 v[86:89], v[172:175], v[204:207], v[86:89]
	v_mfma_f32_16x16x32_bf16 v[82:85], v[180:183], v[204:207], v[82:85]
	v_mfma_f32_16x16x32_bf16 v[70:73], v[172:175], v[212:215], v[70:73]
	v_mfma_f32_16x16x32_bf16 v[66:69], v[180:183], v[212:215], v[66:69]
	v_mfma_f32_16x16x32_bf16 v[118:121], v[176:179], v[192:195], v[118:121]
	v_mfma_f32_16x16x32_bf16 v[114:117], v[184:187], v[192:195], v[114:117]
	v_mfma_f32_16x16x32_bf16 v[102:105], v[176:179], v[200:203], v[102:105]
	v_mfma_f32_16x16x32_bf16 v[98:101], v[184:187], v[200:203], v[98:101]
	v_mfma_f32_16x16x32_bf16 v[86:89], v[176:179], v[208:211], v[86:89]
	v_mfma_f32_16x16x32_bf16 v[82:85], v[184:187], v[208:211], v[82:85]
	v_mfma_f32_16x16x32_bf16 v[70:73], v[176:179], v[216:219], v[70:73]
	v_mfma_f32_16x16x32_bf16 v[66:69], v[184:187], v[216:219], v[66:69]
	s_barrier
; #define PG8_STAGE(bufoff, gbase, voff) do { _Pragma("unroll") for (int _i = 0; _i < 2; ++_i) \
;         __builtin_amdgcn_global_load_lds((const unsigned*)((const char*)(gbase) + (voff)[_i]), (PG8_LAS unsigned*)(lds + (bufoff) + ldsw + _i * 8192), 16, 0, 0); } while (0)
; #define PG8_LDA(dst, b, h) do { _Pragma("unroll") for (int m = 0; m < 4; ++m) _Pragma("unroll") for (int k = 0; k < 2; ++k) dst[m][k] = *(const PG8_LAS bf16x8*)(lds + PG8_SA(b, h) + aoff + m * 2048 + k * 1024); } while (0)
; #define PG8_MMA(ai, bj, At, Bt) do { __builtin_amdgcn_s_setprio(1); _Pragma("unroll") for (int m = 0; m < 4; ++m) _Pragma("unroll") for (int n = 0; n < 2; ++n) _Pragma("unroll") for (int k = 0; k < 2; ++k) \
;         acc[ai][bj][m][n] = __builtin_amdgcn_mfma_f32_16x16x32_bf16(Bt[n][k], At[m][k], acc[ai][bj][m][n], 0, 0, 0); __builtin_amdgcn_s_setprio(0); } while (0)
; #define PG8_WAIT_V(n) asm volatile("s_waitcnt vmcnt(" #n ")" ::: "memory")
; #define PG8_WAIT_L(n) asm volatile("s_waitcnt lgkmcnt(" #n ")" ::: "memory")
; #define PG8_BAR __builtin_amdgcn_s_barrier()
; #define PG8_SCHED __builtin_amdgcn_sched_barrier(0)
; template <class Epi, class Sched, bool ALIGN_EPI = false, bool SP2 = false>
; __device__ __forceinline__ void gemm_phase(PG8_LAS unsigned char* lds, const Gemm g, const Sched& S, const Epi& E) {
;     ...
;         for (int t = 0; t < nt; t += 2) {
;     ...
;             PG8_LDA(At, 1, 1); PG8_STAGE(PG8_SB(1, 0), b3, voffB); PG8_STAGE(PG8_SB(1, 1), b3 + hstep, voffB); PG8_STAGE(PG8_SA(1, 0), a3, voffA);
;             PG8_WAIT_V(8); PG8_WAIT_L(0); PG8_BAR; PG8_MMA(1, 0, At, B0); PG8_MMA(1, 1, At, B1); PG8_BAR; PG8_SCHED;
	s_add_i32 s36, s70, s41
	v_lshl_add_u64 v[158:159], v[158:159], 0, s[24:25]
	s_mov_b32 m0, s36
	ds_read_b128 v[188:191], v162 offset:49152
	ds_read_b128 v[192:195], v162 offset:50176
	ds_read_b128 v[196:199], v162 offset:51200
	ds_read_b128 v[200:203], v162 offset:52224
	ds_read_b128 v[204:207], v162 offset:53248
	ds_read_b128 v[208:211], v162 offset:54272
	ds_read_b128 v[212:215], v162 offset:55296
	ds_read_b128 v[216:219], v162 offset:56320
	global_load_lds_dwordx4 v[158:159], off
	v_lshl_add_u64 v[158:159], v[220:221], 0, s[24:25]
	s_add_i32 m0, s36, 0x2000
	s_add_i32 s36, s71, s41
	global_load_lds_dwordx4 v[158:159], off
	v_lshl_add_u64 v[158:159], v[222:223], 0, s[24:25]
	s_mov_b32 m0, s36
	s_nop 0
	global_load_lds_dwordx4 v[158:159], off
	v_lshl_add_u64 v[158:159], v[224:225], 0, s[24:25]
	s_add_i32 m0, s36, 0x2000
	s_nop 0
	global_load_lds_dwordx4 v[158:159], off
	v_lshl_add_u64 v[158:159], v[226:227], 0, s[24:25]
	s_mov_b32 m0, s52
	s_nop 0
	global_load_lds_dwordx4 v[158:159], off
	v_lshl_add_u64 v[158:159], v[228:229], 0, s[24:25]
	s_mov_b32 m0, s53
	s_nop 0
	global_load_lds_dwordx4 v[158:159], off
	s_waitcnt vmcnt(8)
	s_waitcnt lgkmcnt(0)
	s_barrier
	v_mfma_f32_16x16x32_bf16 v[62:65], v[130:133], v[188:191], v[62:65]
	v_mfma_f32_16x16x32_bf16 v[58:61], v[164:167], v[188:191], v[58:61]
	v_mfma_f32_16x16x32_bf16 v[46:49], v[130:133], v[196:199], v[46:49]
	v_mfma_f32_16x16x32_bf16 v[42:45], v[164:167], v[196:199], v[42:45]
	v_mfma_f32_16x16x32_bf16 v[30:33], v[130:133], v[204:207], v[30:33]
	v_mfma_f32_16x16x32_bf16 v[26:29], v[164:167], v[204:207], v[26:29]
	v_mfma_f32_16x16x32_bf16 v[14:17], v[130:133], v[212:215], v[14:17]
	v_mfma_f32_16x16x32_bf16 v[10:13], v[164:167], v[212:215], v[10:13]
	v_mfma_f32_16x16x32_bf16 v[62:65], v[134:137], v[192:195], v[62:65]
	v_mfma_f32_16x16x32_bf16 v[58:61], v[168:171], v[192:195], v[58:61]
	v_mfma_f32_16x16x32_bf16 v[46:49], v[134:137], v[200:203], v[46:49]
	v_mfma_f32_16x16x32_bf16 v[42:45], v[168:171], v[200:203], v[42:45]
	v_mfma_f32_16x16x32_bf16 v[30:33], v[134:137], v[208:211], v[30:33]
	v_mfma_f32_16x16x32_bf16 v[26:29], v[168:171], v[208:211], v[26:29]
	v_mfma_f32_16x16x32_bf16 v[14:17], v[134:137], v[216:219], v[14:17]
	v_mfma_f32_16x16x32_bf16 v[10:13], v[168:171], v[216:219], v[10:13]
	v_mfma_f32_16x16x32_bf16 v[54:57], v[172:175], v[188:191], v[54:57]
	v_mfma_f32_16x16x32_bf16 v[50:53], v[180:183], v[188:191], v[50:53]
	v_mfma_f32_16x16x32_bf16 v[38:41], v[172:175], v[196:199], v[38:41]
	v_mfma_f32_16x16x32_bf16 v[34:37], v[180:183], v[196:199], v[34:37]
	v_mfma_f32_16x16x32_bf16 v[22:25], v[172:175], v[204:207], v[22:25]
	v_mfma_f32_16x16x32_bf16 v[18:21], v[180:183], v[204:207], v[18:21]
	v_mfma_f32_16x16x32_bf16 v[6:9], v[172:175], v[212:215], v[6:9]
	v_mfma_f32_16x16x32_bf16 v[2:5], v[180:183], v[212:215], v[2:5]
	v_mfma_f32_16x16x32_bf16 v[54:57], v[176:179], v[192:195], v[54:57]
	v_mfma_f32_16x16x32_bf16 v[50:53], v[184:187], v[192:195], v[50:53]
	v_mfma_f32_16x16x32_bf16 v[38:41], v[176:179], v[200:203], v[38:41]
	v_mfma_f32_16x16x32_bf16 v[34:37], v[184:187], v[200:203], v[34:37]
	v_mfma_f32_16x16x32_bf16 v[22:25], v[176:179], v[208:211], v[22:25]
	v_mfma_f32_16x16x32_bf16 v[18:21], v[184:187], v[208:211], v[18:21]
	v_mfma_f32_16x16x32_bf16 v[6:9], v[176:179], v[216:219], v[6:9]
	v_mfma_f32_16x16x32_bf16 v[2:5], v[184:187], v[216:219], v[2:5]
	s_barrier
	s_add_u32 s45, s45, 0x100
	s_addc_u32 s80, s80, 0
	s_add_u32 s34, s34, 0x100
	s_addc_u32 s35, s35, 0
	s_cmp_ge_i32 s81, s54
	s_mov_b32 s36, s81
	s_cbranch_scc0 .LBB0_1154

; #define PG8_STAGE(bufoff, gbase, voff) do { _Pragma("unroll") for (int _i = 0; _i < 2; ++_i) \
;         __builtin_amdgcn_global_load_lds((const unsigned*)((const char*)(gbase) + (voff)[_i]), (PG8_LAS unsigned*)(lds + (bufoff) + ldsw + _i * 8192), 16, 0, 0); } while (0)
; #define PG8_LDA(dst, b, h) do { _Pragma("unroll") for (int m = 0; m < 4; ++m) _Pragma("unroll") for (int k = 0; k < 2; ++k) dst[m][k] = *(const PG8_LAS bf16x8*)(lds + PG8_SA(b, h) + aoff + m * 2048 + k * 1024); } while (0)
; #define PG8_LDB(dst, b, h) do { _Pragma("unroll") for (int n = 0; n < 2; ++n) _Pragma("unroll") for (int k = 0; k < 2; ++k) dst[n][k] = *(const PG8_LAS bf16x8*)(lds + PG8_SB(b, h) + boff + n * 2048 + k * 1024); } while (0)
; #define PG8_MMA(ai, bj, At, Bt) do { __builtin_amdgcn_s_setprio(1); _Pragma("unroll") for (int m = 0; m < 4; ++m) _Pragma("unroll") for (int n = 0; n < 2; ++n) _Pragma("unroll") for (int k = 0; k < 2; ++k) \
;         acc[ai][bj][m][n] = __builtin_amdgcn_mfma_f32_16x16x32_bf16(Bt[n][k], At[m][k], acc[ai][bj][m][n], 0, 0, 0); __builtin_amdgcn_s_setprio(0); } while (0)
; #define PG8_WAIT_V(n) asm volatile("s_waitcnt vmcnt(" #n ")" ::: "memory")
; #define PG8_WAIT_L(n) asm volatile("s_waitcnt lgkmcnt(" #n ")" ::: "memory")
; #define PG8_BAR __builtin_amdgcn_s_barrier()
; #define PG8_SCHED __builtin_amdgcn_sched_barrier(0)
; template <class Epi, class Sched, bool ALIGN_EPI = false, bool SP2 = false>
; __device__ __forceinline__ void gemm_phase(PG8_LAS unsigned char* lds, const Gemm g, const Sched& S, const Epi& E) {
;     ...
;         for (int t = 0; t < nt; t += 2) {
;             const bool last = (t == nt - 2);
;             const char* a1 = cA + (size_t)(t + 1) * kstep;
;             const char* a2 = last ? nA : cA + (size_t)(t + 2) * kstep; const char* b2 = last ? nB : cB + (size_t)(t + 2) * kstep;
;             const char* a3 = a2 + kstep; const char* b3 = b2 + kstep;
;             if (last && has_next) S.a_ready(nxt);
;             if constexpr (SP2) {
;             PG8_LDB(B0, 0, 0); PG8_LDB(B1, 0, 1); PG8_SCHED; PG8_LDA(At, 0, 0); PG8_STAGE(PG8_SA(1, 1), a1 + hstep, voffA);
;             PG8_WAIT_V(8); PG8_WAIT_L(0); PG8_BAR; PG8_MMA(0, 0, At, B0); PG8_MMA(0, 1, At, B1); PG8_BAR; PG8_SCHED;
;             PG8_LDA(At, 0, 1); PG8_STAGE(PG8_SB(0, 0), b2, voffB); PG8_STAGE(PG8_SB(0, 1), b2 + hstep, voffB); PG8_STAGE(PG8_SA(0, 0), a2, voffA);
.LBB0_1375:
	ds_read_b128 v[166:169], v162
	ds_read_b128 v[170:173], v162 offset:1024
	ds_read_b128 v[174:177], v162 offset:2048
	ds_read_b128 v[178:181], v162 offset:3072
	ds_read_b128 v[182:185], v163
	ds_read_b128 v[186:189], v163 offset:1024
	ds_read_b128 v[190:193], v163 offset:2048
	ds_read_b128 v[194:197], v163 offset:3072
	s_add_i32 s87, s36, 2
	s_add_u32 s70, s34, 0x80
	s_addc_u32 s37, s35, 0
	s_cmp_eq_u32 s52, s36
	s_cselect_b32 s36, s4, s70
	s_cselect_b32 s37, s5, s37
	s_cselect_b32 s71, s31, s86
	s_cselect_b32 s70, s30, s81
	v_lshl_add_u64 v[230:231], s[34:35], 0, v[140:141]
	s_add_i32 m0, s42, 0xc000
	ds_read_b128 v[198:201], v164
	ds_read_b128 v[202:205], v164 offset:1024
	ds_read_b128 v[206:209], v164 offset:2048
	ds_read_b128 v[210:213], v164 offset:3072
	ds_read_b128 v[214:217], v164 offset:4096
	ds_read_b128 v[218:221], v164 offset:5120
	ds_read_b128 v[222:225], v164 offset:6144
	ds_read_b128 v[226:229], v164 offset:7168
	global_load_lds_dwordx4 v[230:231], off
	v_lshl_add_u64 v[230:231], s[34:35], 0, v[138:139]
	s_add_i32 m0, s42, 0xe000
	s_nop 0
	global_load_lds_dwordx4 v[230:231], off
	s_waitcnt vmcnt(8)
	s_waitcnt lgkmcnt(0)
	s_barrier
	v_mfma_f32_16x16x32_bf16 v[122:125], v[166:169], v[198:201], v[122:125]
	v_mfma_f32_16x16x32_bf16 v[126:129], v[174:177], v[198:201], v[126:129]
	v_mfma_f32_16x16x32_bf16 v[110:113], v[166:169], v[206:209], v[110:113]
	v_mfma_f32_16x16x32_bf16 v[106:109], v[174:177], v[206:209], v[106:109]
	v_mfma_f32_16x16x32_bf16 v[94:97], v[166:169], v[214:217], v[94:97]
	v_mfma_f32_16x16x32_bf16 v[90:93], v[174:177], v[214:217], v[90:93]
	v_mfma_f32_16x16x32_bf16 v[78:81], v[166:169], v[222:225], v[78:81]
	v_mfma_f32_16x16x32_bf16 v[74:77], v[174:177], v[222:225], v[74:77]
	v_mfma_f32_16x16x32_bf16 v[122:125], v[170:173], v[202:205], v[122:125]
	v_mfma_f32_16x16x32_bf16 v[126:129], v[178:181], v[202:205], v[126:129]
	v_mfma_f32_16x16x32_bf16 v[110:113], v[170:173], v[210:213], v[110:113]
	v_mfma_f32_16x16x32_bf16 v[106:109], v[178:181], v[210:213], v[106:109]
	v_mfma_f32_16x16x32_bf16 v[94:97], v[170:173], v[218:221], v[94:97]
	v_mfma_f32_16x16x32_bf16 v[90:93], v[178:181], v[218:221], v[90:93]
	v_mfma_f32_16x16x32_bf16 v[78:81], v[170:173], v[226:229], v[78:81]
	v_mfma_f32_16x16x32_bf16 v[74:77], v[178:181], v[226:229], v[74:77]
	v_mfma_f32_16x16x32_bf16 v[118:121], v[182:185], v[198:201], v[118:121]
	v_mfma_f32_16x16x32_bf16 v[114:117], v[190:193], v[198:201], v[114:117]
	v_mfma_f32_16x16x32_bf16 v[102:105], v[182:185], v[206:209], v[102:105]
	v_mfma_f32_16x16x32_bf16 v[98:101], v[190:193], v[206:209], v[98:101]
	v_mfma_f32_16x16x32_bf16 v[86:89], v[182:185], v[214:217], v[86:89]
	v_mfma_f32_16x16x32_bf16 v[82:85], v[190:193], v[214:217], v[82:85]
	v_mfma_f32_16x16x32_bf16 v[70:73], v[182:185], v[222:225], v[70:73]
	v_mfma_f32_16x16x32_bf16 v[66:69], v[190:193], v[222:225], v[66:69]
	v_mfma_f32_16x16x32_bf16 v[118:121], v[186:189], v[202:205], v[118:121]
	v_mfma_f32_16x16x32_bf16 v[114:117], v[194:197], v[202:205], v[114:117]
	v_mfma_f32_16x16x32_bf16 v[102:105], v[186:189], v[210:213], v[102:105]
	v_mfma_f32_16x16x32_bf16 v[98:101], v[194:197], v[210:213], v[98:101]
	v_mfma_f32_16x16x32_bf16 v[86:89], v[186:189], v[218:221], v[86:89]
	v_mfma_f32_16x16x32_bf16 v[82:85], v[194:197], v[218:221], v[82:85]
	v_mfma_f32_16x16x32_bf16 v[70:73], v[186:189], v[226:229], v[70:73]
	v_mfma_f32_16x16x32_bf16 v[66:69], v[194:197], v[226:229], v[66:69]
	s_barrier
	s_add_i32 s72, s55, s41
	v_lshl_add_u64 v[230:231], s[70:71], 0, v[132:133]
	s_mov_b32 m0, s72
	ds_read_b128 v[198:201], v164 offset:16384
	ds_read_b128 v[202:205], v164 offset:17408
	ds_read_b128 v[206:209], v164 offset:18432
	ds_read_b128 v[210:213], v164 offset:19456
	ds_read_b128 v[214:217], v164 offset:20480
	ds_read_b128 v[218:221], v164 offset:21504
	ds_read_b128 v[222:225], v164 offset:22528
	ds_read_b128 v[226:229], v164 offset:23552
	global_load_lds_dwordx4 v[230:231], off
	s_add_i32 m0, s72, 0x2000
	v_lshl_add_u64 v[232:233], s[70:71], 0, v[136:137]
	s_add_u32 s70, s70, s14
	s_addc_u32 s71, s71, s15
	s_add_i32 s72, s56, s41
	global_load_lds_dwordx4 v[232:233], off
	v_lshl_add_u64 v[234:235], s[70:71], 0, v[132:133]
	s_mov_b32 m0, s72
	v_lshl_add_u64 v[236:237], s[70:71], 0, v[136:137]
	global_load_lds_dwordx4 v[234:235], off
	s_add_i32 m0, s72, 0x2000
	v_lshl_add_u64 v[238:239], s[36:37], 0, v[130:131]
	global_load_lds_dwordx4 v[236:237], off
	s_mov_b32 m0, s42
	v_lshl_add_u64 v[240:241], s[36:37], 0, v[134:135]
	global_load_lds_dwordx4 v[238:239], off
	s_mov_b32 m0, s43
	s_nop 0
	global_load_lds_dwordx4 v[240:241], off
	s_waitcnt vmcnt(8)
	s_waitcnt lgkmcnt(0)
	s_barrier
; #define PG8_STAGE(bufoff, gbase, voff) do { _Pragma("unroll") for (int _i = 0; _i < 2; ++_i) \
;         __builtin_amdgcn_global_load_lds((const unsigned*)((const char*)(gbase) + (voff)[_i]), (PG8_LAS unsigned*)(lds + (bufoff) + ldsw + _i * 8192), 16, 0, 0); } while (0)
; #define PG8_LDA(dst, b, h) do { _Pragma("unroll") for (int m = 0; m < 4; ++m) _Pragma("unroll") for (int k = 0; k < 2; ++k) dst[m][k] = *(const PG8_LAS bf16x8*)(lds + PG8_SA(b, h) + aoff + m * 2048 + k * 1024); } while (0)
; #define PG8_LDB(dst, b, h) do { _Pragma("unroll") for (int n = 0; n < 2; ++n) _Pragma("unroll") for (int k = 0; k < 2; ++k) dst[n][k] = *(const PG8_LAS bf16x8*)(lds + PG8_SB(b, h) + boff + n * 2048 + k * 1024); } while (0)
; #define PG8_MMA(ai, bj, At, Bt) do { __builtin_amdgcn_s_setprio(1); _Pragma("unroll") for (int m = 0; m < 4; ++m) _Pragma("unroll") for (int n = 0; n < 2; ++n) _Pragma("unroll") for (int k = 0; k < 2; ++k) \
;         acc[ai][bj][m][n] = __builtin_amdgcn_mfma_f32_16x16x32_bf16(Bt[n][k], At[m][k], acc[ai][bj][m][n], 0, 0, 0); __builtin_amdgcn_s_setprio(0); } while (0)
; #define PG8_WAIT_V(n) asm volatile("s_waitcnt vmcnt(" #n ")" ::: "memory")
; #define PG8_WAIT_L(n) asm volatile("s_waitcnt lgkmcnt(" #n ")" ::: "memory")
; #define PG8_BAR __builtin_amdgcn_s_barrier()
; #define PG8_SCHED __builtin_amdgcn_sched_barrier(0)
; template <class Epi, class Sched, bool ALIGN_EPI = false, bool SP2 = false>
; __device__ __forceinline__ void gemm_phase(PG8_LAS unsigned char* lds, const Gemm g, const Sched& S, const Epi& E) {
;     ...
;             PG8_WAIT_V(8); PG8_WAIT_L(0); PG8_BAR; PG8_MMA(1, 0, At, B0); PG8_MMA(1, 1, At, B1); PG8_BAR; PG8_SCHED;
;             PG8_LDB(B0, 1, 0); PG8_LDB(B1, 1, 1); PG8_SCHED; PG8_LDA(At, 1, 0); PG8_STAGE(PG8_SA(0, 1), a2 + hstep, voffA);
;             PG8_WAIT_V(8); PG8_WAIT_L(0); PG8_BAR; PG8_MMA(0, 0, At, B0); PG8_MMA(0, 1, At, B1); PG8_BAR; PG8_SCHED;
	v_mfma_f32_16x16x32_bf16 v[62:65], v[166:169], v[198:201], v[62:65]
	v_mfma_f32_16x16x32_bf16 v[58:61], v[174:177], v[198:201], v[58:61]
	v_mfma_f32_16x16x32_bf16 v[46:49], v[166:169], v[206:209], v[46:49]
	v_mfma_f32_16x16x32_bf16 v[42:45], v[174:177], v[206:209], v[42:45]
	v_mfma_f32_16x16x32_bf16 v[30:33], v[166:169], v[214:217], v[30:33]
	v_mfma_f32_16x16x32_bf16 v[26:29], v[174:177], v[214:217], v[26:29]
	v_mfma_f32_16x16x32_bf16 v[14:17], v[166:169], v[222:225], v[14:17]
	v_mfma_f32_16x16x32_bf16 v[10:13], v[174:177], v[222:225], v[10:13]
	v_mfma_f32_16x16x32_bf16 v[62:65], v[170:173], v[202:205], v[62:65]
	v_mfma_f32_16x16x32_bf16 v[58:61], v[178:181], v[202:205], v[58:61]
	v_mfma_f32_16x16x32_bf16 v[46:49], v[170:173], v[210:213], v[46:49]
	v_mfma_f32_16x16x32_bf16 v[42:45], v[178:181], v[210:213], v[42:45]
	v_mfma_f32_16x16x32_bf16 v[30:33], v[170:173], v[218:221], v[30:33]
	v_mfma_f32_16x16x32_bf16 v[26:29], v[178:181], v[218:221], v[26:29]
	v_mfma_f32_16x16x32_bf16 v[14:17], v[170:173], v[226:229], v[14:17]
	v_mfma_f32_16x16x32_bf16 v[10:13], v[178:181], v[226:229], v[10:13]
	v_mfma_f32_16x16x32_bf16 v[54:57], v[182:185], v[198:201], v[54:57]
	v_mfma_f32_16x16x32_bf16 v[50:53], v[190:193], v[198:201], v[50:53]
	v_mfma_f32_16x16x32_bf16 v[38:41], v[182:185], v[206:209], v[38:41]
	v_mfma_f32_16x16x32_bf16 v[34:37], v[190:193], v[206:209], v[34:37]
	v_mfma_f32_16x16x32_bf16 v[22:25], v[182:185], v[214:217], v[22:25]
	v_mfma_f32_16x16x32_bf16 v[18:21], v[190:193], v[214:217], v[18:21]
	v_mfma_f32_16x16x32_bf16 v[6:9], v[182:185], v[222:225], v[6:9]
	v_mfma_f32_16x16x32_bf16 v[2:5], v[190:193], v[222:225], v[2:5]
	v_mfma_f32_16x16x32_bf16 v[54:57], v[186:189], v[202:205], v[54:57]
	v_mfma_f32_16x16x32_bf16 v[50:53], v[194:197], v[202:205], v[50:53]
	v_mfma_f32_16x16x32_bf16 v[38:41], v[186:189], v[210:213], v[38:41]
	v_mfma_f32_16x16x32_bf16 v[34:37], v[194:197], v[210:213], v[34:37]
	v_mfma_f32_16x16x32_bf16 v[22:25], v[186:189], v[218:221], v[22:25]
	v_mfma_f32_16x16x32_bf16 v[18:21], v[194:197], v[218:221], v[18:21]
	v_mfma_f32_16x16x32_bf16 v[6:9], v[186:189], v[226:229], v[6:9]
	v_mfma_f32_16x16x32_bf16 v[2:5], v[194:197], v[226:229], v[2:5]
	s_barrier
	s_add_i32 s70, 0, 0x18000
	v_add_u32_e32 v165, s70, v160
	s_add_i32 s71, 0, 0x1c000
	ds_read_b128 v[166:169], v165
	ds_read_b128 v[170:173], v165 offset:1024
	ds_read_b128 v[174:177], v165 offset:2048
	ds_read_b128 v[178:181], v165 offset:3072
	v_add_u32_e32 v165, s71, v160
	ds_read_b128 v[182:185], v165
	ds_read_b128 v[186:189], v165 offset:1024
	ds_read_b128 v[190:193], v165 offset:2048
	ds_read_b128 v[194:197], v165 offset:3072
	s_add_u32 s36, s36, s14
	s_addc_u32 s37, s37, s15
	s_mov_b32 m0, s44
	v_lshl_add_u64 v[242:243], s[36:37], 0, v[130:131]
	ds_read_b128 v[198:201], v164 offset:32768
	ds_read_b128 v[202:205], v164 offset:33792
	ds_read_b128 v[206:209], v164 offset:34816
	ds_read_b128 v[210:213], v164 offset:35840
	ds_read_b128 v[214:217], v164 offset:36864
	ds_read_b128 v[218:221], v164 offset:37888
	ds_read_b128 v[222:225], v164 offset:38912
	ds_read_b128 v[226:229], v164 offset:39936
	global_load_lds_dwordx4 v[242:243], off
	v_lshl_add_u64 v[242:243], s[36:37], 0, v[134:135]
	s_mov_b32 m0, s45
	s_nop 0
	global_load_lds_dwordx4 v[242:243], off
	s_waitcnt vmcnt(8)
	s_waitcnt lgkmcnt(0)
	s_barrier
	v_mfma_f32_16x16x32_bf16 v[122:125], v[166:169], v[198:201], v[122:125]
	v_mfma_f32_16x16x32_bf16 v[126:129], v[174:177], v[198:201], v[126:129]
	v_mfma_f32_16x16x32_bf16 v[110:113], v[166:169], v[206:209], v[110:113]
	v_mfma_f32_16x16x32_bf16 v[106:109], v[174:177], v[206:209], v[106:109]
	v_mfma_f32_16x16x32_bf16 v[94:97], v[166:169], v[214:217], v[94:97]
	v_mfma_f32_16x16x32_bf16 v[90:93], v[174:177], v[214:217], v[90:93]
	v_mfma_f32_16x16x32_bf16 v[78:81], v[166:169], v[222:225], v[78:81]
	v_mfma_f32_16x16x32_bf16 v[74:77], v[174:177], v[222:225], v[74:77]
	v_mfma_f32_16x16x32_bf16 v[122:125], v[170:173], v[202:205], v[122:125]
	v_mfma_f32_16x16x32_bf16 v[126:129], v[178:181], v[202:205], v[126:129]
	v_mfma_f32_16x16x32_bf16 v[110:113], v[170:173], v[210:213], v[110:113]
	v_mfma_f32_16x16x32_bf16 v[106:109], v[178:181], v[210:213], v[106:109]
	v_mfma_f32_16x16x32_bf16 v[94:97], v[170:173], v[218:221], v[94:97]
	v_mfma_f32_16x16x32_bf16 v[90:93], v[178:181], v[218:221], v[90:93]
	v_mfma_f32_16x16x32_bf16 v[78:81], v[170:173], v[226:229], v[78:81]
	v_mfma_f32_16x16x32_bf16 v[74:77], v[178:181], v[226:229], v[74:77]
	v_mfma_f32_16x16x32_bf16 v[118:121], v[182:185], v[198:201], v[118:121]
	v_mfma_f32_16x16x32_bf16 v[114:117], v[190:193], v[198:201], v[114:117]
	v_mfma_f32_16x16x32_bf16 v[102:105], v[182:185], v[206:209], v[102:105]
	v_mfma_f32_16x16x32_bf16 v[98:101], v[190:193], v[206:209], v[98:101]
	v_mfma_f32_16x16x32_bf16 v[86:89], v[182:185], v[214:217], v[86:89]
	v_mfma_f32_16x16x32_bf16 v[82:85], v[190:193], v[214:217], v[82:85]
	v_mfma_f32_16x16x32_bf16 v[70:73], v[182:185], v[222:225], v[70:73]
	v_mfma_f32_16x16x32_bf16 v[66:69], v[190:193], v[222:225], v[66:69]
	v_mfma_f32_16x16x32_bf16 v[118:121], v[186:189], v[202:205], v[118:121]
	v_mfma_f32_16x16x32_bf16 v[114:117], v[194:197], v[202:205], v[114:117]
	v_mfma_f32_16x16x32_bf16 v[102:105], v[186:189], v[210:213], v[102:105]
	v_mfma_f32_16x16x32_bf16 v[98:101], v[194:197], v[210:213], v[98:101]
	v_mfma_f32_16x16x32_bf16 v[86:89], v[186:189], v[218:221], v[86:89]
	v_mfma_f32_16x16x32_bf16 v[82:85], v[194:197], v[218:221], v[82:85]
	v_mfma_f32_16x16x32_bf16 v[70:73], v[186:189], v[226:229], v[70:73]
	v_mfma_f32_16x16x32_bf16 v[66:69], v[194:197], v[226:229], v[66:69]
	s_barrier
; #define PG8_STAGE(bufoff, gbase, voff) do { _Pragma("unroll") for (int _i = 0; _i < 2; ++_i) \
;         __builtin_amdgcn_global_load_lds((const unsigned*)((const char*)(gbase) + (voff)[_i]), (PG8_LAS unsigned*)(lds + (bufoff) + ldsw + _i * 8192), 16, 0, 0); } while (0)
; #define PG8_LDA(dst, b, h) do { _Pragma("unroll") for (int m = 0; m < 4; ++m) _Pragma("unroll") for (int k = 0; k < 2; ++k) dst[m][k] = *(const PG8_LAS bf16x8*)(lds + PG8_SA(b, h) + aoff + m * 2048 + k * 1024); } while (0)
; #define PG8_MMA(ai, bj, At, Bt) do { __builtin_amdgcn_s_setprio(1); _Pragma("unroll") for (int m = 0; m < 4; ++m) _Pragma("unroll") for (int n = 0; n < 2; ++n) _Pragma("unroll") for (int k = 0; k < 2; ++k) \
;         acc[ai][bj][m][n] = __builtin_amdgcn_mfma_f32_16x16x32_bf16(Bt[n][k], At[m][k], acc[ai][bj][m][n], 0, 0, 0); __builtin_amdgcn_s_setprio(0); } while (0)
; #define PG8_WAIT_V(n) asm volatile("s_waitcnt vmcnt(" #n ")" ::: "memory")
; #define PG8_WAIT_L(n) asm volatile("s_waitcnt lgkmcnt(" #n ")" ::: "memory")
; #define PG8_BAR __builtin_amdgcn_s_barrier()
; #define PG8_SCHED __builtin_amdgcn_sched_barrier(0)
; template <class Epi, class Sched, bool ALIGN_EPI = false, bool SP2 = false>
; __device__ __forceinline__ void gemm_phase(PG8_LAS unsigned char* lds, const Gemm g, const Sched& S, const Epi& E) {
;     ...
;         for (int t = 0; t < nt; t += 2) {
;     ...
;             PG8_LDA(At, 1, 1); PG8_STAGE(PG8_SB(1, 0), b3, voffB); PG8_STAGE(PG8_SB(1, 1), b3 + hstep, voffB); PG8_STAGE(PG8_SA(1, 0), a3, voffA);
;             PG8_WAIT_V(8); PG8_WAIT_L(0); PG8_BAR; PG8_MMA(1, 0, At, B0); PG8_MMA(1, 1, At, B1); PG8_BAR; PG8_SCHED;
	s_add_i32 s36, s70, s41
	v_lshl_add_u64 v[230:231], v[230:231], 0, s[24:25]
	s_mov_b32 m0, s36
	ds_read_b128 v[198:201], v164 offset:49152
	ds_read_b128 v[202:205], v164 offset:50176
	ds_read_b128 v[206:209], v164 offset:51200
	ds_read_b128 v[210:213], v164 offset:52224
	ds_read_b128 v[214:217], v164 offset:53248
	ds_read_b128 v[218:221], v164 offset:54272
	ds_read_b128 v[222:225], v164 offset:55296
	ds_read_b128 v[226:229], v164 offset:56320
	global_load_lds_dwordx4 v[230:231], off
	v_lshl_add_u64 v[230:231], v[232:233], 0, s[24:25]
	s_add_i32 m0, s36, 0x2000
	s_add_i32 s36, s71, s41
	global_load_lds_dwordx4 v[230:231], off
	v_lshl_add_u64 v[230:231], v[234:235], 0, s[24:25]
	s_mov_b32 m0, s36
	s_nop 0
	global_load_lds_dwordx4 v[230:231], off
	v_lshl_add_u64 v[230:231], v[236:237], 0, s[24:25]
	s_add_i32 m0, s36, 0x2000
	s_nop 0
	global_load_lds_dwordx4 v[230:231], off
	v_lshl_add_u64 v[230:231], v[238:239], 0, s[24:25]
	s_mov_b32 m0, s47
	s_nop 0
	global_load_lds_dwordx4 v[230:231], off
	v_lshl_add_u64 v[230:231], v[240:241], 0, s[24:25]
	s_mov_b32 m0, s48
	s_nop 0
	global_load_lds_dwordx4 v[230:231], off
	s_waitcnt vmcnt(8)
	s_waitcnt lgkmcnt(0)
	s_barrier
	v_mfma_f32_16x16x32_bf16 v[62:65], v[166:169], v[198:201], v[62:65]
	v_mfma_f32_16x16x32_bf16 v[58:61], v[174:177], v[198:201], v[58:61]
	v_mfma_f32_16x16x32_bf16 v[46:49], v[166:169], v[206:209], v[46:49]
	v_mfma_f32_16x16x32_bf16 v[42:45], v[174:177], v[206:209], v[42:45]
	v_mfma_f32_16x16x32_bf16 v[30:33], v[166:169], v[214:217], v[30:33]
	v_mfma_f32_16x16x32_bf16 v[26:29], v[174:177], v[214:217], v[26:29]
	v_mfma_f32_16x16x32_bf16 v[14:17], v[166:169], v[222:225], v[14:17]
	v_mfma_f32_16x16x32_bf16 v[10:13], v[174:177], v[222:225], v[10:13]
	v_mfma_f32_16x16x32_bf16 v[62:65], v[170:173], v[202:205], v[62:65]
	v_mfma_f32_16x16x32_bf16 v[58:61], v[178:181], v[202:205], v[58:61]
	v_mfma_f32_16x16x32_bf16 v[46:49], v[170:173], v[210:213], v[46:49]
	v_mfma_f32_16x16x32_bf16 v[42:45], v[178:181], v[210:213], v[42:45]
	v_mfma_f32_16x16x32_bf16 v[30:33], v[170:173], v[218:221], v[30:33]
	v_mfma_f32_16x16x32_bf16 v[26:29], v[178:181], v[218:221], v[26:29]
	v_mfma_f32_16x16x32_bf16 v[14:17], v[170:173], v[226:229], v[14:17]
	v_mfma_f32_16x16x32_bf16 v[10:13], v[178:181], v[226:229], v[10:13]
	v_mfma_f32_16x16x32_bf16 v[54:57], v[182:185], v[198:201], v[54:57]
	v_mfma_f32_16x16x32_bf16 v[50:53], v[190:193], v[198:201], v[50:53]
	v_mfma_f32_16x16x32_bf16 v[38:41], v[182:185], v[206:209], v[38:41]
	v_mfma_f32_16x16x32_bf16 v[34:37], v[190:193], v[206:209], v[34:37]
	v_mfma_f32_16x16x32_bf16 v[22:25], v[182:185], v[214:217], v[22:25]
	v_mfma_f32_16x16x32_bf16 v[18:21], v[190:193], v[214:217], v[18:21]
	v_mfma_f32_16x16x32_bf16 v[6:9], v[182:185], v[222:225], v[6:9]
	v_mfma_f32_16x16x32_bf16 v[2:5], v[190:193], v[222:225], v[2:5]
	v_mfma_f32_16x16x32_bf16 v[54:57], v[186:189], v[202:205], v[54:57]
	v_mfma_f32_16x16x32_bf16 v[50:53], v[194:197], v[202:205], v[50:53]
	v_mfma_f32_16x16x32_bf16 v[38:41], v[186:189], v[210:213], v[38:41]
	v_mfma_f32_16x16x32_bf16 v[34:37], v[194:197], v[210:213], v[34:37]
	v_mfma_f32_16x16x32_bf16 v[22:25], v[186:189], v[218:221], v[22:25]
	v_mfma_f32_16x16x32_bf16 v[18:21], v[194:197], v[218:221], v[18:21]
	v_mfma_f32_16x16x32_bf16 v[6:9], v[186:189], v[226:229], v[6:9]
	v_mfma_f32_16x16x32_bf16 v[2:5], v[194:197], v[226:229], v[2:5]
	s_barrier
	s_add_u32 s81, s81, 0x100
	s_addc_u32 s86, s86, 0
	s_add_u32 s34, s34, 0x100
	s_addc_u32 s35, s35, 0
	s_cmp_ge_i32 s87, s49
	s_mov_b32 s36, s87
	s_cbranch_scc0 .LBB0_1375

; #define PG8_STAGE(bufoff, gbase, voff) do { _Pragma("unroll") for (int _i = 0; _i < 2; ++_i) \
;         __builtin_amdgcn_global_load_lds((const unsigned*)((const char*)(gbase) + (voff)[_i]), (PG8_LAS unsigned*)(lds + (bufoff) + ldsw + _i * 8192), 16, 0, 0); } while (0)
; #define PG8_LDA(dst, b, h) do { _Pragma("unroll") for (int m = 0; m < 4; ++m) _Pragma("unroll") for (int k = 0; k < 2; ++k) dst[m][k] = *(const PG8_LAS bf16x8*)(lds + PG8_SA(b, h) + aoff + m * 2048 + k * 1024); } while (0)
; #define PG8_LDB(dst, b, h) do { _Pragma("unroll") for (int n = 0; n < 2; ++n) _Pragma("unroll") for (int k = 0; k < 2; ++k) dst[n][k] = *(const PG8_LAS bf16x8*)(lds + PG8_SB(b, h) + boff + n * 2048 + k * 1024); } while (0)
; #define PG8_MMA(ai, bj, At, Bt) do { __builtin_amdgcn_s_setprio(1); _Pragma("unroll") for (int m = 0; m < 4; ++m) _Pragma("unroll") for (int n = 0; n < 2; ++n) _Pragma("unroll") for (int k = 0; k < 2; ++k) \
;         acc[ai][bj][m][n] = __builtin_amdgcn_mfma_f32_16x16x32_bf16(Bt[n][k], At[m][k], acc[ai][bj][m][n], 0, 0, 0); __builtin_amdgcn_s_setprio(0); } while (0)
; #define PG8_WAIT_V(n) asm volatile("s_waitcnt vmcnt(" #n ")" ::: "memory")
; #define PG8_WAIT_L(n) asm volatile("s_waitcnt lgkmcnt(" #n ")" ::: "memory")
; #define PG8_BAR __builtin_amdgcn_s_barrier()
; #define PG8_SCHED __builtin_amdgcn_sched_barrier(0)
; template <class Epi, class Sched, bool ALIGN_EPI = false, bool SP2 = false>
; __device__ __forceinline__ void gemm_phase(PG8_LAS unsigned char* lds, const Gemm g, const Sched& S, const Epi& E) {
;     ...
;         for (int t = 0; t < nt; t += 2) {
;             const bool last = (t == nt - 2);
;             const char* a1 = cA + (size_t)(t + 1) * kstep;
;             const char* a2 = last ? nA : cA + (size_t)(t + 2) * kstep; const char* b2 = last ? nB : cB + (size_t)(t + 2) * kstep;
;             const char* a3 = a2 + kstep; const char* b3 = b2 + kstep;
;             if (last && has_next) S.a_ready(nxt);
;             if constexpr (SP2) {
;             PG8_LDB(B0, 0, 0); PG8_LDB(B1, 0, 1); PG8_SCHED; PG8_LDA(At, 0, 0); PG8_STAGE(PG8_SA(1, 1), a1 + hstep, voffA);
;             PG8_WAIT_V(8); PG8_WAIT_L(0); PG8_BAR; PG8_MMA(0, 0, At, B0); PG8_MMA(0, 1, At, B1); PG8_BAR; PG8_SCHED;
;             PG8_LDA(At, 0, 1); PG8_STAGE(PG8_SB(0, 0), b2, voffB); PG8_STAGE(PG8_SB(0, 1), b2 + hstep, voffB); PG8_STAGE(PG8_SA(0, 0), a2, voffA);
.LBB0_1404:
	ds_read_b128 v[166:169], v162
	ds_read_b128 v[170:173], v162 offset:1024
	ds_read_b128 v[174:177], v162 offset:2048
	ds_read_b128 v[178:181], v162 offset:3072
	ds_read_b128 v[182:185], v163
	ds_read_b128 v[186:189], v163 offset:1024
	ds_read_b128 v[190:193], v163 offset:2048
	ds_read_b128 v[194:197], v163 offset:3072
	s_add_i32 s86, s34, 2
	s_add_u32 s70, s30, 0x80
	s_addc_u32 s35, s31, 0
	s_cmp_eq_u32 s49, s34
	s_cselect_b32 s34, s6, s70
	s_cselect_b32 s35, s7, s35
	s_cselect_b32 s71, s29, s81
	s_cselect_b32 s70, s28, s80
	v_lshl_add_u64 v[230:231], s[30:31], 0, v[140:141]
	s_add_i32 m0, s41, 0xc000
	ds_read_b128 v[198:201], v164
	ds_read_b128 v[202:205], v164 offset:1024
	ds_read_b128 v[206:209], v164 offset:2048
	ds_read_b128 v[210:213], v164 offset:3072
	ds_read_b128 v[214:217], v164 offset:4096
	ds_read_b128 v[218:221], v164 offset:5120
	ds_read_b128 v[222:225], v164 offset:6144
	ds_read_b128 v[226:229], v164 offset:7168
	global_load_lds_dwordx4 v[230:231], off
	v_lshl_add_u64 v[230:231], s[30:31], 0, v[138:139]
	s_add_i32 m0, s41, 0xe000
	s_nop 0
	global_load_lds_dwordx4 v[230:231], off
	s_waitcnt vmcnt(8)
	s_waitcnt lgkmcnt(0)
	s_barrier
	v_mfma_f32_16x16x32_bf16 v[122:125], v[166:169], v[198:201], v[122:125]
	v_mfma_f32_16x16x32_bf16 v[126:129], v[174:177], v[198:201], v[126:129]
	v_mfma_f32_16x16x32_bf16 v[110:113], v[166:169], v[206:209], v[110:113]
	v_mfma_f32_16x16x32_bf16 v[106:109], v[174:177], v[206:209], v[106:109]
	v_mfma_f32_16x16x32_bf16 v[94:97], v[166:169], v[214:217], v[94:97]
	v_mfma_f32_16x16x32_bf16 v[90:93], v[174:177], v[214:217], v[90:93]
	v_mfma_f32_16x16x32_bf16 v[78:81], v[166:169], v[222:225], v[78:81]
	v_mfma_f32_16x16x32_bf16 v[74:77], v[174:177], v[222:225], v[74:77]
	v_mfma_f32_16x16x32_bf16 v[122:125], v[170:173], v[202:205], v[122:125]
	v_mfma_f32_16x16x32_bf16 v[126:129], v[178:181], v[202:205], v[126:129]
	v_mfma_f32_16x16x32_bf16 v[110:113], v[170:173], v[210:213], v[110:113]
	v_mfma_f32_16x16x32_bf16 v[106:109], v[178:181], v[210:213], v[106:109]
	v_mfma_f32_16x16x32_bf16 v[94:97], v[170:173], v[218:221], v[94:97]
	v_mfma_f32_16x16x32_bf16 v[90:93], v[178:181], v[218:221], v[90:93]
	v_mfma_f32_16x16x32_bf16 v[78:81], v[170:173], v[226:229], v[78:81]
	v_mfma_f32_16x16x32_bf16 v[74:77], v[178:181], v[226:229], v[74:77]
	v_mfma_f32_16x16x32_bf16 v[118:121], v[182:185], v[198:201], v[118:121]
	v_mfma_f32_16x16x32_bf16 v[114:117], v[190:193], v[198:201], v[114:117]
	v_mfma_f32_16x16x32_bf16 v[102:105], v[182:185], v[206:209], v[102:105]
	v_mfma_f32_16x16x32_bf16 v[98:101], v[190:193], v[206:209], v[98:101]
	v_mfma_f32_16x16x32_bf16 v[86:89], v[182:185], v[214:217], v[86:89]
	v_mfma_f32_16x16x32_bf16 v[82:85], v[190:193], v[214:217], v[82:85]
	v_mfma_f32_16x16x32_bf16 v[70:73], v[182:185], v[222:225], v[70:73]
	v_mfma_f32_16x16x32_bf16 v[66:69], v[190:193], v[222:225], v[66:69]
	v_mfma_f32_16x16x32_bf16 v[118:121], v[186:189], v[202:205], v[118:121]
	v_mfma_f32_16x16x32_bf16 v[114:117], v[194:197], v[202:205], v[114:117]
	v_mfma_f32_16x16x32_bf16 v[102:105], v[186:189], v[210:213], v[102:105]
	v_mfma_f32_16x16x32_bf16 v[98:101], v[194:197], v[210:213], v[98:101]
	v_mfma_f32_16x16x32_bf16 v[86:89], v[186:189], v[218:221], v[86:89]
	v_mfma_f32_16x16x32_bf16 v[82:85], v[194:197], v[218:221], v[82:85]
	v_mfma_f32_16x16x32_bf16 v[70:73], v[186:189], v[226:229], v[70:73]
	v_mfma_f32_16x16x32_bf16 v[66:69], v[194:197], v[226:229], v[66:69]
	s_barrier
	s_add_i32 s72, s54, s40
	v_lshl_add_u64 v[230:231], s[70:71], 0, v[132:133]
	s_mov_b32 m0, s72
	ds_read_b128 v[198:201], v164 offset:16384
	ds_read_b128 v[202:205], v164 offset:17408
	ds_read_b128 v[206:209], v164 offset:18432
	ds_read_b128 v[210:213], v164 offset:19456
	ds_read_b128 v[214:217], v164 offset:20480
	ds_read_b128 v[218:221], v164 offset:21504
	ds_read_b128 v[222:225], v164 offset:22528
	ds_read_b128 v[226:229], v164 offset:23552
	global_load_lds_dwordx4 v[230:231], off
	s_add_i32 m0, s72, 0x2000
	v_lshl_add_u64 v[232:233], s[70:71], 0, v[136:137]
	s_add_u32 s70, s70, s12
	s_addc_u32 s71, s71, s13
	s_add_i32 s72, s55, s40
	global_load_lds_dwordx4 v[232:233], off
	v_lshl_add_u64 v[234:235], s[70:71], 0, v[132:133]
	s_mov_b32 m0, s72
	v_lshl_add_u64 v[236:237], s[70:71], 0, v[136:137]
	global_load_lds_dwordx4 v[234:235], off
	s_add_i32 m0, s72, 0x2000
	v_lshl_add_u64 v[238:239], s[34:35], 0, v[130:131]
	global_load_lds_dwordx4 v[236:237], off
	s_mov_b32 m0, s41
	v_lshl_add_u64 v[240:241], s[34:35], 0, v[134:135]
	global_load_lds_dwordx4 v[238:239], off
	s_mov_b32 m0, s42
	s_nop 0
	global_load_lds_dwordx4 v[240:241], off
	s_waitcnt vmcnt(8)
	s_waitcnt lgkmcnt(0)
	s_barrier
; #define PG8_STAGE(bufoff, gbase, voff) do { _Pragma("unroll") for (int _i = 0; _i < 2; ++_i) \
;         __builtin_amdgcn_global_load_lds((const unsigned*)((const char*)(gbase) + (voff)[_i]), (PG8_LAS unsigned*)(lds + (bufoff) + ldsw + _i * 8192), 16, 0, 0); } while (0)
; #define PG8_LDA(dst, b, h) do { _Pragma("unroll") for (int m = 0; m < 4; ++m) _Pragma("unroll") for (int k = 0; k < 2; ++k) dst[m][k] = *(const PG8_LAS bf16x8*)(lds + PG8_SA(b, h) + aoff + m * 2048 + k * 1024); } while (0)
; #define PG8_LDB(dst, b, h) do { _Pragma("unroll") for (int n = 0; n < 2; ++n) _Pragma("unroll") for (int k = 0; k < 2; ++k) dst[n][k] = *(const PG8_LAS bf16x8*)(lds + PG8_SB(b, h) + boff + n * 2048 + k * 1024); } while (0)
; #define PG8_MMA(ai, bj, At, Bt) do { __builtin_amdgcn_s_setprio(1); _Pragma("unroll") for (int m = 0; m < 4; ++m) _Pragma("unroll") for (int n = 0; n < 2; ++n) _Pragma("unroll") for (int k = 0; k < 2; ++k) \
;         acc[ai][bj][m][n] = __builtin_amdgcn_mfma_f32_16x16x32_bf16(Bt[n][k], At[m][k], acc[ai][bj][m][n], 0, 0, 0); __builtin_amdgcn_s_setprio(0); } while (0)
; #define PG8_WAIT_V(n) asm volatile("s_waitcnt vmcnt(" #n ")" ::: "memory")
; #define PG8_WAIT_L(n) asm volatile("s_waitcnt lgkmcnt(" #n ")" ::: "memory")
; #define PG8_BAR __builtin_amdgcn_s_barrier()
; #define PG8_SCHED __builtin_amdgcn_sched_barrier(0)
; template <class Epi, class Sched, bool ALIGN_EPI = false, bool SP2 = false>
; __device__ __forceinline__ void gemm_phase(PG8_LAS unsigned char* lds, const Gemm g, const Sched& S, const Epi& E) {
;     ...
;             PG8_WAIT_V(8); PG8_WAIT_L(0); PG8_BAR; PG8_MMA(1, 0, At, B0); PG8_MMA(1, 1, At, B1); PG8_BAR; PG8_SCHED;
;             PG8_LDB(B0, 1, 0); PG8_LDB(B1, 1, 1); PG8_SCHED; PG8_LDA(At, 1, 0); PG8_STAGE(PG8_SA(0, 1), a2 + hstep, voffA);
;             PG8_WAIT_V(8); PG8_WAIT_L(0); PG8_BAR; PG8_MMA(0, 0, At, B0); PG8_MMA(0, 1, At, B1); PG8_BAR; PG8_SCHED;
	v_mfma_f32_16x16x32_bf16 v[62:65], v[166:169], v[198:201], v[62:65]
	v_mfma_f32_16x16x32_bf16 v[58:61], v[174:177], v[198:201], v[58:61]
	v_mfma_f32_16x16x32_bf16 v[46:49], v[166:169], v[206:209], v[46:49]
	v_mfma_f32_16x16x32_bf16 v[42:45], v[174:177], v[206:209], v[42:45]
	v_mfma_f32_16x16x32_bf16 v[30:33], v[166:169], v[214:217], v[30:33]
	v_mfma_f32_16x16x32_bf16 v[26:29], v[174:177], v[214:217], v[26:29]
	v_mfma_f32_16x16x32_bf16 v[14:17], v[166:169], v[222:225], v[14:17]
	v_mfma_f32_16x16x32_bf16 v[10:13], v[174:177], v[222:225], v[10:13]
	v_mfma_f32_16x16x32_bf16 v[62:65], v[170:173], v[202:205], v[62:65]
	v_mfma_f32_16x16x32_bf16 v[58:61], v[178:181], v[202:205], v[58:61]
	v_mfma_f32_16x16x32_bf16 v[46:49], v[170:173], v[210:213], v[46:49]
	v_mfma_f32_16x16x32_bf16 v[42:45], v[178:181], v[210:213], v[42:45]
	v_mfma_f32_16x16x32_bf16 v[30:33], v[170:173], v[218:221], v[30:33]
	v_mfma_f32_16x16x32_bf16 v[26:29], v[178:181], v[218:221], v[26:29]
	v_mfma_f32_16x16x32_bf16 v[14:17], v[170:173], v[226:229], v[14:17]
	v_mfma_f32_16x16x32_bf16 v[10:13], v[178:181], v[226:229], v[10:13]
	v_mfma_f32_16x16x32_bf16 v[54:57], v[182:185], v[198:201], v[54:57]
	v_mfma_f32_16x16x32_bf16 v[50:53], v[190:193], v[198:201], v[50:53]
	v_mfma_f32_16x16x32_bf16 v[38:41], v[182:185], v[206:209], v[38:41]
	v_mfma_f32_16x16x32_bf16 v[34:37], v[190:193], v[206:209], v[34:37]
	v_mfma_f32_16x16x32_bf16 v[22:25], v[182:185], v[214:217], v[22:25]
	v_mfma_f32_16x16x32_bf16 v[18:21], v[190:193], v[214:217], v[18:21]
	v_mfma_f32_16x16x32_bf16 v[6:9], v[182:185], v[222:225], v[6:9]
	v_mfma_f32_16x16x32_bf16 v[2:5], v[190:193], v[222:225], v[2:5]
	v_mfma_f32_16x16x32_bf16 v[54:57], v[186:189], v[202:205], v[54:57]
	v_mfma_f32_16x16x32_bf16 v[50:53], v[194:197], v[202:205], v[50:53]
	v_mfma_f32_16x16x32_bf16 v[38:41], v[186:189], v[210:213], v[38:41]
	v_mfma_f32_16x16x32_bf16 v[34:37], v[194:197], v[210:213], v[34:37]
	v_mfma_f32_16x16x32_bf16 v[22:25], v[186:189], v[218:221], v[22:25]
	v_mfma_f32_16x16x32_bf16 v[18:21], v[194:197], v[218:221], v[18:21]
	v_mfma_f32_16x16x32_bf16 v[6:9], v[186:189], v[226:229], v[6:9]
	v_mfma_f32_16x16x32_bf16 v[2:5], v[194:197], v[226:229], v[2:5]
	s_barrier
	s_add_i32 s70, 0, 0x18000
	v_add_u32_e32 v165, s70, v160
	s_add_i32 s71, 0, 0x1c000
	ds_read_b128 v[166:169], v165
	ds_read_b128 v[170:173], v165 offset:1024
	ds_read_b128 v[174:177], v165 offset:2048
	ds_read_b128 v[178:181], v165 offset:3072
	v_add_u32_e32 v165, s71, v160
	ds_read_b128 v[182:185], v165
	ds_read_b128 v[186:189], v165 offset:1024
	ds_read_b128 v[190:193], v165 offset:2048
	ds_read_b128 v[194:197], v165 offset:3072
	s_add_u32 s34, s34, s12
	s_addc_u32 s35, s35, s13
	s_mov_b32 m0, s43
	v_lshl_add_u64 v[242:243], s[34:35], 0, v[130:131]
	ds_read_b128 v[198:201], v164 offset:32768
	ds_read_b128 v[202:205], v164 offset:33792
	ds_read_b128 v[206:209], v164 offset:34816
	ds_read_b128 v[210:213], v164 offset:35840
	ds_read_b128 v[214:217], v164 offset:36864
	ds_read_b128 v[218:221], v164 offset:37888
	ds_read_b128 v[222:225], v164 offset:38912
	ds_read_b128 v[226:229], v164 offset:39936
	global_load_lds_dwordx4 v[242:243], off
	v_lshl_add_u64 v[242:243], s[34:35], 0, v[134:135]
	s_mov_b32 m0, s44
	s_nop 0
	global_load_lds_dwordx4 v[242:243], off
	s_waitcnt vmcnt(8)
	s_waitcnt lgkmcnt(0)
	s_barrier
	v_mfma_f32_16x16x32_bf16 v[122:125], v[166:169], v[198:201], v[122:125]
	v_mfma_f32_16x16x32_bf16 v[126:129], v[174:177], v[198:201], v[126:129]
	v_mfma_f32_16x16x32_bf16 v[110:113], v[166:169], v[206:209], v[110:113]
	v_mfma_f32_16x16x32_bf16 v[106:109], v[174:177], v[206:209], v[106:109]
	v_mfma_f32_16x16x32_bf16 v[94:97], v[166:169], v[214:217], v[94:97]
	v_mfma_f32_16x16x32_bf16 v[90:93], v[174:177], v[214:217], v[90:93]
	v_mfma_f32_16x16x32_bf16 v[78:81], v[166:169], v[222:225], v[78:81]
	v_mfma_f32_16x16x32_bf16 v[74:77], v[174:177], v[222:225], v[74:77]
	v_mfma_f32_16x16x32_bf16 v[122:125], v[170:173], v[202:205], v[122:125]
	v_mfma_f32_16x16x32_bf16 v[126:129], v[178:181], v[202:205], v[126:129]
	v_mfma_f32_16x16x32_bf16 v[110:113], v[170:173], v[210:213], v[110:113]
	v_mfma_f32_16x16x32_bf16 v[106:109], v[178:181], v[210:213], v[106:109]
	v_mfma_f32_16x16x32_bf16 v[94:97], v[170:173], v[218:221], v[94:97]
	v_mfma_f32_16x16x32_bf16 v[90:93], v[178:181], v[218:221], v[90:93]
	v_mfma_f32_16x16x32_bf16 v[78:81], v[170:173], v[226:229], v[78:81]
	v_mfma_f32_16x16x32_bf16 v[74:77], v[178:181], v[226:229], v[74:77]
	v_mfma_f32_16x16x32_bf16 v[118:121], v[182:185], v[198:201], v[118:121]
	v_mfma_f32_16x16x32_bf16 v[114:117], v[190:193], v[198:201], v[114:117]
	v_mfma_f32_16x16x32_bf16 v[102:105], v[182:185], v[206:209], v[102:105]
	v_mfma_f32_16x16x32_bf16 v[98:101], v[190:193], v[206:209], v[98:101]
	v_mfma_f32_16x16x32_bf16 v[86:89], v[182:185], v[214:217], v[86:89]
	v_mfma_f32_16x16x32_bf16 v[82:85], v[190:193], v[214:217], v[82:85]
	v_mfma_f32_16x16x32_bf16 v[70:73], v[182:185], v[222:225], v[70:73]
	v_mfma_f32_16x16x32_bf16 v[66:69], v[190:193], v[222:225], v[66:69]
	v_mfma_f32_16x16x32_bf16 v[118:121], v[186:189], v[202:205], v[118:121]
	v_mfma_f32_16x16x32_bf16 v[114:117], v[194:197], v[202:205], v[114:117]
	v_mfma_f32_16x16x32_bf16 v[102:105], v[186:189], v[210:213], v[102:105]
	v_mfma_f32_16x16x32_bf16 v[98:101], v[194:197], v[210:213], v[98:101]
	v_mfma_f32_16x16x32_bf16 v[86:89], v[186:189], v[218:221], v[86:89]
	v_mfma_f32_16x16x32_bf16 v[82:85], v[194:197], v[218:221], v[82:85]
	v_mfma_f32_16x16x32_bf16 v[70:73], v[186:189], v[226:229], v[70:73]
	v_mfma_f32_16x16x32_bf16 v[66:69], v[194:197], v[226:229], v[66:69]
	s_barrier
; #define PG8_STAGE(bufoff, gbase, voff) do { _Pragma("unroll") for (int _i = 0; _i < 2; ++_i) \
;         __builtin_amdgcn_global_load_lds((const unsigned*)((const char*)(gbase) + (voff)[_i]), (PG8_LAS unsigned*)(lds + (bufoff) + ldsw + _i * 8192), 16, 0, 0); } while (0)
; #define PG8_LDA(dst, b, h) do { _Pragma("unroll") for (int m = 0; m < 4; ++m) _Pragma("unroll") for (int k = 0; k < 2; ++k) dst[m][k] = *(const PG8_LAS bf16x8*)(lds + PG8_SA(b, h) + aoff + m * 2048 + k * 1024); } while (0)
; #define PG8_MMA(ai, bj, At, Bt) do { __builtin_amdgcn_s_setprio(1); _Pragma("unroll") for (int m = 0; m < 4; ++m) _Pragma("unroll") for (int n = 0; n < 2; ++n) _Pragma("unroll") for (int k = 0; k < 2; ++k) \
;         acc[ai][bj][m][n] = __builtin_amdgcn_mfma_f32_16x16x32_bf16(Bt[n][k], At[m][k], acc[ai][bj][m][n], 0, 0, 0); __builtin_amdgcn_s_setprio(0); } while (0)
; #define PG8_WAIT_V(n) asm volatile("s_waitcnt vmcnt(" #n ")" ::: "memory")
; #define PG8_WAIT_L(n) asm volatile("s_waitcnt lgkmcnt(" #n ")" ::: "memory")
; #define PG8_BAR __builtin_amdgcn_s_barrier()
; #define PG8_SCHED __builtin_amdgcn_sched_barrier(0)
; template <class Epi, class Sched, bool ALIGN_EPI = false, bool SP2 = false>
; __device__ __forceinline__ void gemm_phase(PG8_LAS unsigned char* lds, const Gemm g, const Sched& S, const Epi& E) {
;     ...
;         for (int t = 0; t < nt; t += 2) {
;     ...
;             PG8_LDA(At, 1, 1); PG8_STAGE(PG8_SB(1, 0), b3, voffB); PG8_STAGE(PG8_SB(1, 1), b3 + hstep, voffB); PG8_STAGE(PG8_SA(1, 0), a3, voffA);
;             PG8_WAIT_V(8); PG8_WAIT_L(0); PG8_BAR; PG8_MMA(1, 0, At, B0); PG8_MMA(1, 1, At, B1); PG8_BAR; PG8_SCHED;
	s_add_i32 s34, s70, s40
	v_lshl_add_u64 v[230:231], v[230:231], 0, s[22:23]
	s_mov_b32 m0, s34
	ds_read_b128 v[198:201], v164 offset:49152
	ds_read_b128 v[202:205], v164 offset:50176
	ds_read_b128 v[206:209], v164 offset:51200
	ds_read_b128 v[210:213], v164 offset:52224
	ds_read_b128 v[214:217], v164 offset:53248
	ds_read_b128 v[218:221], v164 offset:54272
	ds_read_b128 v[222:225], v164 offset:55296
	ds_read_b128 v[226:229], v164 offset:56320
	global_load_lds_dwordx4 v[230:231], off
	v_lshl_add_u64 v[230:231], v[232:233], 0, s[22:23]
	s_add_i32 m0, s34, 0x2000
	s_add_i32 s34, s71, s40
	global_load_lds_dwordx4 v[230:231], off
	v_lshl_add_u64 v[230:231], v[234:235], 0, s[22:23]
	s_mov_b32 m0, s34
	s_nop 0
	global_load_lds_dwordx4 v[230:231], off
	v_lshl_add_u64 v[230:231], v[236:237], 0, s[22:23]
	s_add_i32 m0, s34, 0x2000
	s_nop 0
	global_load_lds_dwordx4 v[230:231], off
	v_lshl_add_u64 v[230:231], v[238:239], 0, s[22:23]
	s_mov_b32 m0, s46
	s_nop 0
	global_load_lds_dwordx4 v[230:231], off
	v_lshl_add_u64 v[230:231], v[240:241], 0, s[22:23]
	s_mov_b32 m0, s47
	s_nop 0
	global_load_lds_dwordx4 v[230:231], off
	s_waitcnt vmcnt(8)
	s_waitcnt lgkmcnt(0)
	s_barrier
	v_mfma_f32_16x16x32_bf16 v[62:65], v[166:169], v[198:201], v[62:65]
	v_mfma_f32_16x16x32_bf16 v[58:61], v[174:177], v[198:201], v[58:61]
	v_mfma_f32_16x16x32_bf16 v[46:49], v[166:169], v[206:209], v[46:49]
	v_mfma_f32_16x16x32_bf16 v[42:45], v[174:177], v[206:209], v[42:45]
	v_mfma_f32_16x16x32_bf16 v[30:33], v[166:169], v[214:217], v[30:33]
	v_mfma_f32_16x16x32_bf16 v[26:29], v[174:177], v[214:217], v[26:29]
	v_mfma_f32_16x16x32_bf16 v[14:17], v[166:169], v[222:225], v[14:17]
	v_mfma_f32_16x16x32_bf16 v[10:13], v[174:177], v[222:225], v[10:13]
	v_mfma_f32_16x16x32_bf16 v[62:65], v[170:173], v[202:205], v[62:65]
	v_mfma_f32_16x16x32_bf16 v[58:61], v[178:181], v[202:205], v[58:61]
	v_mfma_f32_16x16x32_bf16 v[46:49], v[170:173], v[210:213], v[46:49]
	v_mfma_f32_16x16x32_bf16 v[42:45], v[178:181], v[210:213], v[42:45]
	v_mfma_f32_16x16x32_bf16 v[30:33], v[170:173], v[218:221], v[30:33]
	v_mfma_f32_16x16x32_bf16 v[26:29], v[178:181], v[218:221], v[26:29]
	v_mfma_f32_16x16x32_bf16 v[14:17], v[170:173], v[226:229], v[14:17]
	v_mfma_f32_16x16x32_bf16 v[10:13], v[178:181], v[226:229], v[10:13]
	v_mfma_f32_16x16x32_bf16 v[54:57], v[182:185], v[198:201], v[54:57]
	v_mfma_f32_16x16x32_bf16 v[50:53], v[190:193], v[198:201], v[50:53]
	v_mfma_f32_16x16x32_bf16 v[38:41], v[182:185], v[206:209], v[38:41]
	v_mfma_f32_16x16x32_bf16 v[34:37], v[190:193], v[206:209], v[34:37]
	v_mfma_f32_16x16x32_bf16 v[22:25], v[182:185], v[214:217], v[22:25]
	v_mfma_f32_16x16x32_bf16 v[18:21], v[190:193], v[214:217], v[18:21]
	v_mfma_f32_16x16x32_bf16 v[6:9], v[182:185], v[222:225], v[6:9]
	v_mfma_f32_16x16x32_bf16 v[2:5], v[190:193], v[222:225], v[2:5]
	v_mfma_f32_16x16x32_bf16 v[54:57], v[186:189], v[202:205], v[54:57]
	v_mfma_f32_16x16x32_bf16 v[50:53], v[194:197], v[202:205], v[50:53]
	v_mfma_f32_16x16x32_bf16 v[38:41], v[186:189], v[210:213], v[38:41]
	v_mfma_f32_16x16x32_bf16 v[34:37], v[194:197], v[210:213], v[34:37]
	v_mfma_f32_16x16x32_bf16 v[22:25], v[186:189], v[218:221], v[22:25]
	v_mfma_f32_16x16x32_bf16 v[18:21], v[194:197], v[218:221], v[18:21]
	v_mfma_f32_16x16x32_bf16 v[6:9], v[186:189], v[226:229], v[6:9]
	v_mfma_f32_16x16x32_bf16 v[2:5], v[194:197], v[226:229], v[2:5]
	s_barrier
	s_add_u32 s80, s80, 0x100
	s_addc_u32 s81, s81, 0
	s_add_u32 s30, s30, 0x100
	s_addc_u32 s31, s31, 0
	s_cmp_ge_i32 s86, s48
	s_mov_b32 s34, s86
	s_cbranch_scc0 .LBB0_1404

; #define PG8_STAGE(bufoff, gbase, voff) do { _Pragma("unroll") for (int _i = 0; _i < 2; ++_i) \
;         __builtin_amdgcn_global_load_lds((const unsigned*)((const char*)(gbase) + (voff)[_i]), (PG8_LAS unsigned*)(lds + (bufoff) + ldsw + _i * 8192), 16, 0, 0); } while (0)
; #define PG8_LDA(dst, b, h) do { _Pragma("unroll") for (int m = 0; m < 4; ++m) _Pragma("unroll") for (int k = 0; k < 2; ++k) dst[m][k] = *(const PG8_LAS bf16x8*)(lds + PG8_SA(b, h) + aoff + m * 2048 + k * 1024); } while (0)
; #define PG8_LDB(dst, b, h) do { _Pragma("unroll") for (int n = 0; n < 2; ++n) _Pragma("unroll") for (int k = 0; k < 2; ++k) dst[n][k] = *(const PG8_LAS bf16x8*)(lds + PG8_SB(b, h) + boff + n * 2048 + k * 1024); } while (0)
; #define PG8_MMA(ai, bj, At, Bt) do { __builtin_amdgcn_s_setprio(1); _Pragma("unroll") for (int m = 0; m < 4; ++m) _Pragma("unroll") for (int n = 0; n < 2; ++n) _Pragma("unroll") for (int k = 0; k < 2; ++k) \
;         acc[ai][bj][m][n] = __builtin_amdgcn_mfma_f32_16x16x32_bf16(Bt[n][k], At[m][k], acc[ai][bj][m][n], 0, 0, 0); __builtin_amdgcn_s_setprio(0); } while (0)
; #define PG8_WAIT_V(n) asm volatile("s_waitcnt vmcnt(" #n ")" ::: "memory")
; #define PG8_BAR __builtin_amdgcn_s_barrier()
; template <class Epi, class Sched, bool ALIGN_EPI = false, bool SP2 = false>
; __device__ __forceinline__ void gemm_phase(PG8_LAS unsigned char* lds, const Gemm g, const Sched& S, const Epi& E) {
;     ...
;         for (int t = 0; t < nt; t += 2) {
;             const bool last = (t == nt - 2);
;             const char* a1 = cA + (size_t)(t + 1) * kstep;
;             const char* a2 = last ? nA : cA + (size_t)(t + 2) * kstep; const char* b2 = last ? nB : cB + (size_t)(t + 2) * kstep;
;             const char* a3 = a2 + kstep; const char* b3 = b2 + kstep;
;             if (last && has_next) S.a_ready(nxt);
;             if constexpr (SP2) {
;             PG8_LDB(B0, 0, 0); PG8_LDB(B1, 0, 1); PG8_SCHED; PG8_LDA(At, 0, 0); PG8_STAGE(PG8_SA(1, 1), a1 + hstep, voffA);
;             PG8_WAIT_V(8); PG8_WAIT_L(0); PG8_BAR; PG8_MMA(0, 0, At, B0); PG8_MMA(0, 1, At, B1); PG8_BAR; PG8_SCHED;
;             PG8_LDA(At, 0, 1); PG8_STAGE(PG8_SB(0, 0), b2, voffB); PG8_STAGE(PG8_SB(0, 1), b2 + hstep, voffB); PG8_STAGE(PG8_SA(0, 0), a2, voffA);
;             PG8_WAIT_V(8); PG8_WAIT_L(0); PG8_BAR; PG8_MMA(1, 0, At, B0); PG8_MMA(1, 1, At, B1); PG8_BAR; PG8_SCHED;
.LBB0_1433:
	ds_read_b128 v[156:159], v1
	ds_read_b128 v[160:163], v1 offset:1024
	ds_read_b128 v[164:167], v1 offset:2048
	ds_read_b128 v[168:171], v1 offset:3072
	ds_read_b128 v[172:175], v146
	ds_read_b128 v[176:179], v146 offset:1024
	ds_read_b128 v[180:183], v146 offset:2048
	ds_read_b128 v[184:187], v146 offset:3072
	s_add_i32 s80, s30, 2
	s_add_u32 s70, s28, 0x80
	s_addc_u32 s31, s29, 0
	s_cmp_eq_u32 s47, s30
	s_cselect_b32 s30, s4, s70
	s_cselect_b32 s31, s5, s31
	s_cselect_b32 s71, s27, s69
	s_cselect_b32 s70, s26, s68
	v_lshl_add_u64 v[152:153], s[28:29], 0, v[140:141]
	s_add_i32 m0, s39, 0xc000
	ds_read_b128 v[188:191], v147
	ds_read_b128 v[192:195], v147 offset:1024
	ds_read_b128 v[196:199], v147 offset:2048
	ds_read_b128 v[200:203], v147 offset:3072
	ds_read_b128 v[204:207], v147 offset:4096
	ds_read_b128 v[208:211], v147 offset:5120
	ds_read_b128 v[212:215], v147 offset:6144
	ds_read_b128 v[216:219], v147 offset:7168
	global_load_lds_dwordx4 v[152:153], off
	v_lshl_add_u64 v[152:153], s[28:29], 0, v[138:139]
	s_add_i32 m0, s39, 0xe000
	s_nop 0
	global_load_lds_dwordx4 v[152:153], off
	s_waitcnt vmcnt(8)
	s_waitcnt lgkmcnt(0)
	s_barrier
	v_mfma_f32_16x16x32_bf16 v[122:125], v[156:159], v[188:191], v[122:125]
	v_mfma_f32_16x16x32_bf16 v[126:129], v[164:167], v[188:191], v[126:129]
	v_mfma_f32_16x16x32_bf16 v[110:113], v[156:159], v[196:199], v[110:113]
	v_mfma_f32_16x16x32_bf16 v[106:109], v[164:167], v[196:199], v[106:109]
	v_mfma_f32_16x16x32_bf16 v[94:97], v[156:159], v[204:207], v[94:97]
	v_mfma_f32_16x16x32_bf16 v[90:93], v[164:167], v[204:207], v[90:93]
	v_mfma_f32_16x16x32_bf16 v[78:81], v[156:159], v[212:215], v[78:81]
	v_mfma_f32_16x16x32_bf16 v[74:77], v[164:167], v[212:215], v[74:77]
	v_mfma_f32_16x16x32_bf16 v[122:125], v[160:163], v[192:195], v[122:125]
	v_mfma_f32_16x16x32_bf16 v[126:129], v[168:171], v[192:195], v[126:129]
	v_mfma_f32_16x16x32_bf16 v[110:113], v[160:163], v[200:203], v[110:113]
	v_mfma_f32_16x16x32_bf16 v[106:109], v[168:171], v[200:203], v[106:109]
	v_mfma_f32_16x16x32_bf16 v[94:97], v[160:163], v[208:211], v[94:97]
	v_mfma_f32_16x16x32_bf16 v[90:93], v[168:171], v[208:211], v[90:93]
	v_mfma_f32_16x16x32_bf16 v[78:81], v[160:163], v[216:219], v[78:81]
	v_mfma_f32_16x16x32_bf16 v[74:77], v[168:171], v[216:219], v[74:77]
	v_mfma_f32_16x16x32_bf16 v[118:121], v[172:175], v[188:191], v[118:121]
	v_mfma_f32_16x16x32_bf16 v[114:117], v[180:183], v[188:191], v[114:117]
	v_mfma_f32_16x16x32_bf16 v[102:105], v[172:175], v[196:199], v[102:105]
	v_mfma_f32_16x16x32_bf16 v[98:101], v[180:183], v[196:199], v[98:101]
	v_mfma_f32_16x16x32_bf16 v[86:89], v[172:175], v[204:207], v[86:89]
	v_mfma_f32_16x16x32_bf16 v[82:85], v[180:183], v[204:207], v[82:85]
	v_mfma_f32_16x16x32_bf16 v[70:73], v[172:175], v[212:215], v[70:73]
	v_mfma_f32_16x16x32_bf16 v[66:69], v[180:183], v[212:215], v[66:69]
	v_mfma_f32_16x16x32_bf16 v[118:121], v[176:179], v[192:195], v[118:121]
	v_mfma_f32_16x16x32_bf16 v[114:117], v[184:187], v[192:195], v[114:117]
	v_mfma_f32_16x16x32_bf16 v[102:105], v[176:179], v[200:203], v[102:105]
	v_mfma_f32_16x16x32_bf16 v[98:101], v[184:187], v[200:203], v[98:101]
	v_mfma_f32_16x16x32_bf16 v[86:89], v[176:179], v[208:211], v[86:89]
	v_mfma_f32_16x16x32_bf16 v[82:85], v[184:187], v[208:211], v[82:85]
	v_mfma_f32_16x16x32_bf16 v[70:73], v[176:179], v[216:219], v[70:73]
	v_mfma_f32_16x16x32_bf16 v[66:69], v[184:187], v[216:219], v[66:69]
	s_barrier
	s_add_i32 s72, s52, s38
	v_lshl_add_u64 v[152:153], s[70:71], 0, v[132:133]
	s_mov_b32 m0, s72
	ds_read_b128 v[188:191], v147 offset:16384
	ds_read_b128 v[192:195], v147 offset:17408
	ds_read_b128 v[196:199], v147 offset:18432
	ds_read_b128 v[200:203], v147 offset:19456
	ds_read_b128 v[204:207], v147 offset:20480
	ds_read_b128 v[208:211], v147 offset:21504
	ds_read_b128 v[212:215], v147 offset:22528
	ds_read_b128 v[216:219], v147 offset:23552
	global_load_lds_dwordx4 v[152:153], off
	s_add_i32 m0, s72, 0x2000
	v_lshl_add_u64 v[220:221], s[70:71], 0, v[136:137]
	s_add_u32 s70, s70, s6
	s_addc_u32 s71, s71, s7
	s_add_i32 s72, s53, s38
	global_load_lds_dwordx4 v[220:221], off
	v_lshl_add_u64 v[222:223], s[70:71], 0, v[132:133]
	s_mov_b32 m0, s72
	v_lshl_add_u64 v[224:225], s[70:71], 0, v[136:137]
	global_load_lds_dwordx4 v[222:223], off
	s_add_i32 m0, s72, 0x2000
	v_lshl_add_u64 v[226:227], s[30:31], 0, v[130:131]
	global_load_lds_dwordx4 v[224:225], off
	s_mov_b32 m0, s39
	v_lshl_add_u64 v[228:229], s[30:31], 0, v[134:135]
	global_load_lds_dwordx4 v[226:227], off
	s_mov_b32 m0, s40
	s_nop 0
	global_load_lds_dwordx4 v[228:229], off
	s_waitcnt vmcnt(8)
	s_waitcnt lgkmcnt(0)
	s_barrier
; #define PG8_STAGE(bufoff, gbase, voff) do { _Pragma("unroll") for (int _i = 0; _i < 2; ++_i) \
;         __builtin_amdgcn_global_load_lds((const unsigned*)((const char*)(gbase) + (voff)[_i]), (PG8_LAS unsigned*)(lds + (bufoff) + ldsw + _i * 8192), 16, 0, 0); } while (0)
; #define PG8_LDA(dst, b, h) do { _Pragma("unroll") for (int m = 0; m < 4; ++m) _Pragma("unroll") for (int k = 0; k < 2; ++k) dst[m][k] = *(const PG8_LAS bf16x8*)(lds + PG8_SA(b, h) + aoff + m * 2048 + k * 1024); } while (0)
; #define PG8_LDB(dst, b, h) do { _Pragma("unroll") for (int n = 0; n < 2; ++n) _Pragma("unroll") for (int k = 0; k < 2; ++k) dst[n][k] = *(const PG8_LAS bf16x8*)(lds + PG8_SB(b, h) + boff + n * 2048 + k * 1024); } while (0)
; #define PG8_MMA(ai, bj, At, Bt) do { __builtin_amdgcn_s_setprio(1); _Pragma("unroll") for (int m = 0; m < 4; ++m) _Pragma("unroll") for (int n = 0; n < 2; ++n) _Pragma("unroll") for (int k = 0; k < 2; ++k) \
;         acc[ai][bj][m][n] = __builtin_amdgcn_mfma_f32_16x16x32_bf16(Bt[n][k], At[m][k], acc[ai][bj][m][n], 0, 0, 0); __builtin_amdgcn_s_setprio(0); } while (0)
; #define PG8_WAIT_V(n) asm volatile("s_waitcnt vmcnt(" #n ")" ::: "memory")
; #define PG8_WAIT_L(n) asm volatile("s_waitcnt lgkmcnt(" #n ")" ::: "memory")
; #define PG8_BAR __builtin_amdgcn_s_barrier()
; #define PG8_SCHED __builtin_amdgcn_sched_barrier(0)
; template <class Epi, class Sched, bool ALIGN_EPI = false, bool SP2 = false>
; __device__ __forceinline__ void gemm_phase(PG8_LAS unsigned char* lds, const Gemm g, const Sched& S, const Epi& E) {
;     ...
;             PG8_WAIT_V(8); PG8_WAIT_L(0); PG8_BAR; PG8_MMA(1, 0, At, B0); PG8_MMA(1, 1, At, B1); PG8_BAR; PG8_SCHED;
;             PG8_LDB(B0, 1, 0); PG8_LDB(B1, 1, 1); PG8_SCHED; PG8_LDA(At, 1, 0); PG8_STAGE(PG8_SA(0, 1), a2 + hstep, voffA);
;             PG8_WAIT_V(8); PG8_WAIT_L(0); PG8_BAR; PG8_MMA(0, 0, At, B0); PG8_MMA(0, 1, At, B1); PG8_BAR; PG8_SCHED;
	v_mfma_f32_16x16x32_bf16 v[62:65], v[156:159], v[188:191], v[62:65]
	v_mfma_f32_16x16x32_bf16 v[58:61], v[164:167], v[188:191], v[58:61]
	v_mfma_f32_16x16x32_bf16 v[46:49], v[156:159], v[196:199], v[46:49]
	v_mfma_f32_16x16x32_bf16 v[42:45], v[164:167], v[196:199], v[42:45]
	v_mfma_f32_16x16x32_bf16 v[30:33], v[156:159], v[204:207], v[30:33]
	v_mfma_f32_16x16x32_bf16 v[26:29], v[164:167], v[204:207], v[26:29]
	v_mfma_f32_16x16x32_bf16 v[14:17], v[156:159], v[212:215], v[14:17]
	v_mfma_f32_16x16x32_bf16 v[10:13], v[164:167], v[212:215], v[10:13]
	v_mfma_f32_16x16x32_bf16 v[62:65], v[160:163], v[192:195], v[62:65]
	v_mfma_f32_16x16x32_bf16 v[58:61], v[168:171], v[192:195], v[58:61]
	v_mfma_f32_16x16x32_bf16 v[46:49], v[160:163], v[200:203], v[46:49]
	v_mfma_f32_16x16x32_bf16 v[42:45], v[168:171], v[200:203], v[42:45]
	v_mfma_f32_16x16x32_bf16 v[30:33], v[160:163], v[208:211], v[30:33]
	v_mfma_f32_16x16x32_bf16 v[26:29], v[168:171], v[208:211], v[26:29]
	v_mfma_f32_16x16x32_bf16 v[14:17], v[160:163], v[216:219], v[14:17]
	v_mfma_f32_16x16x32_bf16 v[10:13], v[168:171], v[216:219], v[10:13]
	v_mfma_f32_16x16x32_bf16 v[54:57], v[172:175], v[188:191], v[54:57]
	v_mfma_f32_16x16x32_bf16 v[50:53], v[180:183], v[188:191], v[50:53]
	v_mfma_f32_16x16x32_bf16 v[38:41], v[172:175], v[196:199], v[38:41]
	v_mfma_f32_16x16x32_bf16 v[34:37], v[180:183], v[196:199], v[34:37]
	v_mfma_f32_16x16x32_bf16 v[22:25], v[172:175], v[204:207], v[22:25]
	v_mfma_f32_16x16x32_bf16 v[18:21], v[180:183], v[204:207], v[18:21]
	v_mfma_f32_16x16x32_bf16 v[6:9], v[172:175], v[212:215], v[6:9]
	v_mfma_f32_16x16x32_bf16 v[2:5], v[180:183], v[212:215], v[2:5]
	v_mfma_f32_16x16x32_bf16 v[54:57], v[176:179], v[192:195], v[54:57]
	v_mfma_f32_16x16x32_bf16 v[50:53], v[184:187], v[192:195], v[50:53]
	v_mfma_f32_16x16x32_bf16 v[38:41], v[176:179], v[200:203], v[38:41]
	v_mfma_f32_16x16x32_bf16 v[34:37], v[184:187], v[200:203], v[34:37]
	v_mfma_f32_16x16x32_bf16 v[22:25], v[176:179], v[208:211], v[22:25]
	v_mfma_f32_16x16x32_bf16 v[18:21], v[184:187], v[208:211], v[18:21]
	v_mfma_f32_16x16x32_bf16 v[6:9], v[176:179], v[216:219], v[6:9]
	v_mfma_f32_16x16x32_bf16 v[2:5], v[184:187], v[216:219], v[2:5]
	s_barrier
	s_add_i32 s70, 0, 0x18000
	v_add_u32_e32 v148, s70, v150
	s_add_i32 s71, 0, 0x1c000
	ds_read_b128 v[156:159], v148
	ds_read_b128 v[160:163], v148 offset:1024
	ds_read_b128 v[164:167], v148 offset:2048
	ds_read_b128 v[168:171], v148 offset:3072
	v_add_u32_e32 v148, s71, v150
	ds_read_b128 v[172:175], v148
	ds_read_b128 v[176:179], v148 offset:1024
	ds_read_b128 v[180:183], v148 offset:2048
	ds_read_b128 v[184:187], v148 offset:3072
	s_add_u32 s30, s30, s6
	s_addc_u32 s31, s31, s7
	s_mov_b32 m0, s41
	v_lshl_add_u64 v[230:231], s[30:31], 0, v[130:131]
	ds_read_b128 v[188:191], v147 offset:32768
	ds_read_b128 v[192:195], v147 offset:33792
	ds_read_b128 v[196:199], v147 offset:34816
	ds_read_b128 v[200:203], v147 offset:35840
	ds_read_b128 v[204:207], v147 offset:36864
	ds_read_b128 v[208:211], v147 offset:37888
	ds_read_b128 v[212:215], v147 offset:38912
	ds_read_b128 v[216:219], v147 offset:39936
	global_load_lds_dwordx4 v[230:231], off
	v_lshl_add_u64 v[230:231], s[30:31], 0, v[134:135]
	s_mov_b32 m0, s42
	s_nop 0
	global_load_lds_dwordx4 v[230:231], off
	s_waitcnt vmcnt(8)
	s_waitcnt lgkmcnt(0)
	s_barrier
	v_mfma_f32_16x16x32_bf16 v[122:125], v[156:159], v[188:191], v[122:125]
	v_mfma_f32_16x16x32_bf16 v[126:129], v[164:167], v[188:191], v[126:129]
	v_mfma_f32_16x16x32_bf16 v[110:113], v[156:159], v[196:199], v[110:113]
	v_mfma_f32_16x16x32_bf16 v[106:109], v[164:167], v[196:199], v[106:109]
	v_mfma_f32_16x16x32_bf16 v[94:97], v[156:159], v[204:207], v[94:97]
	v_mfma_f32_16x16x32_bf16 v[90:93], v[164:167], v[204:207], v[90:93]
	v_mfma_f32_16x16x32_bf16 v[78:81], v[156:159], v[212:215], v[78:81]
	v_mfma_f32_16x16x32_bf16 v[74:77], v[164:167], v[212:215], v[74:77]
	v_mfma_f32_16x16x32_bf16 v[122:125], v[160:163], v[192:195], v[122:125]
	v_mfma_f32_16x16x32_bf16 v[126:129], v[168:171], v[192:195], v[126:129]
	v_mfma_f32_16x16x32_bf16 v[110:113], v[160:163], v[200:203], v[110:113]
	v_mfma_f32_16x16x32_bf16 v[106:109], v[168:171], v[200:203], v[106:109]
	v_mfma_f32_16x16x32_bf16 v[94:97], v[160:163], v[208:211], v[94:97]
	v_mfma_f32_16x16x32_bf16 v[90:93], v[168:171], v[208:211], v[90:93]
	v_mfma_f32_16x16x32_bf16 v[78:81], v[160:163], v[216:219], v[78:81]
	v_mfma_f32_16x16x32_bf16 v[74:77], v[168:171], v[216:219], v[74:77]
	v_mfma_f32_16x16x32_bf16 v[118:121], v[172:175], v[188:191], v[118:121]
	v_mfma_f32_16x16x32_bf16 v[114:117], v[180:183], v[188:191], v[114:117]
	v_mfma_f32_16x16x32_bf16 v[102:105], v[172:175], v[196:199], v[102:105]
	v_mfma_f32_16x16x32_bf16 v[98:101], v[180:183], v[196:199], v[98:101]
	v_mfma_f32_16x16x32_bf16 v[86:89], v[172:175], v[204:207], v[86:89]
	v_mfma_f32_16x16x32_bf16 v[82:85], v[180:183], v[204:207], v[82:85]
	v_mfma_f32_16x16x32_bf16 v[70:73], v[172:175], v[212:215], v[70:73]
	v_mfma_f32_16x16x32_bf16 v[66:69], v[180:183], v[212:215], v[66:69]
	v_mfma_f32_16x16x32_bf16 v[118:121], v[176:179], v[192:195], v[118:121]
	v_mfma_f32_16x16x32_bf16 v[114:117], v[184:187], v[192:195], v[114:117]
	v_mfma_f32_16x16x32_bf16 v[102:105], v[176:179], v[200:203], v[102:105]
	v_mfma_f32_16x16x32_bf16 v[98:101], v[184:187], v[200:203], v[98:101]
	v_mfma_f32_16x16x32_bf16 v[86:89], v[176:179], v[208:211], v[86:89]
	v_mfma_f32_16x16x32_bf16 v[82:85], v[184:187], v[208:211], v[82:85]
	v_mfma_f32_16x16x32_bf16 v[70:73], v[176:179], v[216:219], v[70:73]
	v_mfma_f32_16x16x32_bf16 v[66:69], v[184:187], v[216:219], v[66:69]
	s_barrier
; #define PG8_STAGE(bufoff, gbase, voff) do { _Pragma("unroll") for (int _i = 0; _i < 2; ++_i) \
;         __builtin_amdgcn_global_load_lds((const unsigned*)((const char*)(gbase) + (voff)[_i]), (PG8_LAS unsigned*)(lds + (bufoff) + ldsw + _i * 8192), 16, 0, 0); } while (0)
; #define PG8_LDA(dst, b, h) do { _Pragma("unroll") for (int m = 0; m < 4; ++m) _Pragma("unroll") for (int k = 0; k < 2; ++k) dst[m][k] = *(const PG8_LAS bf16x8*)(lds + PG8_SA(b, h) + aoff + m * 2048 + k * 1024); } while (0)
; #define PG8_MMA(ai, bj, At, Bt) do { __builtin_amdgcn_s_setprio(1); _Pragma("unroll") for (int m = 0; m < 4; ++m) _Pragma("unroll") for (int n = 0; n < 2; ++n) _Pragma("unroll") for (int k = 0; k < 2; ++k) \
;         acc[ai][bj][m][n] = __builtin_amdgcn_mfma_f32_16x16x32_bf16(Bt[n][k], At[m][k], acc[ai][bj][m][n], 0, 0, 0); __builtin_amdgcn_s_setprio(0); } while (0)
; #define PG8_WAIT_V(n) asm volatile("s_waitcnt vmcnt(" #n ")" ::: "memory")
; #define PG8_WAIT_L(n) asm volatile("s_waitcnt lgkmcnt(" #n ")" ::: "memory")
; #define PG8_BAR __builtin_amdgcn_s_barrier()
; #define PG8_SCHED __builtin_amdgcn_sched_barrier(0)
; template <class Epi, class Sched, bool ALIGN_EPI = false, bool SP2 = false>
; __device__ __forceinline__ void gemm_phase(PG8_LAS unsigned char* lds, const Gemm g, const Sched& S, const Epi& E) {
;     ...
;         for (int t = 0; t < nt; t += 2) {
;             const bool last = (t == nt - 2);
;             const char* a1 = cA + (size_t)(t + 1) * kstep;
;             const char* a2 = last ? nA : cA + (size_t)(t + 2) * kstep; const char* b2 = last ? nB : cB + (size_t)(t + 2) * kstep;
;             const char* a3 = a2 + kstep; const char* b3 = b2 + kstep;
;     ...
;             PG8_LDA(At, 1, 1); PG8_STAGE(PG8_SB(1, 0), b3, voffB); PG8_STAGE(PG8_SB(1, 1), b3 + hstep, voffB); PG8_STAGE(PG8_SA(1, 0), a3, voffA);
;             PG8_WAIT_V(8); PG8_WAIT_L(0); PG8_BAR; PG8_MMA(1, 0, At, B0); PG8_MMA(1, 1, At, B1); PG8_BAR; PG8_SCHED;
	s_add_i32 s30, s70, s38
	v_lshl_add_u64 v[152:153], v[152:153], 0, s[20:21]
	s_mov_b32 m0, s30
	ds_read_b128 v[188:191], v147 offset:49152
	ds_read_b128 v[192:195], v147 offset:50176
	ds_read_b128 v[196:199], v147 offset:51200
	ds_read_b128 v[200:203], v147 offset:52224
	ds_read_b128 v[204:207], v147 offset:53248
	ds_read_b128 v[208:211], v147 offset:54272
	ds_read_b128 v[212:215], v147 offset:55296
	ds_read_b128 v[216:219], v147 offset:56320
	global_load_lds_dwordx4 v[152:153], off
	v_lshl_add_u64 v[152:153], v[220:221], 0, s[20:21]
	s_add_i32 m0, s30, 0x2000
	s_add_i32 s30, s71, s38
	global_load_lds_dwordx4 v[152:153], off
	v_lshl_add_u64 v[152:153], v[222:223], 0, s[20:21]
	s_mov_b32 m0, s30
	s_nop 0
	global_load_lds_dwordx4 v[152:153], off
	v_lshl_add_u64 v[152:153], v[224:225], 0, s[20:21]
	s_add_i32 m0, s30, 0x2000
	s_nop 0
	global_load_lds_dwordx4 v[152:153], off
	v_lshl_add_u64 v[152:153], v[226:227], 0, s[20:21]
	s_mov_b32 m0, s44
	s_nop 0
	global_load_lds_dwordx4 v[152:153], off
	v_lshl_add_u64 v[152:153], v[228:229], 0, s[20:21]
	s_mov_b32 m0, s45
	s_nop 0
	global_load_lds_dwordx4 v[152:153], off
	s_waitcnt vmcnt(8)
	s_waitcnt lgkmcnt(0)
	s_barrier
	v_mfma_f32_16x16x32_bf16 v[62:65], v[156:159], v[188:191], v[62:65]
	v_mfma_f32_16x16x32_bf16 v[58:61], v[164:167], v[188:191], v[58:61]
	v_mfma_f32_16x16x32_bf16 v[46:49], v[156:159], v[196:199], v[46:49]
	v_mfma_f32_16x16x32_bf16 v[42:45], v[164:167], v[196:199], v[42:45]
	v_mfma_f32_16x16x32_bf16 v[30:33], v[156:159], v[204:207], v[30:33]
	v_mfma_f32_16x16x32_bf16 v[26:29], v[164:167], v[204:207], v[26:29]
	v_mfma_f32_16x16x32_bf16 v[14:17], v[156:159], v[212:215], v[14:17]
	v_mfma_f32_16x16x32_bf16 v[10:13], v[164:167], v[212:215], v[10:13]
	v_mfma_f32_16x16x32_bf16 v[62:65], v[160:163], v[192:195], v[62:65]
	v_mfma_f32_16x16x32_bf16 v[58:61], v[168:171], v[192:195], v[58:61]
	v_mfma_f32_16x16x32_bf16 v[46:49], v[160:163], v[200:203], v[46:49]
	v_mfma_f32_16x16x32_bf16 v[42:45], v[168:171], v[200:203], v[42:45]
	v_mfma_f32_16x16x32_bf16 v[30:33], v[160:163], v[208:211], v[30:33]
	v_mfma_f32_16x16x32_bf16 v[26:29], v[168:171], v[208:211], v[26:29]
	v_mfma_f32_16x16x32_bf16 v[14:17], v[160:163], v[216:219], v[14:17]
	v_mfma_f32_16x16x32_bf16 v[10:13], v[168:171], v[216:219], v[10:13]
	v_mfma_f32_16x16x32_bf16 v[54:57], v[172:175], v[188:191], v[54:57]
	v_mfma_f32_16x16x32_bf16 v[50:53], v[180:183], v[188:191], v[50:53]
	v_mfma_f32_16x16x32_bf16 v[38:41], v[172:175], v[196:199], v[38:41]
	v_mfma_f32_16x16x32_bf16 v[34:37], v[180:183], v[196:199], v[34:37]
	v_mfma_f32_16x16x32_bf16 v[22:25], v[172:175], v[204:207], v[22:25]
	v_mfma_f32_16x16x32_bf16 v[18:21], v[180:183], v[204:207], v[18:21]
	v_mfma_f32_16x16x32_bf16 v[6:9], v[172:175], v[212:215], v[6:9]
	v_mfma_f32_16x16x32_bf16 v[2:5], v[180:183], v[212:215], v[2:5]
	v_mfma_f32_16x16x32_bf16 v[54:57], v[176:179], v[192:195], v[54:57]
	v_mfma_f32_16x16x32_bf16 v[50:53], v[184:187], v[192:195], v[50:53]
	v_mfma_f32_16x16x32_bf16 v[38:41], v[176:179], v[200:203], v[38:41]
	v_mfma_f32_16x16x32_bf16 v[34:37], v[184:187], v[200:203], v[34:37]
	v_mfma_f32_16x16x32_bf16 v[22:25], v[176:179], v[208:211], v[22:25]
	v_mfma_f32_16x16x32_bf16 v[18:21], v[184:187], v[208:211], v[18:21]
	v_mfma_f32_16x16x32_bf16 v[6:9], v[176:179], v[216:219], v[6:9]
	v_mfma_f32_16x16x32_bf16 v[2:5], v[184:187], v[216:219], v[2:5]
	s_barrier
	s_add_u32 s68, s68, 0x100
	s_addc_u32 s69, s69, 0
	s_add_u32 s28, s28, 0x100
	s_addc_u32 s29, s29, 0
	s_cmp_ge_i32 s80, s46
	s_mov_b32 s30, s80
	s_cbranch_scc0 .LBB0_1433

; #define PG8_STAGE(bufoff, gbase, voff) do { _Pragma("unroll") for (int _i = 0; _i < 2; ++_i) \
;         __builtin_amdgcn_global_load_lds((const unsigned*)((const char*)(gbase) + (voff)[_i]), (PG8_LAS unsigned*)(lds + (bufoff) + ldsw + _i * 8192), 16, 0, 0); } while (0)
; #define PG8_LDA(dst, b, h) do { _Pragma("unroll") for (int m = 0; m < 4; ++m) _Pragma("unroll") for (int k = 0; k < 2; ++k) dst[m][k] = *(const PG8_LAS bf16x8*)(lds + PG8_SA(b, h) + aoff + m * 2048 + k * 1024); } while (0)
; #define PG8_LDB(dst, b, h) do { _Pragma("unroll") for (int n = 0; n < 2; ++n) _Pragma("unroll") for (int k = 0; k < 2; ++k) dst[n][k] = *(const PG8_LAS bf16x8*)(lds + PG8_SB(b, h) + boff + n * 2048 + k * 1024); } while (0)
; #define PG8_MMA(ai, bj, At, Bt) do { __builtin_amdgcn_s_setprio(1); _Pragma("unroll") for (int m = 0; m < 4; ++m) _Pragma("unroll") for (int n = 0; n < 2; ++n) _Pragma("unroll") for (int k = 0; k < 2; ++k) \
;         acc[ai][bj][m][n] = __builtin_amdgcn_mfma_f32_16x16x32_bf16(Bt[n][k], At[m][k], acc[ai][bj][m][n], 0, 0, 0); __builtin_amdgcn_s_setprio(0); } while (0)
; #define PG8_WAIT_V(n) asm volatile("s_waitcnt vmcnt(" #n ")" ::: "memory")
; #define PG8_BAR __builtin_amdgcn_s_barrier()
; template <class Epi, class Sched, bool ALIGN_EPI = false, bool SP2 = false>
; __device__ __forceinline__ void gemm_phase(PG8_LAS unsigned char* lds, const Gemm g, const Sched& S, const Epi& E) {
;     ...
;         for (int t = 0; t < nt; t += 2) {
;             const bool last = (t == nt - 2);
;             const char* a1 = cA + (size_t)(t + 1) * kstep;
;             const char* a2 = last ? nA : cA + (size_t)(t + 2) * kstep; const char* b2 = last ? nB : cB + (size_t)(t + 2) * kstep;
;             const char* a3 = a2 + kstep; const char* b3 = b2 + kstep;
;             if (last && has_next) S.a_ready(nxt);
;             if constexpr (SP2) {
;             PG8_LDB(B0, 0, 0); PG8_LDB(B1, 0, 1); PG8_SCHED; PG8_LDA(At, 0, 0); PG8_STAGE(PG8_SA(1, 1), a1 + hstep, voffA);
;             PG8_WAIT_V(8); PG8_WAIT_L(0); PG8_BAR; PG8_MMA(0, 0, At, B0); PG8_MMA(0, 1, At, B1); PG8_BAR; PG8_SCHED;
;             PG8_LDA(At, 0, 1); PG8_STAGE(PG8_SB(0, 0), b2, voffB); PG8_STAGE(PG8_SB(0, 1), b2 + hstep, voffB); PG8_STAGE(PG8_SA(0, 0), a2, voffA);
;             PG8_WAIT_V(8); PG8_WAIT_L(0); PG8_BAR; PG8_MMA(1, 0, At, B0); PG8_MMA(1, 1, At, B1); PG8_BAR; PG8_SCHED;
.LBB0_1518:
	ds_read_b128 v[146:149], v168
	ds_read_b128 v[172:175], v168 offset:1024
	ds_read_b128 v[176:179], v168 offset:2048
	ds_read_b128 v[180:183], v168 offset:3072
	ds_read_b128 v[184:187], v169
	ds_read_b128 v[188:191], v169 offset:1024
	ds_read_b128 v[192:195], v169 offset:2048
	ds_read_b128 v[196:199], v169 offset:3072
	s_add_i32 s88, s38, 2
	s_add_u32 s70, s36, 0x80
	s_addc_u32 s39, s37, 0
	s_cmp_eq_u32 s53, s38
	s_cselect_b32 s38, s4, s70
	s_cselect_b32 s39, s5, s39
	s_cselect_b32 s71, s35, s87
	s_cselect_b32 s70, s34, s86
	v_lshl_add_u64 v[150:151], s[36:37], 0, v[140:141]
	s_add_i32 m0, s43, 0xc000
	ds_read_b128 v[200:203], v170
	ds_read_b128 v[204:207], v170 offset:1024
	ds_read_b128 v[208:211], v170 offset:2048
	ds_read_b128 v[212:215], v170 offset:3072
	ds_read_b128 v[216:219], v170 offset:4096
	ds_read_b128 v[220:223], v170 offset:5120
	ds_read_b128 v[224:227], v170 offset:6144
	ds_read_b128 v[228:231], v170 offset:7168
	global_load_lds_dwordx4 v[150:151], off
	v_lshl_add_u64 v[150:151], s[36:37], 0, v[138:139]
	s_add_i32 m0, s43, 0xe000
	s_nop 0
	global_load_lds_dwordx4 v[150:151], off
	s_waitcnt vmcnt(8)
	s_waitcnt lgkmcnt(0)
	s_barrier
	v_mfma_f32_16x16x32_bf16 v[122:125], v[146:149], v[200:203], v[122:125]
	v_mfma_f32_16x16x32_bf16 v[126:129], v[176:179], v[200:203], v[126:129]
	v_mfma_f32_16x16x32_bf16 v[110:113], v[146:149], v[208:211], v[110:113]
	v_mfma_f32_16x16x32_bf16 v[106:109], v[176:179], v[208:211], v[106:109]
	v_mfma_f32_16x16x32_bf16 v[94:97], v[146:149], v[216:219], v[94:97]
	v_mfma_f32_16x16x32_bf16 v[90:93], v[176:179], v[216:219], v[90:93]
	v_mfma_f32_16x16x32_bf16 v[78:81], v[146:149], v[224:227], v[78:81]
	v_mfma_f32_16x16x32_bf16 v[74:77], v[176:179], v[224:227], v[74:77]
	v_mfma_f32_16x16x32_bf16 v[122:125], v[172:175], v[204:207], v[122:125]
	v_mfma_f32_16x16x32_bf16 v[126:129], v[180:183], v[204:207], v[126:129]
	v_mfma_f32_16x16x32_bf16 v[110:113], v[172:175], v[212:215], v[110:113]
	v_mfma_f32_16x16x32_bf16 v[106:109], v[180:183], v[212:215], v[106:109]
	v_mfma_f32_16x16x32_bf16 v[94:97], v[172:175], v[220:223], v[94:97]
	v_mfma_f32_16x16x32_bf16 v[90:93], v[180:183], v[220:223], v[90:93]
	v_mfma_f32_16x16x32_bf16 v[78:81], v[172:175], v[228:231], v[78:81]
	v_mfma_f32_16x16x32_bf16 v[74:77], v[180:183], v[228:231], v[74:77]
	v_mfma_f32_16x16x32_bf16 v[118:121], v[184:187], v[200:203], v[118:121]
	v_mfma_f32_16x16x32_bf16 v[114:117], v[192:195], v[200:203], v[114:117]
	v_mfma_f32_16x16x32_bf16 v[102:105], v[184:187], v[208:211], v[102:105]
	v_mfma_f32_16x16x32_bf16 v[98:101], v[192:195], v[208:211], v[98:101]
	v_mfma_f32_16x16x32_bf16 v[86:89], v[184:187], v[216:219], v[86:89]
	v_mfma_f32_16x16x32_bf16 v[82:85], v[192:195], v[216:219], v[82:85]
	v_mfma_f32_16x16x32_bf16 v[70:73], v[184:187], v[224:227], v[70:73]
	v_mfma_f32_16x16x32_bf16 v[66:69], v[192:195], v[224:227], v[66:69]
	v_mfma_f32_16x16x32_bf16 v[118:121], v[188:191], v[204:207], v[118:121]
	v_mfma_f32_16x16x32_bf16 v[114:117], v[196:199], v[204:207], v[114:117]
	v_mfma_f32_16x16x32_bf16 v[102:105], v[188:191], v[212:215], v[102:105]
	v_mfma_f32_16x16x32_bf16 v[98:101], v[196:199], v[212:215], v[98:101]
	v_mfma_f32_16x16x32_bf16 v[86:89], v[188:191], v[220:223], v[86:89]
	v_mfma_f32_16x16x32_bf16 v[82:85], v[196:199], v[220:223], v[82:85]
	v_mfma_f32_16x16x32_bf16 v[70:73], v[188:191], v[228:231], v[70:73]
	v_mfma_f32_16x16x32_bf16 v[66:69], v[196:199], v[228:231], v[66:69]
	s_barrier
	s_add_i32 s72, s56, s42
	v_lshl_add_u64 v[150:151], s[70:71], 0, v[132:133]
	s_mov_b32 m0, s72
	ds_read_b128 v[200:203], v170 offset:16384
	ds_read_b128 v[204:207], v170 offset:17408
	ds_read_b128 v[208:211], v170 offset:18432
	ds_read_b128 v[212:215], v170 offset:19456
	ds_read_b128 v[216:219], v170 offset:20480
	ds_read_b128 v[220:223], v170 offset:21504
	ds_read_b128 v[224:227], v170 offset:22528
	ds_read_b128 v[228:231], v170 offset:23552
	global_load_lds_dwordx4 v[150:151], off
	s_add_i32 m0, s72, 0x2000
	v_lshl_add_u64 v[232:233], s[70:71], 0, v[136:137]
	s_add_u32 s70, s70, s14
	s_addc_u32 s71, s71, s15
	s_add_i32 s72, s57, s42
	global_load_lds_dwordx4 v[232:233], off
	v_lshl_add_u64 v[234:235], s[70:71], 0, v[132:133]
	s_mov_b32 m0, s72
	v_lshl_add_u64 v[236:237], s[70:71], 0, v[136:137]
	global_load_lds_dwordx4 v[234:235], off
	s_add_i32 m0, s72, 0x2000
	v_lshl_add_u64 v[238:239], s[38:39], 0, v[130:131]
	global_load_lds_dwordx4 v[236:237], off
	s_mov_b32 m0, s43
	v_lshl_add_u64 v[240:241], s[38:39], 0, v[134:135]
	global_load_lds_dwordx4 v[238:239], off
	s_mov_b32 m0, s44
	s_nop 0
	global_load_lds_dwordx4 v[240:241], off
	s_waitcnt vmcnt(8)
	s_waitcnt lgkmcnt(0)
	s_barrier
; #define PG8_STAGE(bufoff, gbase, voff) do { _Pragma("unroll") for (int _i = 0; _i < 2; ++_i) \
;         __builtin_amdgcn_global_load_lds((const unsigned*)((const char*)(gbase) + (voff)[_i]), (PG8_LAS unsigned*)(lds + (bufoff) + ldsw + _i * 8192), 16, 0, 0); } while (0)
; #define PG8_LDA(dst, b, h) do { _Pragma("unroll") for (int m = 0; m < 4; ++m) _Pragma("unroll") for (int k = 0; k < 2; ++k) dst[m][k] = *(const PG8_LAS bf16x8*)(lds + PG8_SA(b, h) + aoff + m * 2048 + k * 1024); } while (0)
; #define PG8_LDB(dst, b, h) do { _Pragma("unroll") for (int n = 0; n < 2; ++n) _Pragma("unroll") for (int k = 0; k < 2; ++k) dst[n][k] = *(const PG8_LAS bf16x8*)(lds + PG8_SB(b, h) + boff + n * 2048 + k * 1024); } while (0)
; #define PG8_MMA(ai, bj, At, Bt) do { __builtin_amdgcn_s_setprio(1); _Pragma("unroll") for (int m = 0; m < 4; ++m) _Pragma("unroll") for (int n = 0; n < 2; ++n) _Pragma("unroll") for (int k = 0; k < 2; ++k) \
;         acc[ai][bj][m][n] = __builtin_amdgcn_mfma_f32_16x16x32_bf16(Bt[n][k], At[m][k], acc[ai][bj][m][n], 0, 0, 0); __builtin_amdgcn_s_setprio(0); } while (0)
; #define PG8_WAIT_V(n) asm volatile("s_waitcnt vmcnt(" #n ")" ::: "memory")
; #define PG8_WAIT_L(n) asm volatile("s_waitcnt lgkmcnt(" #n ")" ::: "memory")
; #define PG8_BAR __builtin_amdgcn_s_barrier()
; #define PG8_SCHED __builtin_amdgcn_sched_barrier(0)
; template <class Epi, class Sched, bool ALIGN_EPI = false, bool SP2 = false>
; __device__ __forceinline__ void gemm_phase(PG8_LAS unsigned char* lds, const Gemm g, const Sched& S, const Epi& E) {
;     ...
;             PG8_WAIT_V(8); PG8_WAIT_L(0); PG8_BAR; PG8_MMA(1, 0, At, B0); PG8_MMA(1, 1, At, B1); PG8_BAR; PG8_SCHED;
;             PG8_LDB(B0, 1, 0); PG8_LDB(B1, 1, 1); PG8_SCHED; PG8_LDA(At, 1, 0); PG8_STAGE(PG8_SA(0, 1), a2 + hstep, voffA);
;             PG8_WAIT_V(8); PG8_WAIT_L(0); PG8_BAR; PG8_MMA(0, 0, At, B0); PG8_MMA(0, 1, At, B1); PG8_BAR; PG8_SCHED;
	v_mfma_f32_16x16x32_bf16 v[62:65], v[146:149], v[200:203], v[62:65]
	v_mfma_f32_16x16x32_bf16 v[58:61], v[176:179], v[200:203], v[58:61]
	v_mfma_f32_16x16x32_bf16 v[46:49], v[146:149], v[208:211], v[46:49]
	v_mfma_f32_16x16x32_bf16 v[42:45], v[176:179], v[208:211], v[42:45]
	v_mfma_f32_16x16x32_bf16 v[30:33], v[146:149], v[216:219], v[30:33]
	v_mfma_f32_16x16x32_bf16 v[26:29], v[176:179], v[216:219], v[26:29]
	v_mfma_f32_16x16x32_bf16 v[14:17], v[146:149], v[224:227], v[14:17]
	v_mfma_f32_16x16x32_bf16 v[10:13], v[176:179], v[224:227], v[10:13]
	v_mfma_f32_16x16x32_bf16 v[62:65], v[172:175], v[204:207], v[62:65]
	v_mfma_f32_16x16x32_bf16 v[58:61], v[180:183], v[204:207], v[58:61]
	v_mfma_f32_16x16x32_bf16 v[46:49], v[172:175], v[212:215], v[46:49]
	v_mfma_f32_16x16x32_bf16 v[42:45], v[180:183], v[212:215], v[42:45]
	v_mfma_f32_16x16x32_bf16 v[30:33], v[172:175], v[220:223], v[30:33]
	v_mfma_f32_16x16x32_bf16 v[26:29], v[180:183], v[220:223], v[26:29]
	v_mfma_f32_16x16x32_bf16 v[14:17], v[172:175], v[228:231], v[14:17]
	v_mfma_f32_16x16x32_bf16 v[10:13], v[180:183], v[228:231], v[10:13]
	v_mfma_f32_16x16x32_bf16 v[54:57], v[184:187], v[200:203], v[54:57]
	v_mfma_f32_16x16x32_bf16 v[50:53], v[192:195], v[200:203], v[50:53]
	v_mfma_f32_16x16x32_bf16 v[38:41], v[184:187], v[208:211], v[38:41]
	v_mfma_f32_16x16x32_bf16 v[34:37], v[192:195], v[208:211], v[34:37]
	v_mfma_f32_16x16x32_bf16 v[22:25], v[184:187], v[216:219], v[22:25]
	v_mfma_f32_16x16x32_bf16 v[18:21], v[192:195], v[216:219], v[18:21]
	v_mfma_f32_16x16x32_bf16 v[6:9], v[184:187], v[224:227], v[6:9]
	v_mfma_f32_16x16x32_bf16 v[2:5], v[192:195], v[224:227], v[2:5]
	v_mfma_f32_16x16x32_bf16 v[54:57], v[188:191], v[204:207], v[54:57]
	v_mfma_f32_16x16x32_bf16 v[50:53], v[196:199], v[204:207], v[50:53]
	v_mfma_f32_16x16x32_bf16 v[38:41], v[188:191], v[212:215], v[38:41]
	v_mfma_f32_16x16x32_bf16 v[34:37], v[196:199], v[212:215], v[34:37]
	v_mfma_f32_16x16x32_bf16 v[22:25], v[188:191], v[220:223], v[22:25]
	v_mfma_f32_16x16x32_bf16 v[18:21], v[196:199], v[220:223], v[18:21]
	v_mfma_f32_16x16x32_bf16 v[6:9], v[188:191], v[228:231], v[6:9]
	v_mfma_f32_16x16x32_bf16 v[2:5], v[196:199], v[228:231], v[2:5]
	s_barrier
	s_add_i32 s70, 0, 0x18000
	v_add_u32_e32 v171, s70, v166
	s_add_i32 s71, 0, 0x1c000
	ds_read_b128 v[146:149], v171
	ds_read_b128 v[172:175], v171 offset:1024
	ds_read_b128 v[176:179], v171 offset:2048
	ds_read_b128 v[180:183], v171 offset:3072
	v_add_u32_e32 v171, s71, v166
	ds_read_b128 v[184:187], v171
	ds_read_b128 v[188:191], v171 offset:1024
	ds_read_b128 v[192:195], v171 offset:2048
	ds_read_b128 v[196:199], v171 offset:3072
	s_add_u32 s38, s38, s14
	s_addc_u32 s39, s39, s15
	s_mov_b32 m0, s45
	v_lshl_add_u64 v[242:243], s[38:39], 0, v[130:131]
	ds_read_b128 v[200:203], v170 offset:32768
	ds_read_b128 v[204:207], v170 offset:33792
	ds_read_b128 v[208:211], v170 offset:34816
	ds_read_b128 v[212:215], v170 offset:35840
	ds_read_b128 v[216:219], v170 offset:36864
	ds_read_b128 v[220:223], v170 offset:37888
	ds_read_b128 v[224:227], v170 offset:38912
	ds_read_b128 v[228:231], v170 offset:39936
	global_load_lds_dwordx4 v[242:243], off
	v_lshl_add_u64 v[242:243], s[38:39], 0, v[134:135]
	s_mov_b32 m0, s46
	s_nop 0
	global_load_lds_dwordx4 v[242:243], off
	s_waitcnt vmcnt(8)
	s_waitcnt lgkmcnt(0)
	s_barrier
	v_mfma_f32_16x16x32_bf16 v[122:125], v[146:149], v[200:203], v[122:125]
	v_mfma_f32_16x16x32_bf16 v[126:129], v[176:179], v[200:203], v[126:129]
	v_mfma_f32_16x16x32_bf16 v[110:113], v[146:149], v[208:211], v[110:113]
	v_mfma_f32_16x16x32_bf16 v[106:109], v[176:179], v[208:211], v[106:109]
	v_mfma_f32_16x16x32_bf16 v[94:97], v[146:149], v[216:219], v[94:97]
	v_mfma_f32_16x16x32_bf16 v[90:93], v[176:179], v[216:219], v[90:93]
	v_mfma_f32_16x16x32_bf16 v[78:81], v[146:149], v[224:227], v[78:81]
	v_mfma_f32_16x16x32_bf16 v[74:77], v[176:179], v[224:227], v[74:77]
	v_mfma_f32_16x16x32_bf16 v[122:125], v[172:175], v[204:207], v[122:125]
	v_mfma_f32_16x16x32_bf16 v[126:129], v[180:183], v[204:207], v[126:129]
	v_mfma_f32_16x16x32_bf16 v[110:113], v[172:175], v[212:215], v[110:113]
	v_mfma_f32_16x16x32_bf16 v[106:109], v[180:183], v[212:215], v[106:109]
	v_mfma_f32_16x16x32_bf16 v[94:97], v[172:175], v[220:223], v[94:97]
	v_mfma_f32_16x16x32_bf16 v[90:93], v[180:183], v[220:223], v[90:93]
	v_mfma_f32_16x16x32_bf16 v[78:81], v[172:175], v[228:231], v[78:81]
	v_mfma_f32_16x16x32_bf16 v[74:77], v[180:183], v[228:231], v[74:77]
	v_mfma_f32_16x16x32_bf16 v[118:121], v[184:187], v[200:203], v[118:121]
	v_mfma_f32_16x16x32_bf16 v[114:117], v[192:195], v[200:203], v[114:117]
	v_mfma_f32_16x16x32_bf16 v[102:105], v[184:187], v[208:211], v[102:105]
	v_mfma_f32_16x16x32_bf16 v[98:101], v[192:195], v[208:211], v[98:101]
	v_mfma_f32_16x16x32_bf16 v[86:89], v[184:187], v[216:219], v[86:89]
	v_mfma_f32_16x16x32_bf16 v[82:85], v[192:195], v[216:219], v[82:85]
	v_mfma_f32_16x16x32_bf16 v[70:73], v[184:187], v[224:227], v[70:73]
	v_mfma_f32_16x16x32_bf16 v[66:69], v[192:195], v[224:227], v[66:69]
	v_mfma_f32_16x16x32_bf16 v[118:121], v[188:191], v[204:207], v[118:121]
	v_mfma_f32_16x16x32_bf16 v[114:117], v[196:199], v[204:207], v[114:117]
	v_mfma_f32_16x16x32_bf16 v[102:105], v[188:191], v[212:215], v[102:105]
	v_mfma_f32_16x16x32_bf16 v[98:101], v[196:199], v[212:215], v[98:101]
	v_mfma_f32_16x16x32_bf16 v[86:89], v[188:191], v[220:223], v[86:89]
	v_mfma_f32_16x16x32_bf16 v[82:85], v[196:199], v[220:223], v[82:85]
	v_mfma_f32_16x16x32_bf16 v[70:73], v[188:191], v[228:231], v[70:73]
	v_mfma_f32_16x16x32_bf16 v[66:69], v[196:199], v[228:231], v[66:69]
	s_barrier
; #define PG8_STAGE(bufoff, gbase, voff) do { _Pragma("unroll") for (int _i = 0; _i < 2; ++_i) \
;         __builtin_amdgcn_global_load_lds((const unsigned*)((const char*)(gbase) + (voff)[_i]), (PG8_LAS unsigned*)(lds + (bufoff) + ldsw + _i * 8192), 16, 0, 0); } while (0)
; #define PG8_LDA(dst, b, h) do { _Pragma("unroll") for (int m = 0; m < 4; ++m) _Pragma("unroll") for (int k = 0; k < 2; ++k) dst[m][k] = *(const PG8_LAS bf16x8*)(lds + PG8_SA(b, h) + aoff + m * 2048 + k * 1024); } while (0)
; #define PG8_MMA(ai, bj, At, Bt) do { __builtin_amdgcn_s_setprio(1); _Pragma("unroll") for (int m = 0; m < 4; ++m) _Pragma("unroll") for (int n = 0; n < 2; ++n) _Pragma("unroll") for (int k = 0; k < 2; ++k) \
;         acc[ai][bj][m][n] = __builtin_amdgcn_mfma_f32_16x16x32_bf16(Bt[n][k], At[m][k], acc[ai][bj][m][n], 0, 0, 0); __builtin_amdgcn_s_setprio(0); } while (0)
; #define PG8_WAIT_V(n) asm volatile("s_waitcnt vmcnt(" #n ")" ::: "memory")
; #define PG8_WAIT_L(n) asm volatile("s_waitcnt lgkmcnt(" #n ")" ::: "memory")
; #define PG8_BAR __builtin_amdgcn_s_barrier()
; #define PG8_SCHED __builtin_amdgcn_sched_barrier(0)
; template <class Epi, class Sched, bool ALIGN_EPI = false, bool SP2 = false>
; __device__ __forceinline__ void gemm_phase(PG8_LAS unsigned char* lds, const Gemm g, const Sched& S, const Epi& E) {
;     ...
;         for (int t = 0; t < nt; t += 2) {
;             const bool last = (t == nt - 2);
;             const char* a1 = cA + (size_t)(t + 1) * kstep;
;             const char* a2 = last ? nA : cA + (size_t)(t + 2) * kstep; const char* b2 = last ? nB : cB + (size_t)(t + 2) * kstep;
;             const char* a3 = a2 + kstep; const char* b3 = b2 + kstep;
;     ...
;             PG8_LDA(At, 1, 1); PG8_STAGE(PG8_SB(1, 0), b3, voffB); PG8_STAGE(PG8_SB(1, 1), b3 + hstep, voffB); PG8_STAGE(PG8_SA(1, 0), a3, voffA);
;             PG8_WAIT_V(8); PG8_WAIT_L(0); PG8_BAR; PG8_MMA(1, 0, At, B0); PG8_MMA(1, 1, At, B1); PG8_BAR; PG8_SCHED;
;     ...
;         if constexpr (!Epi::AFTER_DRAIN) { E(acc, cur, wr, wc, fr, fq); S.done(cur); }
	s_add_i32 s38, s70, s42
	v_lshl_add_u64 v[150:151], v[150:151], 0, s[24:25]
	s_mov_b32 m0, s38
	ds_read_b128 v[200:203], v170 offset:49152
	ds_read_b128 v[204:207], v170 offset:50176
	ds_read_b128 v[208:211], v170 offset:51200
	ds_read_b128 v[212:215], v170 offset:52224
	ds_read_b128 v[216:219], v170 offset:53248
	ds_read_b128 v[220:223], v170 offset:54272
	ds_read_b128 v[224:227], v170 offset:55296
	ds_read_b128 v[228:231], v170 offset:56320
	global_load_lds_dwordx4 v[150:151], off
	v_lshl_add_u64 v[150:151], v[232:233], 0, s[24:25]
	s_add_i32 m0, s38, 0x2000
	s_add_i32 s38, s71, s42
	global_load_lds_dwordx4 v[150:151], off
	v_lshl_add_u64 v[150:151], v[234:235], 0, s[24:25]
	s_mov_b32 m0, s38
	s_nop 0
	global_load_lds_dwordx4 v[150:151], off
	v_lshl_add_u64 v[150:151], v[236:237], 0, s[24:25]
	s_add_i32 m0, s38, 0x2000
	s_nop 0
	global_load_lds_dwordx4 v[150:151], off
	v_lshl_add_u64 v[150:151], v[238:239], 0, s[24:25]
	s_mov_b32 m0, s48
	s_nop 0
	global_load_lds_dwordx4 v[150:151], off
	v_lshl_add_u64 v[150:151], v[240:241], 0, s[24:25]
	s_mov_b32 m0, s49
	s_nop 0
	global_load_lds_dwordx4 v[150:151], off
	s_waitcnt vmcnt(8)
	s_waitcnt lgkmcnt(0)
	s_barrier
	v_mfma_f32_16x16x32_bf16 v[62:65], v[146:149], v[200:203], v[62:65]
	v_mfma_f32_16x16x32_bf16 v[58:61], v[176:179], v[200:203], v[58:61]
	v_mfma_f32_16x16x32_bf16 v[46:49], v[146:149], v[208:211], v[46:49]
	v_mfma_f32_16x16x32_bf16 v[42:45], v[176:179], v[208:211], v[42:45]
	v_mfma_f32_16x16x32_bf16 v[30:33], v[146:149], v[216:219], v[30:33]
	v_mfma_f32_16x16x32_bf16 v[26:29], v[176:179], v[216:219], v[26:29]
	v_mfma_f32_16x16x32_bf16 v[14:17], v[146:149], v[224:227], v[14:17]
	v_mfma_f32_16x16x32_bf16 v[10:13], v[176:179], v[224:227], v[10:13]
	v_mfma_f32_16x16x32_bf16 v[62:65], v[172:175], v[204:207], v[62:65]
	v_mfma_f32_16x16x32_bf16 v[58:61], v[180:183], v[204:207], v[58:61]
	v_mfma_f32_16x16x32_bf16 v[46:49], v[172:175], v[212:215], v[46:49]
	v_mfma_f32_16x16x32_bf16 v[42:45], v[180:183], v[212:215], v[42:45]
	v_mfma_f32_16x16x32_bf16 v[30:33], v[172:175], v[220:223], v[30:33]
	v_mfma_f32_16x16x32_bf16 v[26:29], v[180:183], v[220:223], v[26:29]
	v_mfma_f32_16x16x32_bf16 v[14:17], v[172:175], v[228:231], v[14:17]
	v_mfma_f32_16x16x32_bf16 v[10:13], v[180:183], v[228:231], v[10:13]
	v_mfma_f32_16x16x32_bf16 v[54:57], v[184:187], v[200:203], v[54:57]
	v_mfma_f32_16x16x32_bf16 v[50:53], v[192:195], v[200:203], v[50:53]
	v_mfma_f32_16x16x32_bf16 v[38:41], v[184:187], v[208:211], v[38:41]
	v_mfma_f32_16x16x32_bf16 v[34:37], v[192:195], v[208:211], v[34:37]
	v_mfma_f32_16x16x32_bf16 v[22:25], v[184:187], v[216:219], v[22:25]
	v_mfma_f32_16x16x32_bf16 v[18:21], v[192:195], v[216:219], v[18:21]
	v_mfma_f32_16x16x32_bf16 v[6:9], v[184:187], v[224:227], v[6:9]
	v_mfma_f32_16x16x32_bf16 v[2:5], v[192:195], v[224:227], v[2:5]
	v_mfma_f32_16x16x32_bf16 v[54:57], v[188:191], v[204:207], v[54:57]
	v_mfma_f32_16x16x32_bf16 v[50:53], v[196:199], v[204:207], v[50:53]
	v_mfma_f32_16x16x32_bf16 v[38:41], v[188:191], v[212:215], v[38:41]
	v_mfma_f32_16x16x32_bf16 v[34:37], v[196:199], v[212:215], v[34:37]
	v_mfma_f32_16x16x32_bf16 v[22:25], v[188:191], v[220:223], v[22:25]
	v_mfma_f32_16x16x32_bf16 v[18:21], v[196:199], v[220:223], v[18:21]
	v_mfma_f32_16x16x32_bf16 v[6:9], v[188:191], v[228:231], v[6:9]
	v_mfma_f32_16x16x32_bf16 v[2:5], v[196:199], v[228:231], v[2:5]
	s_barrier
	s_add_u32 s86, s86, 0x100
	s_addc_u32 s87, s87, 0
	s_add_u32 s36, s36, 0x100
	s_addc_u32 s37, s37, 0
	s_cmp_ge_i32 s88, s52
	s_mov_b32 s38, s88
	s_cbranch_scc0 .LBB0_1518
	v_readlane_b32 s74, v244, 3
	v_readlane_b32 s88, v244, 5
	v_readlane_b32 s75, v244, 4
	v_readlane_b32 s90, v244, 7
	v_readlane_b32 s91, v244, 8
	v_readlane_b32 s92, v244, 9
	v_readlane_b32 s93, v244, 10
	v_readlane_b32 s94, v244, 11
	v_readlane_b32 s95, v244, 12
	v_readlane_b32 s89, v244, 6

; #define PG8_STAGE(bufoff, gbase, voff) do { _Pragma("unroll") for (int _i = 0; _i < 2; ++_i) \
;         __builtin_amdgcn_global_load_lds((const unsigned*)((const char*)(gbase) + (voff)[_i]), (PG8_LAS unsigned*)(lds + (bufoff) + ldsw + _i * 8192), 16, 0, 0); } while (0)
; #define PG8_LDA(dst, b, h) do { _Pragma("unroll") for (int m = 0; m < 4; ++m) _Pragma("unroll") for (int k = 0; k < 2; ++k) dst[m][k] = *(const PG8_LAS bf16x8*)(lds + PG8_SA(b, h) + aoff + m * 2048 + k * 1024); } while (0)
; #define PG8_LDB(dst, b, h) do { _Pragma("unroll") for (int n = 0; n < 2; ++n) _Pragma("unroll") for (int k = 0; k < 2; ++k) dst[n][k] = *(const PG8_LAS bf16x8*)(lds + PG8_SB(b, h) + boff + n * 2048 + k * 1024); } while (0)
; #define PG8_MMA(ai, bj, At, Bt) do { __builtin_amdgcn_s_setprio(1); _Pragma("unroll") for (int m = 0; m < 4; ++m) _Pragma("unroll") for (int n = 0; n < 2; ++n) _Pragma("unroll") for (int k = 0; k < 2; ++k) \
;         acc[ai][bj][m][n] = __builtin_amdgcn_mfma_f32_16x16x32_bf16(Bt[n][k], At[m][k], acc[ai][bj][m][n], 0, 0, 0); __builtin_amdgcn_s_setprio(0); } while (0)
; #define PG8_WAIT_V(n) asm volatile("s_waitcnt vmcnt(" #n ")" ::: "memory")
; #define PG8_BAR __builtin_amdgcn_s_barrier()
; template <class Epi, class Sched, bool ALIGN_EPI = false, bool SP2 = false>
; __device__ __forceinline__ void gemm_phase(PG8_LAS unsigned char* lds, const Gemm g, const Sched& S, const Epi& E) {
;     ...
;         for (int t = 0; t < nt; t += 2) {
;             const bool last = (t == nt - 2);
;             const char* a1 = cA + (size_t)(t + 1) * kstep;
;             const char* a2 = last ? nA : cA + (size_t)(t + 2) * kstep; const char* b2 = last ? nB : cB + (size_t)(t + 2) * kstep;
;             const char* a3 = a2 + kstep; const char* b3 = b2 + kstep;
;             if (last && has_next) S.a_ready(nxt);
;             if constexpr (SP2) {
;             PG8_LDB(B0, 0, 0); PG8_LDB(B1, 0, 1); PG8_SCHED; PG8_LDA(At, 0, 0); PG8_STAGE(PG8_SA(1, 1), a1 + hstep, voffA);
;             PG8_WAIT_V(8); PG8_WAIT_L(0); PG8_BAR; PG8_MMA(0, 0, At, B0); PG8_MMA(0, 1, At, B1); PG8_BAR; PG8_SCHED;
;             PG8_LDA(At, 0, 1); PG8_STAGE(PG8_SB(0, 0), b2, voffB); PG8_STAGE(PG8_SB(0, 1), b2 + hstep, voffB); PG8_STAGE(PG8_SA(0, 0), a2, voffA);
;             PG8_WAIT_V(8); PG8_WAIT_L(0); PG8_BAR; PG8_MMA(1, 0, At, B0); PG8_MMA(1, 1, At, B1); PG8_BAR; PG8_SCHED;
.LBB0_1548:
	ds_read_b128 v[146:149], v1
	ds_read_b128 v[162:165], v1 offset:1024
	ds_read_b128 v[166:169], v1 offset:2048
	ds_read_b128 v[170:173], v1 offset:3072
	ds_read_b128 v[174:177], v152
	ds_read_b128 v[178:181], v152 offset:1024
	ds_read_b128 v[182:185], v152 offset:2048
	ds_read_b128 v[186:189], v152 offset:3072
	s_add_i32 s68, s28, 2
	s_add_u32 s69, s26, 0x80
	s_addc_u32 s29, s27, 0
	s_cmp_eq_u32 s45, s28
	s_cselect_b32 s28, s4, s69
	s_cselect_b32 s29, s5, s29
	s_cselect_b32 s71, s9, s57
	s_cselect_b32 s70, s8, s56
	v_lshl_add_u64 v[150:151], s[26:27], 0, v[140:141]
	s_add_i32 m0, s37, 0xc000
	ds_read_b128 v[190:193], v153
	ds_read_b128 v[194:197], v153 offset:1024
	ds_read_b128 v[198:201], v153 offset:2048
	ds_read_b128 v[202:205], v153 offset:3072
	ds_read_b128 v[206:209], v153 offset:4096
	ds_read_b128 v[210:213], v153 offset:5120
	ds_read_b128 v[214:217], v153 offset:6144
	ds_read_b128 v[218:221], v153 offset:7168
	global_load_lds_dwordx4 v[150:151], off
	v_lshl_add_u64 v[150:151], s[26:27], 0, v[138:139]
	s_add_i32 m0, s37, 0xe000
	s_nop 0
	global_load_lds_dwordx4 v[150:151], off
	s_waitcnt vmcnt(8)
	s_waitcnt lgkmcnt(0)
	s_barrier
	v_mfma_f32_16x16x32_bf16 v[122:125], v[146:149], v[190:193], v[122:125]
	v_mfma_f32_16x16x32_bf16 v[126:129], v[166:169], v[190:193], v[126:129]
	v_mfma_f32_16x16x32_bf16 v[110:113], v[146:149], v[198:201], v[110:113]
	v_mfma_f32_16x16x32_bf16 v[106:109], v[166:169], v[198:201], v[106:109]
	v_mfma_f32_16x16x32_bf16 v[94:97], v[146:149], v[206:209], v[94:97]
	v_mfma_f32_16x16x32_bf16 v[90:93], v[166:169], v[206:209], v[90:93]
	v_mfma_f32_16x16x32_bf16 v[78:81], v[146:149], v[214:217], v[78:81]
	v_mfma_f32_16x16x32_bf16 v[74:77], v[166:169], v[214:217], v[74:77]
	v_mfma_f32_16x16x32_bf16 v[122:125], v[162:165], v[194:197], v[122:125]
	v_mfma_f32_16x16x32_bf16 v[126:129], v[170:173], v[194:197], v[126:129]
	v_mfma_f32_16x16x32_bf16 v[110:113], v[162:165], v[202:205], v[110:113]
	v_mfma_f32_16x16x32_bf16 v[106:109], v[170:173], v[202:205], v[106:109]
	v_mfma_f32_16x16x32_bf16 v[94:97], v[162:165], v[210:213], v[94:97]
	v_mfma_f32_16x16x32_bf16 v[90:93], v[170:173], v[210:213], v[90:93]
	v_mfma_f32_16x16x32_bf16 v[78:81], v[162:165], v[218:221], v[78:81]
	v_mfma_f32_16x16x32_bf16 v[74:77], v[170:173], v[218:221], v[74:77]
	v_mfma_f32_16x16x32_bf16 v[118:121], v[174:177], v[190:193], v[118:121]
	v_mfma_f32_16x16x32_bf16 v[114:117], v[182:185], v[190:193], v[114:117]
	v_mfma_f32_16x16x32_bf16 v[102:105], v[174:177], v[198:201], v[102:105]
	v_mfma_f32_16x16x32_bf16 v[98:101], v[182:185], v[198:201], v[98:101]
	v_mfma_f32_16x16x32_bf16 v[86:89], v[174:177], v[206:209], v[86:89]
	v_mfma_f32_16x16x32_bf16 v[82:85], v[182:185], v[206:209], v[82:85]
	v_mfma_f32_16x16x32_bf16 v[70:73], v[174:177], v[214:217], v[70:73]
	v_mfma_f32_16x16x32_bf16 v[66:69], v[182:185], v[214:217], v[66:69]
	v_mfma_f32_16x16x32_bf16 v[118:121], v[178:181], v[194:197], v[118:121]
	v_mfma_f32_16x16x32_bf16 v[114:117], v[186:189], v[194:197], v[114:117]
	v_mfma_f32_16x16x32_bf16 v[102:105], v[178:181], v[202:205], v[102:105]
	v_mfma_f32_16x16x32_bf16 v[98:101], v[186:189], v[202:205], v[98:101]
	v_mfma_f32_16x16x32_bf16 v[86:89], v[178:181], v[210:213], v[86:89]
	v_mfma_f32_16x16x32_bf16 v[82:85], v[186:189], v[210:213], v[82:85]
	v_mfma_f32_16x16x32_bf16 v[70:73], v[178:181], v[218:221], v[70:73]
	v_mfma_f32_16x16x32_bf16 v[66:69], v[186:189], v[218:221], v[66:69]
	s_barrier
	s_add_i32 s69, s48, s36
	v_lshl_add_u64 v[150:151], s[70:71], 0, v[132:133]
	s_mov_b32 m0, s69
	ds_read_b128 v[190:193], v153 offset:16384
	ds_read_b128 v[194:197], v153 offset:17408
	ds_read_b128 v[198:201], v153 offset:18432
	ds_read_b128 v[202:205], v153 offset:19456
	ds_read_b128 v[206:209], v153 offset:20480
	ds_read_b128 v[210:213], v153 offset:21504
	ds_read_b128 v[214:217], v153 offset:22528
	ds_read_b128 v[218:221], v153 offset:23552
	global_load_lds_dwordx4 v[150:151], off
	s_add_i32 m0, s69, 0x2000
	v_lshl_add_u64 v[158:159], s[70:71], 0, v[136:137]
	s_add_u32 s70, s70, s10
	s_addc_u32 s71, s71, s11
	s_add_i32 s69, s49, s36
	global_load_lds_dwordx4 v[158:159], off
	v_lshl_add_u64 v[222:223], s[70:71], 0, v[132:133]
	s_mov_b32 m0, s69
	v_lshl_add_u64 v[224:225], s[70:71], 0, v[136:137]
	global_load_lds_dwordx4 v[222:223], off
	s_add_i32 m0, s69, 0x2000
	v_lshl_add_u64 v[226:227], s[28:29], 0, v[130:131]
	global_load_lds_dwordx4 v[224:225], off
	s_mov_b32 m0, s37
	v_lshl_add_u64 v[228:229], s[28:29], 0, v[134:135]
	global_load_lds_dwordx4 v[226:227], off
	s_mov_b32 m0, s38
	s_nop 0
	global_load_lds_dwordx4 v[228:229], off
	s_waitcnt vmcnt(8)
	s_waitcnt lgkmcnt(0)
	s_barrier
; #define PG8_STAGE(bufoff, gbase, voff) do { _Pragma("unroll") for (int _i = 0; _i < 2; ++_i) \
;         __builtin_amdgcn_global_load_lds((const unsigned*)((const char*)(gbase) + (voff)[_i]), (PG8_LAS unsigned*)(lds + (bufoff) + ldsw + _i * 8192), 16, 0, 0); } while (0)
; #define PG8_LDA(dst, b, h) do { _Pragma("unroll") for (int m = 0; m < 4; ++m) _Pragma("unroll") for (int k = 0; k < 2; ++k) dst[m][k] = *(const PG8_LAS bf16x8*)(lds + PG8_SA(b, h) + aoff + m * 2048 + k * 1024); } while (0)
; #define PG8_LDB(dst, b, h) do { _Pragma("unroll") for (int n = 0; n < 2; ++n) _Pragma("unroll") for (int k = 0; k < 2; ++k) dst[n][k] = *(const PG8_LAS bf16x8*)(lds + PG8_SB(b, h) + boff + n * 2048 + k * 1024); } while (0)
; #define PG8_MMA(ai, bj, At, Bt) do { __builtin_amdgcn_s_setprio(1); _Pragma("unroll") for (int m = 0; m < 4; ++m) _Pragma("unroll") for (int n = 0; n < 2; ++n) _Pragma("unroll") for (int k = 0; k < 2; ++k) \
;         acc[ai][bj][m][n] = __builtin_amdgcn_mfma_f32_16x16x32_bf16(Bt[n][k], At[m][k], acc[ai][bj][m][n], 0, 0, 0); __builtin_amdgcn_s_setprio(0); } while (0)
; #define PG8_WAIT_V(n) asm volatile("s_waitcnt vmcnt(" #n ")" ::: "memory")
; #define PG8_WAIT_L(n) asm volatile("s_waitcnt lgkmcnt(" #n ")" ::: "memory")
; #define PG8_BAR __builtin_amdgcn_s_barrier()
; #define PG8_SCHED __builtin_amdgcn_sched_barrier(0)
; template <class Epi, class Sched, bool ALIGN_EPI = false, bool SP2 = false>
; __device__ __forceinline__ void gemm_phase(PG8_LAS unsigned char* lds, const Gemm g, const Sched& S, const Epi& E) {
;     ...
;             PG8_WAIT_V(8); PG8_WAIT_L(0); PG8_BAR; PG8_MMA(1, 0, At, B0); PG8_MMA(1, 1, At, B1); PG8_BAR; PG8_SCHED;
;             PG8_LDB(B0, 1, 0); PG8_LDB(B1, 1, 1); PG8_SCHED; PG8_LDA(At, 1, 0); PG8_STAGE(PG8_SA(0, 1), a2 + hstep, voffA);
;             PG8_WAIT_V(8); PG8_WAIT_L(0); PG8_BAR; PG8_MMA(0, 0, At, B0); PG8_MMA(0, 1, At, B1); PG8_BAR; PG8_SCHED;
	v_mfma_f32_16x16x32_bf16 v[62:65], v[146:149], v[190:193], v[62:65]
	v_mfma_f32_16x16x32_bf16 v[58:61], v[166:169], v[190:193], v[58:61]
	v_mfma_f32_16x16x32_bf16 v[46:49], v[146:149], v[198:201], v[46:49]
	v_mfma_f32_16x16x32_bf16 v[42:45], v[166:169], v[198:201], v[42:45]
	v_mfma_f32_16x16x32_bf16 v[30:33], v[146:149], v[206:209], v[30:33]
	v_mfma_f32_16x16x32_bf16 v[26:29], v[166:169], v[206:209], v[26:29]
	v_mfma_f32_16x16x32_bf16 v[14:17], v[146:149], v[214:217], v[14:17]
	v_mfma_f32_16x16x32_bf16 v[10:13], v[166:169], v[214:217], v[10:13]
	v_mfma_f32_16x16x32_bf16 v[62:65], v[162:165], v[194:197], v[62:65]
	v_mfma_f32_16x16x32_bf16 v[58:61], v[170:173], v[194:197], v[58:61]
	v_mfma_f32_16x16x32_bf16 v[46:49], v[162:165], v[202:205], v[46:49]
	v_mfma_f32_16x16x32_bf16 v[42:45], v[170:173], v[202:205], v[42:45]
	v_mfma_f32_16x16x32_bf16 v[30:33], v[162:165], v[210:213], v[30:33]
	v_mfma_f32_16x16x32_bf16 v[26:29], v[170:173], v[210:213], v[26:29]
	v_mfma_f32_16x16x32_bf16 v[14:17], v[162:165], v[218:221], v[14:17]
	v_mfma_f32_16x16x32_bf16 v[10:13], v[170:173], v[218:221], v[10:13]
	v_mfma_f32_16x16x32_bf16 v[54:57], v[174:177], v[190:193], v[54:57]
	v_mfma_f32_16x16x32_bf16 v[50:53], v[182:185], v[190:193], v[50:53]
	v_mfma_f32_16x16x32_bf16 v[38:41], v[174:177], v[198:201], v[38:41]
	v_mfma_f32_16x16x32_bf16 v[34:37], v[182:185], v[198:201], v[34:37]
	v_mfma_f32_16x16x32_bf16 v[22:25], v[174:177], v[206:209], v[22:25]
	v_mfma_f32_16x16x32_bf16 v[18:21], v[182:185], v[206:209], v[18:21]
	v_mfma_f32_16x16x32_bf16 v[6:9], v[174:177], v[214:217], v[6:9]
	v_mfma_f32_16x16x32_bf16 v[2:5], v[182:185], v[214:217], v[2:5]
	v_mfma_f32_16x16x32_bf16 v[54:57], v[178:181], v[194:197], v[54:57]
	v_mfma_f32_16x16x32_bf16 v[50:53], v[186:189], v[194:197], v[50:53]
	v_mfma_f32_16x16x32_bf16 v[38:41], v[178:181], v[202:205], v[38:41]
	v_mfma_f32_16x16x32_bf16 v[34:37], v[186:189], v[202:205], v[34:37]
	v_mfma_f32_16x16x32_bf16 v[22:25], v[178:181], v[210:213], v[22:25]
	v_mfma_f32_16x16x32_bf16 v[18:21], v[186:189], v[210:213], v[18:21]
	v_mfma_f32_16x16x32_bf16 v[6:9], v[178:181], v[218:221], v[6:9]
	v_mfma_f32_16x16x32_bf16 v[2:5], v[186:189], v[218:221], v[2:5]
	s_barrier
	s_add_i32 s69, 0, 0x18000
	v_add_u32_e32 v154, s69, v156
	s_add_i32 s70, 0, 0x1c000
	ds_read_b128 v[146:149], v154
	ds_read_b128 v[162:165], v154 offset:1024
	ds_read_b128 v[166:169], v154 offset:2048
	ds_read_b128 v[170:173], v154 offset:3072
	v_add_u32_e32 v154, s70, v156
	ds_read_b128 v[174:177], v154
	ds_read_b128 v[178:181], v154 offset:1024
	ds_read_b128 v[182:185], v154 offset:2048
	ds_read_b128 v[186:189], v154 offset:3072
	s_add_u32 s28, s28, s10
	s_addc_u32 s29, s29, s11
	s_mov_b32 m0, s39
	v_lshl_add_u64 v[230:231], s[28:29], 0, v[130:131]
	ds_read_b128 v[190:193], v153 offset:32768
	ds_read_b128 v[194:197], v153 offset:33792
	ds_read_b128 v[198:201], v153 offset:34816
	ds_read_b128 v[202:205], v153 offset:35840
	ds_read_b128 v[206:209], v153 offset:36864
	ds_read_b128 v[210:213], v153 offset:37888
	ds_read_b128 v[214:217], v153 offset:38912
	ds_read_b128 v[218:221], v153 offset:39936
	global_load_lds_dwordx4 v[230:231], off
	v_lshl_add_u64 v[230:231], s[28:29], 0, v[134:135]
	s_mov_b32 m0, s40
	s_nop 0
	global_load_lds_dwordx4 v[230:231], off
	s_waitcnt vmcnt(8)
	s_waitcnt lgkmcnt(0)
	s_barrier
	v_mfma_f32_16x16x32_bf16 v[122:125], v[146:149], v[190:193], v[122:125]
	v_mfma_f32_16x16x32_bf16 v[126:129], v[166:169], v[190:193], v[126:129]
	v_mfma_f32_16x16x32_bf16 v[110:113], v[146:149], v[198:201], v[110:113]
	v_mfma_f32_16x16x32_bf16 v[106:109], v[166:169], v[198:201], v[106:109]
	v_mfma_f32_16x16x32_bf16 v[94:97], v[146:149], v[206:209], v[94:97]
	v_mfma_f32_16x16x32_bf16 v[90:93], v[166:169], v[206:209], v[90:93]
	v_mfma_f32_16x16x32_bf16 v[78:81], v[146:149], v[214:217], v[78:81]
	v_mfma_f32_16x16x32_bf16 v[74:77], v[166:169], v[214:217], v[74:77]
	v_mfma_f32_16x16x32_bf16 v[122:125], v[162:165], v[194:197], v[122:125]
	v_mfma_f32_16x16x32_bf16 v[126:129], v[170:173], v[194:197], v[126:129]
	v_mfma_f32_16x16x32_bf16 v[110:113], v[162:165], v[202:205], v[110:113]
	v_mfma_f32_16x16x32_bf16 v[106:109], v[170:173], v[202:205], v[106:109]
	v_mfma_f32_16x16x32_bf16 v[94:97], v[162:165], v[210:213], v[94:97]
	v_mfma_f32_16x16x32_bf16 v[90:93], v[170:173], v[210:213], v[90:93]
	v_mfma_f32_16x16x32_bf16 v[78:81], v[162:165], v[218:221], v[78:81]
	v_mfma_f32_16x16x32_bf16 v[74:77], v[170:173], v[218:221], v[74:77]
	v_mfma_f32_16x16x32_bf16 v[118:121], v[174:177], v[190:193], v[118:121]
	v_mfma_f32_16x16x32_bf16 v[114:117], v[182:185], v[190:193], v[114:117]
	v_mfma_f32_16x16x32_bf16 v[102:105], v[174:177], v[198:201], v[102:105]
	v_mfma_f32_16x16x32_bf16 v[98:101], v[182:185], v[198:201], v[98:101]
	v_mfma_f32_16x16x32_bf16 v[86:89], v[174:177], v[206:209], v[86:89]
	v_mfma_f32_16x16x32_bf16 v[82:85], v[182:185], v[206:209], v[82:85]
	v_mfma_f32_16x16x32_bf16 v[70:73], v[174:177], v[214:217], v[70:73]
	v_mfma_f32_16x16x32_bf16 v[66:69], v[182:185], v[214:217], v[66:69]
	v_mfma_f32_16x16x32_bf16 v[118:121], v[178:181], v[194:197], v[118:121]
	v_mfma_f32_16x16x32_bf16 v[114:117], v[186:189], v[194:197], v[114:117]
	v_mfma_f32_16x16x32_bf16 v[102:105], v[178:181], v[202:205], v[102:105]
	v_mfma_f32_16x16x32_bf16 v[98:101], v[186:189], v[202:205], v[98:101]
	v_mfma_f32_16x16x32_bf16 v[86:89], v[178:181], v[210:213], v[86:89]
	v_mfma_f32_16x16x32_bf16 v[82:85], v[186:189], v[210:213], v[82:85]
	v_mfma_f32_16x16x32_bf16 v[70:73], v[178:181], v[218:221], v[70:73]
	v_mfma_f32_16x16x32_bf16 v[66:69], v[186:189], v[218:221], v[66:69]
	s_barrier
; #define PG8_STAGE(bufoff, gbase, voff) do { _Pragma("unroll") for (int _i = 0; _i < 2; ++_i) \
;         __builtin_amdgcn_global_load_lds((const unsigned*)((const char*)(gbase) + (voff)[_i]), (PG8_LAS unsigned*)(lds + (bufoff) + ldsw + _i * 8192), 16, 0, 0); } while (0)
; #define PG8_LDA(dst, b, h) do { _Pragma("unroll") for (int m = 0; m < 4; ++m) _Pragma("unroll") for (int k = 0; k < 2; ++k) dst[m][k] = *(const PG8_LAS bf16x8*)(lds + PG8_SA(b, h) + aoff + m * 2048 + k * 1024); } while (0)
; #define PG8_MMA(ai, bj, At, Bt) do { __builtin_amdgcn_s_setprio(1); _Pragma("unroll") for (int m = 0; m < 4; ++m) _Pragma("unroll") for (int n = 0; n < 2; ++n) _Pragma("unroll") for (int k = 0; k < 2; ++k) \
;         acc[ai][bj][m][n] = __builtin_amdgcn_mfma_f32_16x16x32_bf16(Bt[n][k], At[m][k], acc[ai][bj][m][n], 0, 0, 0); __builtin_amdgcn_s_setprio(0); } while (0)
; #define PG8_WAIT_V(n) asm volatile("s_waitcnt vmcnt(" #n ")" ::: "memory")
; #define PG8_WAIT_L(n) asm volatile("s_waitcnt lgkmcnt(" #n ")" ::: "memory")
; #define PG8_BAR __builtin_amdgcn_s_barrier()
; #define PG8_SCHED __builtin_amdgcn_sched_barrier(0)
; template <class Epi, class Sched, bool ALIGN_EPI = false, bool SP2 = false>
; __device__ __forceinline__ void gemm_phase(PG8_LAS unsigned char* lds, const Gemm g, const Sched& S, const Epi& E) {
;     ...
;         for (int t = 0; t < nt; t += 2) {
;             const bool last = (t == nt - 2);
;             const char* a1 = cA + (size_t)(t + 1) * kstep;
;             const char* a2 = last ? nA : cA + (size_t)(t + 2) * kstep; const char* b2 = last ? nB : cB + (size_t)(t + 2) * kstep;
;             const char* a3 = a2 + kstep; const char* b3 = b2 + kstep;
;     ...
;             PG8_LDA(At, 1, 1); PG8_STAGE(PG8_SB(1, 0), b3, voffB); PG8_STAGE(PG8_SB(1, 1), b3 + hstep, voffB); PG8_STAGE(PG8_SA(1, 0), a3, voffA);
;             PG8_WAIT_V(8); PG8_WAIT_L(0); PG8_BAR; PG8_MMA(1, 0, At, B0); PG8_MMA(1, 1, At, B1); PG8_BAR; PG8_SCHED;
	s_add_i32 s28, s69, s36
	v_lshl_add_u64 v[150:151], v[150:151], 0, s[20:21]
	s_mov_b32 m0, s28
	ds_read_b128 v[190:193], v153 offset:49152
	ds_read_b128 v[194:197], v153 offset:50176
	ds_read_b128 v[198:201], v153 offset:51200
	ds_read_b128 v[202:205], v153 offset:52224
	ds_read_b128 v[206:209], v153 offset:53248
	ds_read_b128 v[210:213], v153 offset:54272
	ds_read_b128 v[214:217], v153 offset:55296
	ds_read_b128 v[218:221], v153 offset:56320
	global_load_lds_dwordx4 v[150:151], off
	v_lshl_add_u64 v[150:151], v[158:159], 0, s[20:21]
	s_add_i32 m0, s28, 0x2000
	s_add_i32 s28, s70, s36
	global_load_lds_dwordx4 v[150:151], off
	v_lshl_add_u64 v[150:151], v[222:223], 0, s[20:21]
	s_mov_b32 m0, s28
	s_nop 0
	global_load_lds_dwordx4 v[150:151], off
	v_lshl_add_u64 v[150:151], v[224:225], 0, s[20:21]
	s_add_i32 m0, s28, 0x2000
	s_nop 0
	global_load_lds_dwordx4 v[150:151], off
	v_lshl_add_u64 v[150:151], v[226:227], 0, s[20:21]
	s_mov_b32 m0, s42
	s_nop 0
	global_load_lds_dwordx4 v[150:151], off
	v_lshl_add_u64 v[150:151], v[228:229], 0, s[20:21]
	s_mov_b32 m0, s43
	s_nop 0
	global_load_lds_dwordx4 v[150:151], off
	s_waitcnt vmcnt(8)
	s_waitcnt lgkmcnt(0)
	s_barrier
	v_mfma_f32_16x16x32_bf16 v[62:65], v[146:149], v[190:193], v[62:65]
	v_mfma_f32_16x16x32_bf16 v[58:61], v[166:169], v[190:193], v[58:61]
	v_mfma_f32_16x16x32_bf16 v[46:49], v[146:149], v[198:201], v[46:49]
	v_mfma_f32_16x16x32_bf16 v[42:45], v[166:169], v[198:201], v[42:45]
	v_mfma_f32_16x16x32_bf16 v[30:33], v[146:149], v[206:209], v[30:33]
	v_mfma_f32_16x16x32_bf16 v[26:29], v[166:169], v[206:209], v[26:29]
	v_mfma_f32_16x16x32_bf16 v[14:17], v[146:149], v[214:217], v[14:17]
	v_mfma_f32_16x16x32_bf16 v[10:13], v[166:169], v[214:217], v[10:13]
	v_mfma_f32_16x16x32_bf16 v[62:65], v[162:165], v[194:197], v[62:65]
	v_mfma_f32_16x16x32_bf16 v[58:61], v[170:173], v[194:197], v[58:61]
	v_mfma_f32_16x16x32_bf16 v[46:49], v[162:165], v[202:205], v[46:49]
	v_mfma_f32_16x16x32_bf16 v[42:45], v[170:173], v[202:205], v[42:45]
	v_mfma_f32_16x16x32_bf16 v[30:33], v[162:165], v[210:213], v[30:33]
	v_mfma_f32_16x16x32_bf16 v[26:29], v[170:173], v[210:213], v[26:29]
	v_mfma_f32_16x16x32_bf16 v[14:17], v[162:165], v[218:221], v[14:17]
	v_mfma_f32_16x16x32_bf16 v[10:13], v[170:173], v[218:221], v[10:13]
	v_mfma_f32_16x16x32_bf16 v[54:57], v[174:177], v[190:193], v[54:57]
	v_mfma_f32_16x16x32_bf16 v[50:53], v[182:185], v[190:193], v[50:53]
	v_mfma_f32_16x16x32_bf16 v[38:41], v[174:177], v[198:201], v[38:41]
	v_mfma_f32_16x16x32_bf16 v[34:37], v[182:185], v[198:201], v[34:37]
	v_mfma_f32_16x16x32_bf16 v[22:25], v[174:177], v[206:209], v[22:25]
	v_mfma_f32_16x16x32_bf16 v[18:21], v[182:185], v[206:209], v[18:21]
	v_mfma_f32_16x16x32_bf16 v[6:9], v[174:177], v[214:217], v[6:9]
	v_mfma_f32_16x16x32_bf16 v[2:5], v[182:185], v[214:217], v[2:5]
	v_mfma_f32_16x16x32_bf16 v[54:57], v[178:181], v[194:197], v[54:57]
	v_mfma_f32_16x16x32_bf16 v[50:53], v[186:189], v[194:197], v[50:53]
	v_mfma_f32_16x16x32_bf16 v[38:41], v[178:181], v[202:205], v[38:41]
	v_mfma_f32_16x16x32_bf16 v[34:37], v[186:189], v[202:205], v[34:37]
	v_mfma_f32_16x16x32_bf16 v[22:25], v[178:181], v[210:213], v[22:25]
	v_mfma_f32_16x16x32_bf16 v[18:21], v[186:189], v[210:213], v[18:21]
	v_mfma_f32_16x16x32_bf16 v[6:9], v[178:181], v[218:221], v[6:9]
	v_mfma_f32_16x16x32_bf16 v[2:5], v[186:189], v[218:221], v[2:5]
	s_barrier
	s_add_u32 s56, s56, 0x100
	s_addc_u32 s57, s57, 0
	s_add_u32 s26, s26, 0x100
	s_addc_u32 s27, s27, 0
	s_cmp_ge_i32 s68, s44
	s_mov_b32 s28, s68
	s_cbranch_scc0 .LBB0_1548

; #define PG8_STAGE(bufoff, gbase, voff) do { _Pragma("unroll") for (int _i = 0; _i < 2; ++_i) \
;         __builtin_amdgcn_global_load_lds((const unsigned*)((const char*)(gbase) + (voff)[_i]), (PG8_LAS unsigned*)(lds + (bufoff) + ldsw + _i * 8192), 16, 0, 0); } while (0)
; #define PG8_LDA(dst, b, h) do { _Pragma("unroll") for (int m = 0; m < 4; ++m) _Pragma("unroll") for (int k = 0; k < 2; ++k) dst[m][k] = *(const PG8_LAS bf16x8*)(lds + PG8_SA(b, h) + aoff + m * 2048 + k * 1024); } while (0)
; #define PG8_LDB(dst, b, h) do { _Pragma("unroll") for (int n = 0; n < 2; ++n) _Pragma("unroll") for (int k = 0; k < 2; ++k) dst[n][k] = *(const PG8_LAS bf16x8*)(lds + PG8_SB(b, h) + boff + n * 2048 + k * 1024); } while (0)
; #define PG8_MMA(ai, bj, At, Bt) do { __builtin_amdgcn_s_setprio(1); _Pragma("unroll") for (int m = 0; m < 4; ++m) _Pragma("unroll") for (int n = 0; n < 2; ++n) _Pragma("unroll") for (int k = 0; k < 2; ++k) \
;         acc[ai][bj][m][n] = __builtin_amdgcn_mfma_f32_16x16x32_bf16(Bt[n][k], At[m][k], acc[ai][bj][m][n], 0, 0, 0); __builtin_amdgcn_s_setprio(0); } while (0)
; #define PG8_WAIT_V(n) asm volatile("s_waitcnt vmcnt(" #n ")" ::: "memory")
; #define PG8_BAR __builtin_amdgcn_s_barrier()
; template <class Epi, class Sched, bool ALIGN_EPI = false, bool SP2 = false>
; __device__ __forceinline__ void gemm_phase(PG8_LAS unsigned char* lds, const Gemm g, const Sched& S, const Epi& E) {
;     ...
;         for (int t = 0; t < nt; t += 2) {
;             const bool last = (t == nt - 2);
;             const char* a1 = cA + (size_t)(t + 1) * kstep;
;             const char* a2 = last ? nA : cA + (size_t)(t + 2) * kstep; const char* b2 = last ? nB : cB + (size_t)(t + 2) * kstep;
;             const char* a3 = a2 + kstep; const char* b3 = b2 + kstep;
;             if (last && has_next) S.a_ready(nxt);
;             if constexpr (SP2) {
;             PG8_LDB(B0, 0, 0); PG8_LDB(B1, 0, 1); PG8_SCHED; PG8_LDA(At, 0, 0); PG8_STAGE(PG8_SA(1, 1), a1 + hstep, voffA);
;             PG8_WAIT_V(8); PG8_WAIT_L(0); PG8_BAR; PG8_MMA(0, 0, At, B0); PG8_MMA(0, 1, At, B1); PG8_BAR; PG8_SCHED;
;             PG8_LDA(At, 0, 1); PG8_STAGE(PG8_SB(0, 0), b2, voffB); PG8_STAGE(PG8_SB(0, 1), b2 + hstep, voffB); PG8_STAGE(PG8_SA(0, 0), a2, voffA);
;             PG8_WAIT_V(8); PG8_WAIT_L(0); PG8_BAR; PG8_MMA(1, 0, At, B0); PG8_MMA(1, 1, At, B1); PG8_BAR; PG8_SCHED;
.LBB0_1724:
	ds_read_b128 v[148:151], v157
	ds_read_b128 v[152:155], v157 offset:1024
	ds_read_b128 v[160:163], v157 offset:2048
	ds_read_b128 v[164:167], v157 offset:3072
	ds_read_b128 v[168:171], v158
	ds_read_b128 v[172:175], v158 offset:1024
	ds_read_b128 v[176:179], v158 offset:2048
	ds_read_b128 v[180:183], v158 offset:3072
	s_add_i32 s80, s38, 2
	s_add_u32 s70, s36, 0x80
	s_addc_u32 s39, s37, 0
	s_cmp_eq_u32 s59, s38
	s_cselect_b32 s38, s4, s70
	s_cselect_b32 s39, s5, s39
	s_cselect_b32 s71, s35, s45
	s_cselect_b32 s70, s34, s44
	v_lshl_add_u64 v[216:217], s[36:37], 0, v[142:143]
	s_add_i32 m0, s48, 0xc000
	ds_read_b128 v[184:187], v159
	ds_read_b128 v[188:191], v159 offset:1024
	ds_read_b128 v[192:195], v159 offset:2048
	ds_read_b128 v[196:199], v159 offset:3072
	ds_read_b128 v[200:203], v159 offset:4096
	ds_read_b128 v[204:207], v159 offset:5120
	ds_read_b128 v[208:211], v159 offset:6144
	ds_read_b128 v[212:215], v159 offset:7168
	global_load_lds_dwordx4 v[216:217], off
	v_lshl_add_u64 v[216:217], s[36:37], 0, v[140:141]
	s_add_i32 m0, s48, 0xe000
	s_nop 0
	global_load_lds_dwordx4 v[216:217], off
	s_waitcnt vmcnt(8)
	s_waitcnt lgkmcnt(0)
	s_barrier
	v_mfma_f32_16x16x32_bf16 v[122:125], v[148:151], v[184:187], v[122:125]
	v_mfma_f32_16x16x32_bf16 v[126:129], v[160:163], v[184:187], v[126:129]
	v_mfma_f32_16x16x32_bf16 v[110:113], v[148:151], v[192:195], v[110:113]
	v_mfma_f32_16x16x32_bf16 v[106:109], v[160:163], v[192:195], v[106:109]
	v_mfma_f32_16x16x32_bf16 v[94:97], v[148:151], v[200:203], v[94:97]
	v_mfma_f32_16x16x32_bf16 v[90:93], v[160:163], v[200:203], v[90:93]
	v_mfma_f32_16x16x32_bf16 v[78:81], v[148:151], v[208:211], v[78:81]
	v_mfma_f32_16x16x32_bf16 v[74:77], v[160:163], v[208:211], v[74:77]
	v_mfma_f32_16x16x32_bf16 v[122:125], v[152:155], v[188:191], v[122:125]
	v_mfma_f32_16x16x32_bf16 v[126:129], v[164:167], v[188:191], v[126:129]
	v_mfma_f32_16x16x32_bf16 v[110:113], v[152:155], v[196:199], v[110:113]
	v_mfma_f32_16x16x32_bf16 v[106:109], v[164:167], v[196:199], v[106:109]
	v_mfma_f32_16x16x32_bf16 v[94:97], v[152:155], v[204:207], v[94:97]
	v_mfma_f32_16x16x32_bf16 v[90:93], v[164:167], v[204:207], v[90:93]
	v_mfma_f32_16x16x32_bf16 v[78:81], v[152:155], v[212:215], v[78:81]
	v_mfma_f32_16x16x32_bf16 v[74:77], v[164:167], v[212:215], v[74:77]
	v_mfma_f32_16x16x32_bf16 v[118:121], v[168:171], v[184:187], v[118:121]
	v_mfma_f32_16x16x32_bf16 v[114:117], v[176:179], v[184:187], v[114:117]
	v_mfma_f32_16x16x32_bf16 v[102:105], v[168:171], v[192:195], v[102:105]
	v_mfma_f32_16x16x32_bf16 v[98:101], v[176:179], v[192:195], v[98:101]
	v_mfma_f32_16x16x32_bf16 v[86:89], v[168:171], v[200:203], v[86:89]
	v_mfma_f32_16x16x32_bf16 v[82:85], v[176:179], v[200:203], v[82:85]
	v_mfma_f32_16x16x32_bf16 v[70:73], v[168:171], v[208:211], v[70:73]
	v_mfma_f32_16x16x32_bf16 v[66:69], v[176:179], v[208:211], v[66:69]
	v_mfma_f32_16x16x32_bf16 v[118:121], v[172:175], v[188:191], v[118:121]
	v_mfma_f32_16x16x32_bf16 v[114:117], v[180:183], v[188:191], v[114:117]
	v_mfma_f32_16x16x32_bf16 v[102:105], v[172:175], v[196:199], v[102:105]
	v_mfma_f32_16x16x32_bf16 v[98:101], v[180:183], v[196:199], v[98:101]
	v_mfma_f32_16x16x32_bf16 v[86:89], v[172:175], v[204:207], v[86:89]
	v_mfma_f32_16x16x32_bf16 v[82:85], v[180:183], v[204:207], v[82:85]
	v_mfma_f32_16x16x32_bf16 v[70:73], v[172:175], v[212:215], v[70:73]
	v_mfma_f32_16x16x32_bf16 v[66:69], v[180:183], v[212:215], v[66:69]
	s_barrier
	s_add_i32 s72, s62, s47
	v_lshl_add_u64 v[216:217], s[70:71], 0, v[134:135]
	s_mov_b32 m0, s72
	ds_read_b128 v[184:187], v159 offset:16384
	ds_read_b128 v[188:191], v159 offset:17408
	ds_read_b128 v[192:195], v159 offset:18432
	ds_read_b128 v[196:199], v159 offset:19456
	ds_read_b128 v[200:203], v159 offset:20480
	ds_read_b128 v[204:207], v159 offset:21504
	ds_read_b128 v[208:211], v159 offset:22528
	ds_read_b128 v[212:215], v159 offset:23552
	global_load_lds_dwordx4 v[216:217], off
	s_add_i32 m0, s72, 0x2000
	v_lshl_add_u64 v[218:219], s[70:71], 0, v[138:139]
	s_add_u32 s70, s70, s8
	s_addc_u32 s71, s71, s9
	s_add_i32 s72, s63, s47
	global_load_lds_dwordx4 v[218:219], off
	v_lshl_add_u64 v[220:221], s[70:71], 0, v[134:135]
	s_mov_b32 m0, s72
	v_lshl_add_u64 v[222:223], s[70:71], 0, v[138:139]
	global_load_lds_dwordx4 v[220:221], off
	s_add_i32 m0, s72, 0x2000
	v_lshl_add_u64 v[224:225], s[38:39], 0, v[132:133]
	global_load_lds_dwordx4 v[222:223], off
	s_mov_b32 m0, s48
	v_lshl_add_u64 v[226:227], s[38:39], 0, v[136:137]
	global_load_lds_dwordx4 v[224:225], off
	s_mov_b32 m0, s49
	s_nop 0
	global_load_lds_dwordx4 v[226:227], off
	s_waitcnt vmcnt(8)
	s_waitcnt lgkmcnt(0)
	s_barrier
; #define PG8_STAGE(bufoff, gbase, voff) do { _Pragma("unroll") for (int _i = 0; _i < 2; ++_i) \
;         __builtin_amdgcn_global_load_lds((const unsigned*)((const char*)(gbase) + (voff)[_i]), (PG8_LAS unsigned*)(lds + (bufoff) + ldsw + _i * 8192), 16, 0, 0); } while (0)
; #define PG8_LDA(dst, b, h) do { _Pragma("unroll") for (int m = 0; m < 4; ++m) _Pragma("unroll") for (int k = 0; k < 2; ++k) dst[m][k] = *(const PG8_LAS bf16x8*)(lds + PG8_SA(b, h) + aoff + m * 2048 + k * 1024); } while (0)
; #define PG8_LDB(dst, b, h) do { _Pragma("unroll") for (int n = 0; n < 2; ++n) _Pragma("unroll") for (int k = 0; k < 2; ++k) dst[n][k] = *(const PG8_LAS bf16x8*)(lds + PG8_SB(b, h) + boff + n * 2048 + k * 1024); } while (0)
; #define PG8_MMA(ai, bj, At, Bt) do { __builtin_amdgcn_s_setprio(1); _Pragma("unroll") for (int m = 0; m < 4; ++m) _Pragma("unroll") for (int n = 0; n < 2; ++n) _Pragma("unroll") for (int k = 0; k < 2; ++k) \
;         acc[ai][bj][m][n] = __builtin_amdgcn_mfma_f32_16x16x32_bf16(Bt[n][k], At[m][k], acc[ai][bj][m][n], 0, 0, 0); __builtin_amdgcn_s_setprio(0); } while (0)
; #define PG8_WAIT_V(n) asm volatile("s_waitcnt vmcnt(" #n ")" ::: "memory")
; #define PG8_WAIT_L(n) asm volatile("s_waitcnt lgkmcnt(" #n ")" ::: "memory")
; #define PG8_BAR __builtin_amdgcn_s_barrier()
; #define PG8_SCHED __builtin_amdgcn_sched_barrier(0)
; template <class Epi, class Sched, bool ALIGN_EPI = false, bool SP2 = false>
; __device__ __forceinline__ void gemm_phase(PG8_LAS unsigned char* lds, const Gemm g, const Sched& S, const Epi& E) {
;     ...
;             PG8_WAIT_V(8); PG8_WAIT_L(0); PG8_BAR; PG8_MMA(1, 0, At, B0); PG8_MMA(1, 1, At, B1); PG8_BAR; PG8_SCHED;
;             PG8_LDB(B0, 1, 0); PG8_LDB(B1, 1, 1); PG8_SCHED; PG8_LDA(At, 1, 0); PG8_STAGE(PG8_SA(0, 1), a2 + hstep, voffA);
;             PG8_WAIT_V(8); PG8_WAIT_L(0); PG8_BAR; PG8_MMA(0, 0, At, B0); PG8_MMA(0, 1, At, B1); PG8_BAR; PG8_SCHED;
	v_mfma_f32_16x16x32_bf16 v[62:65], v[148:151], v[184:187], v[62:65]
	v_mfma_f32_16x16x32_bf16 v[58:61], v[160:163], v[184:187], v[58:61]
	v_mfma_f32_16x16x32_bf16 v[46:49], v[148:151], v[192:195], v[46:49]
	v_mfma_f32_16x16x32_bf16 v[42:45], v[160:163], v[192:195], v[42:45]
	v_mfma_f32_16x16x32_bf16 v[30:33], v[148:151], v[200:203], v[30:33]
	v_mfma_f32_16x16x32_bf16 v[26:29], v[160:163], v[200:203], v[26:29]
	v_mfma_f32_16x16x32_bf16 v[14:17], v[148:151], v[208:211], v[14:17]
	v_mfma_f32_16x16x32_bf16 v[10:13], v[160:163], v[208:211], v[10:13]
	v_mfma_f32_16x16x32_bf16 v[62:65], v[152:155], v[188:191], v[62:65]
	v_mfma_f32_16x16x32_bf16 v[58:61], v[164:167], v[188:191], v[58:61]
	v_mfma_f32_16x16x32_bf16 v[46:49], v[152:155], v[196:199], v[46:49]
	v_mfma_f32_16x16x32_bf16 v[42:45], v[164:167], v[196:199], v[42:45]
	v_mfma_f32_16x16x32_bf16 v[30:33], v[152:155], v[204:207], v[30:33]
	v_mfma_f32_16x16x32_bf16 v[26:29], v[164:167], v[204:207], v[26:29]
	v_mfma_f32_16x16x32_bf16 v[14:17], v[152:155], v[212:215], v[14:17]
	v_mfma_f32_16x16x32_bf16 v[10:13], v[164:167], v[212:215], v[10:13]
	v_mfma_f32_16x16x32_bf16 v[54:57], v[168:171], v[184:187], v[54:57]
	v_mfma_f32_16x16x32_bf16 v[50:53], v[176:179], v[184:187], v[50:53]
	v_mfma_f32_16x16x32_bf16 v[38:41], v[168:171], v[192:195], v[38:41]
	v_mfma_f32_16x16x32_bf16 v[34:37], v[176:179], v[192:195], v[34:37]
	v_mfma_f32_16x16x32_bf16 v[22:25], v[168:171], v[200:203], v[22:25]
	v_mfma_f32_16x16x32_bf16 v[18:21], v[176:179], v[200:203], v[18:21]
	v_mfma_f32_16x16x32_bf16 v[6:9], v[168:171], v[208:211], v[6:9]
	v_mfma_f32_16x16x32_bf16 v[2:5], v[176:179], v[208:211], v[2:5]
	v_mfma_f32_16x16x32_bf16 v[54:57], v[172:175], v[188:191], v[54:57]
	v_mfma_f32_16x16x32_bf16 v[50:53], v[180:183], v[188:191], v[50:53]
	v_mfma_f32_16x16x32_bf16 v[38:41], v[172:175], v[196:199], v[38:41]
	v_mfma_f32_16x16x32_bf16 v[34:37], v[180:183], v[196:199], v[34:37]
	v_mfma_f32_16x16x32_bf16 v[22:25], v[172:175], v[204:207], v[22:25]
	v_mfma_f32_16x16x32_bf16 v[18:21], v[180:183], v[204:207], v[18:21]
	v_mfma_f32_16x16x32_bf16 v[6:9], v[172:175], v[212:215], v[6:9]
	v_mfma_f32_16x16x32_bf16 v[2:5], v[180:183], v[212:215], v[2:5]
	s_barrier
	s_add_i32 s70, 0, 0x18000
	s_add_i32 s71, 0, 0x1c000
	v_add_u32_e32 v164, s70, v156
	v_add_u32_e32 v180, s71, v156
	ds_read_b128 v[148:151], v164
	ds_read_b128 v[152:155], v164 offset:1024
	ds_read_b128 v[160:163], v164 offset:2048
	ds_read_b128 v[164:167], v164 offset:3072
	ds_read_b128 v[168:171], v180
	ds_read_b128 v[172:175], v180 offset:1024
	ds_read_b128 v[176:179], v180 offset:2048
	ds_read_b128 v[180:183], v180 offset:3072
	s_add_u32 s38, s38, s8
	s_addc_u32 s39, s39, s9
	s_mov_b32 m0, s52
	v_lshl_add_u64 v[228:229], s[38:39], 0, v[132:133]
	ds_read_b128 v[184:187], v159 offset:32768
	ds_read_b128 v[188:191], v159 offset:33792
	ds_read_b128 v[192:195], v159 offset:34816
	ds_read_b128 v[196:199], v159 offset:35840
	ds_read_b128 v[200:203], v159 offset:36864
	ds_read_b128 v[204:207], v159 offset:37888
	ds_read_b128 v[208:211], v159 offset:38912
	ds_read_b128 v[212:215], v159 offset:39936
	global_load_lds_dwordx4 v[228:229], off
	v_lshl_add_u64 v[228:229], s[38:39], 0, v[136:137]
	s_mov_b32 m0, s53
	s_nop 0
	global_load_lds_dwordx4 v[228:229], off
	s_waitcnt vmcnt(8)
	s_waitcnt lgkmcnt(0)
	s_barrier
	v_mfma_f32_16x16x32_bf16 v[122:125], v[148:151], v[184:187], v[122:125]
	v_mfma_f32_16x16x32_bf16 v[126:129], v[160:163], v[184:187], v[126:129]
	v_mfma_f32_16x16x32_bf16 v[110:113], v[148:151], v[192:195], v[110:113]
	v_mfma_f32_16x16x32_bf16 v[106:109], v[160:163], v[192:195], v[106:109]
	v_mfma_f32_16x16x32_bf16 v[94:97], v[148:151], v[200:203], v[94:97]
	v_mfma_f32_16x16x32_bf16 v[90:93], v[160:163], v[200:203], v[90:93]
	v_mfma_f32_16x16x32_bf16 v[78:81], v[148:151], v[208:211], v[78:81]
	v_mfma_f32_16x16x32_bf16 v[74:77], v[160:163], v[208:211], v[74:77]
	v_mfma_f32_16x16x32_bf16 v[122:125], v[152:155], v[188:191], v[122:125]
	v_mfma_f32_16x16x32_bf16 v[126:129], v[164:167], v[188:191], v[126:129]
	v_mfma_f32_16x16x32_bf16 v[110:113], v[152:155], v[196:199], v[110:113]
	v_mfma_f32_16x16x32_bf16 v[106:109], v[164:167], v[196:199], v[106:109]
	v_mfma_f32_16x16x32_bf16 v[94:97], v[152:155], v[204:207], v[94:97]
	v_mfma_f32_16x16x32_bf16 v[90:93], v[164:167], v[204:207], v[90:93]
	v_mfma_f32_16x16x32_bf16 v[78:81], v[152:155], v[212:215], v[78:81]
	v_mfma_f32_16x16x32_bf16 v[74:77], v[164:167], v[212:215], v[74:77]
	v_mfma_f32_16x16x32_bf16 v[118:121], v[168:171], v[184:187], v[118:121]
	v_mfma_f32_16x16x32_bf16 v[114:117], v[176:179], v[184:187], v[114:117]
	v_mfma_f32_16x16x32_bf16 v[102:105], v[168:171], v[192:195], v[102:105]
	v_mfma_f32_16x16x32_bf16 v[98:101], v[176:179], v[192:195], v[98:101]
	v_mfma_f32_16x16x32_bf16 v[86:89], v[168:171], v[200:203], v[86:89]
	v_mfma_f32_16x16x32_bf16 v[82:85], v[176:179], v[200:203], v[82:85]
	v_mfma_f32_16x16x32_bf16 v[70:73], v[168:171], v[208:211], v[70:73]
	v_mfma_f32_16x16x32_bf16 v[66:69], v[176:179], v[208:211], v[66:69]
	v_mfma_f32_16x16x32_bf16 v[118:121], v[172:175], v[188:191], v[118:121]
	v_mfma_f32_16x16x32_bf16 v[114:117], v[180:183], v[188:191], v[114:117]
	v_mfma_f32_16x16x32_bf16 v[102:105], v[172:175], v[196:199], v[102:105]
	v_mfma_f32_16x16x32_bf16 v[98:101], v[180:183], v[196:199], v[98:101]
	v_mfma_f32_16x16x32_bf16 v[86:89], v[172:175], v[204:207], v[86:89]
	v_mfma_f32_16x16x32_bf16 v[82:85], v[180:183], v[204:207], v[82:85]
	v_mfma_f32_16x16x32_bf16 v[70:73], v[172:175], v[212:215], v[70:73]
	v_mfma_f32_16x16x32_bf16 v[66:69], v[180:183], v[212:215], v[66:69]
	s_barrier
; #define PG8_STAGE(bufoff, gbase, voff) do { _Pragma("unroll") for (int _i = 0; _i < 2; ++_i) \
;         __builtin_amdgcn_global_load_lds((const unsigned*)((const char*)(gbase) + (voff)[_i]), (PG8_LAS unsigned*)(lds + (bufoff) + ldsw + _i * 8192), 16, 0, 0); } while (0)
; #define PG8_LDA(dst, b, h) do { _Pragma("unroll") for (int m = 0; m < 4; ++m) _Pragma("unroll") for (int k = 0; k < 2; ++k) dst[m][k] = *(const PG8_LAS bf16x8*)(lds + PG8_SA(b, h) + aoff + m * 2048 + k * 1024); } while (0)
; #define PG8_MMA(ai, bj, At, Bt) do { __builtin_amdgcn_s_setprio(1); _Pragma("unroll") for (int m = 0; m < 4; ++m) _Pragma("unroll") for (int n = 0; n < 2; ++n) _Pragma("unroll") for (int k = 0; k < 2; ++k) \
;         acc[ai][bj][m][n] = __builtin_amdgcn_mfma_f32_16x16x32_bf16(Bt[n][k], At[m][k], acc[ai][bj][m][n], 0, 0, 0); __builtin_amdgcn_s_setprio(0); } while (0)
; #define PG8_WAIT_V(n) asm volatile("s_waitcnt vmcnt(" #n ")" ::: "memory")
; #define PG8_WAIT_L(n) asm volatile("s_waitcnt lgkmcnt(" #n ")" ::: "memory")
; #define PG8_BAR __builtin_amdgcn_s_barrier()
; #define PG8_SCHED __builtin_amdgcn_sched_barrier(0)
; template <class Epi, class Sched, bool ALIGN_EPI = false, bool SP2 = false>
; __device__ __forceinline__ void gemm_phase(PG8_LAS unsigned char* lds, const Gemm g, const Sched& S, const Epi& E) {
;     ...
;         for (int t = 0; t < nt; t += 2) {
;             const bool last = (t == nt - 2);
;             const char* a1 = cA + (size_t)(t + 1) * kstep;
;             const char* a2 = last ? nA : cA + (size_t)(t + 2) * kstep; const char* b2 = last ? nB : cB + (size_t)(t + 2) * kstep;
;             const char* a3 = a2 + kstep; const char* b3 = b2 + kstep;
;     ...
;             PG8_LDA(At, 1, 1); PG8_STAGE(PG8_SB(1, 0), b3, voffB); PG8_STAGE(PG8_SB(1, 1), b3 + hstep, voffB); PG8_STAGE(PG8_SA(1, 0), a3, voffA);
;             PG8_WAIT_V(8); PG8_WAIT_L(0); PG8_BAR; PG8_MMA(1, 0, At, B0); PG8_MMA(1, 1, At, B1); PG8_BAR; PG8_SCHED;
	s_add_i32 s38, s70, s47
	v_lshl_add_u64 v[216:217], v[216:217], 0, s[24:25]
	s_mov_b32 m0, s38
	ds_read_b128 v[184:187], v159 offset:49152
	ds_read_b128 v[188:191], v159 offset:50176
	ds_read_b128 v[192:195], v159 offset:51200
	ds_read_b128 v[196:199], v159 offset:52224
	ds_read_b128 v[200:203], v159 offset:53248
	ds_read_b128 v[204:207], v159 offset:54272
	ds_read_b128 v[208:211], v159 offset:55296
	ds_read_b128 v[212:215], v159 offset:56320
	global_load_lds_dwordx4 v[216:217], off
	v_lshl_add_u64 v[216:217], v[218:219], 0, s[24:25]
	s_add_i32 m0, s38, 0x2000
	s_add_i32 s38, s71, s47
	global_load_lds_dwordx4 v[216:217], off
	v_lshl_add_u64 v[216:217], v[220:221], 0, s[24:25]
	s_mov_b32 m0, s38
	s_nop 0
	global_load_lds_dwordx4 v[216:217], off
	v_lshl_add_u64 v[216:217], v[222:223], 0, s[24:25]
	s_add_i32 m0, s38, 0x2000
	s_nop 0
	global_load_lds_dwordx4 v[216:217], off
	v_lshl_add_u64 v[216:217], v[224:225], 0, s[24:25]
	s_mov_b32 m0, s55
	s_nop 0
	global_load_lds_dwordx4 v[216:217], off
	v_lshl_add_u64 v[216:217], v[226:227], 0, s[24:25]
	s_mov_b32 m0, s56
	s_nop 0
	global_load_lds_dwordx4 v[216:217], off
	s_waitcnt vmcnt(8)
	s_waitcnt lgkmcnt(0)
	s_barrier
	v_mfma_f32_16x16x32_bf16 v[62:65], v[148:151], v[184:187], v[62:65]
	v_mfma_f32_16x16x32_bf16 v[58:61], v[160:163], v[184:187], v[58:61]
	v_mfma_f32_16x16x32_bf16 v[46:49], v[148:151], v[192:195], v[46:49]
	v_mfma_f32_16x16x32_bf16 v[42:45], v[160:163], v[192:195], v[42:45]
	v_mfma_f32_16x16x32_bf16 v[30:33], v[148:151], v[200:203], v[30:33]
	v_mfma_f32_16x16x32_bf16 v[26:29], v[160:163], v[200:203], v[26:29]
	v_mfma_f32_16x16x32_bf16 v[14:17], v[148:151], v[208:211], v[14:17]
	v_mfma_f32_16x16x32_bf16 v[10:13], v[160:163], v[208:211], v[10:13]
	v_mfma_f32_16x16x32_bf16 v[62:65], v[152:155], v[188:191], v[62:65]
	v_mfma_f32_16x16x32_bf16 v[58:61], v[164:167], v[188:191], v[58:61]
	v_mfma_f32_16x16x32_bf16 v[46:49], v[152:155], v[196:199], v[46:49]
	v_mfma_f32_16x16x32_bf16 v[42:45], v[164:167], v[196:199], v[42:45]
	v_mfma_f32_16x16x32_bf16 v[30:33], v[152:155], v[204:207], v[30:33]
	v_mfma_f32_16x16x32_bf16 v[26:29], v[164:167], v[204:207], v[26:29]
	v_mfma_f32_16x16x32_bf16 v[14:17], v[152:155], v[212:215], v[14:17]
	v_mfma_f32_16x16x32_bf16 v[10:13], v[164:167], v[212:215], v[10:13]
	v_mfma_f32_16x16x32_bf16 v[54:57], v[168:171], v[184:187], v[54:57]
	v_mfma_f32_16x16x32_bf16 v[50:53], v[176:179], v[184:187], v[50:53]
	v_mfma_f32_16x16x32_bf16 v[38:41], v[168:171], v[192:195], v[38:41]
	v_mfma_f32_16x16x32_bf16 v[34:37], v[176:179], v[192:195], v[34:37]
	v_mfma_f32_16x16x32_bf16 v[22:25], v[168:171], v[200:203], v[22:25]
	v_mfma_f32_16x16x32_bf16 v[18:21], v[176:179], v[200:203], v[18:21]
	v_mfma_f32_16x16x32_bf16 v[6:9], v[168:171], v[208:211], v[6:9]
	v_mfma_f32_16x16x32_bf16 v[2:5], v[176:179], v[208:211], v[2:5]
	v_mfma_f32_16x16x32_bf16 v[54:57], v[172:175], v[188:191], v[54:57]
	v_mfma_f32_16x16x32_bf16 v[50:53], v[180:183], v[188:191], v[50:53]
	v_mfma_f32_16x16x32_bf16 v[38:41], v[172:175], v[196:199], v[38:41]
	v_mfma_f32_16x16x32_bf16 v[34:37], v[180:183], v[196:199], v[34:37]
	v_mfma_f32_16x16x32_bf16 v[22:25], v[172:175], v[204:207], v[22:25]
	v_mfma_f32_16x16x32_bf16 v[18:21], v[180:183], v[204:207], v[18:21]
	v_mfma_f32_16x16x32_bf16 v[6:9], v[172:175], v[212:215], v[6:9]
	v_mfma_f32_16x16x32_bf16 v[2:5], v[180:183], v[212:215], v[2:5]
	s_barrier
	s_add_u32 s44, s44, 0x100
	s_addc_u32 s45, s45, 0
	s_add_u32 s36, s36, 0x100
	s_addc_u32 s37, s37, 0
	s_cmp_ge_i32 s80, s57
	s_mov_b32 s38, s80
	s_cbranch_scc0 .LBB0_1724

; #define PG8_STAGE(bufoff, gbase, voff) do { _Pragma("unroll") for (int _i = 0; _i < 2; ++_i) \
;         __builtin_amdgcn_global_load_lds((const unsigned*)((const char*)(gbase) + (voff)[_i]), (PG8_LAS unsigned*)(lds + (bufoff) + ldsw + _i * 8192), 16, 0, 0); } while (0)
; #define PG8_LDA(dst, b, h) do { _Pragma("unroll") for (int m = 0; m < 4; ++m) _Pragma("unroll") for (int k = 0; k < 2; ++k) dst[m][k] = *(const PG8_LAS bf16x8*)(lds + PG8_SA(b, h) + aoff + m * 2048 + k * 1024); } while (0)
; #define PG8_LDB(dst, b, h) do { _Pragma("unroll") for (int n = 0; n < 2; ++n) _Pragma("unroll") for (int k = 0; k < 2; ++k) dst[n][k] = *(const PG8_LAS bf16x8*)(lds + PG8_SB(b, h) + boff + n * 2048 + k * 1024); } while (0)
; #define PG8_MMA(ai, bj, At, Bt) do { __builtin_amdgcn_s_setprio(1); _Pragma("unroll") for (int m = 0; m < 4; ++m) _Pragma("unroll") for (int n = 0; n < 2; ++n) _Pragma("unroll") for (int k = 0; k < 2; ++k) \
;         acc[ai][bj][m][n] = __builtin_amdgcn_mfma_f32_16x16x32_bf16(Bt[n][k], At[m][k], acc[ai][bj][m][n], 0, 0, 0); __builtin_amdgcn_s_setprio(0); } while (0)
; #define PG8_WAIT_V(n) asm volatile("s_waitcnt vmcnt(" #n ")" ::: "memory")
; #define PG8_BAR __builtin_amdgcn_s_barrier()
; template <class Epi, class Sched, bool ALIGN_EPI = false, bool SP2 = false>
; __device__ __forceinline__ void gemm_phase(PG8_LAS unsigned char* lds, const Gemm g, const Sched& S, const Epi& E) {
;     ...
;         for (int t = 0; t < nt; t += 2) {
;             const bool last = (t == nt - 2);
;             const char* a1 = cA + (size_t)(t + 1) * kstep;
;             const char* a2 = last ? nA : cA + (size_t)(t + 2) * kstep; const char* b2 = last ? nB : cB + (size_t)(t + 2) * kstep;
;             const char* a3 = a2 + kstep; const char* b3 = b2 + kstep;
;             if (last && has_next) S.a_ready(nxt);
;             if constexpr (SP2) {
;             PG8_LDB(B0, 0, 0); PG8_LDB(B1, 0, 1); PG8_SCHED; PG8_LDA(At, 0, 0); PG8_STAGE(PG8_SA(1, 1), a1 + hstep, voffA);
;             PG8_WAIT_V(8); PG8_WAIT_L(0); PG8_BAR; PG8_MMA(0, 0, At, B0); PG8_MMA(0, 1, At, B1); PG8_BAR; PG8_SCHED;
;             PG8_LDA(At, 0, 1); PG8_STAGE(PG8_SB(0, 0), b2, voffB); PG8_STAGE(PG8_SB(0, 1), b2 + hstep, voffB); PG8_STAGE(PG8_SA(0, 0), a2, voffA);
;             PG8_WAIT_V(8); PG8_WAIT_L(0); PG8_BAR; PG8_MMA(1, 0, At, B0); PG8_MMA(1, 1, At, B1); PG8_BAR; PG8_SCHED;
.LBB0_1809:
	ds_read_b128 v[152:155], v148
	ds_read_b128 v[156:159], v148 offset:1024
	ds_read_b128 v[160:163], v148 offset:2048
	ds_read_b128 v[164:167], v148 offset:3072
	ds_read_b128 v[168:171], v149
	ds_read_b128 v[172:175], v149 offset:1024
	ds_read_b128 v[176:179], v149 offset:2048
	ds_read_b128 v[180:183], v149 offset:3072
	s_add_i32 s56, s26, 2
	s_add_u32 s57, s24, 0x80
	s_addc_u32 s27, s25, 0
	s_cmp_eq_u32 s43, s26
	s_cselect_b32 s26, s4, s57
	s_cselect_b32 s27, s5, s27
	s_cselect_b32 s59, s23, s55
	s_cselect_b32 s58, s22, s54
	v_lshl_add_u64 v[216:217], s[24:25], 0, v[140:141]
	s_add_i32 m0, s35, 0xc000
	ds_read_b128 v[184:187], v150
	ds_read_b128 v[188:191], v150 offset:1024
	ds_read_b128 v[192:195], v150 offset:2048
	ds_read_b128 v[196:199], v150 offset:3072
	ds_read_b128 v[200:203], v150 offset:4096
	ds_read_b128 v[204:207], v150 offset:5120
	ds_read_b128 v[208:211], v150 offset:6144
	ds_read_b128 v[212:215], v150 offset:7168
	global_load_lds_dwordx4 v[216:217], off
	v_lshl_add_u64 v[216:217], s[24:25], 0, v[138:139]
	s_add_i32 m0, s35, 0xe000
	s_nop 0
	global_load_lds_dwordx4 v[216:217], off
	s_waitcnt vmcnt(8)
	s_waitcnt lgkmcnt(0)
	s_barrier
	v_mfma_f32_16x16x32_bf16 v[122:125], v[152:155], v[184:187], v[122:125]
	v_mfma_f32_16x16x32_bf16 v[126:129], v[160:163], v[184:187], v[126:129]
	v_mfma_f32_16x16x32_bf16 v[110:113], v[152:155], v[192:195], v[110:113]
	v_mfma_f32_16x16x32_bf16 v[106:109], v[160:163], v[192:195], v[106:109]
	v_mfma_f32_16x16x32_bf16 v[94:97], v[152:155], v[200:203], v[94:97]
	v_mfma_f32_16x16x32_bf16 v[90:93], v[160:163], v[200:203], v[90:93]
	v_mfma_f32_16x16x32_bf16 v[78:81], v[152:155], v[208:211], v[78:81]
	v_mfma_f32_16x16x32_bf16 v[74:77], v[160:163], v[208:211], v[74:77]
	v_mfma_f32_16x16x32_bf16 v[122:125], v[156:159], v[188:191], v[122:125]
	v_mfma_f32_16x16x32_bf16 v[126:129], v[164:167], v[188:191], v[126:129]
	v_mfma_f32_16x16x32_bf16 v[110:113], v[156:159], v[196:199], v[110:113]
	v_mfma_f32_16x16x32_bf16 v[106:109], v[164:167], v[196:199], v[106:109]
	v_mfma_f32_16x16x32_bf16 v[94:97], v[156:159], v[204:207], v[94:97]
	v_mfma_f32_16x16x32_bf16 v[90:93], v[164:167], v[204:207], v[90:93]
	v_mfma_f32_16x16x32_bf16 v[78:81], v[156:159], v[212:215], v[78:81]
	v_mfma_f32_16x16x32_bf16 v[74:77], v[164:167], v[212:215], v[74:77]
	v_mfma_f32_16x16x32_bf16 v[118:121], v[168:171], v[184:187], v[118:121]
	v_mfma_f32_16x16x32_bf16 v[114:117], v[176:179], v[184:187], v[114:117]
	v_mfma_f32_16x16x32_bf16 v[102:105], v[168:171], v[192:195], v[102:105]
	v_mfma_f32_16x16x32_bf16 v[98:101], v[176:179], v[192:195], v[98:101]
	v_mfma_f32_16x16x32_bf16 v[86:89], v[168:171], v[200:203], v[86:89]
	v_mfma_f32_16x16x32_bf16 v[82:85], v[176:179], v[200:203], v[82:85]
	v_mfma_f32_16x16x32_bf16 v[70:73], v[168:171], v[208:211], v[70:73]
	v_mfma_f32_16x16x32_bf16 v[66:69], v[176:179], v[208:211], v[66:69]
	v_mfma_f32_16x16x32_bf16 v[118:121], v[172:175], v[188:191], v[118:121]
	v_mfma_f32_16x16x32_bf16 v[114:117], v[180:183], v[188:191], v[114:117]
	v_mfma_f32_16x16x32_bf16 v[102:105], v[172:175], v[196:199], v[102:105]
	v_mfma_f32_16x16x32_bf16 v[98:101], v[180:183], v[196:199], v[98:101]
	v_mfma_f32_16x16x32_bf16 v[86:89], v[172:175], v[204:207], v[86:89]
	v_mfma_f32_16x16x32_bf16 v[82:85], v[180:183], v[204:207], v[82:85]
	v_mfma_f32_16x16x32_bf16 v[70:73], v[172:175], v[212:215], v[70:73]
	v_mfma_f32_16x16x32_bf16 v[66:69], v[180:183], v[212:215], v[66:69]
	s_barrier
	s_add_i32 s57, s46, s34
	v_lshl_add_u64 v[216:217], s[58:59], 0, v[132:133]
	s_mov_b32 m0, s57
	ds_read_b128 v[184:187], v150 offset:16384
	ds_read_b128 v[188:191], v150 offset:17408
	ds_read_b128 v[192:195], v150 offset:18432
	ds_read_b128 v[196:199], v150 offset:19456
	ds_read_b128 v[200:203], v150 offset:20480
	ds_read_b128 v[204:207], v150 offset:21504
	ds_read_b128 v[208:211], v150 offset:22528
	ds_read_b128 v[212:215], v150 offset:23552
	global_load_lds_dwordx4 v[216:217], off
	s_add_i32 m0, s57, 0x2000
	v_lshl_add_u64 v[218:219], s[58:59], 0, v[136:137]
	s_add_u32 s58, s58, s8
	s_addc_u32 s59, s59, s9
	s_add_i32 s57, s47, s34
	global_load_lds_dwordx4 v[218:219], off
	v_lshl_add_u64 v[220:221], s[58:59], 0, v[132:133]
	s_mov_b32 m0, s57
	v_lshl_add_u64 v[222:223], s[58:59], 0, v[136:137]
	global_load_lds_dwordx4 v[220:221], off
	s_add_i32 m0, s57, 0x2000
	v_lshl_add_u64 v[224:225], s[26:27], 0, v[130:131]
	global_load_lds_dwordx4 v[222:223], off
	s_mov_b32 m0, s35
	v_lshl_add_u64 v[226:227], s[26:27], 0, v[134:135]
	global_load_lds_dwordx4 v[224:225], off
	s_mov_b32 m0, s36
	s_nop 0
	global_load_lds_dwordx4 v[226:227], off
	s_waitcnt vmcnt(8)
	s_waitcnt lgkmcnt(0)
	s_barrier
; #define PG8_STAGE(bufoff, gbase, voff) do { _Pragma("unroll") for (int _i = 0; _i < 2; ++_i) \
;         __builtin_amdgcn_global_load_lds((const unsigned*)((const char*)(gbase) + (voff)[_i]), (PG8_LAS unsigned*)(lds + (bufoff) + ldsw + _i * 8192), 16, 0, 0); } while (0)
; #define PG8_LDA(dst, b, h) do { _Pragma("unroll") for (int m = 0; m < 4; ++m) _Pragma("unroll") for (int k = 0; k < 2; ++k) dst[m][k] = *(const PG8_LAS bf16x8*)(lds + PG8_SA(b, h) + aoff + m * 2048 + k * 1024); } while (0)
; #define PG8_LDB(dst, b, h) do { _Pragma("unroll") for (int n = 0; n < 2; ++n) _Pragma("unroll") for (int k = 0; k < 2; ++k) dst[n][k] = *(const PG8_LAS bf16x8*)(lds + PG8_SB(b, h) + boff + n * 2048 + k * 1024); } while (0)
; #define PG8_MMA(ai, bj, At, Bt) do { __builtin_amdgcn_s_setprio(1); _Pragma("unroll") for (int m = 0; m < 4; ++m) _Pragma("unroll") for (int n = 0; n < 2; ++n) _Pragma("unroll") for (int k = 0; k < 2; ++k) \
;         acc[ai][bj][m][n] = __builtin_amdgcn_mfma_f32_16x16x32_bf16(Bt[n][k], At[m][k], acc[ai][bj][m][n], 0, 0, 0); __builtin_amdgcn_s_setprio(0); } while (0)
; #define PG8_WAIT_V(n) asm volatile("s_waitcnt vmcnt(" #n ")" ::: "memory")
; #define PG8_WAIT_L(n) asm volatile("s_waitcnt lgkmcnt(" #n ")" ::: "memory")
; #define PG8_BAR __builtin_amdgcn_s_barrier()
; #define PG8_SCHED __builtin_amdgcn_sched_barrier(0)
; template <class Epi, class Sched, bool ALIGN_EPI = false, bool SP2 = false>
; __device__ __forceinline__ void gemm_phase(PG8_LAS unsigned char* lds, const Gemm g, const Sched& S, const Epi& E) {
;     ...
;             PG8_WAIT_V(8); PG8_WAIT_L(0); PG8_BAR; PG8_MMA(1, 0, At, B0); PG8_MMA(1, 1, At, B1); PG8_BAR; PG8_SCHED;
;             PG8_LDB(B0, 1, 0); PG8_LDB(B1, 1, 1); PG8_SCHED; PG8_LDA(At, 1, 0); PG8_STAGE(PG8_SA(0, 1), a2 + hstep, voffA);
;             PG8_WAIT_V(8); PG8_WAIT_L(0); PG8_BAR; PG8_MMA(0, 0, At, B0); PG8_MMA(0, 1, At, B1); PG8_BAR; PG8_SCHED;
	v_mfma_f32_16x16x32_bf16 v[62:65], v[152:155], v[184:187], v[62:65]
	v_mfma_f32_16x16x32_bf16 v[58:61], v[160:163], v[184:187], v[58:61]
	v_mfma_f32_16x16x32_bf16 v[46:49], v[152:155], v[192:195], v[46:49]
	v_mfma_f32_16x16x32_bf16 v[42:45], v[160:163], v[192:195], v[42:45]
	v_mfma_f32_16x16x32_bf16 v[30:33], v[152:155], v[200:203], v[30:33]
	v_mfma_f32_16x16x32_bf16 v[26:29], v[160:163], v[200:203], v[26:29]
	v_mfma_f32_16x16x32_bf16 v[14:17], v[152:155], v[208:211], v[14:17]
	v_mfma_f32_16x16x32_bf16 v[10:13], v[160:163], v[208:211], v[10:13]
	v_mfma_f32_16x16x32_bf16 v[62:65], v[156:159], v[188:191], v[62:65]
	v_mfma_f32_16x16x32_bf16 v[58:61], v[164:167], v[188:191], v[58:61]
	v_mfma_f32_16x16x32_bf16 v[46:49], v[156:159], v[196:199], v[46:49]
	v_mfma_f32_16x16x32_bf16 v[42:45], v[164:167], v[196:199], v[42:45]
	v_mfma_f32_16x16x32_bf16 v[30:33], v[156:159], v[204:207], v[30:33]
	v_mfma_f32_16x16x32_bf16 v[26:29], v[164:167], v[204:207], v[26:29]
	v_mfma_f32_16x16x32_bf16 v[14:17], v[156:159], v[212:215], v[14:17]
	v_mfma_f32_16x16x32_bf16 v[10:13], v[164:167], v[212:215], v[10:13]
	v_mfma_f32_16x16x32_bf16 v[54:57], v[168:171], v[184:187], v[54:57]
	v_mfma_f32_16x16x32_bf16 v[50:53], v[176:179], v[184:187], v[50:53]
	v_mfma_f32_16x16x32_bf16 v[38:41], v[168:171], v[192:195], v[38:41]
	v_mfma_f32_16x16x32_bf16 v[34:37], v[176:179], v[192:195], v[34:37]
	v_mfma_f32_16x16x32_bf16 v[22:25], v[168:171], v[200:203], v[22:25]
	v_mfma_f32_16x16x32_bf16 v[18:21], v[176:179], v[200:203], v[18:21]
	v_mfma_f32_16x16x32_bf16 v[6:9], v[168:171], v[208:211], v[6:9]
	v_mfma_f32_16x16x32_bf16 v[2:5], v[176:179], v[208:211], v[2:5]
	v_mfma_f32_16x16x32_bf16 v[54:57], v[172:175], v[188:191], v[54:57]
	v_mfma_f32_16x16x32_bf16 v[50:53], v[180:183], v[188:191], v[50:53]
	v_mfma_f32_16x16x32_bf16 v[38:41], v[172:175], v[196:199], v[38:41]
	v_mfma_f32_16x16x32_bf16 v[34:37], v[180:183], v[196:199], v[34:37]
	v_mfma_f32_16x16x32_bf16 v[22:25], v[172:175], v[204:207], v[22:25]
	v_mfma_f32_16x16x32_bf16 v[18:21], v[180:183], v[204:207], v[18:21]
	v_mfma_f32_16x16x32_bf16 v[6:9], v[172:175], v[212:215], v[6:9]
	v_mfma_f32_16x16x32_bf16 v[2:5], v[180:183], v[212:215], v[2:5]
	s_barrier
	s_add_i32 s57, 0, 0x18000
	v_add_u32_e32 v151, s57, v146
	s_add_i32 s58, 0, 0x1c000
	ds_read_b128 v[152:155], v151
	ds_read_b128 v[156:159], v151 offset:1024
	ds_read_b128 v[160:163], v151 offset:2048
	ds_read_b128 v[164:167], v151 offset:3072
	v_add_u32_e32 v151, s58, v146
	ds_read_b128 v[168:171], v151
	ds_read_b128 v[172:175], v151 offset:1024
	ds_read_b128 v[176:179], v151 offset:2048
	ds_read_b128 v[180:183], v151 offset:3072
	s_add_u32 s26, s26, s8
	s_addc_u32 s27, s27, s9
	s_mov_b32 m0, s37
	v_lshl_add_u64 v[228:229], s[26:27], 0, v[130:131]
	ds_read_b128 v[184:187], v150 offset:32768
	ds_read_b128 v[188:191], v150 offset:33792
	ds_read_b128 v[192:195], v150 offset:34816
	ds_read_b128 v[196:199], v150 offset:35840
	ds_read_b128 v[200:203], v150 offset:36864
	ds_read_b128 v[204:207], v150 offset:37888
	ds_read_b128 v[208:211], v150 offset:38912
	ds_read_b128 v[212:215], v150 offset:39936
	global_load_lds_dwordx4 v[228:229], off
	v_lshl_add_u64 v[228:229], s[26:27], 0, v[134:135]
	s_mov_b32 m0, s38
	s_nop 0
	global_load_lds_dwordx4 v[228:229], off
	s_waitcnt vmcnt(8)
	s_waitcnt lgkmcnt(0)
	s_barrier
	v_mfma_f32_16x16x32_bf16 v[122:125], v[152:155], v[184:187], v[122:125]
	v_mfma_f32_16x16x32_bf16 v[126:129], v[160:163], v[184:187], v[126:129]
	v_mfma_f32_16x16x32_bf16 v[110:113], v[152:155], v[192:195], v[110:113]
	v_mfma_f32_16x16x32_bf16 v[106:109], v[160:163], v[192:195], v[106:109]
	v_mfma_f32_16x16x32_bf16 v[94:97], v[152:155], v[200:203], v[94:97]
	v_mfma_f32_16x16x32_bf16 v[90:93], v[160:163], v[200:203], v[90:93]
	v_mfma_f32_16x16x32_bf16 v[78:81], v[152:155], v[208:211], v[78:81]
	v_mfma_f32_16x16x32_bf16 v[74:77], v[160:163], v[208:211], v[74:77]
	v_mfma_f32_16x16x32_bf16 v[122:125], v[156:159], v[188:191], v[122:125]
	v_mfma_f32_16x16x32_bf16 v[126:129], v[164:167], v[188:191], v[126:129]
	v_mfma_f32_16x16x32_bf16 v[110:113], v[156:159], v[196:199], v[110:113]
	v_mfma_f32_16x16x32_bf16 v[106:109], v[164:167], v[196:199], v[106:109]
	v_mfma_f32_16x16x32_bf16 v[94:97], v[156:159], v[204:207], v[94:97]
	v_mfma_f32_16x16x32_bf16 v[90:93], v[164:167], v[204:207], v[90:93]
	v_mfma_f32_16x16x32_bf16 v[78:81], v[156:159], v[212:215], v[78:81]
	v_mfma_f32_16x16x32_bf16 v[74:77], v[164:167], v[212:215], v[74:77]
	v_mfma_f32_16x16x32_bf16 v[118:121], v[168:171], v[184:187], v[118:121]
	v_mfma_f32_16x16x32_bf16 v[114:117], v[176:179], v[184:187], v[114:117]
	v_mfma_f32_16x16x32_bf16 v[102:105], v[168:171], v[192:195], v[102:105]
	v_mfma_f32_16x16x32_bf16 v[98:101], v[176:179], v[192:195], v[98:101]
	v_mfma_f32_16x16x32_bf16 v[86:89], v[168:171], v[200:203], v[86:89]
	v_mfma_f32_16x16x32_bf16 v[82:85], v[176:179], v[200:203], v[82:85]
	v_mfma_f32_16x16x32_bf16 v[70:73], v[168:171], v[208:211], v[70:73]
	v_mfma_f32_16x16x32_bf16 v[66:69], v[176:179], v[208:211], v[66:69]
	v_mfma_f32_16x16x32_bf16 v[118:121], v[172:175], v[188:191], v[118:121]
	v_mfma_f32_16x16x32_bf16 v[114:117], v[180:183], v[188:191], v[114:117]
	v_mfma_f32_16x16x32_bf16 v[102:105], v[172:175], v[196:199], v[102:105]
	v_mfma_f32_16x16x32_bf16 v[98:101], v[180:183], v[196:199], v[98:101]
	v_mfma_f32_16x16x32_bf16 v[86:89], v[172:175], v[204:207], v[86:89]
	v_mfma_f32_16x16x32_bf16 v[82:85], v[180:183], v[204:207], v[82:85]
	v_mfma_f32_16x16x32_bf16 v[70:73], v[172:175], v[212:215], v[70:73]
	v_mfma_f32_16x16x32_bf16 v[66:69], v[180:183], v[212:215], v[66:69]
	s_barrier
; #define PG8_STAGE(bufoff, gbase, voff) do { _Pragma("unroll") for (int _i = 0; _i < 2; ++_i) \
;         __builtin_amdgcn_global_load_lds((const unsigned*)((const char*)(gbase) + (voff)[_i]), (PG8_LAS unsigned*)(lds + (bufoff) + ldsw + _i * 8192), 16, 0, 0); } while (0)
; #define PG8_LDA(dst, b, h) do { _Pragma("unroll") for (int m = 0; m < 4; ++m) _Pragma("unroll") for (int k = 0; k < 2; ++k) dst[m][k] = *(const PG8_LAS bf16x8*)(lds + PG8_SA(b, h) + aoff + m * 2048 + k * 1024); } while (0)
; #define PG8_MMA(ai, bj, At, Bt) do { __builtin_amdgcn_s_setprio(1); _Pragma("unroll") for (int m = 0; m < 4; ++m) _Pragma("unroll") for (int n = 0; n < 2; ++n) _Pragma("unroll") for (int k = 0; k < 2; ++k) \
;         acc[ai][bj][m][n] = __builtin_amdgcn_mfma_f32_16x16x32_bf16(Bt[n][k], At[m][k], acc[ai][bj][m][n], 0, 0, 0); __builtin_amdgcn_s_setprio(0); } while (0)
; #define PG8_WAIT_V(n) asm volatile("s_waitcnt vmcnt(" #n ")" ::: "memory")
; #define PG8_WAIT_L(n) asm volatile("s_waitcnt lgkmcnt(" #n ")" ::: "memory")
; #define PG8_BAR __builtin_amdgcn_s_barrier()
; #define PG8_SCHED __builtin_amdgcn_sched_barrier(0)
; template <class Epi, class Sched, bool ALIGN_EPI = false, bool SP2 = false>
; __device__ __forceinline__ void gemm_phase(PG8_LAS unsigned char* lds, const Gemm g, const Sched& S, const Epi& E) {
;     ...
;         for (int t = 0; t < nt; t += 2) {
;             const bool last = (t == nt - 2);
;             const char* a1 = cA + (size_t)(t + 1) * kstep;
;             const char* a2 = last ? nA : cA + (size_t)(t + 2) * kstep; const char* b2 = last ? nB : cB + (size_t)(t + 2) * kstep;
;             const char* a3 = a2 + kstep; const char* b3 = b2 + kstep;
;     ...
;             PG8_LDA(At, 1, 1); PG8_STAGE(PG8_SB(1, 0), b3, voffB); PG8_STAGE(PG8_SB(1, 1), b3 + hstep, voffB); PG8_STAGE(PG8_SA(1, 0), a3, voffA);
;             PG8_WAIT_V(8); PG8_WAIT_L(0); PG8_BAR; PG8_MMA(1, 0, At, B0); PG8_MMA(1, 1, At, B1); PG8_BAR; PG8_SCHED;
	s_add_i32 s26, s57, s34
	v_lshl_add_u64 v[216:217], v[216:217], 0, s[16:17]
	s_mov_b32 m0, s26
	ds_read_b128 v[184:187], v150 offset:49152
	ds_read_b128 v[188:191], v150 offset:50176
	ds_read_b128 v[192:195], v150 offset:51200
	ds_read_b128 v[196:199], v150 offset:52224
	ds_read_b128 v[200:203], v150 offset:53248
	ds_read_b128 v[204:207], v150 offset:54272
	ds_read_b128 v[208:211], v150 offset:55296
	ds_read_b128 v[212:215], v150 offset:56320
	global_load_lds_dwordx4 v[216:217], off
	v_lshl_add_u64 v[216:217], v[218:219], 0, s[16:17]
	s_add_i32 m0, s26, 0x2000
	s_add_i32 s26, s58, s34
	global_load_lds_dwordx4 v[216:217], off
	v_lshl_add_u64 v[216:217], v[220:221], 0, s[16:17]
	s_mov_b32 m0, s26
	s_nop 0
	global_load_lds_dwordx4 v[216:217], off
	v_lshl_add_u64 v[216:217], v[222:223], 0, s[16:17]
	s_add_i32 m0, s26, 0x2000
	s_nop 0
	global_load_lds_dwordx4 v[216:217], off
	v_lshl_add_u64 v[216:217], v[224:225], 0, s[16:17]
	s_mov_b32 m0, s40
	s_nop 0
	global_load_lds_dwordx4 v[216:217], off
	v_lshl_add_u64 v[216:217], v[226:227], 0, s[16:17]
	s_mov_b32 m0, s41
	s_nop 0
	global_load_lds_dwordx4 v[216:217], off
	s_waitcnt vmcnt(8)
	s_waitcnt lgkmcnt(0)
	s_barrier
	v_mfma_f32_16x16x32_bf16 v[62:65], v[152:155], v[184:187], v[62:65]
	v_mfma_f32_16x16x32_bf16 v[58:61], v[160:163], v[184:187], v[58:61]
	v_mfma_f32_16x16x32_bf16 v[46:49], v[152:155], v[192:195], v[46:49]
	v_mfma_f32_16x16x32_bf16 v[42:45], v[160:163], v[192:195], v[42:45]
	v_mfma_f32_16x16x32_bf16 v[30:33], v[152:155], v[200:203], v[30:33]
	v_mfma_f32_16x16x32_bf16 v[26:29], v[160:163], v[200:203], v[26:29]
	v_mfma_f32_16x16x32_bf16 v[14:17], v[152:155], v[208:211], v[14:17]
	v_mfma_f32_16x16x32_bf16 v[10:13], v[160:163], v[208:211], v[10:13]
	v_mfma_f32_16x16x32_bf16 v[62:65], v[156:159], v[188:191], v[62:65]
	v_mfma_f32_16x16x32_bf16 v[58:61], v[164:167], v[188:191], v[58:61]
	v_mfma_f32_16x16x32_bf16 v[46:49], v[156:159], v[196:199], v[46:49]
	v_mfma_f32_16x16x32_bf16 v[42:45], v[164:167], v[196:199], v[42:45]
	v_mfma_f32_16x16x32_bf16 v[30:33], v[156:159], v[204:207], v[30:33]
	v_mfma_f32_16x16x32_bf16 v[26:29], v[164:167], v[204:207], v[26:29]
	v_mfma_f32_16x16x32_bf16 v[14:17], v[156:159], v[212:215], v[14:17]
	v_mfma_f32_16x16x32_bf16 v[10:13], v[164:167], v[212:215], v[10:13]
	v_mfma_f32_16x16x32_bf16 v[54:57], v[168:171], v[184:187], v[54:57]
	v_mfma_f32_16x16x32_bf16 v[50:53], v[176:179], v[184:187], v[50:53]
	v_mfma_f32_16x16x32_bf16 v[38:41], v[168:171], v[192:195], v[38:41]
	v_mfma_f32_16x16x32_bf16 v[34:37], v[176:179], v[192:195], v[34:37]
	v_mfma_f32_16x16x32_bf16 v[22:25], v[168:171], v[200:203], v[22:25]
	v_mfma_f32_16x16x32_bf16 v[18:21], v[176:179], v[200:203], v[18:21]
	v_mfma_f32_16x16x32_bf16 v[6:9], v[168:171], v[208:211], v[6:9]
	v_mfma_f32_16x16x32_bf16 v[2:5], v[176:179], v[208:211], v[2:5]
	v_mfma_f32_16x16x32_bf16 v[54:57], v[172:175], v[188:191], v[54:57]
	v_mfma_f32_16x16x32_bf16 v[50:53], v[180:183], v[188:191], v[50:53]
	v_mfma_f32_16x16x32_bf16 v[38:41], v[172:175], v[196:199], v[38:41]
	v_mfma_f32_16x16x32_bf16 v[34:37], v[180:183], v[196:199], v[34:37]
	v_mfma_f32_16x16x32_bf16 v[22:25], v[172:175], v[204:207], v[22:25]
	v_mfma_f32_16x16x32_bf16 v[18:21], v[180:183], v[204:207], v[18:21]
	v_mfma_f32_16x16x32_bf16 v[6:9], v[172:175], v[212:215], v[6:9]
	v_mfma_f32_16x16x32_bf16 v[2:5], v[180:183], v[212:215], v[2:5]
	s_barrier
	s_add_u32 s54, s54, 0x100
	s_addc_u32 s55, s55, 0
	s_add_u32 s24, s24, 0x100
	s_addc_u32 s25, s25, 0
	s_cmp_ge_i32 s56, s42
	s_mov_b32 s26, s56
	s_cbranch_scc0 .LBB0_1809

; #define PG8_STAGE(bufoff, gbase, voff) do { _Pragma("unroll") for (int _i = 0; _i < 2; ++_i) \
;         __builtin_amdgcn_global_load_lds((const unsigned*)((const char*)(gbase) + (voff)[_i]), (PG8_LAS unsigned*)(lds + (bufoff) + ldsw + _i * 8192), 16, 0, 0); } while (0)
; #define PG8_LDA(dst, b, h) do { _Pragma("unroll") for (int m = 0; m < 4; ++m) _Pragma("unroll") for (int k = 0; k < 2; ++k) dst[m][k] = *(const PG8_LAS bf16x8*)(lds + PG8_SA(b, h) + aoff + m * 2048 + k * 1024); } while (0)
; #define PG8_LDB(dst, b, h) do { _Pragma("unroll") for (int n = 0; n < 2; ++n) _Pragma("unroll") for (int k = 0; k < 2; ++k) dst[n][k] = *(const PG8_LAS bf16x8*)(lds + PG8_SB(b, h) + boff + n * 2048 + k * 1024); } while (0)
; #define PG8_MMA(ai, bj, At, Bt) do { __builtin_amdgcn_s_setprio(1); _Pragma("unroll") for (int m = 0; m < 4; ++m) _Pragma("unroll") for (int n = 0; n < 2; ++n) _Pragma("unroll") for (int k = 0; k < 2; ++k) \
;         acc[ai][bj][m][n] = __builtin_amdgcn_mfma_f32_16x16x32_bf16(Bt[n][k], At[m][k], acc[ai][bj][m][n], 0, 0, 0); __builtin_amdgcn_s_setprio(0); } while (0)
; #define PG8_WAIT_V(n) asm volatile("s_waitcnt vmcnt(" #n ")" ::: "memory")
; #define PG8_BAR __builtin_amdgcn_s_barrier()
; template <class Epi, class Sched, bool ALIGN_EPI = false, bool SP2 = false>
; __device__ __forceinline__ void gemm_phase(PG8_LAS unsigned char* lds, const Gemm g, const Sched& S, const Epi& E) {
;     ...
;         for (int t = 0; t < nt; t += 2) {
;             const bool last = (t == nt - 2);
;             const char* a1 = cA + (size_t)(t + 1) * kstep;
;             const char* a2 = last ? nA : cA + (size_t)(t + 2) * kstep; const char* b2 = last ? nB : cB + (size_t)(t + 2) * kstep;
;             const char* a3 = a2 + kstep; const char* b3 = b2 + kstep;
;             if (last && has_next) S.a_ready(nxt);
;             if constexpr (SP2) {
;             PG8_LDB(B0, 0, 0); PG8_LDB(B1, 0, 1); PG8_SCHED; PG8_LDA(At, 0, 0); PG8_STAGE(PG8_SA(1, 1), a1 + hstep, voffA);
;             PG8_WAIT_V(8); PG8_WAIT_L(0); PG8_BAR; PG8_MMA(0, 0, At, B0); PG8_MMA(0, 1, At, B1); PG8_BAR; PG8_SCHED;
;             PG8_LDA(At, 0, 1); PG8_STAGE(PG8_SB(0, 0), b2, voffB); PG8_STAGE(PG8_SB(0, 1), b2 + hstep, voffB); PG8_STAGE(PG8_SA(0, 0), a2, voffA);
;             PG8_WAIT_V(8); PG8_WAIT_L(0); PG8_BAR; PG8_MMA(1, 0, At, B0); PG8_MMA(1, 1, At, B1); PG8_BAR; PG8_SCHED;
.LBB0_1976:
	ds_read_b128 v[152:155], v148
	ds_read_b128 v[156:159], v148 offset:1024
	ds_read_b128 v[160:163], v148 offset:2048
	ds_read_b128 v[164:167], v148 offset:3072
	ds_read_b128 v[168:171], v149
	ds_read_b128 v[172:175], v149 offset:1024
	ds_read_b128 v[176:179], v149 offset:2048
	ds_read_b128 v[180:183], v149 offset:3072
	s_add_i32 s58, s26, 2
	s_add_u32 s59, s24, 0x80
	s_addc_u32 s27, s25, 0
	s_cmp_eq_u32 s44, s26
	s_cselect_b32 s26, s4, s59
	s_cselect_b32 s27, s5, s27
	s_cselect_b32 s61, s23, s57
	s_cselect_b32 s60, s22, s56
	v_lshl_add_u64 v[216:217], s[24:25], 0, v[140:141]
	s_add_i32 m0, s36, 0xc000
	ds_read_b128 v[184:187], v150
	ds_read_b128 v[188:191], v150 offset:1024
	ds_read_b128 v[192:195], v150 offset:2048
	ds_read_b128 v[196:199], v150 offset:3072
	ds_read_b128 v[200:203], v150 offset:4096
	ds_read_b128 v[204:207], v150 offset:5120
	ds_read_b128 v[208:211], v150 offset:6144
	ds_read_b128 v[212:215], v150 offset:7168
	global_load_lds_dwordx4 v[216:217], off
	v_lshl_add_u64 v[216:217], s[24:25], 0, v[138:139]
	s_add_i32 m0, s36, 0xe000
	s_nop 0
	global_load_lds_dwordx4 v[216:217], off
	s_waitcnt vmcnt(8)
	s_waitcnt lgkmcnt(0)
	s_barrier
	v_mfma_f32_16x16x32_bf16 v[122:125], v[152:155], v[184:187], v[122:125]
	v_mfma_f32_16x16x32_bf16 v[118:121], v[160:163], v[184:187], v[118:121]
	v_mfma_f32_16x16x32_bf16 v[110:113], v[152:155], v[192:195], v[110:113]
	v_mfma_f32_16x16x32_bf16 v[102:105], v[160:163], v[192:195], v[102:105]
	v_mfma_f32_16x16x32_bf16 v[94:97], v[152:155], v[200:203], v[94:97]
	v_mfma_f32_16x16x32_bf16 v[86:89], v[160:163], v[200:203], v[86:89]
	v_mfma_f32_16x16x32_bf16 v[78:81], v[152:155], v[208:211], v[78:81]
	v_mfma_f32_16x16x32_bf16 v[70:73], v[160:163], v[208:211], v[70:73]
	v_mfma_f32_16x16x32_bf16 v[122:125], v[156:159], v[188:191], v[122:125]
	v_mfma_f32_16x16x32_bf16 v[118:121], v[164:167], v[188:191], v[118:121]
	v_mfma_f32_16x16x32_bf16 v[110:113], v[156:159], v[196:199], v[110:113]
	v_mfma_f32_16x16x32_bf16 v[102:105], v[164:167], v[196:199], v[102:105]
	v_mfma_f32_16x16x32_bf16 v[94:97], v[156:159], v[204:207], v[94:97]
	v_mfma_f32_16x16x32_bf16 v[86:89], v[164:167], v[204:207], v[86:89]
	v_mfma_f32_16x16x32_bf16 v[78:81], v[156:159], v[212:215], v[78:81]
	v_mfma_f32_16x16x32_bf16 v[70:73], v[164:167], v[212:215], v[70:73]
	v_mfma_f32_16x16x32_bf16 v[126:129], v[168:171], v[184:187], v[126:129]
	v_mfma_f32_16x16x32_bf16 v[114:117], v[176:179], v[184:187], v[114:117]
	v_mfma_f32_16x16x32_bf16 v[106:109], v[168:171], v[192:195], v[106:109]
	v_mfma_f32_16x16x32_bf16 v[98:101], v[176:179], v[192:195], v[98:101]
	v_mfma_f32_16x16x32_bf16 v[90:93], v[168:171], v[200:203], v[90:93]
	v_mfma_f32_16x16x32_bf16 v[82:85], v[176:179], v[200:203], v[82:85]
	v_mfma_f32_16x16x32_bf16 v[74:77], v[168:171], v[208:211], v[74:77]
	v_mfma_f32_16x16x32_bf16 v[66:69], v[176:179], v[208:211], v[66:69]
	v_mfma_f32_16x16x32_bf16 v[126:129], v[172:175], v[188:191], v[126:129]
	v_mfma_f32_16x16x32_bf16 v[114:117], v[180:183], v[188:191], v[114:117]
	v_mfma_f32_16x16x32_bf16 v[106:109], v[172:175], v[196:199], v[106:109]
	v_mfma_f32_16x16x32_bf16 v[98:101], v[180:183], v[196:199], v[98:101]
	v_mfma_f32_16x16x32_bf16 v[90:93], v[172:175], v[204:207], v[90:93]
	v_mfma_f32_16x16x32_bf16 v[82:85], v[180:183], v[204:207], v[82:85]
	v_mfma_f32_16x16x32_bf16 v[74:77], v[172:175], v[212:215], v[74:77]
	v_mfma_f32_16x16x32_bf16 v[66:69], v[180:183], v[212:215], v[66:69]
	s_barrier
	s_add_i32 s59, s47, s31
	v_lshl_add_u64 v[216:217], s[60:61], 0, v[134:135]
	s_mov_b32 m0, s59
	ds_read_b128 v[184:187], v150 offset:16384
	ds_read_b128 v[188:191], v150 offset:17408
	ds_read_b128 v[192:195], v150 offset:18432
	ds_read_b128 v[196:199], v150 offset:19456
	ds_read_b128 v[200:203], v150 offset:20480
	ds_read_b128 v[204:207], v150 offset:21504
	ds_read_b128 v[208:211], v150 offset:22528
	ds_read_b128 v[212:215], v150 offset:23552
	global_load_lds_dwordx4 v[216:217], off
	s_add_i32 m0, s59, 0x2000
	v_lshl_add_u64 v[218:219], s[60:61], 0, v[130:131]
	s_add_u32 s60, s60, s8
	s_addc_u32 s61, s61, s9
	s_add_i32 s59, s48, s31
	global_load_lds_dwordx4 v[218:219], off
	v_lshl_add_u64 v[220:221], s[60:61], 0, v[134:135]
	s_mov_b32 m0, s59
	v_lshl_add_u64 v[222:223], s[60:61], 0, v[130:131]
	global_load_lds_dwordx4 v[220:221], off
	s_add_i32 m0, s59, 0x2000
	v_lshl_add_u64 v[224:225], s[26:27], 0, v[136:137]
	global_load_lds_dwordx4 v[222:223], off
	s_mov_b32 m0, s36
	v_lshl_add_u64 v[226:227], s[26:27], 0, v[132:133]
	global_load_lds_dwordx4 v[224:225], off
	s_mov_b32 m0, s37
	s_nop 0
	global_load_lds_dwordx4 v[226:227], off
	s_waitcnt vmcnt(8)
	s_waitcnt lgkmcnt(0)
	s_barrier
; #define PG8_STAGE(bufoff, gbase, voff) do { _Pragma("unroll") for (int _i = 0; _i < 2; ++_i) \
;         __builtin_amdgcn_global_load_lds((const unsigned*)((const char*)(gbase) + (voff)[_i]), (PG8_LAS unsigned*)(lds + (bufoff) + ldsw + _i * 8192), 16, 0, 0); } while (0)
; #define PG8_LDA(dst, b, h) do { _Pragma("unroll") for (int m = 0; m < 4; ++m) _Pragma("unroll") for (int k = 0; k < 2; ++k) dst[m][k] = *(const PG8_LAS bf16x8*)(lds + PG8_SA(b, h) + aoff + m * 2048 + k * 1024); } while (0)
; #define PG8_LDB(dst, b, h) do { _Pragma("unroll") for (int n = 0; n < 2; ++n) _Pragma("unroll") for (int k = 0; k < 2; ++k) dst[n][k] = *(const PG8_LAS bf16x8*)(lds + PG8_SB(b, h) + boff + n * 2048 + k * 1024); } while (0)
; #define PG8_MMA(ai, bj, At, Bt) do { __builtin_amdgcn_s_setprio(1); _Pragma("unroll") for (int m = 0; m < 4; ++m) _Pragma("unroll") for (int n = 0; n < 2; ++n) _Pragma("unroll") for (int k = 0; k < 2; ++k) \
;         acc[ai][bj][m][n] = __builtin_amdgcn_mfma_f32_16x16x32_bf16(Bt[n][k], At[m][k], acc[ai][bj][m][n], 0, 0, 0); __builtin_amdgcn_s_setprio(0); } while (0)
; #define PG8_WAIT_V(n) asm volatile("s_waitcnt vmcnt(" #n ")" ::: "memory")
; #define PG8_WAIT_L(n) asm volatile("s_waitcnt lgkmcnt(" #n ")" ::: "memory")
; #define PG8_BAR __builtin_amdgcn_s_barrier()
; #define PG8_SCHED __builtin_amdgcn_sched_barrier(0)
; template <class Epi, class Sched, bool ALIGN_EPI = false, bool SP2 = false>
; __device__ __forceinline__ void gemm_phase(PG8_LAS unsigned char* lds, const Gemm g, const Sched& S, const Epi& E) {
;     ...
;             PG8_WAIT_V(8); PG8_WAIT_L(0); PG8_BAR; PG8_MMA(1, 0, At, B0); PG8_MMA(1, 1, At, B1); PG8_BAR; PG8_SCHED;
;             PG8_LDB(B0, 1, 0); PG8_LDB(B1, 1, 1); PG8_SCHED; PG8_LDA(At, 1, 0); PG8_STAGE(PG8_SA(0, 1), a2 + hstep, voffA);
;             PG8_WAIT_V(8); PG8_WAIT_L(0); PG8_BAR; PG8_MMA(0, 0, At, B0); PG8_MMA(0, 1, At, B1); PG8_BAR; PG8_SCHED;
	v_mfma_f32_16x16x32_bf16 v[62:65], v[152:155], v[184:187], v[62:65]
	v_mfma_f32_16x16x32_bf16 v[54:57], v[160:163], v[184:187], v[54:57]
	v_mfma_f32_16x16x32_bf16 v[46:49], v[152:155], v[192:195], v[46:49]
	v_mfma_f32_16x16x32_bf16 v[38:41], v[160:163], v[192:195], v[38:41]
	v_mfma_f32_16x16x32_bf16 v[30:33], v[152:155], v[200:203], v[30:33]
	v_mfma_f32_16x16x32_bf16 v[22:25], v[160:163], v[200:203], v[22:25]
	v_mfma_f32_16x16x32_bf16 v[14:17], v[152:155], v[208:211], v[14:17]
	v_mfma_f32_16x16x32_bf16 v[6:9], v[160:163], v[208:211], v[6:9]
	v_mfma_f32_16x16x32_bf16 v[62:65], v[156:159], v[188:191], v[62:65]
	v_mfma_f32_16x16x32_bf16 v[54:57], v[164:167], v[188:191], v[54:57]
	v_mfma_f32_16x16x32_bf16 v[46:49], v[156:159], v[196:199], v[46:49]
	v_mfma_f32_16x16x32_bf16 v[38:41], v[164:167], v[196:199], v[38:41]
	v_mfma_f32_16x16x32_bf16 v[30:33], v[156:159], v[204:207], v[30:33]
	v_mfma_f32_16x16x32_bf16 v[22:25], v[164:167], v[204:207], v[22:25]
	v_mfma_f32_16x16x32_bf16 v[14:17], v[156:159], v[212:215], v[14:17]
	v_mfma_f32_16x16x32_bf16 v[6:9], v[164:167], v[212:215], v[6:9]
	v_mfma_f32_16x16x32_bf16 v[58:61], v[168:171], v[184:187], v[58:61]
	v_mfma_f32_16x16x32_bf16 v[50:53], v[176:179], v[184:187], v[50:53]
	v_mfma_f32_16x16x32_bf16 v[42:45], v[168:171], v[192:195], v[42:45]
	v_mfma_f32_16x16x32_bf16 v[34:37], v[176:179], v[192:195], v[34:37]
	v_mfma_f32_16x16x32_bf16 v[26:29], v[168:171], v[200:203], v[26:29]
	v_mfma_f32_16x16x32_bf16 v[18:21], v[176:179], v[200:203], v[18:21]
	v_mfma_f32_16x16x32_bf16 v[10:13], v[168:171], v[208:211], v[10:13]
	v_mfma_f32_16x16x32_bf16 v[2:5], v[176:179], v[208:211], v[2:5]
	v_mfma_f32_16x16x32_bf16 v[58:61], v[172:175], v[188:191], v[58:61]
	v_mfma_f32_16x16x32_bf16 v[50:53], v[180:183], v[188:191], v[50:53]
	v_mfma_f32_16x16x32_bf16 v[42:45], v[172:175], v[196:199], v[42:45]
	v_mfma_f32_16x16x32_bf16 v[34:37], v[180:183], v[196:199], v[34:37]
	v_mfma_f32_16x16x32_bf16 v[26:29], v[172:175], v[204:207], v[26:29]
	v_mfma_f32_16x16x32_bf16 v[18:21], v[180:183], v[204:207], v[18:21]
	v_mfma_f32_16x16x32_bf16 v[10:13], v[172:175], v[212:215], v[10:13]
	v_mfma_f32_16x16x32_bf16 v[2:5], v[180:183], v[212:215], v[2:5]
	s_barrier
	s_add_i32 s59, 0, 0x18000
	v_add_u32_e32 v151, s59, v146
	s_add_i32 s60, 0, 0x1c000
	ds_read_b128 v[152:155], v151
	ds_read_b128 v[156:159], v151 offset:1024
	ds_read_b128 v[160:163], v151 offset:2048
	ds_read_b128 v[164:167], v151 offset:3072
	v_add_u32_e32 v151, s60, v146
	ds_read_b128 v[168:171], v151
	ds_read_b128 v[172:175], v151 offset:1024
	ds_read_b128 v[176:179], v151 offset:2048
	ds_read_b128 v[180:183], v151 offset:3072
	s_add_u32 s26, s26, s8
	s_addc_u32 s27, s27, s9
	s_mov_b32 m0, s38
	v_lshl_add_u64 v[228:229], s[26:27], 0, v[136:137]
	ds_read_b128 v[184:187], v150 offset:32768
	ds_read_b128 v[188:191], v150 offset:33792
	ds_read_b128 v[192:195], v150 offset:34816
	ds_read_b128 v[196:199], v150 offset:35840
	ds_read_b128 v[200:203], v150 offset:36864
	ds_read_b128 v[204:207], v150 offset:37888
	ds_read_b128 v[208:211], v150 offset:38912
	ds_read_b128 v[212:215], v150 offset:39936
	global_load_lds_dwordx4 v[228:229], off
	v_lshl_add_u64 v[228:229], s[26:27], 0, v[132:133]
	s_mov_b32 m0, s39
	s_nop 0
	global_load_lds_dwordx4 v[228:229], off
	s_waitcnt vmcnt(8)
	s_waitcnt lgkmcnt(0)
	s_barrier
	v_mfma_f32_16x16x32_bf16 v[122:125], v[152:155], v[184:187], v[122:125]
	v_mfma_f32_16x16x32_bf16 v[118:121], v[160:163], v[184:187], v[118:121]
	v_mfma_f32_16x16x32_bf16 v[110:113], v[152:155], v[192:195], v[110:113]
	v_mfma_f32_16x16x32_bf16 v[102:105], v[160:163], v[192:195], v[102:105]
	v_mfma_f32_16x16x32_bf16 v[94:97], v[152:155], v[200:203], v[94:97]
	v_mfma_f32_16x16x32_bf16 v[86:89], v[160:163], v[200:203], v[86:89]
	v_mfma_f32_16x16x32_bf16 v[78:81], v[152:155], v[208:211], v[78:81]
	v_mfma_f32_16x16x32_bf16 v[70:73], v[160:163], v[208:211], v[70:73]
	v_mfma_f32_16x16x32_bf16 v[122:125], v[156:159], v[188:191], v[122:125]
	v_mfma_f32_16x16x32_bf16 v[118:121], v[164:167], v[188:191], v[118:121]
	v_mfma_f32_16x16x32_bf16 v[110:113], v[156:159], v[196:199], v[110:113]
	v_mfma_f32_16x16x32_bf16 v[102:105], v[164:167], v[196:199], v[102:105]
	v_mfma_f32_16x16x32_bf16 v[94:97], v[156:159], v[204:207], v[94:97]
	v_mfma_f32_16x16x32_bf16 v[86:89], v[164:167], v[204:207], v[86:89]
	v_mfma_f32_16x16x32_bf16 v[78:81], v[156:159], v[212:215], v[78:81]
	v_mfma_f32_16x16x32_bf16 v[70:73], v[164:167], v[212:215], v[70:73]
	v_mfma_f32_16x16x32_bf16 v[126:129], v[168:171], v[184:187], v[126:129]
	v_mfma_f32_16x16x32_bf16 v[114:117], v[176:179], v[184:187], v[114:117]
	v_mfma_f32_16x16x32_bf16 v[106:109], v[168:171], v[192:195], v[106:109]
	v_mfma_f32_16x16x32_bf16 v[98:101], v[176:179], v[192:195], v[98:101]
	v_mfma_f32_16x16x32_bf16 v[90:93], v[168:171], v[200:203], v[90:93]
	v_mfma_f32_16x16x32_bf16 v[82:85], v[176:179], v[200:203], v[82:85]
	v_mfma_f32_16x16x32_bf16 v[74:77], v[168:171], v[208:211], v[74:77]
	v_mfma_f32_16x16x32_bf16 v[66:69], v[176:179], v[208:211], v[66:69]
	v_mfma_f32_16x16x32_bf16 v[126:129], v[172:175], v[188:191], v[126:129]
	v_mfma_f32_16x16x32_bf16 v[114:117], v[180:183], v[188:191], v[114:117]
	v_mfma_f32_16x16x32_bf16 v[106:109], v[172:175], v[196:199], v[106:109]
	v_mfma_f32_16x16x32_bf16 v[98:101], v[180:183], v[196:199], v[98:101]
	v_mfma_f32_16x16x32_bf16 v[90:93], v[172:175], v[204:207], v[90:93]
	v_mfma_f32_16x16x32_bf16 v[82:85], v[180:183], v[204:207], v[82:85]
	v_mfma_f32_16x16x32_bf16 v[74:77], v[172:175], v[212:215], v[74:77]
	v_mfma_f32_16x16x32_bf16 v[66:69], v[180:183], v[212:215], v[66:69]
	s_barrier
; #define PG8_STAGE(bufoff, gbase, voff) do { _Pragma("unroll") for (int _i = 0; _i < 2; ++_i) \
;         __builtin_amdgcn_global_load_lds((const unsigned*)((const char*)(gbase) + (voff)[_i]), (PG8_LAS unsigned*)(lds + (bufoff) + ldsw + _i * 8192), 16, 0, 0); } while (0)
; #define PG8_LDA(dst, b, h) do { _Pragma("unroll") for (int m = 0; m < 4; ++m) _Pragma("unroll") for (int k = 0; k < 2; ++k) dst[m][k] = *(const PG8_LAS bf16x8*)(lds + PG8_SA(b, h) + aoff + m * 2048 + k * 1024); } while (0)
; #define PG8_MMA(ai, bj, At, Bt) do { __builtin_amdgcn_s_setprio(1); _Pragma("unroll") for (int m = 0; m < 4; ++m) _Pragma("unroll") for (int n = 0; n < 2; ++n) _Pragma("unroll") for (int k = 0; k < 2; ++k) \
;         acc[ai][bj][m][n] = __builtin_amdgcn_mfma_f32_16x16x32_bf16(Bt[n][k], At[m][k], acc[ai][bj][m][n], 0, 0, 0); __builtin_amdgcn_s_setprio(0); } while (0)
; #define PG8_WAIT_V(n) asm volatile("s_waitcnt vmcnt(" #n ")" ::: "memory")
; #define PG8_WAIT_L(n) asm volatile("s_waitcnt lgkmcnt(" #n ")" ::: "memory")
; #define PG8_BAR __builtin_amdgcn_s_barrier()
; #define PG8_SCHED __builtin_amdgcn_sched_barrier(0)
; template <class Epi, class Sched, bool ALIGN_EPI = false, bool SP2 = false>
; __device__ __forceinline__ void gemm_phase(PG8_LAS unsigned char* lds, const Gemm g, const Sched& S, const Epi& E) {
;     ...
;         for (int t = 0; t < nt; t += 2) {
;             const bool last = (t == nt - 2);
;             const char* a1 = cA + (size_t)(t + 1) * kstep;
;             const char* a2 = last ? nA : cA + (size_t)(t + 2) * kstep; const char* b2 = last ? nB : cB + (size_t)(t + 2) * kstep;
;             const char* a3 = a2 + kstep; const char* b3 = b2 + kstep;
;     ...
;             PG8_LDA(At, 1, 1); PG8_STAGE(PG8_SB(1, 0), b3, voffB); PG8_STAGE(PG8_SB(1, 1), b3 + hstep, voffB); PG8_STAGE(PG8_SA(1, 0), a3, voffA);
;             PG8_WAIT_V(8); PG8_WAIT_L(0); PG8_BAR; PG8_MMA(1, 0, At, B0); PG8_MMA(1, 1, At, B1); PG8_BAR; PG8_SCHED;
	s_add_i32 s26, s59, s31
	v_lshl_add_u64 v[216:217], v[216:217], 0, s[16:17]
	s_mov_b32 m0, s26
	ds_read_b128 v[184:187], v150 offset:49152
	ds_read_b128 v[188:191], v150 offset:50176
	ds_read_b128 v[192:195], v150 offset:51200
	ds_read_b128 v[196:199], v150 offset:52224
	ds_read_b128 v[200:203], v150 offset:53248
	ds_read_b128 v[204:207], v150 offset:54272
	ds_read_b128 v[208:211], v150 offset:55296
	ds_read_b128 v[212:215], v150 offset:56320
	global_load_lds_dwordx4 v[216:217], off
	v_lshl_add_u64 v[216:217], v[218:219], 0, s[16:17]
	s_add_i32 m0, s26, 0x2000
	s_add_i32 s26, s60, s31
	global_load_lds_dwordx4 v[216:217], off
	v_lshl_add_u64 v[216:217], v[220:221], 0, s[16:17]
	s_mov_b32 m0, s26
	s_nop 0
	global_load_lds_dwordx4 v[216:217], off
	v_lshl_add_u64 v[216:217], v[222:223], 0, s[16:17]
	s_add_i32 m0, s26, 0x2000
	s_nop 0
	global_load_lds_dwordx4 v[216:217], off
	v_lshl_add_u64 v[216:217], v[224:225], 0, s[16:17]
	s_mov_b32 m0, s41
	s_nop 0
	global_load_lds_dwordx4 v[216:217], off
	v_lshl_add_u64 v[216:217], v[226:227], 0, s[16:17]
	s_mov_b32 m0, s42
	s_nop 0
	global_load_lds_dwordx4 v[216:217], off
	s_waitcnt vmcnt(8)
	s_waitcnt lgkmcnt(0)
	s_barrier
	v_mfma_f32_16x16x32_bf16 v[62:65], v[152:155], v[184:187], v[62:65]
	v_mfma_f32_16x16x32_bf16 v[54:57], v[160:163], v[184:187], v[54:57]
	v_mfma_f32_16x16x32_bf16 v[46:49], v[152:155], v[192:195], v[46:49]
	v_mfma_f32_16x16x32_bf16 v[38:41], v[160:163], v[192:195], v[38:41]
	v_mfma_f32_16x16x32_bf16 v[30:33], v[152:155], v[200:203], v[30:33]
	v_mfma_f32_16x16x32_bf16 v[22:25], v[160:163], v[200:203], v[22:25]
	v_mfma_f32_16x16x32_bf16 v[14:17], v[152:155], v[208:211], v[14:17]
	v_mfma_f32_16x16x32_bf16 v[6:9], v[160:163], v[208:211], v[6:9]
	v_mfma_f32_16x16x32_bf16 v[62:65], v[156:159], v[188:191], v[62:65]
	v_mfma_f32_16x16x32_bf16 v[54:57], v[164:167], v[188:191], v[54:57]
	v_mfma_f32_16x16x32_bf16 v[46:49], v[156:159], v[196:199], v[46:49]
	v_mfma_f32_16x16x32_bf16 v[38:41], v[164:167], v[196:199], v[38:41]
	v_mfma_f32_16x16x32_bf16 v[30:33], v[156:159], v[204:207], v[30:33]
	v_mfma_f32_16x16x32_bf16 v[22:25], v[164:167], v[204:207], v[22:25]
	v_mfma_f32_16x16x32_bf16 v[14:17], v[156:159], v[212:215], v[14:17]
	v_mfma_f32_16x16x32_bf16 v[6:9], v[164:167], v[212:215], v[6:9]
	v_mfma_f32_16x16x32_bf16 v[58:61], v[168:171], v[184:187], v[58:61]
	v_mfma_f32_16x16x32_bf16 v[50:53], v[176:179], v[184:187], v[50:53]
	v_mfma_f32_16x16x32_bf16 v[42:45], v[168:171], v[192:195], v[42:45]
	v_mfma_f32_16x16x32_bf16 v[34:37], v[176:179], v[192:195], v[34:37]
	v_mfma_f32_16x16x32_bf16 v[26:29], v[168:171], v[200:203], v[26:29]
	v_mfma_f32_16x16x32_bf16 v[18:21], v[176:179], v[200:203], v[18:21]
	v_mfma_f32_16x16x32_bf16 v[10:13], v[168:171], v[208:211], v[10:13]
	v_mfma_f32_16x16x32_bf16 v[2:5], v[176:179], v[208:211], v[2:5]
	v_mfma_f32_16x16x32_bf16 v[58:61], v[172:175], v[188:191], v[58:61]
	v_mfma_f32_16x16x32_bf16 v[50:53], v[180:183], v[188:191], v[50:53]
	v_mfma_f32_16x16x32_bf16 v[42:45], v[172:175], v[196:199], v[42:45]
	v_mfma_f32_16x16x32_bf16 v[34:37], v[180:183], v[196:199], v[34:37]
	v_mfma_f32_16x16x32_bf16 v[26:29], v[172:175], v[204:207], v[26:29]
	v_mfma_f32_16x16x32_bf16 v[18:21], v[180:183], v[204:207], v[18:21]
	v_mfma_f32_16x16x32_bf16 v[10:13], v[172:175], v[212:215], v[10:13]
	v_mfma_f32_16x16x32_bf16 v[2:5], v[180:183], v[212:215], v[2:5]
	s_barrier
	s_add_u32 s56, s56, 0x100
	s_addc_u32 s57, s57, 0
	s_add_u32 s24, s24, 0x100
	s_addc_u32 s25, s25, 0
	s_cmp_ge_i32 s58, s43
	s_mov_b32 s26, s58
	s_cbranch_scc0 .LBB0_1976
